# GEMM K-loops (16 instances): LDS-DMA source addresses via scalar base + 32-bit lane offset (no 64-bit VALU adds), second K-tile via offset:128 with M0-128, dropped redundant setprio pairs / duplicate
# speedup vs baseline: 1.0597x; 1.0055x over previous
; #define PG8_STAGE(bufoff, gbase, voff) do { _Pragma("unroll") for (int _i = 0; _i < 2; ++_i) \
;         __builtin_amdgcn_global_load_lds((const unsigned*)((const char*)(gbase) + (voff)[_i]), (PG8_LAS unsigned*)(lds + (bufoff) + ldsw + _i * 8192), 16, 0, 0); } while (0)
; #define PG8_LDA(dst, b, h) do { _Pragma("unroll") for (int m = 0; m < 4; ++m) _Pragma("unroll") for (int k = 0; k < 2; ++k) dst[m][k] = *(const PG8_LAS bf16x8*)(lds + PG8_SA(b, h) + aoff + m * 2048 + k * 1024); } while (0)
; #define PG8_LDB(dst, b, h) do { _Pragma("unroll") for (int n = 0; n < 2; ++n) _Pragma("unroll") for (int k = 0; k < 2; ++k) dst[n][k] = *(const PG8_LAS bf16x8*)(lds + PG8_SB(b, h) + boff + n * 2048 + k * 1024); } while (0)
; #define PG8_MMA(ai, bj, At, Bt) do { __builtin_amdgcn_s_setprio(1); _Pragma("unroll") for (int m = 0; m < 4; ++m) _Pragma("unroll") for (int n = 0; n < 2; ++n) _Pragma("unroll") for (int k = 0; k < 2; ++k) \
;         acc[ai][bj][m][n] = __builtin_amdgcn_mfma_f32_16x16x32_bf16(Bt[n][k], At[m][k], acc[ai][bj][m][n], 0, 0, 0); __builtin_amdgcn_s_setprio(0); } while (0)
; #define PG8_WAIT_V(n) asm volatile("s_waitcnt vmcnt(" #n ")" ::: "memory")
; #define PG8_BAR __builtin_amdgcn_s_barrier()
; template <class Epi, class Sched, bool ALIGN_EPI = false, bool SP2 = false>
; __device__ __forceinline__ void gemm_phase(PG8_LAS unsigned char* lds, const Gemm g, const Sched& S, const Epi& E) {
;     ...
;         for (int t = 0; t < nt; t += 2) {
;             const bool last = (t == nt - 2);
;             const char* a1 = cA + (size_t)(t + 1) * kstep;
;             const char* a2 = last ? nA : cA + (size_t)(t + 2) * kstep; const char* b2 = last ? nB : cB + (size_t)(t + 2) * kstep;
;             const char* a3 = a2 + kstep; const char* b3 = b2 + kstep;
;             if (last && has_next) S.a_ready(nxt);
;             if constexpr (SP2) {
;             PG8_LDB(B0, 0, 0); PG8_LDB(B1, 0, 1); PG8_SCHED; PG8_LDA(At, 0, 0); PG8_STAGE(PG8_SA(1, 1), a1 + hstepA, voffA);
;             PG8_WAIT_V(8); PG8_WAIT_L(0); PG8_BAR; PG8_MMA(0, 0, At, B0); PG8_MMA(0, 1, At, B1); PG8_BAR; PG8_SCHED;
;             PG8_LDA(At, 0, 1); PG8_STAGE(PG8_SB(0, 0), b2, voffB); PG8_STAGE(PG8_SB(0, 1), b2 + hstep, voffB); PG8_STAGE(PG8_SA(0, 0), a2, voffA);
;             PG8_WAIT_V(8); PG8_WAIT_L(0); PG8_BAR; PG8_MMA(1, 0, At, B0); PG8_MMA(1, 1, At, B1); PG8_BAR; PG8_SCHED;
.LBB0_258:
	ds_read_b128 v[164:167], v161
	ds_read_b128 v[168:171], v161 offset:1024
	ds_read_b128 v[172:175], v161 offset:2048
	ds_read_b128 v[176:179], v161 offset:3072
	ds_read_b128 v[180:183], v162
	ds_read_b128 v[184:187], v162 offset:1024
	ds_read_b128 v[190:193], v162 offset:2048
	ds_read_b128 v[194:197], v162 offset:3072
	s_add_i32 s65, s36, 2
	s_add_u32 s66, s10, 0xfffc0080
	s_addc_u32 s37, s11, -1
	s_cmp_eq_u32 s56, s36
	s_cselect_b32 s36, s64, s66
	s_cselect_b32 s37, s29, s37
	s_cselect_b32 s67, s31, s39
	s_cselect_b32 s66, s30, s38
	s_add_i32 m0, s48, 0xc000
	ds_read_b128 v[198:201], v163
	ds_read_b128 v[202:205], v163 offset:1024
	ds_read_b128 v[206:209], v163 offset:2048
	ds_read_b128 v[210:213], v163 offset:3072
	ds_read_b128 v[214:217], v163 offset:4096
	ds_read_b128 v[218:221], v163 offset:5120
	ds_read_b128 v[222:225], v163 offset:6144
	ds_read_b128 v[226:229], v163 offset:7168
	global_load_lds_dwordx4 v138, s[10:11]
	s_add_i32 m0, s48, 0xe000
	s_nop 0
	global_load_lds_dwordx4 v142, s[10:11]
	s_waitcnt vmcnt(8)
	s_waitcnt lgkmcnt(0)
	s_barrier
	s_setprio 1
	v_mfma_f32_16x16x32_bf16 v[124:127], v[164:167], v[198:201], v[124:127]
	v_mfma_f32_16x16x32_bf16 v[120:123], v[172:175], v[198:201], v[120:123]
	v_mfma_f32_16x16x32_bf16 v[108:111], v[164:167], v[206:209], v[108:111]
	v_mfma_f32_16x16x32_bf16 v[104:107], v[172:175], v[206:209], v[104:107]
	v_mfma_f32_16x16x32_bf16 v[92:95], v[164:167], v[214:217], v[92:95]
	v_mfma_f32_16x16x32_bf16 v[88:91], v[172:175], v[214:217], v[88:91]
	v_mfma_f32_16x16x32_bf16 v[76:79], v[164:167], v[222:225], v[76:79]
	v_mfma_f32_16x16x32_bf16 v[72:75], v[172:175], v[222:225], v[72:75]
	v_mfma_f32_16x16x32_bf16 v[124:127], v[168:171], v[202:205], v[124:127]
	v_mfma_f32_16x16x32_bf16 v[120:123], v[176:179], v[202:205], v[120:123]
	v_mfma_f32_16x16x32_bf16 v[108:111], v[168:171], v[210:213], v[108:111]
	v_mfma_f32_16x16x32_bf16 v[104:107], v[176:179], v[210:213], v[104:107]
	v_mfma_f32_16x16x32_bf16 v[92:95], v[168:171], v[218:221], v[92:95]
	v_mfma_f32_16x16x32_bf16 v[88:91], v[176:179], v[218:221], v[88:91]
	v_mfma_f32_16x16x32_bf16 v[76:79], v[168:171], v[226:229], v[76:79]
	v_mfma_f32_16x16x32_bf16 v[72:75], v[176:179], v[226:229], v[72:75]
	v_mfma_f32_16x16x32_bf16 v[116:119], v[180:183], v[198:201], v[116:119]
	v_mfma_f32_16x16x32_bf16 v[112:115], v[190:193], v[198:201], v[112:115]
	v_mfma_f32_16x16x32_bf16 v[100:103], v[180:183], v[206:209], v[100:103]
	v_mfma_f32_16x16x32_bf16 v[96:99], v[190:193], v[206:209], v[96:99]
	v_mfma_f32_16x16x32_bf16 v[84:87], v[180:183], v[214:217], v[84:87]
	v_mfma_f32_16x16x32_bf16 v[80:83], v[190:193], v[214:217], v[80:83]
	v_mfma_f32_16x16x32_bf16 v[68:71], v[180:183], v[222:225], v[68:71]
	v_mfma_f32_16x16x32_bf16 v[64:67], v[190:193], v[222:225], v[64:67]
	v_mfma_f32_16x16x32_bf16 v[116:119], v[184:187], v[202:205], v[116:119]
	v_mfma_f32_16x16x32_bf16 v[112:115], v[194:197], v[202:205], v[112:115]
	v_mfma_f32_16x16x32_bf16 v[100:103], v[184:187], v[210:213], v[100:103]
	v_mfma_f32_16x16x32_bf16 v[96:99], v[194:197], v[210:213], v[96:99]
	v_mfma_f32_16x16x32_bf16 v[84:87], v[184:187], v[218:221], v[84:87]
	v_mfma_f32_16x16x32_bf16 v[80:83], v[194:197], v[218:221], v[80:83]
	v_mfma_f32_16x16x32_bf16 v[68:71], v[184:187], v[226:229], v[68:71]
	v_mfma_f32_16x16x32_bf16 v[64:67], v[194:197], v[226:229], v[64:67]
	s_setprio 0
	s_barrier
	s_add_i32 s68, s57, s47
	s_mov_b32 m0, s68
	ds_read_b128 v[198:201], v163 offset:16384
	ds_read_b128 v[202:205], v163 offset:17408
	ds_read_b128 v[206:209], v163 offset:18432
	ds_read_b128 v[210:213], v163 offset:19456
	ds_read_b128 v[214:217], v163 offset:20480
	ds_read_b128 v[218:221], v163 offset:21504
	ds_read_b128 v[222:225], v163 offset:22528
	ds_read_b128 v[226:229], v163 offset:23552
	global_load_lds_dwordx4 v136, s[66:67]
	s_add_i32 m0, s68, 0x2000
	s_mov_b64 s[100:101], s[66:67]
	s_add_i32 s68, s58, s47
	global_load_lds_dwordx4 v134, s[66:67]
	s_add_u32 s66, s66, s16
	s_addc_u32 s67, s67, s17
	s_mov_b32 m0, s68
	s_nop 0
	global_load_lds_dwordx4 v136, s[66:67]
	s_add_i32 m0, s68, 0x2000
	s_nop 0
	global_load_lds_dwordx4 v134, s[66:67]
	s_mov_b32 m0, s48
	s_nop 0
	global_load_lds_dwordx4 v128, s[36:37]
	s_mov_b32 m0, s49
	s_nop 0
	global_load_lds_dwordx4 v130, s[36:37]
	s_waitcnt vmcnt(8)
	s_waitcnt lgkmcnt(0)
	s_barrier
	s_setprio 1
	v_mfma_f32_16x16x32_bf16 v[60:63], v[164:167], v[198:201], v[60:63]
	v_mfma_f32_16x16x32_bf16 v[56:59], v[172:175], v[198:201], v[56:59]
	v_mfma_f32_16x16x32_bf16 v[44:47], v[164:167], v[206:209], v[44:47]
	v_mfma_f32_16x16x32_bf16 v[40:43], v[172:175], v[206:209], v[40:43]
	v_mfma_f32_16x16x32_bf16 v[28:31], v[164:167], v[214:217], v[28:31]
	v_mfma_f32_16x16x32_bf16 v[24:27], v[172:175], v[214:217], v[24:27]
	v_mfma_f32_16x16x32_bf16 v[12:15], v[164:167], v[222:225], v[12:15]
	v_mfma_f32_16x16x32_bf16 v[8:11], v[172:175], v[222:225], v[8:11]
	v_mfma_f32_16x16x32_bf16 v[60:63], v[168:171], v[202:205], v[60:63]
	v_mfma_f32_16x16x32_bf16 v[56:59], v[176:179], v[202:205], v[56:59]
	v_mfma_f32_16x16x32_bf16 v[44:47], v[168:171], v[210:213], v[44:47]
	v_mfma_f32_16x16x32_bf16 v[40:43], v[176:179], v[210:213], v[40:43]
	v_mfma_f32_16x16x32_bf16 v[28:31], v[168:171], v[218:221], v[28:31]
	v_mfma_f32_16x16x32_bf16 v[24:27], v[176:179], v[218:221], v[24:27]
	v_mfma_f32_16x16x32_bf16 v[12:15], v[168:171], v[226:229], v[12:15]
	v_mfma_f32_16x16x32_bf16 v[8:11], v[176:179], v[226:229], v[8:11]
	v_mfma_f32_16x16x32_bf16 v[52:55], v[180:183], v[198:201], v[52:55]
	v_mfma_f32_16x16x32_bf16 v[48:51], v[190:193], v[198:201], v[48:51]
	v_mfma_f32_16x16x32_bf16 v[36:39], v[180:183], v[206:209], v[36:39]
	v_mfma_f32_16x16x32_bf16 v[32:35], v[190:193], v[206:209], v[32:35]
	v_mfma_f32_16x16x32_bf16 v[20:23], v[180:183], v[214:217], v[20:23]
	v_mfma_f32_16x16x32_bf16 v[16:19], v[190:193], v[214:217], v[16:19]
	v_mfma_f32_16x16x32_bf16 v[4:7], v[180:183], v[222:225], v[4:7]
	v_mfma_f32_16x16x32_bf16 v[0:3], v[190:193], v[222:225], v[0:3]
	v_mfma_f32_16x16x32_bf16 v[52:55], v[184:187], v[202:205], v[52:55]
	v_mfma_f32_16x16x32_bf16 v[48:51], v[194:197], v[202:205], v[48:51]
	v_mfma_f32_16x16x32_bf16 v[36:39], v[184:187], v[210:213], v[36:39]
	v_mfma_f32_16x16x32_bf16 v[32:35], v[194:197], v[210:213], v[32:35]
	v_mfma_f32_16x16x32_bf16 v[20:23], v[184:187], v[218:221], v[20:23]
	v_mfma_f32_16x16x32_bf16 v[16:19], v[194:197], v[218:221], v[16:19]
	v_mfma_f32_16x16x32_bf16 v[4:7], v[184:187], v[226:229], v[4:7]
	v_mfma_f32_16x16x32_bf16 v[0:3], v[194:197], v[226:229], v[0:3]
	s_setprio 0
	s_barrier
; #define PG8_STAGE(bufoff, gbase, voff) do { _Pragma("unroll") for (int _i = 0; _i < 2; ++_i) \
;         __builtin_amdgcn_global_load_lds((const unsigned*)((const char*)(gbase) + (voff)[_i]), (PG8_LAS unsigned*)(lds + (bufoff) + ldsw + _i * 8192), 16, 0, 0); } while (0)
; #define PG8_LDA(dst, b, h) do { _Pragma("unroll") for (int m = 0; m < 4; ++m) _Pragma("unroll") for (int k = 0; k < 2; ++k) dst[m][k] = *(const PG8_LAS bf16x8*)(lds + PG8_SA(b, h) + aoff + m * 2048 + k * 1024); } while (0)
; #define PG8_LDB(dst, b, h) do { _Pragma("unroll") for (int n = 0; n < 2; ++n) _Pragma("unroll") for (int k = 0; k < 2; ++k) dst[n][k] = *(const PG8_LAS bf16x8*)(lds + PG8_SB(b, h) + boff + n * 2048 + k * 1024); } while (0)
; #define PG8_MMA(ai, bj, At, Bt) do { __builtin_amdgcn_s_setprio(1); _Pragma("unroll") for (int m = 0; m < 4; ++m) _Pragma("unroll") for (int n = 0; n < 2; ++n) _Pragma("unroll") for (int k = 0; k < 2; ++k) \
;         acc[ai][bj][m][n] = __builtin_amdgcn_mfma_f32_16x16x32_bf16(Bt[n][k], At[m][k], acc[ai][bj][m][n], 0, 0, 0); __builtin_amdgcn_s_setprio(0); } while (0)
; #define PG8_WAIT_V(n) asm volatile("s_waitcnt vmcnt(" #n ")" ::: "memory")
; #define PG8_WAIT_L(n) asm volatile("s_waitcnt lgkmcnt(" #n ")" ::: "memory")
; #define PG8_BAR __builtin_amdgcn_s_barrier()
; #define PG8_SCHED __builtin_amdgcn_sched_barrier(0)
; template <class Epi, class Sched, bool ALIGN_EPI = false, bool SP2 = false>
; __device__ __forceinline__ void gemm_phase(PG8_LAS unsigned char* lds, const Gemm g, const Sched& S, const Epi& E) {
;     ...
;             PG8_LDB(B0, 1, 0); PG8_LDB(B1, 1, 1); PG8_SCHED; PG8_LDA(At, 1, 0); PG8_STAGE(PG8_SA(0, 1), a2 + hstepA, voffA);
;             PG8_WAIT_V(8); PG8_WAIT_L(0); PG8_BAR; PG8_MMA(0, 0, At, B0); PG8_MMA(0, 1, At, B1); PG8_BAR; PG8_SCHED;
;             PG8_LDA(At, 1, 1); PG8_STAGE(PG8_SB(1, 0), b3, voffB); PG8_STAGE(PG8_SB(1, 1), b3 + hstep, voffB); PG8_STAGE(PG8_SA(1, 0), a3, voffA);
;             PG8_WAIT_V(8); PG8_WAIT_L(0); PG8_BAR; PG8_MMA(1, 0, At, B0); PG8_MMA(1, 1, At, B1); PG8_BAR; PG8_SCHED;
	s_add_i32 s66, 0, 0x18000
	s_add_i32 s67, 0, 0x1c000
	v_add_u32_e32 v176, s66, v159
	v_add_u32_e32 v189, s67, v159
	ds_read_b128 v[164:167], v176
	ds_read_b128 v[168:171], v176 offset:1024
	ds_read_b128 v[172:175], v176 offset:2048
	ds_read_b128 v[176:179], v176 offset:3072
	ds_read_b128 v[180:183], v189
	ds_read_b128 v[184:187], v189 offset:1024
	ds_read_b128 v[190:193], v189 offset:2048
	ds_read_b128 v[194:197], v189 offset:3072
	s_mov_b64 vcc, s[36:37]
	s_add_u32 s36, s36, 0x40000
	s_addc_u32 s37, s37, 0
	s_mov_b32 m0, s50
	ds_read_b128 v[198:201], v163 offset:32768
	ds_read_b128 v[202:205], v163 offset:33792
	ds_read_b128 v[206:209], v163 offset:34816
	ds_read_b128 v[210:213], v163 offset:35840
	ds_read_b128 v[214:217], v163 offset:36864
	ds_read_b128 v[218:221], v163 offset:37888
	ds_read_b128 v[222:225], v163 offset:38912
	ds_read_b128 v[226:229], v163 offset:39936
	global_load_lds_dwordx4 v128, s[36:37]
	s_mov_b32 m0, s51
	s_nop 0
	global_load_lds_dwordx4 v130, s[36:37]
	s_waitcnt vmcnt(8)
	s_waitcnt lgkmcnt(0)
	s_barrier
	s_setprio 1
	v_mfma_f32_16x16x32_bf16 v[124:127], v[164:167], v[198:201], v[124:127]
	v_mfma_f32_16x16x32_bf16 v[120:123], v[172:175], v[198:201], v[120:123]
	v_mfma_f32_16x16x32_bf16 v[108:111], v[164:167], v[206:209], v[108:111]
	v_mfma_f32_16x16x32_bf16 v[104:107], v[172:175], v[206:209], v[104:107]
	v_mfma_f32_16x16x32_bf16 v[92:95], v[164:167], v[214:217], v[92:95]
	v_mfma_f32_16x16x32_bf16 v[88:91], v[172:175], v[214:217], v[88:91]
	v_mfma_f32_16x16x32_bf16 v[76:79], v[164:167], v[222:225], v[76:79]
	v_mfma_f32_16x16x32_bf16 v[72:75], v[172:175], v[222:225], v[72:75]
	v_mfma_f32_16x16x32_bf16 v[124:127], v[168:171], v[202:205], v[124:127]
	v_mfma_f32_16x16x32_bf16 v[120:123], v[176:179], v[202:205], v[120:123]
	v_mfma_f32_16x16x32_bf16 v[108:111], v[168:171], v[210:213], v[108:111]
	v_mfma_f32_16x16x32_bf16 v[104:107], v[176:179], v[210:213], v[104:107]
	v_mfma_f32_16x16x32_bf16 v[92:95], v[168:171], v[218:221], v[92:95]
	v_mfma_f32_16x16x32_bf16 v[88:91], v[176:179], v[218:221], v[88:91]
	v_mfma_f32_16x16x32_bf16 v[76:79], v[168:171], v[226:229], v[76:79]
	v_mfma_f32_16x16x32_bf16 v[72:75], v[176:179], v[226:229], v[72:75]
	v_mfma_f32_16x16x32_bf16 v[116:119], v[180:183], v[198:201], v[116:119]
	v_mfma_f32_16x16x32_bf16 v[112:115], v[190:193], v[198:201], v[112:115]
	v_mfma_f32_16x16x32_bf16 v[100:103], v[180:183], v[206:209], v[100:103]
	v_mfma_f32_16x16x32_bf16 v[96:99], v[190:193], v[206:209], v[96:99]
	v_mfma_f32_16x16x32_bf16 v[84:87], v[180:183], v[214:217], v[84:87]
	v_mfma_f32_16x16x32_bf16 v[80:83], v[190:193], v[214:217], v[80:83]
	v_mfma_f32_16x16x32_bf16 v[68:71], v[180:183], v[222:225], v[68:71]
	v_mfma_f32_16x16x32_bf16 v[64:67], v[190:193], v[222:225], v[64:67]
	v_mfma_f32_16x16x32_bf16 v[116:119], v[184:187], v[202:205], v[116:119]
	v_mfma_f32_16x16x32_bf16 v[112:115], v[194:197], v[202:205], v[112:115]
	v_mfma_f32_16x16x32_bf16 v[100:103], v[184:187], v[210:213], v[100:103]
	v_mfma_f32_16x16x32_bf16 v[96:99], v[194:197], v[210:213], v[96:99]
	v_mfma_f32_16x16x32_bf16 v[84:87], v[184:187], v[218:221], v[84:87]
	v_mfma_f32_16x16x32_bf16 v[80:83], v[194:197], v[218:221], v[80:83]
	v_mfma_f32_16x16x32_bf16 v[68:71], v[184:187], v[226:229], v[68:71]
	v_mfma_f32_16x16x32_bf16 v[64:67], v[194:197], v[226:229], v[64:67]
	s_setprio 0
	s_barrier
	s_add_i32 s36, s66, s47
	s_add_i32 m0, s36, 0xffffff80
	ds_read_b128 v[198:201], v163 offset:49152
	ds_read_b128 v[202:205], v163 offset:50176
	ds_read_b128 v[206:209], v163 offset:51200
	ds_read_b128 v[210:213], v163 offset:52224
	ds_read_b128 v[214:217], v163 offset:53248
	ds_read_b128 v[218:221], v163 offset:54272
	ds_read_b128 v[222:225], v163 offset:55296
	ds_read_b128 v[226:229], v163 offset:56320
	global_load_lds_dwordx4 v136, s[100:101] offset:128
	s_add_i32 m0, s36, 0x1f80
	s_add_i32 s36, s67, s47
	global_load_lds_dwordx4 v134, s[100:101] offset:128
	s_add_u32 s100, s100, s16
	s_addc_u32 s101, s101, s17
	s_add_i32 m0, s36, 0xffffff80
	s_nop 0
	global_load_lds_dwordx4 v136, s[100:101] offset:128
	s_add_i32 m0, s36, 0x1f80
	s_nop 0
	global_load_lds_dwordx4 v134, s[100:101] offset:128
	s_add_i32 m0, s52, 0xffffff80
	s_nop 0
	global_load_lds_dwordx4 v128, vcc offset:128
	s_add_i32 m0, s53, 0xffffff80
	s_nop 0
	global_load_lds_dwordx4 v130, vcc offset:128
	s_waitcnt vmcnt(8)
	s_waitcnt lgkmcnt(0)
	s_barrier
	s_setprio 1
	v_mfma_f32_16x16x32_bf16 v[60:63], v[164:167], v[198:201], v[60:63]
	v_mfma_f32_16x16x32_bf16 v[56:59], v[172:175], v[198:201], v[56:59]
	v_mfma_f32_16x16x32_bf16 v[44:47], v[164:167], v[206:209], v[44:47]
	v_mfma_f32_16x16x32_bf16 v[40:43], v[172:175], v[206:209], v[40:43]
	v_mfma_f32_16x16x32_bf16 v[28:31], v[164:167], v[214:217], v[28:31]
	v_mfma_f32_16x16x32_bf16 v[24:27], v[172:175], v[214:217], v[24:27]
	v_mfma_f32_16x16x32_bf16 v[12:15], v[164:167], v[222:225], v[12:15]
	v_mfma_f32_16x16x32_bf16 v[8:11], v[172:175], v[222:225], v[8:11]
	v_mfma_f32_16x16x32_bf16 v[60:63], v[168:171], v[202:205], v[60:63]
	v_mfma_f32_16x16x32_bf16 v[56:59], v[176:179], v[202:205], v[56:59]
	v_mfma_f32_16x16x32_bf16 v[44:47], v[168:171], v[210:213], v[44:47]
	v_mfma_f32_16x16x32_bf16 v[40:43], v[176:179], v[210:213], v[40:43]
	v_mfma_f32_16x16x32_bf16 v[28:31], v[168:171], v[218:221], v[28:31]
	v_mfma_f32_16x16x32_bf16 v[24:27], v[176:179], v[218:221], v[24:27]
	v_mfma_f32_16x16x32_bf16 v[12:15], v[168:171], v[226:229], v[12:15]
	v_mfma_f32_16x16x32_bf16 v[8:11], v[176:179], v[226:229], v[8:11]
	v_mfma_f32_16x16x32_bf16 v[52:55], v[180:183], v[198:201], v[52:55]
	v_mfma_f32_16x16x32_bf16 v[48:51], v[190:193], v[198:201], v[48:51]
	v_mfma_f32_16x16x32_bf16 v[36:39], v[180:183], v[206:209], v[36:39]
	v_mfma_f32_16x16x32_bf16 v[32:35], v[190:193], v[206:209], v[32:35]
	v_mfma_f32_16x16x32_bf16 v[20:23], v[180:183], v[214:217], v[20:23]
	v_mfma_f32_16x16x32_bf16 v[16:19], v[190:193], v[214:217], v[16:19]
	v_mfma_f32_16x16x32_bf16 v[4:7], v[180:183], v[222:225], v[4:7]
	v_mfma_f32_16x16x32_bf16 v[0:3], v[190:193], v[222:225], v[0:3]
	v_mfma_f32_16x16x32_bf16 v[52:55], v[184:187], v[202:205], v[52:55]
	v_mfma_f32_16x16x32_bf16 v[48:51], v[194:197], v[202:205], v[48:51]
	v_mfma_f32_16x16x32_bf16 v[36:39], v[184:187], v[210:213], v[36:39]
	v_mfma_f32_16x16x32_bf16 v[32:35], v[194:197], v[210:213], v[32:35]
	v_mfma_f32_16x16x32_bf16 v[20:23], v[184:187], v[218:221], v[20:23]
	v_mfma_f32_16x16x32_bf16 v[16:19], v[194:197], v[218:221], v[16:19]
	v_mfma_f32_16x16x32_bf16 v[4:7], v[184:187], v[226:229], v[4:7]
	v_mfma_f32_16x16x32_bf16 v[0:3], v[194:197], v[226:229], v[0:3]
	s_setprio 0
	s_barrier
	s_add_u32 s10, s10, 0x100
	s_addc_u32 s11, s11, 0
	s_add_u32 s38, s38, 0x100
	s_addc_u32 s39, s39, 0
	s_cmp_ge_i32 s65, s54
	s_mov_b32 s36, s65
	s_cbranch_scc0 .LBB0_258

; #define PG8_STAGE(bufoff, gbase, voff) do { _Pragma("unroll") for (int _i = 0; _i < 2; ++_i) \
;         __builtin_amdgcn_global_load_lds((const unsigned*)((const char*)(gbase) + (voff)[_i]), (PG8_LAS unsigned*)(lds + (bufoff) + ldsw + _i * 8192), 16, 0, 0); } while (0)
; #define PG8_LDA(dst, b, h) do { _Pragma("unroll") for (int m = 0; m < 4; ++m) _Pragma("unroll") for (int k = 0; k < 2; ++k) dst[m][k] = *(const PG8_LAS bf16x8*)(lds + PG8_SA(b, h) + aoff + m * 2048 + k * 1024); } while (0)
; #define PG8_LDB(dst, b, h) do { _Pragma("unroll") for (int n = 0; n < 2; ++n) _Pragma("unroll") for (int k = 0; k < 2; ++k) dst[n][k] = *(const PG8_LAS bf16x8*)(lds + PG8_SB(b, h) + boff + n * 2048 + k * 1024); } while (0)
; #define PG8_MMA(ai, bj, At, Bt) do { __builtin_amdgcn_s_setprio(1); _Pragma("unroll") for (int m = 0; m < 4; ++m) _Pragma("unroll") for (int n = 0; n < 2; ++n) _Pragma("unroll") for (int k = 0; k < 2; ++k) \
;         acc[ai][bj][m][n] = __builtin_amdgcn_mfma_f32_16x16x32_bf16(Bt[n][k], At[m][k], acc[ai][bj][m][n], 0, 0, 0); __builtin_amdgcn_s_setprio(0); } while (0)
; #define PG8_WAIT_V(n) asm volatile("s_waitcnt vmcnt(" #n ")" ::: "memory")
; #define PG8_BAR __builtin_amdgcn_s_barrier()
; template <class Epi, class Sched, bool ALIGN_EPI = false, bool SP2 = false>
; __device__ __forceinline__ void gemm_phase(PG8_LAS unsigned char* lds, const Gemm g, const Sched& S, const Epi& E) {
;     ...
;         for (int t = 0; t < nt; t += 2) {
;             const bool last = (t == nt - 2);
;             const char* a1 = cA + (size_t)(t + 1) * kstep;
;             const char* a2 = last ? nA : cA + (size_t)(t + 2) * kstep; const char* b2 = last ? nB : cB + (size_t)(t + 2) * kstep;
;             const char* a3 = a2 + kstep; const char* b3 = b2 + kstep;
;             if (last && has_next) S.a_ready(nxt);
;             if constexpr (SP2) {
;             PG8_LDB(B0, 0, 0); PG8_LDB(B1, 0, 1); PG8_SCHED; PG8_LDA(At, 0, 0); PG8_STAGE(PG8_SA(1, 1), a1 + hstepA, voffA);
;             PG8_WAIT_V(8); PG8_WAIT_L(0); PG8_BAR; PG8_MMA(0, 0, At, B0); PG8_MMA(0, 1, At, B1); PG8_BAR; PG8_SCHED;
;             PG8_LDA(At, 0, 1); PG8_STAGE(PG8_SB(0, 0), b2, voffB); PG8_STAGE(PG8_SB(0, 1), b2 + hstep, voffB); PG8_STAGE(PG8_SA(0, 0), a2, voffA);
;             PG8_WAIT_V(8); PG8_WAIT_L(0); PG8_BAR; PG8_MMA(1, 0, At, B0); PG8_MMA(1, 1, At, B1); PG8_BAR; PG8_SCHED;
.LBB0_282:
	ds_read_b128 v[148:151], v144
	ds_read_b128 v[152:155], v144 offset:1024
	ds_read_b128 v[156:159], v144 offset:2048
	ds_read_b128 v[160:163], v144 offset:3072
	ds_read_b128 v[164:167], v145
	ds_read_b128 v[168:171], v145 offset:1024
	ds_read_b128 v[172:175], v145 offset:2048
	ds_read_b128 v[176:179], v145 offset:3072
	s_add_i32 s61, s34, 2
	s_add_u32 s62, s30, 0xfffc0080
	s_addc_u32 s35, s31, -1
	s_cmp_eq_u32 s52, s34
	s_cselect_b32 s34, s36, s62
	s_cselect_b32 s35, s5, s35
	s_cselect_b32 s63, s27, s60
	s_cselect_b32 s62, s26, s37
	s_add_i32 m0, s33, 0xc000
	ds_read_b128 v[180:183], v146
	ds_read_b128 v[184:187], v146 offset:1024
	ds_read_b128 v[190:193], v146 offset:2048
	ds_read_b128 v[194:197], v146 offset:3072
	ds_read_b128 v[198:201], v146 offset:4096
	ds_read_b128 v[202:205], v146 offset:5120
	ds_read_b128 v[206:209], v146 offset:6144
	ds_read_b128 v[210:213], v146 offset:7168
	global_load_lds_dwordx4 v138, s[30:31]
	s_add_i32 m0, s33, 0xe000
	s_nop 0
	global_load_lds_dwordx4 v140, s[30:31]
	s_waitcnt vmcnt(8)
	s_waitcnt lgkmcnt(0)
	s_barrier
	s_setprio 1
	v_mfma_f32_16x16x32_bf16 v[124:127], v[148:151], v[180:183], v[124:127]
	v_mfma_f32_16x16x32_bf16 v[120:123], v[156:159], v[180:183], v[120:123]
	v_mfma_f32_16x16x32_bf16 v[108:111], v[148:151], v[190:193], v[108:111]
	v_mfma_f32_16x16x32_bf16 v[104:107], v[156:159], v[190:193], v[104:107]
	v_mfma_f32_16x16x32_bf16 v[92:95], v[148:151], v[198:201], v[92:95]
	v_mfma_f32_16x16x32_bf16 v[88:91], v[156:159], v[198:201], v[88:91]
	v_mfma_f32_16x16x32_bf16 v[76:79], v[148:151], v[206:209], v[76:79]
	v_mfma_f32_16x16x32_bf16 v[72:75], v[156:159], v[206:209], v[72:75]
	v_mfma_f32_16x16x32_bf16 v[124:127], v[152:155], v[184:187], v[124:127]
	v_mfma_f32_16x16x32_bf16 v[120:123], v[160:163], v[184:187], v[120:123]
	v_mfma_f32_16x16x32_bf16 v[108:111], v[152:155], v[194:197], v[108:111]
	v_mfma_f32_16x16x32_bf16 v[104:107], v[160:163], v[194:197], v[104:107]
	v_mfma_f32_16x16x32_bf16 v[92:95], v[152:155], v[202:205], v[92:95]
	v_mfma_f32_16x16x32_bf16 v[88:91], v[160:163], v[202:205], v[88:91]
	v_mfma_f32_16x16x32_bf16 v[76:79], v[152:155], v[210:213], v[76:79]
	v_mfma_f32_16x16x32_bf16 v[72:75], v[160:163], v[210:213], v[72:75]
	v_mfma_f32_16x16x32_bf16 v[116:119], v[164:167], v[180:183], v[116:119]
	v_mfma_f32_16x16x32_bf16 v[112:115], v[172:175], v[180:183], v[112:115]
	v_mfma_f32_16x16x32_bf16 v[100:103], v[164:167], v[190:193], v[100:103]
	v_mfma_f32_16x16x32_bf16 v[96:99], v[172:175], v[190:193], v[96:99]
	v_mfma_f32_16x16x32_bf16 v[84:87], v[164:167], v[198:201], v[84:87]
	v_mfma_f32_16x16x32_bf16 v[80:83], v[172:175], v[198:201], v[80:83]
	v_mfma_f32_16x16x32_bf16 v[68:71], v[164:167], v[206:209], v[68:71]
	v_mfma_f32_16x16x32_bf16 v[64:67], v[172:175], v[206:209], v[64:67]
	v_mfma_f32_16x16x32_bf16 v[116:119], v[168:171], v[184:187], v[116:119]
	v_mfma_f32_16x16x32_bf16 v[112:115], v[176:179], v[184:187], v[112:115]
	v_mfma_f32_16x16x32_bf16 v[100:103], v[168:171], v[194:197], v[100:103]
	v_mfma_f32_16x16x32_bf16 v[96:99], v[176:179], v[194:197], v[96:99]
	v_mfma_f32_16x16x32_bf16 v[84:87], v[168:171], v[202:205], v[84:87]
	v_mfma_f32_16x16x32_bf16 v[80:83], v[176:179], v[202:205], v[80:83]
	v_mfma_f32_16x16x32_bf16 v[68:71], v[168:171], v[210:213], v[68:71]
	v_mfma_f32_16x16x32_bf16 v[64:67], v[176:179], v[210:213], v[64:67]
	s_setprio 0
	s_barrier
	s_add_i32 s64, s53, s44
	s_mov_b32 m0, s64
	ds_read_b128 v[180:183], v146 offset:16384
	ds_read_b128 v[184:187], v146 offset:17408
	ds_read_b128 v[190:193], v146 offset:18432
	ds_read_b128 v[194:197], v146 offset:19456
	ds_read_b128 v[198:201], v146 offset:20480
	ds_read_b128 v[202:205], v146 offset:21504
	ds_read_b128 v[206:209], v146 offset:22528
	ds_read_b128 v[210:213], v146 offset:23552
	global_load_lds_dwordx4 v132, s[62:63]
	s_add_i32 m0, s64, 0x2000
	s_mov_b64 s[100:101], s[62:63]
	s_add_i32 s64, s54, s44
	global_load_lds_dwordx4 v134, s[62:63]
	s_add_u32 s62, s62, s16
	s_addc_u32 s63, s63, s17
	s_mov_b32 m0, s64
	s_nop 0
	global_load_lds_dwordx4 v132, s[62:63]
	s_add_i32 m0, s64, 0x2000
	s_nop 0
	global_load_lds_dwordx4 v134, s[62:63]
	s_mov_b32 m0, s33
	s_nop 0
	global_load_lds_dwordx4 v128, s[34:35]
	s_mov_b32 m0, s43
	s_nop 0
	global_load_lds_dwordx4 v130, s[34:35]
	s_waitcnt vmcnt(8)
	s_waitcnt lgkmcnt(0)
	s_barrier
	s_setprio 1
	v_mfma_f32_16x16x32_bf16 v[60:63], v[148:151], v[180:183], v[60:63]
	v_mfma_f32_16x16x32_bf16 v[56:59], v[156:159], v[180:183], v[56:59]
	v_mfma_f32_16x16x32_bf16 v[44:47], v[148:151], v[190:193], v[44:47]
	v_mfma_f32_16x16x32_bf16 v[40:43], v[156:159], v[190:193], v[40:43]
	v_mfma_f32_16x16x32_bf16 v[28:31], v[148:151], v[198:201], v[28:31]
	v_mfma_f32_16x16x32_bf16 v[24:27], v[156:159], v[198:201], v[24:27]
	v_mfma_f32_16x16x32_bf16 v[12:15], v[148:151], v[206:209], v[12:15]
	v_mfma_f32_16x16x32_bf16 v[8:11], v[156:159], v[206:209], v[8:11]
	v_mfma_f32_16x16x32_bf16 v[60:63], v[152:155], v[184:187], v[60:63]
	v_mfma_f32_16x16x32_bf16 v[56:59], v[160:163], v[184:187], v[56:59]
	v_mfma_f32_16x16x32_bf16 v[44:47], v[152:155], v[194:197], v[44:47]
	v_mfma_f32_16x16x32_bf16 v[40:43], v[160:163], v[194:197], v[40:43]
	v_mfma_f32_16x16x32_bf16 v[28:31], v[152:155], v[202:205], v[28:31]
	v_mfma_f32_16x16x32_bf16 v[24:27], v[160:163], v[202:205], v[24:27]
	v_mfma_f32_16x16x32_bf16 v[12:15], v[152:155], v[210:213], v[12:15]
	v_mfma_f32_16x16x32_bf16 v[8:11], v[160:163], v[210:213], v[8:11]
	v_mfma_f32_16x16x32_bf16 v[52:55], v[164:167], v[180:183], v[52:55]
	v_mfma_f32_16x16x32_bf16 v[48:51], v[172:175], v[180:183], v[48:51]
	v_mfma_f32_16x16x32_bf16 v[36:39], v[164:167], v[190:193], v[36:39]
	v_mfma_f32_16x16x32_bf16 v[32:35], v[172:175], v[190:193], v[32:35]
	v_mfma_f32_16x16x32_bf16 v[20:23], v[164:167], v[198:201], v[20:23]
	v_mfma_f32_16x16x32_bf16 v[16:19], v[172:175], v[198:201], v[16:19]
	v_mfma_f32_16x16x32_bf16 v[4:7], v[164:167], v[206:209], v[4:7]
	v_mfma_f32_16x16x32_bf16 v[0:3], v[172:175], v[206:209], v[0:3]
	v_mfma_f32_16x16x32_bf16 v[52:55], v[168:171], v[184:187], v[52:55]
	v_mfma_f32_16x16x32_bf16 v[48:51], v[176:179], v[184:187], v[48:51]
	v_mfma_f32_16x16x32_bf16 v[36:39], v[168:171], v[194:197], v[36:39]
	v_mfma_f32_16x16x32_bf16 v[32:35], v[176:179], v[194:197], v[32:35]
	v_mfma_f32_16x16x32_bf16 v[20:23], v[168:171], v[202:205], v[20:23]
	v_mfma_f32_16x16x32_bf16 v[16:19], v[176:179], v[202:205], v[16:19]
	v_mfma_f32_16x16x32_bf16 v[4:7], v[168:171], v[210:213], v[4:7]
	v_mfma_f32_16x16x32_bf16 v[0:3], v[176:179], v[210:213], v[0:3]
	s_setprio 0
	s_barrier
; #define PG8_STAGE(bufoff, gbase, voff) do { _Pragma("unroll") for (int _i = 0; _i < 2; ++_i) \
;         __builtin_amdgcn_global_load_lds((const unsigned*)((const char*)(gbase) + (voff)[_i]), (PG8_LAS unsigned*)(lds + (bufoff) + ldsw + _i * 8192), 16, 0, 0); } while (0)
; #define PG8_LDA(dst, b, h) do { _Pragma("unroll") for (int m = 0; m < 4; ++m) _Pragma("unroll") for (int k = 0; k < 2; ++k) dst[m][k] = *(const PG8_LAS bf16x8*)(lds + PG8_SA(b, h) + aoff + m * 2048 + k * 1024); } while (0)
; #define PG8_LDB(dst, b, h) do { _Pragma("unroll") for (int n = 0; n < 2; ++n) _Pragma("unroll") for (int k = 0; k < 2; ++k) dst[n][k] = *(const PG8_LAS bf16x8*)(lds + PG8_SB(b, h) + boff + n * 2048 + k * 1024); } while (0)
; #define PG8_MMA(ai, bj, At, Bt) do { __builtin_amdgcn_s_setprio(1); _Pragma("unroll") for (int m = 0; m < 4; ++m) _Pragma("unroll") for (int n = 0; n < 2; ++n) _Pragma("unroll") for (int k = 0; k < 2; ++k) \
;         acc[ai][bj][m][n] = __builtin_amdgcn_mfma_f32_16x16x32_bf16(Bt[n][k], At[m][k], acc[ai][bj][m][n], 0, 0, 0); __builtin_amdgcn_s_setprio(0); } while (0)
; #define PG8_WAIT_V(n) asm volatile("s_waitcnt vmcnt(" #n ")" ::: "memory")
; #define PG8_WAIT_L(n) asm volatile("s_waitcnt lgkmcnt(" #n ")" ::: "memory")
; #define PG8_BAR __builtin_amdgcn_s_barrier()
; #define PG8_SCHED __builtin_amdgcn_sched_barrier(0)
; template <class Epi, class Sched, bool ALIGN_EPI = false, bool SP2 = false>
; __device__ __forceinline__ void gemm_phase(PG8_LAS unsigned char* lds, const Gemm g, const Sched& S, const Epi& E) {
;     ...
;             PG8_LDB(B0, 1, 0); PG8_LDB(B1, 1, 1); PG8_SCHED; PG8_LDA(At, 1, 0); PG8_STAGE(PG8_SA(0, 1), a2 + hstepA, voffA);
;             PG8_WAIT_V(8); PG8_WAIT_L(0); PG8_BAR; PG8_MMA(0, 0, At, B0); PG8_MMA(0, 1, At, B1); PG8_BAR; PG8_SCHED;
;             PG8_LDA(At, 1, 1); PG8_STAGE(PG8_SB(1, 0), b3, voffB); PG8_STAGE(PG8_SB(1, 1), b3 + hstep, voffB); PG8_STAGE(PG8_SA(1, 0), a3, voffA);
;             PG8_WAIT_V(8); PG8_WAIT_L(0); PG8_BAR; PG8_MMA(1, 0, At, B0); PG8_MMA(1, 1, At, B1); PG8_BAR; PG8_SCHED;
	s_add_i32 s62, 0, 0x18000
	v_add_u32_e32 v147, s62, v142
	s_add_i32 s63, 0, 0x1c000
	ds_read_b128 v[148:151], v147
	ds_read_b128 v[152:155], v147 offset:1024
	ds_read_b128 v[156:159], v147 offset:2048
	ds_read_b128 v[160:163], v147 offset:3072
	v_add_u32_e32 v147, s63, v142
	ds_read_b128 v[164:167], v147
	ds_read_b128 v[168:171], v147 offset:1024
	ds_read_b128 v[172:175], v147 offset:2048
	ds_read_b128 v[176:179], v147 offset:3072
	s_mov_b64 vcc, s[34:35]
	s_add_u32 s34, s34, 0x40000
	s_addc_u32 s35, s35, 0
	s_mov_b32 m0, s45
	ds_read_b128 v[180:183], v146 offset:32768
	ds_read_b128 v[184:187], v146 offset:33792
	ds_read_b128 v[190:193], v146 offset:34816
	ds_read_b128 v[194:197], v146 offset:35840
	ds_read_b128 v[198:201], v146 offset:36864
	ds_read_b128 v[202:205], v146 offset:37888
	ds_read_b128 v[206:209], v146 offset:38912
	ds_read_b128 v[210:213], v146 offset:39936
	global_load_lds_dwordx4 v128, s[34:35]
	s_mov_b32 m0, s47
	s_nop 0
	global_load_lds_dwordx4 v130, s[34:35]
	s_waitcnt vmcnt(8)
	s_waitcnt lgkmcnt(0)
	s_barrier
	s_setprio 1
	v_mfma_f32_16x16x32_bf16 v[124:127], v[148:151], v[180:183], v[124:127]
	v_mfma_f32_16x16x32_bf16 v[120:123], v[156:159], v[180:183], v[120:123]
	v_mfma_f32_16x16x32_bf16 v[108:111], v[148:151], v[190:193], v[108:111]
	v_mfma_f32_16x16x32_bf16 v[104:107], v[156:159], v[190:193], v[104:107]
	v_mfma_f32_16x16x32_bf16 v[92:95], v[148:151], v[198:201], v[92:95]
	v_mfma_f32_16x16x32_bf16 v[88:91], v[156:159], v[198:201], v[88:91]
	v_mfma_f32_16x16x32_bf16 v[76:79], v[148:151], v[206:209], v[76:79]
	v_mfma_f32_16x16x32_bf16 v[72:75], v[156:159], v[206:209], v[72:75]
	v_mfma_f32_16x16x32_bf16 v[124:127], v[152:155], v[184:187], v[124:127]
	v_mfma_f32_16x16x32_bf16 v[120:123], v[160:163], v[184:187], v[120:123]
	v_mfma_f32_16x16x32_bf16 v[108:111], v[152:155], v[194:197], v[108:111]
	v_mfma_f32_16x16x32_bf16 v[104:107], v[160:163], v[194:197], v[104:107]
	v_mfma_f32_16x16x32_bf16 v[92:95], v[152:155], v[202:205], v[92:95]
	v_mfma_f32_16x16x32_bf16 v[88:91], v[160:163], v[202:205], v[88:91]
	v_mfma_f32_16x16x32_bf16 v[76:79], v[152:155], v[210:213], v[76:79]
	v_mfma_f32_16x16x32_bf16 v[72:75], v[160:163], v[210:213], v[72:75]
	v_mfma_f32_16x16x32_bf16 v[116:119], v[164:167], v[180:183], v[116:119]
	v_mfma_f32_16x16x32_bf16 v[112:115], v[172:175], v[180:183], v[112:115]
	v_mfma_f32_16x16x32_bf16 v[100:103], v[164:167], v[190:193], v[100:103]
	v_mfma_f32_16x16x32_bf16 v[96:99], v[172:175], v[190:193], v[96:99]
	v_mfma_f32_16x16x32_bf16 v[84:87], v[164:167], v[198:201], v[84:87]
	v_mfma_f32_16x16x32_bf16 v[80:83], v[172:175], v[198:201], v[80:83]
	v_mfma_f32_16x16x32_bf16 v[68:71], v[164:167], v[206:209], v[68:71]
	v_mfma_f32_16x16x32_bf16 v[64:67], v[172:175], v[206:209], v[64:67]
	v_mfma_f32_16x16x32_bf16 v[116:119], v[168:171], v[184:187], v[116:119]
	v_mfma_f32_16x16x32_bf16 v[112:115], v[176:179], v[184:187], v[112:115]
	v_mfma_f32_16x16x32_bf16 v[100:103], v[168:171], v[194:197], v[100:103]
	v_mfma_f32_16x16x32_bf16 v[96:99], v[176:179], v[194:197], v[96:99]
	v_mfma_f32_16x16x32_bf16 v[84:87], v[168:171], v[202:205], v[84:87]
	v_mfma_f32_16x16x32_bf16 v[80:83], v[176:179], v[202:205], v[80:83]
	v_mfma_f32_16x16x32_bf16 v[68:71], v[168:171], v[210:213], v[68:71]
	v_mfma_f32_16x16x32_bf16 v[64:67], v[176:179], v[210:213], v[64:67]
	s_setprio 0
	s_barrier
	s_add_i32 s34, s62, s44
	s_add_i32 m0, s34, 0xffffff80
	ds_read_b128 v[180:183], v146 offset:49152
	ds_read_b128 v[184:187], v146 offset:50176
	ds_read_b128 v[190:193], v146 offset:51200
	ds_read_b128 v[194:197], v146 offset:52224
	ds_read_b128 v[198:201], v146 offset:53248
	ds_read_b128 v[202:205], v146 offset:54272
	ds_read_b128 v[206:209], v146 offset:55296
	ds_read_b128 v[210:213], v146 offset:56320
	global_load_lds_dwordx4 v132, s[100:101] offset:128
	s_add_i32 m0, s34, 0x1f80
	s_add_i32 s34, s63, s44
	global_load_lds_dwordx4 v134, s[100:101] offset:128
	s_add_u32 s100, s100, s16
	s_addc_u32 s101, s101, s17
	s_add_i32 m0, s34, 0xffffff80
	s_nop 0
	global_load_lds_dwordx4 v132, s[100:101] offset:128
	s_add_i32 m0, s34, 0x1f80
	s_nop 0
	global_load_lds_dwordx4 v134, s[100:101] offset:128
	s_add_i32 m0, s48, 0xffffff80
	s_nop 0
	global_load_lds_dwordx4 v128, vcc offset:128
	s_add_i32 m0, s49, 0xffffff80
	s_nop 0
	global_load_lds_dwordx4 v130, vcc offset:128
	s_waitcnt vmcnt(8)
	s_waitcnt lgkmcnt(0)
	s_barrier
	s_setprio 1
	v_mfma_f32_16x16x32_bf16 v[60:63], v[148:151], v[180:183], v[60:63]
	v_mfma_f32_16x16x32_bf16 v[56:59], v[156:159], v[180:183], v[56:59]
	v_mfma_f32_16x16x32_bf16 v[44:47], v[148:151], v[190:193], v[44:47]
	v_mfma_f32_16x16x32_bf16 v[40:43], v[156:159], v[190:193], v[40:43]
	v_mfma_f32_16x16x32_bf16 v[28:31], v[148:151], v[198:201], v[28:31]
	v_mfma_f32_16x16x32_bf16 v[24:27], v[156:159], v[198:201], v[24:27]
	v_mfma_f32_16x16x32_bf16 v[12:15], v[148:151], v[206:209], v[12:15]
	v_mfma_f32_16x16x32_bf16 v[8:11], v[156:159], v[206:209], v[8:11]
	v_mfma_f32_16x16x32_bf16 v[60:63], v[152:155], v[184:187], v[60:63]
	v_mfma_f32_16x16x32_bf16 v[56:59], v[160:163], v[184:187], v[56:59]
	v_mfma_f32_16x16x32_bf16 v[44:47], v[152:155], v[194:197], v[44:47]
	v_mfma_f32_16x16x32_bf16 v[40:43], v[160:163], v[194:197], v[40:43]
	v_mfma_f32_16x16x32_bf16 v[28:31], v[152:155], v[202:205], v[28:31]
	v_mfma_f32_16x16x32_bf16 v[24:27], v[160:163], v[202:205], v[24:27]
	v_mfma_f32_16x16x32_bf16 v[12:15], v[152:155], v[210:213], v[12:15]
	v_mfma_f32_16x16x32_bf16 v[8:11], v[160:163], v[210:213], v[8:11]
	v_mfma_f32_16x16x32_bf16 v[52:55], v[164:167], v[180:183], v[52:55]
	v_mfma_f32_16x16x32_bf16 v[48:51], v[172:175], v[180:183], v[48:51]
	v_mfma_f32_16x16x32_bf16 v[36:39], v[164:167], v[190:193], v[36:39]
	v_mfma_f32_16x16x32_bf16 v[32:35], v[172:175], v[190:193], v[32:35]
	v_mfma_f32_16x16x32_bf16 v[20:23], v[164:167], v[198:201], v[20:23]
	v_mfma_f32_16x16x32_bf16 v[16:19], v[172:175], v[198:201], v[16:19]
	v_mfma_f32_16x16x32_bf16 v[4:7], v[164:167], v[206:209], v[4:7]
	v_mfma_f32_16x16x32_bf16 v[0:3], v[172:175], v[206:209], v[0:3]
	v_mfma_f32_16x16x32_bf16 v[52:55], v[168:171], v[184:187], v[52:55]
	v_mfma_f32_16x16x32_bf16 v[48:51], v[176:179], v[184:187], v[48:51]
	v_mfma_f32_16x16x32_bf16 v[36:39], v[168:171], v[194:197], v[36:39]
	v_mfma_f32_16x16x32_bf16 v[32:35], v[176:179], v[194:197], v[32:35]
	v_mfma_f32_16x16x32_bf16 v[20:23], v[168:171], v[202:205], v[20:23]
	v_mfma_f32_16x16x32_bf16 v[16:19], v[176:179], v[202:205], v[16:19]
	v_mfma_f32_16x16x32_bf16 v[4:7], v[168:171], v[210:213], v[4:7]
	v_mfma_f32_16x16x32_bf16 v[0:3], v[176:179], v[210:213], v[0:3]
	s_setprio 0
	s_barrier
	s_add_u32 s30, s30, 0x100
	s_addc_u32 s31, s31, 0
	s_add_u32 s37, s37, 0x100
	s_addc_u32 s60, s60, 0
	s_cmp_ge_i32 s61, s50
	s_mov_b32 s34, s61
	s_cbranch_scc0 .LBB0_282

; #define PG8_STAGE(bufoff, gbase, voff) do { _Pragma("unroll") for (int _i = 0; _i < 2; ++_i) \
;         __builtin_amdgcn_global_load_lds((const unsigned*)((const char*)(gbase) + (voff)[_i]), (PG8_LAS unsigned*)(lds + (bufoff) + ldsw + _i * 8192), 16, 0, 0); } while (0)
; #define PG8_LDA(dst, b, h) do { _Pragma("unroll") for (int m = 0; m < 4; ++m) _Pragma("unroll") for (int k = 0; k < 2; ++k) dst[m][k] = *(const PG8_LAS bf16x8*)(lds + PG8_SA(b, h) + aoff + m * 2048 + k * 1024); } while (0)
; #define PG8_LDB(dst, b, h) do { _Pragma("unroll") for (int n = 0; n < 2; ++n) _Pragma("unroll") for (int k = 0; k < 2; ++k) dst[n][k] = *(const PG8_LAS bf16x8*)(lds + PG8_SB(b, h) + boff + n * 2048 + k * 1024); } while (0)
; #define PG8_MMA(ai, bj, At, Bt) do { __builtin_amdgcn_s_setprio(1); _Pragma("unroll") for (int m = 0; m < 4; ++m) _Pragma("unroll") for (int n = 0; n < 2; ++n) _Pragma("unroll") for (int k = 0; k < 2; ++k) \
;         acc[ai][bj][m][n] = __builtin_amdgcn_mfma_f32_16x16x32_bf16(Bt[n][k], At[m][k], acc[ai][bj][m][n], 0, 0, 0); __builtin_amdgcn_s_setprio(0); } while (0)
; #define PG8_WAIT_V(n) asm volatile("s_waitcnt vmcnt(" #n ")" ::: "memory")
; #define PG8_BAR __builtin_amdgcn_s_barrier()
; template <class Epi, class Sched, bool ALIGN_EPI = false, bool SP2 = false>
; __device__ __forceinline__ void gemm_phase(PG8_LAS unsigned char* lds, const Gemm g, const Sched& S, const Epi& E) {
;     ...
;         for (int t = 0; t < nt; t += 2) {
;             const bool last = (t == nt - 2);
;             const char* a1 = cA + (size_t)(t + 1) * kstep;
;             const char* a2 = last ? nA : cA + (size_t)(t + 2) * kstep; const char* b2 = last ? nB : cB + (size_t)(t + 2) * kstep;
;             const char* a3 = a2 + kstep; const char* b3 = b2 + kstep;
;             if (last && has_next) S.a_ready(nxt);
;             if constexpr (SP2) {
;             PG8_LDB(B0, 0, 0); PG8_LDB(B1, 0, 1); PG8_SCHED; PG8_LDA(At, 0, 0); PG8_STAGE(PG8_SA(1, 1), a1 + hstepA, voffA);
;             PG8_WAIT_V(8); PG8_WAIT_L(0); PG8_BAR; PG8_MMA(0, 0, At, B0); PG8_MMA(0, 1, At, B1); PG8_BAR; PG8_SCHED;
;             PG8_LDA(At, 0, 1); PG8_STAGE(PG8_SB(0, 0), b2, voffB); PG8_STAGE(PG8_SB(0, 1), b2 + hstep, voffB); PG8_STAGE(PG8_SA(0, 0), a2, voffA);
;             PG8_WAIT_V(8); PG8_WAIT_L(0); PG8_BAR; PG8_MMA(1, 0, At, B0); PG8_MMA(1, 1, At, B1); PG8_BAR; PG8_SCHED;
.LBB0_368:
	ds_read_b128 v[154:157], v150
	ds_read_b128 v[158:161], v150 offset:1024
	ds_read_b128 v[162:165], v150 offset:2048
	ds_read_b128 v[166:169], v150 offset:3072
	ds_read_b128 v[170:173], v151
	ds_read_b128 v[174:177], v151 offset:1024
	ds_read_b128 v[178:181], v151 offset:2048
	ds_read_b128 v[182:185], v151 offset:3072
	s_add_i32 s64, s28, 2
	s_add_u32 s65, s26, 0xfffe0080
	s_addc_u32 s29, s27, -1
	s_cmp_eq_u32 s50, s28
	s_cselect_b32 s28, s30, s65
	s_cselect_b32 s29, s13, s29
	s_cselect_b32 s67, s21, s63
	s_cselect_b32 s66, s20, s62
	s_mov_b32 m0, s54
	ds_read_b128 v[190:193], v152
	ds_read_b128 v[194:197], v152 offset:1024
	ds_read_b128 v[198:201], v152 offset:2048
	ds_read_b128 v[202:205], v152 offset:3072
	ds_read_b128 v[206:209], v152 offset:4096
	ds_read_b128 v[210:213], v152 offset:5120
	ds_read_b128 v[214:217], v152 offset:6144
	ds_read_b128 v[218:221], v152 offset:7168
	global_load_lds_dwordx4 v138, s[26:27]
	s_mov_b32 m0, s55
	s_nop 0
	global_load_lds_dwordx4 v140, s[26:27]
	s_waitcnt vmcnt(8)
	s_waitcnt lgkmcnt(0)
	s_barrier
	s_setprio 1
	v_mfma_f32_16x16x32_bf16 v[124:127], v[154:157], v[190:193], v[124:127]
	v_mfma_f32_16x16x32_bf16 v[120:123], v[162:165], v[190:193], v[120:123]
	v_mfma_f32_16x16x32_bf16 v[108:111], v[154:157], v[198:201], v[108:111]
	v_mfma_f32_16x16x32_bf16 v[104:107], v[162:165], v[198:201], v[104:107]
	v_mfma_f32_16x16x32_bf16 v[92:95], v[154:157], v[206:209], v[92:95]
	v_mfma_f32_16x16x32_bf16 v[88:91], v[162:165], v[206:209], v[88:91]
	v_mfma_f32_16x16x32_bf16 v[76:79], v[154:157], v[214:217], v[76:79]
	v_mfma_f32_16x16x32_bf16 v[72:75], v[162:165], v[214:217], v[72:75]
	v_mfma_f32_16x16x32_bf16 v[124:127], v[158:161], v[194:197], v[124:127]
	v_mfma_f32_16x16x32_bf16 v[120:123], v[166:169], v[194:197], v[120:123]
	v_mfma_f32_16x16x32_bf16 v[108:111], v[158:161], v[202:205], v[108:111]
	v_mfma_f32_16x16x32_bf16 v[104:107], v[166:169], v[202:205], v[104:107]
	v_mfma_f32_16x16x32_bf16 v[92:95], v[158:161], v[210:213], v[92:95]
	v_mfma_f32_16x16x32_bf16 v[88:91], v[166:169], v[210:213], v[88:91]
	v_mfma_f32_16x16x32_bf16 v[76:79], v[158:161], v[218:221], v[76:79]
	v_mfma_f32_16x16x32_bf16 v[72:75], v[166:169], v[218:221], v[72:75]
	v_mfma_f32_16x16x32_bf16 v[116:119], v[170:173], v[190:193], v[116:119]
	v_mfma_f32_16x16x32_bf16 v[112:115], v[178:181], v[190:193], v[112:115]
	v_mfma_f32_16x16x32_bf16 v[100:103], v[170:173], v[198:201], v[100:103]
	v_mfma_f32_16x16x32_bf16 v[96:99], v[178:181], v[198:201], v[96:99]
	v_mfma_f32_16x16x32_bf16 v[84:87], v[170:173], v[206:209], v[84:87]
	v_mfma_f32_16x16x32_bf16 v[80:83], v[178:181], v[206:209], v[80:83]
	v_mfma_f32_16x16x32_bf16 v[68:71], v[170:173], v[214:217], v[68:71]
	v_mfma_f32_16x16x32_bf16 v[64:67], v[178:181], v[214:217], v[64:67]
	v_mfma_f32_16x16x32_bf16 v[116:119], v[174:177], v[194:197], v[116:119]
	v_mfma_f32_16x16x32_bf16 v[112:115], v[182:185], v[194:197], v[112:115]
	v_mfma_f32_16x16x32_bf16 v[100:103], v[174:177], v[202:205], v[100:103]
	v_mfma_f32_16x16x32_bf16 v[96:99], v[182:185], v[202:205], v[96:99]
	v_mfma_f32_16x16x32_bf16 v[84:87], v[174:177], v[210:213], v[84:87]
	v_mfma_f32_16x16x32_bf16 v[80:83], v[182:185], v[210:213], v[80:83]
	v_mfma_f32_16x16x32_bf16 v[68:71], v[174:177], v[218:221], v[68:71]
	v_mfma_f32_16x16x32_bf16 v[64:67], v[182:185], v[218:221], v[64:67]
	s_setprio 0
	s_barrier
	s_mov_b32 m0, s56
	s_mov_b64 s[100:101], s[66:67]
	ds_read_b128 v[190:193], v152 offset:16384
	ds_read_b128 v[194:197], v152 offset:17408
	ds_read_b128 v[198:201], v152 offset:18432
	ds_read_b128 v[202:205], v152 offset:19456
	ds_read_b128 v[206:209], v152 offset:20480
	ds_read_b128 v[210:213], v152 offset:21504
	ds_read_b128 v[214:217], v152 offset:22528
	ds_read_b128 v[218:221], v152 offset:23552
	global_load_lds_dwordx4 v134, s[66:67]
	s_mov_b32 m0, s57
	s_nop 0
	global_load_lds_dwordx4 v132, s[66:67]
	s_add_u32 s66, s66, s4
	s_addc_u32 s67, s67, s5
	s_mov_b32 m0, s58
	s_nop 0
	global_load_lds_dwordx4 v134, s[66:67]
	s_mov_b32 m0, s59
	s_nop 0
	global_load_lds_dwordx4 v132, s[66:67]
	s_mov_b32 m0, s38
	s_nop 0
	global_load_lds_dwordx4 v130, s[28:29]
	s_mov_b32 m0, s39
	s_nop 0
	global_load_lds_dwordx4 v128, s[28:29]
	s_waitcnt vmcnt(8)
	s_waitcnt lgkmcnt(0)
	s_barrier
	s_setprio 1
	v_mfma_f32_16x16x32_bf16 v[60:63], v[154:157], v[190:193], v[60:63]
	v_mfma_f32_16x16x32_bf16 v[56:59], v[162:165], v[190:193], v[56:59]
	v_mfma_f32_16x16x32_bf16 v[44:47], v[154:157], v[198:201], v[44:47]
	v_mfma_f32_16x16x32_bf16 v[40:43], v[162:165], v[198:201], v[40:43]
	v_mfma_f32_16x16x32_bf16 v[28:31], v[154:157], v[206:209], v[28:31]
	v_mfma_f32_16x16x32_bf16 v[24:27], v[162:165], v[206:209], v[24:27]
	v_mfma_f32_16x16x32_bf16 v[12:15], v[154:157], v[214:217], v[12:15]
	v_mfma_f32_16x16x32_bf16 v[8:11], v[162:165], v[214:217], v[8:11]
	v_mfma_f32_16x16x32_bf16 v[60:63], v[158:161], v[194:197], v[60:63]
	v_mfma_f32_16x16x32_bf16 v[56:59], v[166:169], v[194:197], v[56:59]
	v_mfma_f32_16x16x32_bf16 v[44:47], v[158:161], v[202:205], v[44:47]
	v_mfma_f32_16x16x32_bf16 v[40:43], v[166:169], v[202:205], v[40:43]
	v_mfma_f32_16x16x32_bf16 v[28:31], v[158:161], v[210:213], v[28:31]
	v_mfma_f32_16x16x32_bf16 v[24:27], v[166:169], v[210:213], v[24:27]
	v_mfma_f32_16x16x32_bf16 v[12:15], v[158:161], v[218:221], v[12:15]
	v_mfma_f32_16x16x32_bf16 v[8:11], v[166:169], v[218:221], v[8:11]
	v_mfma_f32_16x16x32_bf16 v[52:55], v[170:173], v[190:193], v[52:55]
	v_mfma_f32_16x16x32_bf16 v[48:51], v[178:181], v[190:193], v[48:51]
	v_mfma_f32_16x16x32_bf16 v[36:39], v[170:173], v[198:201], v[36:39]
	v_mfma_f32_16x16x32_bf16 v[32:35], v[178:181], v[198:201], v[32:35]
	v_mfma_f32_16x16x32_bf16 v[20:23], v[170:173], v[206:209], v[20:23]
	v_mfma_f32_16x16x32_bf16 v[16:19], v[178:181], v[206:209], v[16:19]
	v_mfma_f32_16x16x32_bf16 v[4:7], v[170:173], v[214:217], v[4:7]
	v_mfma_f32_16x16x32_bf16 v[0:3], v[178:181], v[214:217], v[0:3]
	v_mfma_f32_16x16x32_bf16 v[52:55], v[174:177], v[194:197], v[52:55]
	v_mfma_f32_16x16x32_bf16 v[48:51], v[182:185], v[194:197], v[48:51]
	v_mfma_f32_16x16x32_bf16 v[36:39], v[174:177], v[202:205], v[36:39]
	v_mfma_f32_16x16x32_bf16 v[32:35], v[182:185], v[202:205], v[32:35]
	v_mfma_f32_16x16x32_bf16 v[20:23], v[174:177], v[210:213], v[20:23]
	v_mfma_f32_16x16x32_bf16 v[16:19], v[182:185], v[210:213], v[16:19]
	v_mfma_f32_16x16x32_bf16 v[4:7], v[174:177], v[218:221], v[4:7]
	v_mfma_f32_16x16x32_bf16 v[0:3], v[182:185], v[218:221], v[0:3]
	s_setprio 0
	s_barrier
; #define PG8_STAGE(bufoff, gbase, voff) do { _Pragma("unroll") for (int _i = 0; _i < 2; ++_i) \
;         __builtin_amdgcn_global_load_lds((const unsigned*)((const char*)(gbase) + (voff)[_i]), (PG8_LAS unsigned*)(lds + (bufoff) + ldsw + _i * 8192), 16, 0, 0); } while (0)
; #define PG8_LDA(dst, b, h) do { _Pragma("unroll") for (int m = 0; m < 4; ++m) _Pragma("unroll") for (int k = 0; k < 2; ++k) dst[m][k] = *(const PG8_LAS bf16x8*)(lds + PG8_SA(b, h) + aoff + m * 2048 + k * 1024); } while (0)
; #define PG8_LDB(dst, b, h) do { _Pragma("unroll") for (int n = 0; n < 2; ++n) _Pragma("unroll") for (int k = 0; k < 2; ++k) dst[n][k] = *(const PG8_LAS bf16x8*)(lds + PG8_SB(b, h) + boff + n * 2048 + k * 1024); } while (0)
; #define PG8_MMA(ai, bj, At, Bt) do { __builtin_amdgcn_s_setprio(1); _Pragma("unroll") for (int m = 0; m < 4; ++m) _Pragma("unroll") for (int n = 0; n < 2; ++n) _Pragma("unroll") for (int k = 0; k < 2; ++k) \
;         acc[ai][bj][m][n] = __builtin_amdgcn_mfma_f32_16x16x32_bf16(Bt[n][k], At[m][k], acc[ai][bj][m][n], 0, 0, 0); __builtin_amdgcn_s_setprio(0); } while (0)
; #define PG8_WAIT_V(n) asm volatile("s_waitcnt vmcnt(" #n ")" ::: "memory")
; #define PG8_WAIT_L(n) asm volatile("s_waitcnt lgkmcnt(" #n ")" ::: "memory")
; #define PG8_BAR __builtin_amdgcn_s_barrier()
; #define PG8_SCHED __builtin_amdgcn_sched_barrier(0)
; template <class Epi, class Sched, bool ALIGN_EPI = false, bool SP2 = false>
; __device__ __forceinline__ void gemm_phase(PG8_LAS unsigned char* lds, const Gemm g, const Sched& S, const Epi& E) {
;     ...
;             PG8_LDB(B0, 1, 0); PG8_LDB(B1, 1, 1); PG8_SCHED; PG8_LDA(At, 1, 0); PG8_STAGE(PG8_SA(0, 1), a2 + hstepA, voffA);
;             PG8_WAIT_V(8); PG8_WAIT_L(0); PG8_BAR; PG8_MMA(0, 0, At, B0); PG8_MMA(0, 1, At, B1); PG8_BAR; PG8_SCHED;
;             PG8_LDA(At, 1, 1); PG8_STAGE(PG8_SB(1, 0), b3, voffB); PG8_STAGE(PG8_SB(1, 1), b3 + hstep, voffB); PG8_STAGE(PG8_SA(1, 0), a3, voffA);
;             PG8_WAIT_V(8); PG8_WAIT_L(0); PG8_BAR; PG8_MMA(1, 0, At, B0); PG8_MMA(1, 1, At, B1); PG8_BAR; PG8_SCHED;
	s_add_i32 s65, 0, 0x18000
	s_add_i32 s66, 0, 0x1c000
	v_add_u32_e32 v166, s65, v149
	v_add_u32_e32 v182, s66, v149
	ds_read_b128 v[154:157], v166
	ds_read_b128 v[158:161], v166 offset:1024
	ds_read_b128 v[162:165], v166 offset:2048
	ds_read_b128 v[166:169], v166 offset:3072
	ds_read_b128 v[170:173], v182
	ds_read_b128 v[174:177], v182 offset:1024
	ds_read_b128 v[178:181], v182 offset:2048
	ds_read_b128 v[182:185], v182 offset:3072
	s_mov_b64 vcc, s[28:29]
	s_add_u32 s28, s28, 0x20000
	s_addc_u32 s29, s29, 0
	s_mov_b32 m0, s40
	ds_read_b128 v[190:193], v152 offset:32768
	ds_read_b128 v[194:197], v152 offset:33792
	ds_read_b128 v[198:201], v152 offset:34816
	ds_read_b128 v[202:205], v152 offset:35840
	ds_read_b128 v[206:209], v152 offset:36864
	ds_read_b128 v[210:213], v152 offset:37888
	ds_read_b128 v[214:217], v152 offset:38912
	ds_read_b128 v[218:221], v152 offset:39936
	global_load_lds_dwordx4 v130, s[28:29]
	s_mov_b32 m0, s41
	s_nop 0
	global_load_lds_dwordx4 v128, s[28:29]
	s_waitcnt vmcnt(8)
	s_waitcnt lgkmcnt(0)
	s_barrier
	s_setprio 1
	v_mfma_f32_16x16x32_bf16 v[124:127], v[154:157], v[190:193], v[124:127]
	v_mfma_f32_16x16x32_bf16 v[120:123], v[162:165], v[190:193], v[120:123]
	v_mfma_f32_16x16x32_bf16 v[108:111], v[154:157], v[198:201], v[108:111]
	v_mfma_f32_16x16x32_bf16 v[104:107], v[162:165], v[198:201], v[104:107]
	v_mfma_f32_16x16x32_bf16 v[92:95], v[154:157], v[206:209], v[92:95]
	v_mfma_f32_16x16x32_bf16 v[88:91], v[162:165], v[206:209], v[88:91]
	v_mfma_f32_16x16x32_bf16 v[76:79], v[154:157], v[214:217], v[76:79]
	v_mfma_f32_16x16x32_bf16 v[72:75], v[162:165], v[214:217], v[72:75]
	v_mfma_f32_16x16x32_bf16 v[124:127], v[158:161], v[194:197], v[124:127]
	v_mfma_f32_16x16x32_bf16 v[120:123], v[166:169], v[194:197], v[120:123]
	v_mfma_f32_16x16x32_bf16 v[108:111], v[158:161], v[202:205], v[108:111]
	v_mfma_f32_16x16x32_bf16 v[104:107], v[166:169], v[202:205], v[104:107]
	v_mfma_f32_16x16x32_bf16 v[92:95], v[158:161], v[210:213], v[92:95]
	v_mfma_f32_16x16x32_bf16 v[88:91], v[166:169], v[210:213], v[88:91]
	v_mfma_f32_16x16x32_bf16 v[76:79], v[158:161], v[218:221], v[76:79]
	v_mfma_f32_16x16x32_bf16 v[72:75], v[166:169], v[218:221], v[72:75]
	v_mfma_f32_16x16x32_bf16 v[116:119], v[170:173], v[190:193], v[116:119]
	v_mfma_f32_16x16x32_bf16 v[112:115], v[178:181], v[190:193], v[112:115]
	v_mfma_f32_16x16x32_bf16 v[100:103], v[170:173], v[198:201], v[100:103]
	v_mfma_f32_16x16x32_bf16 v[96:99], v[178:181], v[198:201], v[96:99]
	v_mfma_f32_16x16x32_bf16 v[84:87], v[170:173], v[206:209], v[84:87]
	v_mfma_f32_16x16x32_bf16 v[80:83], v[178:181], v[206:209], v[80:83]
	v_mfma_f32_16x16x32_bf16 v[68:71], v[170:173], v[214:217], v[68:71]
	v_mfma_f32_16x16x32_bf16 v[64:67], v[178:181], v[214:217], v[64:67]
	v_mfma_f32_16x16x32_bf16 v[116:119], v[174:177], v[194:197], v[116:119]
	v_mfma_f32_16x16x32_bf16 v[112:115], v[182:185], v[194:197], v[112:115]
	v_mfma_f32_16x16x32_bf16 v[100:103], v[174:177], v[202:205], v[100:103]
	v_mfma_f32_16x16x32_bf16 v[96:99], v[182:185], v[202:205], v[96:99]
	v_mfma_f32_16x16x32_bf16 v[84:87], v[174:177], v[210:213], v[84:87]
	v_mfma_f32_16x16x32_bf16 v[80:83], v[182:185], v[210:213], v[80:83]
	v_mfma_f32_16x16x32_bf16 v[68:71], v[174:177], v[218:221], v[68:71]
	v_mfma_f32_16x16x32_bf16 v[64:67], v[182:185], v[218:221], v[64:67]
	s_setprio 0
	s_barrier
	s_add_i32 s28, s65, s37
	s_add_i32 m0, s28, 0xffffff80
	ds_read_b128 v[190:193], v152 offset:49152
	ds_read_b128 v[194:197], v152 offset:50176
	ds_read_b128 v[198:201], v152 offset:51200
	ds_read_b128 v[202:205], v152 offset:52224
	ds_read_b128 v[206:209], v152 offset:53248
	ds_read_b128 v[210:213], v152 offset:54272
	ds_read_b128 v[214:217], v152 offset:55296
	ds_read_b128 v[218:221], v152 offset:56320
	global_load_lds_dwordx4 v134, s[100:101] offset:128
	s_add_i32 m0, s28, 0x1f80
	s_add_i32 s28, s66, s37
	global_load_lds_dwordx4 v132, s[100:101] offset:128
	s_add_u32 s100, s100, s4
	s_addc_u32 s101, s101, s5
	s_add_i32 m0, s28, 0xffffff80
	s_nop 0
	global_load_lds_dwordx4 v134, s[100:101] offset:128
	s_add_i32 m0, s28, 0x1f80
	s_nop 0
	global_load_lds_dwordx4 v132, s[100:101] offset:128
	s_add_i32 m0, s43, 0xffffff80
	s_nop 0
	global_load_lds_dwordx4 v130, vcc offset:128
	s_add_i32 m0, s44, 0xffffff80
	s_nop 0
	global_load_lds_dwordx4 v128, vcc offset:128
	s_waitcnt vmcnt(8)
	s_waitcnt lgkmcnt(0)
	s_barrier
	s_setprio 1
	v_mfma_f32_16x16x32_bf16 v[60:63], v[154:157], v[190:193], v[60:63]
	v_mfma_f32_16x16x32_bf16 v[56:59], v[162:165], v[190:193], v[56:59]
	v_mfma_f32_16x16x32_bf16 v[44:47], v[154:157], v[198:201], v[44:47]
	v_mfma_f32_16x16x32_bf16 v[40:43], v[162:165], v[198:201], v[40:43]
	v_mfma_f32_16x16x32_bf16 v[28:31], v[154:157], v[206:209], v[28:31]
	v_mfma_f32_16x16x32_bf16 v[24:27], v[162:165], v[206:209], v[24:27]
	v_mfma_f32_16x16x32_bf16 v[12:15], v[154:157], v[214:217], v[12:15]
	v_mfma_f32_16x16x32_bf16 v[8:11], v[162:165], v[214:217], v[8:11]
	v_mfma_f32_16x16x32_bf16 v[60:63], v[158:161], v[194:197], v[60:63]
	v_mfma_f32_16x16x32_bf16 v[56:59], v[166:169], v[194:197], v[56:59]
	v_mfma_f32_16x16x32_bf16 v[44:47], v[158:161], v[202:205], v[44:47]
	v_mfma_f32_16x16x32_bf16 v[40:43], v[166:169], v[202:205], v[40:43]
	v_mfma_f32_16x16x32_bf16 v[28:31], v[158:161], v[210:213], v[28:31]
	v_mfma_f32_16x16x32_bf16 v[24:27], v[166:169], v[210:213], v[24:27]
	v_mfma_f32_16x16x32_bf16 v[12:15], v[158:161], v[218:221], v[12:15]
	v_mfma_f32_16x16x32_bf16 v[8:11], v[166:169], v[218:221], v[8:11]
	v_mfma_f32_16x16x32_bf16 v[52:55], v[170:173], v[190:193], v[52:55]
	v_mfma_f32_16x16x32_bf16 v[48:51], v[178:181], v[190:193], v[48:51]
	v_mfma_f32_16x16x32_bf16 v[36:39], v[170:173], v[198:201], v[36:39]
	v_mfma_f32_16x16x32_bf16 v[32:35], v[178:181], v[198:201], v[32:35]
	v_mfma_f32_16x16x32_bf16 v[20:23], v[170:173], v[206:209], v[20:23]
	v_mfma_f32_16x16x32_bf16 v[16:19], v[178:181], v[206:209], v[16:19]
	v_mfma_f32_16x16x32_bf16 v[4:7], v[170:173], v[214:217], v[4:7]
	v_mfma_f32_16x16x32_bf16 v[0:3], v[178:181], v[214:217], v[0:3]
	v_mfma_f32_16x16x32_bf16 v[52:55], v[174:177], v[194:197], v[52:55]
	v_mfma_f32_16x16x32_bf16 v[48:51], v[182:185], v[194:197], v[48:51]
	v_mfma_f32_16x16x32_bf16 v[36:39], v[174:177], v[202:205], v[36:39]
	v_mfma_f32_16x16x32_bf16 v[32:35], v[182:185], v[202:205], v[32:35]
	v_mfma_f32_16x16x32_bf16 v[20:23], v[174:177], v[210:213], v[20:23]
	v_mfma_f32_16x16x32_bf16 v[16:19], v[182:185], v[210:213], v[16:19]
	v_mfma_f32_16x16x32_bf16 v[4:7], v[174:177], v[218:221], v[4:7]
	v_mfma_f32_16x16x32_bf16 v[0:3], v[182:185], v[218:221], v[0:3]
	s_setprio 0
	s_barrier
	s_add_u32 s26, s26, 0x100
	s_addc_u32 s27, s27, 0
	s_add_u32 s62, s62, 0x100
	s_addc_u32 s63, s63, 0
	s_cmp_ge_i32 s64, s48
	s_mov_b32 s28, s64
	s_cbranch_scc0 .LBB0_368

; #define PG8_STAGE(bufoff, gbase, voff) do { _Pragma("unroll") for (int _i = 0; _i < 2; ++_i) \
;         __builtin_amdgcn_global_load_lds((const unsigned*)((const char*)(gbase) + (voff)[_i]), (PG8_LAS unsigned*)(lds + (bufoff) + ldsw + _i * 8192), 16, 0, 0); } while (0)
; #define PG8_LDA(dst, b, h) do { _Pragma("unroll") for (int m = 0; m < 4; ++m) _Pragma("unroll") for (int k = 0; k < 2; ++k) dst[m][k] = *(const PG8_LAS bf16x8*)(lds + PG8_SA(b, h) + aoff + m * 2048 + k * 1024); } while (0)
; #define PG8_LDB(dst, b, h) do { _Pragma("unroll") for (int n = 0; n < 2; ++n) _Pragma("unroll") for (int k = 0; k < 2; ++k) dst[n][k] = *(const PG8_LAS bf16x8*)(lds + PG8_SB(b, h) + boff + n * 2048 + k * 1024); } while (0)
; #define PG8_MMA(ai, bj, At, Bt) do { __builtin_amdgcn_s_setprio(1); _Pragma("unroll") for (int m = 0; m < 4; ++m) _Pragma("unroll") for (int n = 0; n < 2; ++n) _Pragma("unroll") for (int k = 0; k < 2; ++k) \
;         acc[ai][bj][m][n] = __builtin_amdgcn_mfma_f32_16x16x32_bf16(Bt[n][k], At[m][k], acc[ai][bj][m][n], 0, 0, 0); __builtin_amdgcn_s_setprio(0); } while (0)
; #define PG8_WAIT_V(n) asm volatile("s_waitcnt vmcnt(" #n ")" ::: "memory")
; #define PG8_BAR __builtin_amdgcn_s_barrier()
; template <class Epi, class Sched, bool ALIGN_EPI = false, bool SP2 = false>
; __device__ __forceinline__ void gemm_phase(PG8_LAS unsigned char* lds, const Gemm g, const Sched& S, const Epi& E) {
;     ...
;         for (int t = 0; t < nt; t += 2) {
;             const bool last = (t == nt - 2);
;             const char* a1 = cA + (size_t)(t + 1) * kstep;
;             const char* a2 = last ? nA : cA + (size_t)(t + 2) * kstep; const char* b2 = last ? nB : cB + (size_t)(t + 2) * kstep;
;             const char* a3 = a2 + kstep; const char* b3 = b2 + kstep;
;             if (last && has_next) S.a_ready(nxt);
;             if constexpr (SP2) {
;             PG8_LDB(B0, 0, 0); PG8_LDB(B1, 0, 1); PG8_SCHED; PG8_LDA(At, 0, 0); PG8_STAGE(PG8_SA(1, 1), a1 + hstepA, voffA);
;             PG8_WAIT_V(8); PG8_WAIT_L(0); PG8_BAR; PG8_MMA(0, 0, At, B0); PG8_MMA(0, 1, At, B1); PG8_BAR; PG8_SCHED;
;             PG8_LDA(At, 0, 1); PG8_STAGE(PG8_SB(0, 0), b2, voffB); PG8_STAGE(PG8_SB(0, 1), b2 + hstep, voffB); PG8_STAGE(PG8_SA(0, 0), a2, voffA);
;             PG8_WAIT_V(8); PG8_WAIT_L(0); PG8_BAR; PG8_MMA(1, 0, At, B0); PG8_MMA(1, 1, At, B1); PG8_BAR; PG8_SCHED;
.LBB0_523:
	ds_read_b128 v[154:157], v149
	ds_read_b128 v[158:161], v149 offset:1024
	ds_read_b128 v[162:165], v149 offset:2048
	ds_read_b128 v[166:169], v149 offset:3072
	ds_read_b128 v[170:173], v150
	ds_read_b128 v[174:177], v150 offset:1024
	ds_read_b128 v[178:181], v150 offset:2048
	ds_read_b128 v[182:185], v150 offset:3072
	s_add_i32 s61, s30, 2
	s_add_u32 s62, s4, 0xfffe0080
	s_addc_u32 s31, s5, -1
	s_cmp_eq_u32 s52, s30
	s_cselect_b32 s30, s34, s62
	s_cselect_b32 s31, s15, s31
	s_cselect_b32 s63, s25, s60
	s_cselect_b32 s62, s24, s59
	s_add_i32 m0, s41, 0xc000
	ds_read_b128 v[190:193], v151
	ds_read_b128 v[194:197], v151 offset:1024
	ds_read_b128 v[198:201], v151 offset:2048
	ds_read_b128 v[202:205], v151 offset:3072
	ds_read_b128 v[206:209], v151 offset:4096
	ds_read_b128 v[210:213], v151 offset:5120
	ds_read_b128 v[214:217], v151 offset:6144
	ds_read_b128 v[218:221], v151 offset:7168
	global_load_lds_dwordx4 v138, s[4:5]
	s_add_i32 m0, s41, 0xe000
	s_nop 0
	global_load_lds_dwordx4 v140, s[4:5]
	s_waitcnt vmcnt(8)
	s_waitcnt lgkmcnt(0)
	s_barrier
	s_setprio 1
	v_mfma_f32_16x16x32_bf16 v[124:127], v[154:157], v[190:193], v[124:127]
	v_mfma_f32_16x16x32_bf16 v[120:123], v[162:165], v[190:193], v[120:123]
	v_mfma_f32_16x16x32_bf16 v[108:111], v[154:157], v[198:201], v[108:111]
	v_mfma_f32_16x16x32_bf16 v[104:107], v[162:165], v[198:201], v[104:107]
	v_mfma_f32_16x16x32_bf16 v[92:95], v[154:157], v[206:209], v[92:95]
	v_mfma_f32_16x16x32_bf16 v[88:91], v[162:165], v[206:209], v[88:91]
	v_mfma_f32_16x16x32_bf16 v[76:79], v[154:157], v[214:217], v[76:79]
	v_mfma_f32_16x16x32_bf16 v[72:75], v[162:165], v[214:217], v[72:75]
	v_mfma_f32_16x16x32_bf16 v[124:127], v[158:161], v[194:197], v[124:127]
	v_mfma_f32_16x16x32_bf16 v[120:123], v[166:169], v[194:197], v[120:123]
	v_mfma_f32_16x16x32_bf16 v[108:111], v[158:161], v[202:205], v[108:111]
	v_mfma_f32_16x16x32_bf16 v[104:107], v[166:169], v[202:205], v[104:107]
	v_mfma_f32_16x16x32_bf16 v[92:95], v[158:161], v[210:213], v[92:95]
	v_mfma_f32_16x16x32_bf16 v[88:91], v[166:169], v[210:213], v[88:91]
	v_mfma_f32_16x16x32_bf16 v[76:79], v[158:161], v[218:221], v[76:79]
	v_mfma_f32_16x16x32_bf16 v[72:75], v[166:169], v[218:221], v[72:75]
	v_mfma_f32_16x16x32_bf16 v[116:119], v[170:173], v[190:193], v[116:119]
	v_mfma_f32_16x16x32_bf16 v[112:115], v[178:181], v[190:193], v[112:115]
	v_mfma_f32_16x16x32_bf16 v[100:103], v[170:173], v[198:201], v[100:103]
	v_mfma_f32_16x16x32_bf16 v[96:99], v[178:181], v[198:201], v[96:99]
	v_mfma_f32_16x16x32_bf16 v[84:87], v[170:173], v[206:209], v[84:87]
	v_mfma_f32_16x16x32_bf16 v[80:83], v[178:181], v[206:209], v[80:83]
	v_mfma_f32_16x16x32_bf16 v[68:71], v[170:173], v[214:217], v[68:71]
	v_mfma_f32_16x16x32_bf16 v[64:67], v[178:181], v[214:217], v[64:67]
	v_mfma_f32_16x16x32_bf16 v[116:119], v[174:177], v[194:197], v[116:119]
	v_mfma_f32_16x16x32_bf16 v[112:115], v[182:185], v[194:197], v[112:115]
	v_mfma_f32_16x16x32_bf16 v[100:103], v[174:177], v[202:205], v[100:103]
	v_mfma_f32_16x16x32_bf16 v[96:99], v[182:185], v[202:205], v[96:99]
	v_mfma_f32_16x16x32_bf16 v[84:87], v[174:177], v[210:213], v[84:87]
	v_mfma_f32_16x16x32_bf16 v[80:83], v[182:185], v[210:213], v[80:83]
	v_mfma_f32_16x16x32_bf16 v[68:71], v[174:177], v[218:221], v[68:71]
	v_mfma_f32_16x16x32_bf16 v[64:67], v[182:185], v[218:221], v[64:67]
	s_setprio 0
	s_barrier
	s_add_i32 s64, s54, s40
	s_mov_b32 m0, s64
	ds_read_b128 v[190:193], v151 offset:16384
	ds_read_b128 v[194:197], v151 offset:17408
	ds_read_b128 v[198:201], v151 offset:18432
	ds_read_b128 v[202:205], v151 offset:19456
	ds_read_b128 v[206:209], v151 offset:20480
	ds_read_b128 v[210:213], v151 offset:21504
	ds_read_b128 v[214:217], v151 offset:22528
	ds_read_b128 v[218:221], v151 offset:23552
	global_load_lds_dwordx4 v134, s[62:63]
	s_add_i32 m0, s64, 0x2000
	s_mov_b64 s[100:101], s[62:63]
	s_add_i32 s64, s55, s40
	global_load_lds_dwordx4 v132, s[62:63]
	s_add_u32 s62, s62, s10
	s_addc_u32 s63, s63, s11
	s_mov_b32 m0, s64
	s_nop 0
	global_load_lds_dwordx4 v134, s[62:63]
	s_add_i32 m0, s64, 0x2000
	s_nop 0
	global_load_lds_dwordx4 v132, s[62:63]
	s_mov_b32 m0, s41
	s_nop 0
	global_load_lds_dwordx4 v130, s[30:31]
	s_mov_b32 m0, s42
	s_nop 0
	global_load_lds_dwordx4 v128, s[30:31]
	s_waitcnt vmcnt(8)
	s_waitcnt lgkmcnt(0)
	s_barrier
	s_setprio 1
	v_mfma_f32_16x16x32_bf16 v[60:63], v[154:157], v[190:193], v[60:63]
	v_mfma_f32_16x16x32_bf16 v[56:59], v[162:165], v[190:193], v[56:59]
	v_mfma_f32_16x16x32_bf16 v[44:47], v[154:157], v[198:201], v[44:47]
	v_mfma_f32_16x16x32_bf16 v[40:43], v[162:165], v[198:201], v[40:43]
	v_mfma_f32_16x16x32_bf16 v[28:31], v[154:157], v[206:209], v[28:31]
	v_mfma_f32_16x16x32_bf16 v[24:27], v[162:165], v[206:209], v[24:27]
	v_mfma_f32_16x16x32_bf16 v[12:15], v[154:157], v[214:217], v[12:15]
	v_mfma_f32_16x16x32_bf16 v[8:11], v[162:165], v[214:217], v[8:11]
	v_mfma_f32_16x16x32_bf16 v[60:63], v[158:161], v[194:197], v[60:63]
	v_mfma_f32_16x16x32_bf16 v[56:59], v[166:169], v[194:197], v[56:59]
	v_mfma_f32_16x16x32_bf16 v[44:47], v[158:161], v[202:205], v[44:47]
	v_mfma_f32_16x16x32_bf16 v[40:43], v[166:169], v[202:205], v[40:43]
	v_mfma_f32_16x16x32_bf16 v[28:31], v[158:161], v[210:213], v[28:31]
	v_mfma_f32_16x16x32_bf16 v[24:27], v[166:169], v[210:213], v[24:27]
	v_mfma_f32_16x16x32_bf16 v[12:15], v[158:161], v[218:221], v[12:15]
	v_mfma_f32_16x16x32_bf16 v[8:11], v[166:169], v[218:221], v[8:11]
	v_mfma_f32_16x16x32_bf16 v[52:55], v[170:173], v[190:193], v[52:55]
	v_mfma_f32_16x16x32_bf16 v[48:51], v[178:181], v[190:193], v[48:51]
	v_mfma_f32_16x16x32_bf16 v[36:39], v[170:173], v[198:201], v[36:39]
	v_mfma_f32_16x16x32_bf16 v[32:35], v[178:181], v[198:201], v[32:35]
	v_mfma_f32_16x16x32_bf16 v[20:23], v[170:173], v[206:209], v[20:23]
	v_mfma_f32_16x16x32_bf16 v[16:19], v[178:181], v[206:209], v[16:19]
	v_mfma_f32_16x16x32_bf16 v[4:7], v[170:173], v[214:217], v[4:7]
	v_mfma_f32_16x16x32_bf16 v[0:3], v[178:181], v[214:217], v[0:3]
	v_mfma_f32_16x16x32_bf16 v[52:55], v[174:177], v[194:197], v[52:55]
	v_mfma_f32_16x16x32_bf16 v[48:51], v[182:185], v[194:197], v[48:51]
	v_mfma_f32_16x16x32_bf16 v[36:39], v[174:177], v[202:205], v[36:39]
	v_mfma_f32_16x16x32_bf16 v[32:35], v[182:185], v[202:205], v[32:35]
	v_mfma_f32_16x16x32_bf16 v[20:23], v[174:177], v[210:213], v[20:23]
	v_mfma_f32_16x16x32_bf16 v[16:19], v[182:185], v[210:213], v[16:19]
	v_mfma_f32_16x16x32_bf16 v[4:7], v[174:177], v[218:221], v[4:7]
	v_mfma_f32_16x16x32_bf16 v[0:3], v[182:185], v[218:221], v[0:3]
	s_setprio 0
	s_barrier
; #define PG8_STAGE(bufoff, gbase, voff) do { _Pragma("unroll") for (int _i = 0; _i < 2; ++_i) \
;         __builtin_amdgcn_global_load_lds((const unsigned*)((const char*)(gbase) + (voff)[_i]), (PG8_LAS unsigned*)(lds + (bufoff) + ldsw + _i * 8192), 16, 0, 0); } while (0)
; #define PG8_LDA(dst, b, h) do { _Pragma("unroll") for (int m = 0; m < 4; ++m) _Pragma("unroll") for (int k = 0; k < 2; ++k) dst[m][k] = *(const PG8_LAS bf16x8*)(lds + PG8_SA(b, h) + aoff + m * 2048 + k * 1024); } while (0)
; #define PG8_LDB(dst, b, h) do { _Pragma("unroll") for (int n = 0; n < 2; ++n) _Pragma("unroll") for (int k = 0; k < 2; ++k) dst[n][k] = *(const PG8_LAS bf16x8*)(lds + PG8_SB(b, h) + boff + n * 2048 + k * 1024); } while (0)
; #define PG8_MMA(ai, bj, At, Bt) do { __builtin_amdgcn_s_setprio(1); _Pragma("unroll") for (int m = 0; m < 4; ++m) _Pragma("unroll") for (int n = 0; n < 2; ++n) _Pragma("unroll") for (int k = 0; k < 2; ++k) \
;         acc[ai][bj][m][n] = __builtin_amdgcn_mfma_f32_16x16x32_bf16(Bt[n][k], At[m][k], acc[ai][bj][m][n], 0, 0, 0); __builtin_amdgcn_s_setprio(0); } while (0)
; #define PG8_WAIT_V(n) asm volatile("s_waitcnt vmcnt(" #n ")" ::: "memory")
; #define PG8_WAIT_L(n) asm volatile("s_waitcnt lgkmcnt(" #n ")" ::: "memory")
; #define PG8_BAR __builtin_amdgcn_s_barrier()
; #define PG8_SCHED __builtin_amdgcn_sched_barrier(0)
; template <class Epi, class Sched, bool ALIGN_EPI = false, bool SP2 = false>
; __device__ __forceinline__ void gemm_phase(PG8_LAS unsigned char* lds, const Gemm g, const Sched& S, const Epi& E) {
;     ...
;             PG8_LDB(B0, 1, 0); PG8_LDB(B1, 1, 1); PG8_SCHED; PG8_LDA(At, 1, 0); PG8_STAGE(PG8_SA(0, 1), a2 + hstepA, voffA);
;             PG8_WAIT_V(8); PG8_WAIT_L(0); PG8_BAR; PG8_MMA(0, 0, At, B0); PG8_MMA(0, 1, At, B1); PG8_BAR; PG8_SCHED;
;             PG8_LDA(At, 1, 1); PG8_STAGE(PG8_SB(1, 0), b3, voffB); PG8_STAGE(PG8_SB(1, 1), b3 + hstep, voffB); PG8_STAGE(PG8_SA(1, 0), a3, voffA);
;             PG8_WAIT_V(8); PG8_WAIT_L(0); PG8_BAR; PG8_MMA(1, 0, At, B0); PG8_MMA(1, 1, At, B1); PG8_BAR; PG8_SCHED;
	s_add_i32 s62, 0, 0x18000
	s_add_i32 s63, 0, 0x1c000
	v_add_u32_e32 v166, s62, v147
	v_add_u32_e32 v182, s63, v147
	ds_read_b128 v[154:157], v166
	ds_read_b128 v[158:161], v166 offset:1024
	ds_read_b128 v[162:165], v166 offset:2048
	ds_read_b128 v[166:169], v166 offset:3072
	ds_read_b128 v[170:173], v182
	ds_read_b128 v[174:177], v182 offset:1024
	ds_read_b128 v[178:181], v182 offset:2048
	ds_read_b128 v[182:185], v182 offset:3072
	s_mov_b64 vcc, s[30:31]
	s_add_u32 s30, s30, 0x20000
	s_addc_u32 s31, s31, 0
	s_mov_b32 m0, s43
	ds_read_b128 v[190:193], v151 offset:32768
	ds_read_b128 v[194:197], v151 offset:33792
	ds_read_b128 v[198:201], v151 offset:34816
	ds_read_b128 v[202:205], v151 offset:35840
	ds_read_b128 v[206:209], v151 offset:36864
	ds_read_b128 v[210:213], v151 offset:37888
	ds_read_b128 v[214:217], v151 offset:38912
	ds_read_b128 v[218:221], v151 offset:39936
	global_load_lds_dwordx4 v130, s[30:31]
	s_mov_b32 m0, s44
	s_nop 0
	global_load_lds_dwordx4 v128, s[30:31]
	s_waitcnt vmcnt(8)
	s_waitcnt lgkmcnt(0)
	s_barrier
	s_setprio 1
	v_mfma_f32_16x16x32_bf16 v[124:127], v[154:157], v[190:193], v[124:127]
	v_mfma_f32_16x16x32_bf16 v[120:123], v[162:165], v[190:193], v[120:123]
	v_mfma_f32_16x16x32_bf16 v[108:111], v[154:157], v[198:201], v[108:111]
	v_mfma_f32_16x16x32_bf16 v[104:107], v[162:165], v[198:201], v[104:107]
	v_mfma_f32_16x16x32_bf16 v[92:95], v[154:157], v[206:209], v[92:95]
	v_mfma_f32_16x16x32_bf16 v[88:91], v[162:165], v[206:209], v[88:91]
	v_mfma_f32_16x16x32_bf16 v[76:79], v[154:157], v[214:217], v[76:79]
	v_mfma_f32_16x16x32_bf16 v[72:75], v[162:165], v[214:217], v[72:75]
	v_mfma_f32_16x16x32_bf16 v[124:127], v[158:161], v[194:197], v[124:127]
	v_mfma_f32_16x16x32_bf16 v[120:123], v[166:169], v[194:197], v[120:123]
	v_mfma_f32_16x16x32_bf16 v[108:111], v[158:161], v[202:205], v[108:111]
	v_mfma_f32_16x16x32_bf16 v[104:107], v[166:169], v[202:205], v[104:107]
	v_mfma_f32_16x16x32_bf16 v[92:95], v[158:161], v[210:213], v[92:95]
	v_mfma_f32_16x16x32_bf16 v[88:91], v[166:169], v[210:213], v[88:91]
	v_mfma_f32_16x16x32_bf16 v[76:79], v[158:161], v[218:221], v[76:79]
	v_mfma_f32_16x16x32_bf16 v[72:75], v[166:169], v[218:221], v[72:75]
	v_mfma_f32_16x16x32_bf16 v[116:119], v[170:173], v[190:193], v[116:119]
	v_mfma_f32_16x16x32_bf16 v[112:115], v[178:181], v[190:193], v[112:115]
	v_mfma_f32_16x16x32_bf16 v[100:103], v[170:173], v[198:201], v[100:103]
	v_mfma_f32_16x16x32_bf16 v[96:99], v[178:181], v[198:201], v[96:99]
	v_mfma_f32_16x16x32_bf16 v[84:87], v[170:173], v[206:209], v[84:87]
	v_mfma_f32_16x16x32_bf16 v[80:83], v[178:181], v[206:209], v[80:83]
	v_mfma_f32_16x16x32_bf16 v[68:71], v[170:173], v[214:217], v[68:71]
	v_mfma_f32_16x16x32_bf16 v[64:67], v[178:181], v[214:217], v[64:67]
	v_mfma_f32_16x16x32_bf16 v[116:119], v[174:177], v[194:197], v[116:119]
	v_mfma_f32_16x16x32_bf16 v[112:115], v[182:185], v[194:197], v[112:115]
	v_mfma_f32_16x16x32_bf16 v[100:103], v[174:177], v[202:205], v[100:103]
	v_mfma_f32_16x16x32_bf16 v[96:99], v[182:185], v[202:205], v[96:99]
	v_mfma_f32_16x16x32_bf16 v[84:87], v[174:177], v[210:213], v[84:87]
	v_mfma_f32_16x16x32_bf16 v[80:83], v[182:185], v[210:213], v[80:83]
	v_mfma_f32_16x16x32_bf16 v[68:71], v[174:177], v[218:221], v[68:71]
	v_mfma_f32_16x16x32_bf16 v[64:67], v[182:185], v[218:221], v[64:67]
	s_setprio 0
	s_barrier
	s_add_i32 s30, s62, s40
	s_add_i32 m0, s30, 0xffffff80
	ds_read_b128 v[190:193], v151 offset:49152
	ds_read_b128 v[194:197], v151 offset:50176
	ds_read_b128 v[198:201], v151 offset:51200
	ds_read_b128 v[202:205], v151 offset:52224
	ds_read_b128 v[206:209], v151 offset:53248
	ds_read_b128 v[210:213], v151 offset:54272
	ds_read_b128 v[214:217], v151 offset:55296
	ds_read_b128 v[218:221], v151 offset:56320
	global_load_lds_dwordx4 v134, s[100:101] offset:128
	s_add_i32 m0, s30, 0x1f80
	s_add_i32 s30, s63, s40
	global_load_lds_dwordx4 v132, s[100:101] offset:128
	s_add_u32 s100, s100, s10
	s_addc_u32 s101, s101, s11
	s_add_i32 m0, s30, 0xffffff80
	s_nop 0
	global_load_lds_dwordx4 v134, s[100:101] offset:128
	s_add_i32 m0, s30, 0x1f80
	s_nop 0
	global_load_lds_dwordx4 v132, s[100:101] offset:128
	s_add_i32 m0, s48, 0xffffff80
	s_nop 0
	global_load_lds_dwordx4 v130, vcc offset:128
	s_add_i32 m0, s49, 0xffffff80
	s_nop 0
	global_load_lds_dwordx4 v128, vcc offset:128
	s_waitcnt vmcnt(8)
	s_waitcnt lgkmcnt(0)
	s_barrier
	s_setprio 1
	v_mfma_f32_16x16x32_bf16 v[60:63], v[154:157], v[190:193], v[60:63]
	v_mfma_f32_16x16x32_bf16 v[56:59], v[162:165], v[190:193], v[56:59]
	v_mfma_f32_16x16x32_bf16 v[44:47], v[154:157], v[198:201], v[44:47]
	v_mfma_f32_16x16x32_bf16 v[40:43], v[162:165], v[198:201], v[40:43]
	v_mfma_f32_16x16x32_bf16 v[28:31], v[154:157], v[206:209], v[28:31]
	v_mfma_f32_16x16x32_bf16 v[24:27], v[162:165], v[206:209], v[24:27]
	v_mfma_f32_16x16x32_bf16 v[12:15], v[154:157], v[214:217], v[12:15]
	v_mfma_f32_16x16x32_bf16 v[8:11], v[162:165], v[214:217], v[8:11]
	v_mfma_f32_16x16x32_bf16 v[60:63], v[158:161], v[194:197], v[60:63]
	v_mfma_f32_16x16x32_bf16 v[56:59], v[166:169], v[194:197], v[56:59]
	v_mfma_f32_16x16x32_bf16 v[44:47], v[158:161], v[202:205], v[44:47]
	v_mfma_f32_16x16x32_bf16 v[40:43], v[166:169], v[202:205], v[40:43]
	v_mfma_f32_16x16x32_bf16 v[28:31], v[158:161], v[210:213], v[28:31]
	v_mfma_f32_16x16x32_bf16 v[24:27], v[166:169], v[210:213], v[24:27]
	v_mfma_f32_16x16x32_bf16 v[12:15], v[158:161], v[218:221], v[12:15]
	v_mfma_f32_16x16x32_bf16 v[8:11], v[166:169], v[218:221], v[8:11]
	v_mfma_f32_16x16x32_bf16 v[52:55], v[170:173], v[190:193], v[52:55]
	v_mfma_f32_16x16x32_bf16 v[48:51], v[178:181], v[190:193], v[48:51]
	v_mfma_f32_16x16x32_bf16 v[36:39], v[170:173], v[198:201], v[36:39]
	v_mfma_f32_16x16x32_bf16 v[32:35], v[178:181], v[198:201], v[32:35]
	v_mfma_f32_16x16x32_bf16 v[20:23], v[170:173], v[206:209], v[20:23]
	v_mfma_f32_16x16x32_bf16 v[16:19], v[178:181], v[206:209], v[16:19]
	v_mfma_f32_16x16x32_bf16 v[4:7], v[170:173], v[214:217], v[4:7]
	v_mfma_f32_16x16x32_bf16 v[0:3], v[178:181], v[214:217], v[0:3]
	v_mfma_f32_16x16x32_bf16 v[52:55], v[174:177], v[194:197], v[52:55]
	v_mfma_f32_16x16x32_bf16 v[48:51], v[182:185], v[194:197], v[48:51]
	v_mfma_f32_16x16x32_bf16 v[36:39], v[174:177], v[202:205], v[36:39]
	v_mfma_f32_16x16x32_bf16 v[32:35], v[182:185], v[202:205], v[32:35]
	v_mfma_f32_16x16x32_bf16 v[20:23], v[174:177], v[210:213], v[20:23]
	v_mfma_f32_16x16x32_bf16 v[16:19], v[182:185], v[210:213], v[16:19]
	v_mfma_f32_16x16x32_bf16 v[4:7], v[174:177], v[218:221], v[4:7]
	v_mfma_f32_16x16x32_bf16 v[0:3], v[182:185], v[218:221], v[0:3]
	s_setprio 0
	s_barrier
	s_add_u32 s4, s4, 0x100
	s_addc_u32 s5, s5, 0
	s_add_u32 s59, s59, 0x100
	s_addc_u32 s60, s60, 0
	s_cmp_ge_i32 s61, s51
	s_mov_b32 s30, s61
	s_cbranch_scc0 .LBB0_523

; #define PG8_STAGE(bufoff, gbase, voff) do { _Pragma("unroll") for (int _i = 0; _i < 2; ++_i) \
;         __builtin_amdgcn_global_load_lds((const unsigned*)((const char*)(gbase) + (voff)[_i]), (PG8_LAS unsigned*)(lds + (bufoff) + ldsw + _i * 8192), 16, 0, 0); } while (0)
; #define PG8_LDA(dst, b, h) do { _Pragma("unroll") for (int m = 0; m < 4; ++m) _Pragma("unroll") for (int k = 0; k < 2; ++k) dst[m][k] = *(const PG8_LAS bf16x8*)(lds + PG8_SA(b, h) + aoff + m * 2048 + k * 1024); } while (0)
; #define PG8_LDB(dst, b, h) do { _Pragma("unroll") for (int n = 0; n < 2; ++n) _Pragma("unroll") for (int k = 0; k < 2; ++k) dst[n][k] = *(const PG8_LAS bf16x8*)(lds + PG8_SB(b, h) + boff + n * 2048 + k * 1024); } while (0)
; #define PG8_MMA(ai, bj, At, Bt) do { __builtin_amdgcn_s_setprio(1); _Pragma("unroll") for (int m = 0; m < 4; ++m) _Pragma("unroll") for (int n = 0; n < 2; ++n) _Pragma("unroll") for (int k = 0; k < 2; ++k) \
;         acc[ai][bj][m][n] = __builtin_amdgcn_mfma_f32_16x16x32_bf16(Bt[n][k], At[m][k], acc[ai][bj][m][n], 0, 0, 0); __builtin_amdgcn_s_setprio(0); } while (0)
; #define PG8_WAIT_V(n) asm volatile("s_waitcnt vmcnt(" #n ")" ::: "memory")
; #define PG8_BAR __builtin_amdgcn_s_barrier()
; template <class Epi, class Sched, bool ALIGN_EPI = false, bool SP2 = false>
; __device__ __forceinline__ void gemm_phase(PG8_LAS unsigned char* lds, const Gemm g, const Sched& S, const Epi& E) {
;     ...
;         for (int t = 0; t < nt; t += 2) {
;             const bool last = (t == nt - 2);
;             const char* a1 = cA + (size_t)(t + 1) * kstep;
;             const char* a2 = last ? nA : cA + (size_t)(t + 2) * kstep; const char* b2 = last ? nB : cB + (size_t)(t + 2) * kstep;
;             const char* a3 = a2 + kstep; const char* b3 = b2 + kstep;
;             if (last && has_next) S.a_ready(nxt);
;             if constexpr (SP2) {
;             PG8_LDB(B0, 0, 0); PG8_LDB(B1, 0, 1); PG8_SCHED; PG8_LDA(At, 0, 0); PG8_STAGE(PG8_SA(1, 1), a1 + hstepA, voffA);
;             PG8_WAIT_V(8); PG8_WAIT_L(0); PG8_BAR; PG8_MMA(0, 0, At, B0); PG8_MMA(0, 1, At, B1); PG8_BAR; PG8_SCHED;
;             PG8_LDA(At, 0, 1); PG8_STAGE(PG8_SB(0, 0), b2, voffB); PG8_STAGE(PG8_SB(0, 1), b2 + hstep, voffB); PG8_STAGE(PG8_SA(0, 0), a2, voffA);
;             PG8_WAIT_V(8); PG8_WAIT_L(0); PG8_BAR; PG8_MMA(1, 0, At, B0); PG8_MMA(1, 1, At, B1); PG8_BAR; PG8_SCHED;
.LBB0_601:
	ds_read_b128 v[150:153], v147
	ds_read_b128 v[154:157], v147 offset:1024
	ds_read_b128 v[158:161], v147 offset:2048
	ds_read_b128 v[162:165], v147 offset:3072
	ds_read_b128 v[166:169], v148
	ds_read_b128 v[170:173], v148 offset:1024
	ds_read_b128 v[174:177], v148 offset:2048
	ds_read_b128 v[178:181], v148 offset:3072
	s_add_i32 s60, s30, 2
	s_add_u32 s61, s10, 0xfffc0080
	s_addc_u32 s31, s11, -1
	s_cmp_eq_u32 s51, s30
	s_cselect_b32 s30, s59, s61
	s_cselect_b32 s31, s23, s31
	s_cselect_b32 s63, s25, s35
	s_cselect_b32 s62, s24, s34
	s_add_i32 m0, s29, 0xc000
	ds_read_b128 v[182:185], v149
	ds_read_b128 v[190:193], v149 offset:1024
	ds_read_b128 v[194:197], v149 offset:2048
	ds_read_b128 v[198:201], v149 offset:3072
	ds_read_b128 v[202:205], v149 offset:4096
	ds_read_b128 v[206:209], v149 offset:5120
	ds_read_b128 v[210:213], v149 offset:6144
	ds_read_b128 v[214:217], v149 offset:7168
	global_load_lds_dwordx4 v136, s[10:11]
	s_add_i32 m0, s29, 0xe000
	s_nop 0
	global_load_lds_dwordx4 v138, s[10:11]
	s_waitcnt vmcnt(8)
	s_waitcnt lgkmcnt(0)
	s_barrier
	s_setprio 1
	v_mfma_f32_16x16x32_bf16 v[120:123], v[150:153], v[182:185], v[120:123]
	v_mfma_f32_16x16x32_bf16 v[112:115], v[158:161], v[182:185], v[112:115]
	v_mfma_f32_16x16x32_bf16 v[104:107], v[150:153], v[194:197], v[104:107]
	v_mfma_f32_16x16x32_bf16 v[96:99], v[158:161], v[194:197], v[96:99]
	v_mfma_f32_16x16x32_bf16 v[88:91], v[150:153], v[202:205], v[88:91]
	v_mfma_f32_16x16x32_bf16 v[80:83], v[158:161], v[202:205], v[80:83]
	v_mfma_f32_16x16x32_bf16 v[72:75], v[150:153], v[210:213], v[72:75]
	v_mfma_f32_16x16x32_bf16 v[64:67], v[158:161], v[210:213], v[64:67]
	v_mfma_f32_16x16x32_bf16 v[120:123], v[154:157], v[190:193], v[120:123]
	v_mfma_f32_16x16x32_bf16 v[112:115], v[162:165], v[190:193], v[112:115]
	v_mfma_f32_16x16x32_bf16 v[104:107], v[154:157], v[198:201], v[104:107]
	v_mfma_f32_16x16x32_bf16 v[96:99], v[162:165], v[198:201], v[96:99]
	v_mfma_f32_16x16x32_bf16 v[88:91], v[154:157], v[206:209], v[88:91]
	v_mfma_f32_16x16x32_bf16 v[80:83], v[162:165], v[206:209], v[80:83]
	v_mfma_f32_16x16x32_bf16 v[72:75], v[154:157], v[214:217], v[72:75]
	v_mfma_f32_16x16x32_bf16 v[64:67], v[162:165], v[214:217], v[64:67]
	v_mfma_f32_16x16x32_bf16 v[124:127], v[166:169], v[182:185], v[124:127]
	v_mfma_f32_16x16x32_bf16 v[116:119], v[174:177], v[182:185], v[116:119]
	v_mfma_f32_16x16x32_bf16 v[108:111], v[166:169], v[194:197], v[108:111]
	v_mfma_f32_16x16x32_bf16 v[100:103], v[174:177], v[194:197], v[100:103]
	v_mfma_f32_16x16x32_bf16 v[92:95], v[166:169], v[202:205], v[92:95]
	v_mfma_f32_16x16x32_bf16 v[84:87], v[174:177], v[202:205], v[84:87]
	v_mfma_f32_16x16x32_bf16 v[76:79], v[166:169], v[210:213], v[76:79]
	v_mfma_f32_16x16x32_bf16 v[68:71], v[174:177], v[210:213], v[68:71]
	v_mfma_f32_16x16x32_bf16 v[124:127], v[170:173], v[190:193], v[124:127]
	v_mfma_f32_16x16x32_bf16 v[116:119], v[178:181], v[190:193], v[116:119]
	v_mfma_f32_16x16x32_bf16 v[108:111], v[170:173], v[198:201], v[108:111]
	v_mfma_f32_16x16x32_bf16 v[100:103], v[178:181], v[198:201], v[100:103]
	v_mfma_f32_16x16x32_bf16 v[92:95], v[170:173], v[206:209], v[92:95]
	v_mfma_f32_16x16x32_bf16 v[84:87], v[178:181], v[206:209], v[84:87]
	v_mfma_f32_16x16x32_bf16 v[76:79], v[170:173], v[214:217], v[76:79]
	v_mfma_f32_16x16x32_bf16 v[68:71], v[178:181], v[214:217], v[68:71]
	s_setprio 0
	s_barrier
	s_add_i32 s61, s52, s38
	s_mov_b32 m0, s61
	ds_read_b128 v[182:185], v149 offset:16384
	ds_read_b128 v[190:193], v149 offset:17408
	ds_read_b128 v[194:197], v149 offset:18432
	ds_read_b128 v[198:201], v149 offset:19456
	ds_read_b128 v[202:205], v149 offset:20480
	ds_read_b128 v[206:209], v149 offset:21504
	ds_read_b128 v[210:213], v149 offset:22528
	ds_read_b128 v[214:217], v149 offset:23552
	global_load_lds_dwordx4 v134, s[62:63]
	s_add_i32 m0, s61, 0x2000
	s_mov_b64 s[100:101], s[62:63]
	s_add_i32 s61, s53, s38
	global_load_lds_dwordx4 v132, s[62:63]
	s_add_u32 s62, s62, s4
	s_addc_u32 s63, s63, s5
	s_mov_b32 m0, s61
	s_nop 0
	global_load_lds_dwordx4 v134, s[62:63]
	s_add_i32 m0, s61, 0x2000
	s_nop 0
	global_load_lds_dwordx4 v132, s[62:63]
	s_mov_b32 m0, s29
	s_nop 0
	global_load_lds_dwordx4 v128, s[30:31]
	s_mov_b32 m0, s41
	s_nop 0
	global_load_lds_dwordx4 v130, s[30:31]
	s_waitcnt vmcnt(8)
	s_waitcnt lgkmcnt(0)
	s_barrier
	s_setprio 1
	v_mfma_f32_16x16x32_bf16 v[56:59], v[150:153], v[182:185], v[56:59]
	v_mfma_f32_16x16x32_bf16 v[48:51], v[158:161], v[182:185], v[48:51]
	v_mfma_f32_16x16x32_bf16 v[40:43], v[150:153], v[194:197], v[40:43]
	v_mfma_f32_16x16x32_bf16 v[32:35], v[158:161], v[194:197], v[32:35]
	v_mfma_f32_16x16x32_bf16 v[24:27], v[150:153], v[202:205], v[24:27]
	v_mfma_f32_16x16x32_bf16 v[16:19], v[158:161], v[202:205], v[16:19]
	v_mfma_f32_16x16x32_bf16 v[8:11], v[150:153], v[210:213], v[8:11]
	v_mfma_f32_16x16x32_bf16 v[0:3], v[158:161], v[210:213], v[0:3]
	v_mfma_f32_16x16x32_bf16 v[56:59], v[154:157], v[190:193], v[56:59]
	v_mfma_f32_16x16x32_bf16 v[48:51], v[162:165], v[190:193], v[48:51]
	v_mfma_f32_16x16x32_bf16 v[40:43], v[154:157], v[198:201], v[40:43]
	v_mfma_f32_16x16x32_bf16 v[32:35], v[162:165], v[198:201], v[32:35]
	v_mfma_f32_16x16x32_bf16 v[24:27], v[154:157], v[206:209], v[24:27]
	v_mfma_f32_16x16x32_bf16 v[16:19], v[162:165], v[206:209], v[16:19]
	v_mfma_f32_16x16x32_bf16 v[8:11], v[154:157], v[214:217], v[8:11]
	v_mfma_f32_16x16x32_bf16 v[0:3], v[162:165], v[214:217], v[0:3]
	v_mfma_f32_16x16x32_bf16 v[60:63], v[166:169], v[182:185], v[60:63]
	v_mfma_f32_16x16x32_bf16 v[52:55], v[174:177], v[182:185], v[52:55]
	v_mfma_f32_16x16x32_bf16 v[44:47], v[166:169], v[194:197], v[44:47]
	v_mfma_f32_16x16x32_bf16 v[36:39], v[174:177], v[194:197], v[36:39]
	v_mfma_f32_16x16x32_bf16 v[28:31], v[166:169], v[202:205], v[28:31]
	v_mfma_f32_16x16x32_bf16 v[20:23], v[174:177], v[202:205], v[20:23]
	v_mfma_f32_16x16x32_bf16 v[12:15], v[166:169], v[210:213], v[12:15]
	v_mfma_f32_16x16x32_bf16 v[4:7], v[174:177], v[210:213], v[4:7]
	v_mfma_f32_16x16x32_bf16 v[60:63], v[170:173], v[190:193], v[60:63]
	v_mfma_f32_16x16x32_bf16 v[52:55], v[178:181], v[190:193], v[52:55]
	v_mfma_f32_16x16x32_bf16 v[44:47], v[170:173], v[198:201], v[44:47]
	v_mfma_f32_16x16x32_bf16 v[36:39], v[178:181], v[198:201], v[36:39]
	v_mfma_f32_16x16x32_bf16 v[28:31], v[170:173], v[206:209], v[28:31]
	v_mfma_f32_16x16x32_bf16 v[20:23], v[178:181], v[206:209], v[20:23]
	v_mfma_f32_16x16x32_bf16 v[12:15], v[170:173], v[214:217], v[12:15]
	v_mfma_f32_16x16x32_bf16 v[4:7], v[178:181], v[214:217], v[4:7]
	s_setprio 0
	s_barrier
; #define PG8_STAGE(bufoff, gbase, voff) do { _Pragma("unroll") for (int _i = 0; _i < 2; ++_i) \
;         __builtin_amdgcn_global_load_lds((const unsigned*)((const char*)(gbase) + (voff)[_i]), (PG8_LAS unsigned*)(lds + (bufoff) + ldsw + _i * 8192), 16, 0, 0); } while (0)
; #define PG8_LDA(dst, b, h) do { _Pragma("unroll") for (int m = 0; m < 4; ++m) _Pragma("unroll") for (int k = 0; k < 2; ++k) dst[m][k] = *(const PG8_LAS bf16x8*)(lds + PG8_SA(b, h) + aoff + m * 2048 + k * 1024); } while (0)
; #define PG8_LDB(dst, b, h) do { _Pragma("unroll") for (int n = 0; n < 2; ++n) _Pragma("unroll") for (int k = 0; k < 2; ++k) dst[n][k] = *(const PG8_LAS bf16x8*)(lds + PG8_SB(b, h) + boff + n * 2048 + k * 1024); } while (0)
; #define PG8_MMA(ai, bj, At, Bt) do { __builtin_amdgcn_s_setprio(1); _Pragma("unroll") for (int m = 0; m < 4; ++m) _Pragma("unroll") for (int n = 0; n < 2; ++n) _Pragma("unroll") for (int k = 0; k < 2; ++k) \
;         acc[ai][bj][m][n] = __builtin_amdgcn_mfma_f32_16x16x32_bf16(Bt[n][k], At[m][k], acc[ai][bj][m][n], 0, 0, 0); __builtin_amdgcn_s_setprio(0); } while (0)
; #define PG8_WAIT_V(n) asm volatile("s_waitcnt vmcnt(" #n ")" ::: "memory")
; #define PG8_WAIT_L(n) asm volatile("s_waitcnt lgkmcnt(" #n ")" ::: "memory")
; #define PG8_BAR __builtin_amdgcn_s_barrier()
; #define PG8_SCHED __builtin_amdgcn_sched_barrier(0)
; template <class Epi, class Sched, bool ALIGN_EPI = false, bool SP2 = false>
; __device__ __forceinline__ void gemm_phase(PG8_LAS unsigned char* lds, const Gemm g, const Sched& S, const Epi& E) {
;     ...
;             PG8_LDB(B0, 1, 0); PG8_LDB(B1, 1, 1); PG8_SCHED; PG8_LDA(At, 1, 0); PG8_STAGE(PG8_SA(0, 1), a2 + hstepA, voffA);
;             PG8_WAIT_V(8); PG8_WAIT_L(0); PG8_BAR; PG8_MMA(0, 0, At, B0); PG8_MMA(0, 1, At, B1); PG8_BAR; PG8_SCHED;
;             PG8_LDA(At, 1, 1); PG8_STAGE(PG8_SB(1, 0), b3, voffB); PG8_STAGE(PG8_SB(1, 1), b3 + hstep, voffB); PG8_STAGE(PG8_SA(1, 0), a3, voffA);
;             PG8_WAIT_V(8); PG8_WAIT_L(0); PG8_BAR; PG8_MMA(1, 0, At, B0); PG8_MMA(1, 1, At, B1); PG8_BAR; PG8_SCHED;
	s_add_i32 s61, 0, 0x18000
	s_add_i32 s62, 0, 0x1c000
	v_add_u32_e32 v162, s61, v145
	v_add_u32_e32 v178, s62, v145
	ds_read_b128 v[150:153], v162
	ds_read_b128 v[154:157], v162 offset:1024
	ds_read_b128 v[158:161], v162 offset:2048
	ds_read_b128 v[162:165], v162 offset:3072
	ds_read_b128 v[166:169], v178
	ds_read_b128 v[170:173], v178 offset:1024
	ds_read_b128 v[174:177], v178 offset:2048
	ds_read_b128 v[178:181], v178 offset:3072
	s_mov_b64 vcc, s[30:31]
	s_add_u32 s30, s30, 0x40000
	s_addc_u32 s31, s31, 0
	s_mov_b32 m0, s42
	ds_read_b128 v[182:185], v149 offset:32768
	ds_read_b128 v[190:193], v149 offset:33792
	ds_read_b128 v[194:197], v149 offset:34816
	ds_read_b128 v[198:201], v149 offset:35840
	ds_read_b128 v[202:205], v149 offset:36864
	ds_read_b128 v[206:209], v149 offset:37888
	ds_read_b128 v[210:213], v149 offset:38912
	ds_read_b128 v[214:217], v149 offset:39936
	global_load_lds_dwordx4 v128, s[30:31]
	s_mov_b32 m0, s43
	s_nop 0
	global_load_lds_dwordx4 v130, s[30:31]
	s_waitcnt vmcnt(8)
	s_waitcnt lgkmcnt(0)
	s_barrier
	s_setprio 1
	v_mfma_f32_16x16x32_bf16 v[120:123], v[150:153], v[182:185], v[120:123]
	v_mfma_f32_16x16x32_bf16 v[112:115], v[158:161], v[182:185], v[112:115]
	v_mfma_f32_16x16x32_bf16 v[104:107], v[150:153], v[194:197], v[104:107]
	v_mfma_f32_16x16x32_bf16 v[96:99], v[158:161], v[194:197], v[96:99]
	v_mfma_f32_16x16x32_bf16 v[88:91], v[150:153], v[202:205], v[88:91]
	v_mfma_f32_16x16x32_bf16 v[80:83], v[158:161], v[202:205], v[80:83]
	v_mfma_f32_16x16x32_bf16 v[72:75], v[150:153], v[210:213], v[72:75]
	v_mfma_f32_16x16x32_bf16 v[64:67], v[158:161], v[210:213], v[64:67]
	v_mfma_f32_16x16x32_bf16 v[120:123], v[154:157], v[190:193], v[120:123]
	v_mfma_f32_16x16x32_bf16 v[112:115], v[162:165], v[190:193], v[112:115]
	v_mfma_f32_16x16x32_bf16 v[104:107], v[154:157], v[198:201], v[104:107]
	v_mfma_f32_16x16x32_bf16 v[96:99], v[162:165], v[198:201], v[96:99]
	v_mfma_f32_16x16x32_bf16 v[88:91], v[154:157], v[206:209], v[88:91]
	v_mfma_f32_16x16x32_bf16 v[80:83], v[162:165], v[206:209], v[80:83]
	v_mfma_f32_16x16x32_bf16 v[72:75], v[154:157], v[214:217], v[72:75]
	v_mfma_f32_16x16x32_bf16 v[64:67], v[162:165], v[214:217], v[64:67]
	v_mfma_f32_16x16x32_bf16 v[124:127], v[166:169], v[182:185], v[124:127]
	v_mfma_f32_16x16x32_bf16 v[116:119], v[174:177], v[182:185], v[116:119]
	v_mfma_f32_16x16x32_bf16 v[108:111], v[166:169], v[194:197], v[108:111]
	v_mfma_f32_16x16x32_bf16 v[100:103], v[174:177], v[194:197], v[100:103]
	v_mfma_f32_16x16x32_bf16 v[92:95], v[166:169], v[202:205], v[92:95]
	v_mfma_f32_16x16x32_bf16 v[84:87], v[174:177], v[202:205], v[84:87]
	v_mfma_f32_16x16x32_bf16 v[76:79], v[166:169], v[210:213], v[76:79]
	v_mfma_f32_16x16x32_bf16 v[68:71], v[174:177], v[210:213], v[68:71]
	v_mfma_f32_16x16x32_bf16 v[124:127], v[170:173], v[190:193], v[124:127]
	v_mfma_f32_16x16x32_bf16 v[116:119], v[178:181], v[190:193], v[116:119]
	v_mfma_f32_16x16x32_bf16 v[108:111], v[170:173], v[198:201], v[108:111]
	v_mfma_f32_16x16x32_bf16 v[100:103], v[178:181], v[198:201], v[100:103]
	v_mfma_f32_16x16x32_bf16 v[92:95], v[170:173], v[206:209], v[92:95]
	v_mfma_f32_16x16x32_bf16 v[84:87], v[178:181], v[206:209], v[84:87]
	v_mfma_f32_16x16x32_bf16 v[76:79], v[170:173], v[214:217], v[76:79]
	v_mfma_f32_16x16x32_bf16 v[68:71], v[178:181], v[214:217], v[68:71]
	s_setprio 0
	s_barrier
	s_add_i32 s30, s61, s38
	s_add_i32 m0, s30, 0xffffff80
	ds_read_b128 v[182:185], v149 offset:49152
	ds_read_b128 v[190:193], v149 offset:50176
	ds_read_b128 v[194:197], v149 offset:51200
	ds_read_b128 v[198:201], v149 offset:52224
	ds_read_b128 v[202:205], v149 offset:53248
	ds_read_b128 v[206:209], v149 offset:54272
	ds_read_b128 v[210:213], v149 offset:55296
	ds_read_b128 v[214:217], v149 offset:56320
	global_load_lds_dwordx4 v134, s[100:101] offset:128
	s_add_i32 m0, s30, 0x1f80
	s_add_i32 s30, s62, s38
	global_load_lds_dwordx4 v132, s[100:101] offset:128
	s_add_u32 s100, s100, s4
	s_addc_u32 s101, s101, s5
	s_add_i32 m0, s30, 0xffffff80
	s_nop 0
	global_load_lds_dwordx4 v134, s[100:101] offset:128
	s_add_i32 m0, s30, 0x1f80
	s_nop 0
	global_load_lds_dwordx4 v132, s[100:101] offset:128
	s_add_i32 m0, s47, 0xffffff80
	s_nop 0
	global_load_lds_dwordx4 v128, vcc offset:128
	s_add_i32 m0, s48, 0xffffff80
	s_nop 0
	global_load_lds_dwordx4 v130, vcc offset:128
	s_waitcnt vmcnt(8)
	s_waitcnt lgkmcnt(0)
	s_barrier
	s_setprio 1
	v_mfma_f32_16x16x32_bf16 v[56:59], v[150:153], v[182:185], v[56:59]
	v_mfma_f32_16x16x32_bf16 v[48:51], v[158:161], v[182:185], v[48:51]
	v_mfma_f32_16x16x32_bf16 v[40:43], v[150:153], v[194:197], v[40:43]
	v_mfma_f32_16x16x32_bf16 v[32:35], v[158:161], v[194:197], v[32:35]
	v_mfma_f32_16x16x32_bf16 v[24:27], v[150:153], v[202:205], v[24:27]
	v_mfma_f32_16x16x32_bf16 v[16:19], v[158:161], v[202:205], v[16:19]
	v_mfma_f32_16x16x32_bf16 v[8:11], v[150:153], v[210:213], v[8:11]
	v_mfma_f32_16x16x32_bf16 v[0:3], v[158:161], v[210:213], v[0:3]
	v_mfma_f32_16x16x32_bf16 v[56:59], v[154:157], v[190:193], v[56:59]
	v_mfma_f32_16x16x32_bf16 v[48:51], v[162:165], v[190:193], v[48:51]
	v_mfma_f32_16x16x32_bf16 v[40:43], v[154:157], v[198:201], v[40:43]
	v_mfma_f32_16x16x32_bf16 v[32:35], v[162:165], v[198:201], v[32:35]
	v_mfma_f32_16x16x32_bf16 v[24:27], v[154:157], v[206:209], v[24:27]
	v_mfma_f32_16x16x32_bf16 v[16:19], v[162:165], v[206:209], v[16:19]
	v_mfma_f32_16x16x32_bf16 v[8:11], v[154:157], v[214:217], v[8:11]
	v_mfma_f32_16x16x32_bf16 v[0:3], v[162:165], v[214:217], v[0:3]
	v_mfma_f32_16x16x32_bf16 v[60:63], v[166:169], v[182:185], v[60:63]
	v_mfma_f32_16x16x32_bf16 v[52:55], v[174:177], v[182:185], v[52:55]
	v_mfma_f32_16x16x32_bf16 v[44:47], v[166:169], v[194:197], v[44:47]
	v_mfma_f32_16x16x32_bf16 v[36:39], v[174:177], v[194:197], v[36:39]
	v_mfma_f32_16x16x32_bf16 v[28:31], v[166:169], v[202:205], v[28:31]
	v_mfma_f32_16x16x32_bf16 v[20:23], v[174:177], v[202:205], v[20:23]
	v_mfma_f32_16x16x32_bf16 v[12:15], v[166:169], v[210:213], v[12:15]
	v_mfma_f32_16x16x32_bf16 v[4:7], v[174:177], v[210:213], v[4:7]
	v_mfma_f32_16x16x32_bf16 v[60:63], v[170:173], v[190:193], v[60:63]
	v_mfma_f32_16x16x32_bf16 v[52:55], v[178:181], v[190:193], v[52:55]
	v_mfma_f32_16x16x32_bf16 v[44:47], v[170:173], v[198:201], v[44:47]
	v_mfma_f32_16x16x32_bf16 v[36:39], v[178:181], v[198:201], v[36:39]
	v_mfma_f32_16x16x32_bf16 v[28:31], v[170:173], v[206:209], v[28:31]
	v_mfma_f32_16x16x32_bf16 v[20:23], v[178:181], v[206:209], v[20:23]
	v_mfma_f32_16x16x32_bf16 v[12:15], v[170:173], v[214:217], v[12:15]
	v_mfma_f32_16x16x32_bf16 v[4:7], v[178:181], v[214:217], v[4:7]
	s_setprio 0
	s_barrier
	s_add_u32 s10, s10, 0x100
	s_addc_u32 s11, s11, 0
	s_add_u32 s34, s34, 0x100
	s_addc_u32 s35, s35, 0
	s_cmp_ge_i32 s60, s50
	s_mov_b32 s30, s60
	s_cbranch_scc0 .LBB0_601

; #define PG8_STAGE(bufoff, gbase, voff) do { _Pragma("unroll") for (int _i = 0; _i < 2; ++_i) \
;         __builtin_amdgcn_global_load_lds((const unsigned*)((const char*)(gbase) + (voff)[_i]), (PG8_LAS unsigned*)(lds + (bufoff) + ldsw + _i * 8192), 16, 0, 0); } while (0)
; #define PG8_LDA(dst, b, h) do { _Pragma("unroll") for (int m = 0; m < 4; ++m) _Pragma("unroll") for (int k = 0; k < 2; ++k) dst[m][k] = *(const PG8_LAS bf16x8*)(lds + PG8_SA(b, h) + aoff + m * 2048 + k * 1024); } while (0)
; #define PG8_LDB(dst, b, h) do { _Pragma("unroll") for (int n = 0; n < 2; ++n) _Pragma("unroll") for (int k = 0; k < 2; ++k) dst[n][k] = *(const PG8_LAS bf16x8*)(lds + PG8_SB(b, h) + boff + n * 2048 + k * 1024); } while (0)
; #define PG8_MMA(ai, bj, At, Bt) do { __builtin_amdgcn_s_setprio(1); _Pragma("unroll") for (int m = 0; m < 4; ++m) _Pragma("unroll") for (int n = 0; n < 2; ++n) _Pragma("unroll") for (int k = 0; k < 2; ++k) \
;         acc[ai][bj][m][n] = __builtin_amdgcn_mfma_f32_16x16x32_bf16(Bt[n][k], At[m][k], acc[ai][bj][m][n], 0, 0, 0); __builtin_amdgcn_s_setprio(0); } while (0)
; #define PG8_WAIT_V(n) asm volatile("s_waitcnt vmcnt(" #n ")" ::: "memory")
; #define PG8_BAR __builtin_amdgcn_s_barrier()
; template <class Epi, class Sched, bool ALIGN_EPI = false, bool SP2 = false>
; __device__ __forceinline__ void gemm_phase(PG8_LAS unsigned char* lds, const Gemm g, const Sched& S, const Epi& E) {
;     ...
;         for (int t = 0; t < nt; t += 2) {
;             const bool last = (t == nt - 2);
;             const char* a1 = cA + (size_t)(t + 1) * kstep;
;             const char* a2 = last ? nA : cA + (size_t)(t + 2) * kstep; const char* b2 = last ? nB : cB + (size_t)(t + 2) * kstep;
;             const char* a3 = a2 + kstep; const char* b3 = b2 + kstep;
;             if (last && has_next) S.a_ready(nxt);
;             if constexpr (SP2) {
;             PG8_LDB(B0, 0, 0); PG8_LDB(B1, 0, 1); PG8_SCHED; PG8_LDA(At, 0, 0); PG8_STAGE(PG8_SA(1, 1), a1 + hstepA, voffA);
;             PG8_WAIT_V(8); PG8_WAIT_L(0); PG8_BAR; PG8_MMA(0, 0, At, B0); PG8_MMA(0, 1, At, B1); PG8_BAR; PG8_SCHED;
;             PG8_LDA(At, 0, 1); PG8_STAGE(PG8_SB(0, 0), b2, voffB); PG8_STAGE(PG8_SB(0, 1), b2 + hstep, voffB); PG8_STAGE(PG8_SA(0, 0), a2, voffA);
;             PG8_WAIT_V(8); PG8_WAIT_L(0); PG8_BAR; PG8_MMA(1, 0, At, B0); PG8_MMA(1, 1, At, B1); PG8_BAR; PG8_SCHED;
.LBB0_681:
	ds_read_b128 v[128:131], v175
	ds_read_b128 v[132:135], v175 offset:1024
	ds_read_b128 v[136:139], v175 offset:2048
	ds_read_b128 v[140:143], v175 offset:3072
	ds_read_b128 v[162:165], v176
	ds_read_b128 v[166:169], v176 offset:1024
	ds_read_b128 v[180:183], v176 offset:2048
	ds_read_b128 v[184:187], v176 offset:3072
	s_add_i32 s71, s48, 2
	s_add_u32 s72, s8, 0xfffc0080
	s_addc_u32 s49, s9, -1
	s_cmp_eq_u32 s64, s48
	s_cselect_b32 s48, s70, s72
	s_cselect_b32 s49, s39, s49
	s_cselect_b32 s73, s41, s51
	s_cselect_b32 s72, s40, s50
	s_add_i32 m0, s45, 0xc000
	ds_read_b128 v[190:193], v177
	ds_read_b128 v[194:197], v177 offset:1024
	ds_read_b128 v[198:201], v177 offset:2048
	ds_read_b128 v[202:205], v177 offset:3072
	ds_read_b128 v[206:209], v177 offset:4096
	ds_read_b128 v[210:213], v177 offset:5120
	ds_read_b128 v[214:217], v177 offset:6144
	ds_read_b128 v[218:221], v177 offset:7168
	global_load_lds_dwordx4 v154, s[8:9]
	s_add_i32 m0, s45, 0xe000
	s_nop 0
	global_load_lds_dwordx4 v156, s[8:9]
	s_waitcnt vmcnt(8)
	s_waitcnt lgkmcnt(0)
	s_barrier
	s_setprio 1
	v_mfma_f32_16x16x32_bf16 v[124:127], v[128:131], v[190:193], v[124:127]
	v_mfma_f32_16x16x32_bf16 v[120:123], v[136:139], v[190:193], v[120:123]
	v_mfma_f32_16x16x32_bf16 v[108:111], v[128:131], v[198:201], v[108:111]
	v_mfma_f32_16x16x32_bf16 v[104:107], v[136:139], v[198:201], v[104:107]
	v_mfma_f32_16x16x32_bf16 v[92:95], v[128:131], v[206:209], v[92:95]
	v_mfma_f32_16x16x32_bf16 v[88:91], v[136:139], v[206:209], v[88:91]
	v_mfma_f32_16x16x32_bf16 v[76:79], v[128:131], v[214:217], v[76:79]
	v_mfma_f32_16x16x32_bf16 v[72:75], v[136:139], v[214:217], v[72:75]
	v_mfma_f32_16x16x32_bf16 v[124:127], v[132:135], v[194:197], v[124:127]
	v_mfma_f32_16x16x32_bf16 v[120:123], v[140:143], v[194:197], v[120:123]
	v_mfma_f32_16x16x32_bf16 v[108:111], v[132:135], v[202:205], v[108:111]
	v_mfma_f32_16x16x32_bf16 v[104:107], v[140:143], v[202:205], v[104:107]
	v_mfma_f32_16x16x32_bf16 v[92:95], v[132:135], v[210:213], v[92:95]
	v_mfma_f32_16x16x32_bf16 v[88:91], v[140:143], v[210:213], v[88:91]
	v_mfma_f32_16x16x32_bf16 v[76:79], v[132:135], v[218:221], v[76:79]
	v_mfma_f32_16x16x32_bf16 v[72:75], v[140:143], v[218:221], v[72:75]
	v_mfma_f32_16x16x32_bf16 v[116:119], v[162:165], v[190:193], v[116:119]
	v_mfma_f32_16x16x32_bf16 v[112:115], v[180:183], v[190:193], v[112:115]
	v_mfma_f32_16x16x32_bf16 v[100:103], v[162:165], v[198:201], v[100:103]
	v_mfma_f32_16x16x32_bf16 v[96:99], v[180:183], v[198:201], v[96:99]
	v_mfma_f32_16x16x32_bf16 v[84:87], v[162:165], v[206:209], v[84:87]
	v_mfma_f32_16x16x32_bf16 v[80:83], v[180:183], v[206:209], v[80:83]
	v_mfma_f32_16x16x32_bf16 v[68:71], v[162:165], v[214:217], v[68:71]
	v_mfma_f32_16x16x32_bf16 v[64:67], v[180:183], v[214:217], v[64:67]
	v_mfma_f32_16x16x32_bf16 v[116:119], v[166:169], v[194:197], v[116:119]
	v_mfma_f32_16x16x32_bf16 v[112:115], v[184:187], v[194:197], v[112:115]
	v_mfma_f32_16x16x32_bf16 v[100:103], v[166:169], v[202:205], v[100:103]
	v_mfma_f32_16x16x32_bf16 v[96:99], v[184:187], v[202:205], v[96:99]
	v_mfma_f32_16x16x32_bf16 v[84:87], v[166:169], v[210:213], v[84:87]
	v_mfma_f32_16x16x32_bf16 v[80:83], v[184:187], v[210:213], v[80:83]
	v_mfma_f32_16x16x32_bf16 v[68:71], v[166:169], v[218:221], v[68:71]
	v_mfma_f32_16x16x32_bf16 v[64:67], v[184:187], v[218:221], v[64:67]
	s_setprio 0
	s_barrier
	s_add_i32 s74, s65, s53
	s_mov_b32 m0, s74
	ds_read_b128 v[190:193], v177 offset:16384
	ds_read_b128 v[194:197], v177 offset:17408
	ds_read_b128 v[198:201], v177 offset:18432
	ds_read_b128 v[202:205], v177 offset:19456
	ds_read_b128 v[206:209], v177 offset:20480
	ds_read_b128 v[210:213], v177 offset:21504
	ds_read_b128 v[214:217], v177 offset:22528
	ds_read_b128 v[218:221], v177 offset:23552
	global_load_lds_dwordx4 v150, s[72:73]
	s_add_i32 m0, s74, 0x2000
	s_mov_b64 s[100:101], s[72:73]
	s_add_i32 s74, s66, s53
	global_load_lds_dwordx4 v148, s[72:73]
	s_add_u32 s72, s72, s10
	s_addc_u32 s73, s73, s11
	s_mov_b32 m0, s74
	s_nop 0
	global_load_lds_dwordx4 v150, s[72:73]
	s_add_i32 m0, s74, 0x2000
	s_nop 0
	global_load_lds_dwordx4 v148, s[72:73]
	s_mov_b32 m0, s45
	s_nop 0
	global_load_lds_dwordx4 v144, s[48:49]
	s_mov_b32 m0, s55
	s_nop 0
	global_load_lds_dwordx4 v146, s[48:49]
	s_waitcnt vmcnt(8)
	s_waitcnt lgkmcnt(0)
	s_barrier
	s_setprio 1
	v_mfma_f32_16x16x32_bf16 v[60:63], v[128:131], v[190:193], v[60:63]
	v_mfma_f32_16x16x32_bf16 v[56:59], v[136:139], v[190:193], v[56:59]
	v_mfma_f32_16x16x32_bf16 v[44:47], v[128:131], v[198:201], v[44:47]
	v_mfma_f32_16x16x32_bf16 v[40:43], v[136:139], v[198:201], v[40:43]
	v_mfma_f32_16x16x32_bf16 v[28:31], v[128:131], v[206:209], v[28:31]
	v_mfma_f32_16x16x32_bf16 v[24:27], v[136:139], v[206:209], v[24:27]
	v_mfma_f32_16x16x32_bf16 v[12:15], v[128:131], v[214:217], v[12:15]
	v_mfma_f32_16x16x32_bf16 v[8:11], v[136:139], v[214:217], v[8:11]
	v_mfma_f32_16x16x32_bf16 v[60:63], v[132:135], v[194:197], v[60:63]
	v_mfma_f32_16x16x32_bf16 v[56:59], v[140:143], v[194:197], v[56:59]
	v_mfma_f32_16x16x32_bf16 v[44:47], v[132:135], v[202:205], v[44:47]
	v_mfma_f32_16x16x32_bf16 v[40:43], v[140:143], v[202:205], v[40:43]
	v_mfma_f32_16x16x32_bf16 v[28:31], v[132:135], v[210:213], v[28:31]
	v_mfma_f32_16x16x32_bf16 v[24:27], v[140:143], v[210:213], v[24:27]
	v_mfma_f32_16x16x32_bf16 v[12:15], v[132:135], v[218:221], v[12:15]
	v_mfma_f32_16x16x32_bf16 v[8:11], v[140:143], v[218:221], v[8:11]
	v_mfma_f32_16x16x32_bf16 v[52:55], v[162:165], v[190:193], v[52:55]
	v_mfma_f32_16x16x32_bf16 v[48:51], v[180:183], v[190:193], v[48:51]
	v_mfma_f32_16x16x32_bf16 v[36:39], v[162:165], v[198:201], v[36:39]
	v_mfma_f32_16x16x32_bf16 v[32:35], v[180:183], v[198:201], v[32:35]
	v_mfma_f32_16x16x32_bf16 v[20:23], v[162:165], v[206:209], v[20:23]
	v_mfma_f32_16x16x32_bf16 v[16:19], v[180:183], v[206:209], v[16:19]
	v_mfma_f32_16x16x32_bf16 v[4:7], v[162:165], v[214:217], v[4:7]
	v_mfma_f32_16x16x32_bf16 v[0:3], v[180:183], v[214:217], v[0:3]
	v_mfma_f32_16x16x32_bf16 v[52:55], v[166:169], v[194:197], v[52:55]
	v_mfma_f32_16x16x32_bf16 v[48:51], v[184:187], v[194:197], v[48:51]
	v_mfma_f32_16x16x32_bf16 v[36:39], v[166:169], v[202:205], v[36:39]
	v_mfma_f32_16x16x32_bf16 v[32:35], v[184:187], v[202:205], v[32:35]
	v_mfma_f32_16x16x32_bf16 v[20:23], v[166:169], v[210:213], v[20:23]
	v_mfma_f32_16x16x32_bf16 v[16:19], v[184:187], v[210:213], v[16:19]
	v_mfma_f32_16x16x32_bf16 v[4:7], v[166:169], v[218:221], v[4:7]
	v_mfma_f32_16x16x32_bf16 v[0:3], v[184:187], v[218:221], v[0:3]
	s_setprio 0
	s_barrier
; #define PG8_STAGE(bufoff, gbase, voff) do { _Pragma("unroll") for (int _i = 0; _i < 2; ++_i) \
;         __builtin_amdgcn_global_load_lds((const unsigned*)((const char*)(gbase) + (voff)[_i]), (PG8_LAS unsigned*)(lds + (bufoff) + ldsw + _i * 8192), 16, 0, 0); } while (0)
; #define PG8_LDA(dst, b, h) do { _Pragma("unroll") for (int m = 0; m < 4; ++m) _Pragma("unroll") for (int k = 0; k < 2; ++k) dst[m][k] = *(const PG8_LAS bf16x8*)(lds + PG8_SA(b, h) + aoff + m * 2048 + k * 1024); } while (0)
; #define PG8_LDB(dst, b, h) do { _Pragma("unroll") for (int n = 0; n < 2; ++n) _Pragma("unroll") for (int k = 0; k < 2; ++k) dst[n][k] = *(const PG8_LAS bf16x8*)(lds + PG8_SB(b, h) + boff + n * 2048 + k * 1024); } while (0)
; #define PG8_MMA(ai, bj, At, Bt) do { __builtin_amdgcn_s_setprio(1); _Pragma("unroll") for (int m = 0; m < 4; ++m) _Pragma("unroll") for (int n = 0; n < 2; ++n) _Pragma("unroll") for (int k = 0; k < 2; ++k) \
;         acc[ai][bj][m][n] = __builtin_amdgcn_mfma_f32_16x16x32_bf16(Bt[n][k], At[m][k], acc[ai][bj][m][n], 0, 0, 0); __builtin_amdgcn_s_setprio(0); } while (0)
; #define PG8_WAIT_V(n) asm volatile("s_waitcnt vmcnt(" #n ")" ::: "memory")
; #define PG8_WAIT_L(n) asm volatile("s_waitcnt lgkmcnt(" #n ")" ::: "memory")
; #define PG8_BAR __builtin_amdgcn_s_barrier()
; #define PG8_SCHED __builtin_amdgcn_sched_barrier(0)
; template <class Epi, class Sched, bool ALIGN_EPI = false, bool SP2 = false>
; __device__ __forceinline__ void gemm_phase(PG8_LAS unsigned char* lds, const Gemm g, const Sched& S, const Epi& E) {
;     ...
;             PG8_LDB(B0, 1, 0); PG8_LDB(B1, 1, 1); PG8_SCHED; PG8_LDA(At, 1, 0); PG8_STAGE(PG8_SA(0, 1), a2 + hstepA, voffA);
;             PG8_WAIT_V(8); PG8_WAIT_L(0); PG8_BAR; PG8_MMA(0, 0, At, B0); PG8_MMA(0, 1, At, B1); PG8_BAR; PG8_SCHED;
;             PG8_LDA(At, 1, 1); PG8_STAGE(PG8_SB(1, 0), b3, voffB); PG8_STAGE(PG8_SB(1, 1), b3 + hstep, voffB); PG8_STAGE(PG8_SA(1, 0), a3, voffA);
;             PG8_WAIT_V(8); PG8_WAIT_L(0); PG8_BAR; PG8_MMA(1, 0, At, B0); PG8_MMA(1, 1, At, B1); PG8_BAR; PG8_SCHED;
	s_add_i32 s72, 0, 0x18000
	s_add_i32 s73, 0, 0x1c000
	v_add_u32_e32 v140, s72, v173
	v_add_u32_e32 v152, s73, v173
	ds_read_b128 v[128:131], v140
	ds_read_b128 v[132:135], v140 offset:1024
	ds_read_b128 v[136:139], v140 offset:2048
	ds_read_b128 v[140:143], v140 offset:3072
	ds_read_b128 v[162:165], v152
	ds_read_b128 v[166:169], v152 offset:1024
	ds_read_b128 v[180:183], v152 offset:2048
	ds_read_b128 v[184:187], v152 offset:3072
	s_mov_b64 vcc, s[48:49]
	s_add_u32 s48, s48, 0x40000
	s_addc_u32 s49, s49, 0
	s_mov_b32 m0, s56
	ds_read_b128 v[190:193], v177 offset:32768
	ds_read_b128 v[194:197], v177 offset:33792
	ds_read_b128 v[198:201], v177 offset:34816
	ds_read_b128 v[202:205], v177 offset:35840
	ds_read_b128 v[206:209], v177 offset:36864
	ds_read_b128 v[210:213], v177 offset:37888
	ds_read_b128 v[214:217], v177 offset:38912
	ds_read_b128 v[218:221], v177 offset:39936
	global_load_lds_dwordx4 v144, s[48:49]
	s_mov_b32 m0, s57
	s_nop 0
	global_load_lds_dwordx4 v146, s[48:49]
	s_waitcnt vmcnt(8)
	s_waitcnt lgkmcnt(0)
	s_barrier
	s_setprio 1
	v_mfma_f32_16x16x32_bf16 v[124:127], v[128:131], v[190:193], v[124:127]
	v_mfma_f32_16x16x32_bf16 v[120:123], v[136:139], v[190:193], v[120:123]
	v_mfma_f32_16x16x32_bf16 v[108:111], v[128:131], v[198:201], v[108:111]
	v_mfma_f32_16x16x32_bf16 v[104:107], v[136:139], v[198:201], v[104:107]
	v_mfma_f32_16x16x32_bf16 v[92:95], v[128:131], v[206:209], v[92:95]
	v_mfma_f32_16x16x32_bf16 v[88:91], v[136:139], v[206:209], v[88:91]
	v_mfma_f32_16x16x32_bf16 v[76:79], v[128:131], v[214:217], v[76:79]
	v_mfma_f32_16x16x32_bf16 v[72:75], v[136:139], v[214:217], v[72:75]
	v_mfma_f32_16x16x32_bf16 v[124:127], v[132:135], v[194:197], v[124:127]
	v_mfma_f32_16x16x32_bf16 v[120:123], v[140:143], v[194:197], v[120:123]
	v_mfma_f32_16x16x32_bf16 v[108:111], v[132:135], v[202:205], v[108:111]
	v_mfma_f32_16x16x32_bf16 v[104:107], v[140:143], v[202:205], v[104:107]
	v_mfma_f32_16x16x32_bf16 v[92:95], v[132:135], v[210:213], v[92:95]
	v_mfma_f32_16x16x32_bf16 v[88:91], v[140:143], v[210:213], v[88:91]
	v_mfma_f32_16x16x32_bf16 v[76:79], v[132:135], v[218:221], v[76:79]
	v_mfma_f32_16x16x32_bf16 v[72:75], v[140:143], v[218:221], v[72:75]
	v_mfma_f32_16x16x32_bf16 v[116:119], v[162:165], v[190:193], v[116:119]
	v_mfma_f32_16x16x32_bf16 v[112:115], v[180:183], v[190:193], v[112:115]
	v_mfma_f32_16x16x32_bf16 v[100:103], v[162:165], v[198:201], v[100:103]
	v_mfma_f32_16x16x32_bf16 v[96:99], v[180:183], v[198:201], v[96:99]
	v_mfma_f32_16x16x32_bf16 v[84:87], v[162:165], v[206:209], v[84:87]
	v_mfma_f32_16x16x32_bf16 v[80:83], v[180:183], v[206:209], v[80:83]
	v_mfma_f32_16x16x32_bf16 v[68:71], v[162:165], v[214:217], v[68:71]
	v_mfma_f32_16x16x32_bf16 v[64:67], v[180:183], v[214:217], v[64:67]
	v_mfma_f32_16x16x32_bf16 v[116:119], v[166:169], v[194:197], v[116:119]
	v_mfma_f32_16x16x32_bf16 v[112:115], v[184:187], v[194:197], v[112:115]
	v_mfma_f32_16x16x32_bf16 v[100:103], v[166:169], v[202:205], v[100:103]
	v_mfma_f32_16x16x32_bf16 v[96:99], v[184:187], v[202:205], v[96:99]
	v_mfma_f32_16x16x32_bf16 v[84:87], v[166:169], v[210:213], v[84:87]
	v_mfma_f32_16x16x32_bf16 v[80:83], v[184:187], v[210:213], v[80:83]
	v_mfma_f32_16x16x32_bf16 v[68:71], v[166:169], v[218:221], v[68:71]
	v_mfma_f32_16x16x32_bf16 v[64:67], v[184:187], v[218:221], v[64:67]
	s_setprio 0
	s_barrier
	s_add_i32 s48, s72, s53
	s_add_i32 m0, s48, 0xffffff80
	ds_read_b128 v[190:193], v177 offset:49152
	ds_read_b128 v[194:197], v177 offset:50176
	ds_read_b128 v[198:201], v177 offset:51200
	ds_read_b128 v[202:205], v177 offset:52224
	ds_read_b128 v[206:209], v177 offset:53248
	ds_read_b128 v[210:213], v177 offset:54272
	ds_read_b128 v[214:217], v177 offset:55296
	ds_read_b128 v[218:221], v177 offset:56320
	global_load_lds_dwordx4 v150, s[100:101] offset:128
	s_add_i32 m0, s48, 0x1f80
	s_add_i32 s48, s73, s53
	global_load_lds_dwordx4 v148, s[100:101] offset:128
	s_add_u32 s100, s100, s10
	s_addc_u32 s101, s101, s11
	s_add_i32 m0, s48, 0xffffff80
	s_nop 0
	global_load_lds_dwordx4 v150, s[100:101] offset:128
	s_add_i32 m0, s48, 0x1f80
	s_nop 0
	global_load_lds_dwordx4 v148, s[100:101] offset:128
	s_add_i32 m0, s60, 0xffffff80
	s_nop 0
	global_load_lds_dwordx4 v144, vcc offset:128
	s_add_i32 m0, s61, 0xffffff80
	s_nop 0
	global_load_lds_dwordx4 v146, vcc offset:128
	s_waitcnt vmcnt(8)
	s_waitcnt lgkmcnt(0)
	s_barrier
	s_setprio 1
	v_mfma_f32_16x16x32_bf16 v[60:63], v[128:131], v[190:193], v[60:63]
	v_mfma_f32_16x16x32_bf16 v[56:59], v[136:139], v[190:193], v[56:59]
	v_mfma_f32_16x16x32_bf16 v[44:47], v[128:131], v[198:201], v[44:47]
	v_mfma_f32_16x16x32_bf16 v[40:43], v[136:139], v[198:201], v[40:43]
	v_mfma_f32_16x16x32_bf16 v[28:31], v[128:131], v[206:209], v[28:31]
	v_mfma_f32_16x16x32_bf16 v[24:27], v[136:139], v[206:209], v[24:27]
	v_mfma_f32_16x16x32_bf16 v[12:15], v[128:131], v[214:217], v[12:15]
	v_mfma_f32_16x16x32_bf16 v[8:11], v[136:139], v[214:217], v[8:11]
	v_mfma_f32_16x16x32_bf16 v[60:63], v[132:135], v[194:197], v[60:63]
	v_mfma_f32_16x16x32_bf16 v[56:59], v[140:143], v[194:197], v[56:59]
	v_mfma_f32_16x16x32_bf16 v[44:47], v[132:135], v[202:205], v[44:47]
	v_mfma_f32_16x16x32_bf16 v[40:43], v[140:143], v[202:205], v[40:43]
	v_mfma_f32_16x16x32_bf16 v[28:31], v[132:135], v[210:213], v[28:31]
	v_mfma_f32_16x16x32_bf16 v[24:27], v[140:143], v[210:213], v[24:27]
	v_mfma_f32_16x16x32_bf16 v[12:15], v[132:135], v[218:221], v[12:15]
	v_mfma_f32_16x16x32_bf16 v[8:11], v[140:143], v[218:221], v[8:11]
	v_mfma_f32_16x16x32_bf16 v[52:55], v[162:165], v[190:193], v[52:55]
	v_mfma_f32_16x16x32_bf16 v[48:51], v[180:183], v[190:193], v[48:51]
	v_mfma_f32_16x16x32_bf16 v[36:39], v[162:165], v[198:201], v[36:39]
	v_mfma_f32_16x16x32_bf16 v[32:35], v[180:183], v[198:201], v[32:35]
	v_mfma_f32_16x16x32_bf16 v[20:23], v[162:165], v[206:209], v[20:23]
	v_mfma_f32_16x16x32_bf16 v[16:19], v[180:183], v[206:209], v[16:19]
	v_mfma_f32_16x16x32_bf16 v[4:7], v[162:165], v[214:217], v[4:7]
	v_mfma_f32_16x16x32_bf16 v[0:3], v[180:183], v[214:217], v[0:3]
	v_mfma_f32_16x16x32_bf16 v[52:55], v[166:169], v[194:197], v[52:55]
	v_mfma_f32_16x16x32_bf16 v[48:51], v[184:187], v[194:197], v[48:51]
	v_mfma_f32_16x16x32_bf16 v[36:39], v[166:169], v[202:205], v[36:39]
	v_mfma_f32_16x16x32_bf16 v[32:35], v[184:187], v[202:205], v[32:35]
	v_mfma_f32_16x16x32_bf16 v[20:23], v[166:169], v[210:213], v[20:23]
	v_mfma_f32_16x16x32_bf16 v[16:19], v[184:187], v[210:213], v[16:19]
	v_mfma_f32_16x16x32_bf16 v[4:7], v[166:169], v[218:221], v[4:7]
	v_mfma_f32_16x16x32_bf16 v[0:3], v[184:187], v[218:221], v[0:3]
	s_setprio 0
	s_barrier
	s_add_u32 s8, s8, 0x100
	s_addc_u32 s9, s9, 0
	s_add_u32 s50, s50, 0x100
	s_addc_u32 s51, s51, 0
	s_cmp_ge_i32 s71, s63
	s_mov_b32 s48, s71
	s_cbranch_scc0 .LBB0_681

; #define PG8_STAGE(bufoff, gbase, voff) do { _Pragma("unroll") for (int _i = 0; _i < 2; ++_i) \
;         __builtin_amdgcn_global_load_lds((const unsigned*)((const char*)(gbase) + (voff)[_i]), (PG8_LAS unsigned*)(lds + (bufoff) + ldsw + _i * 8192), 16, 0, 0); } while (0)
; #define PG8_LDA(dst, b, h) do { _Pragma("unroll") for (int m = 0; m < 4; ++m) _Pragma("unroll") for (int k = 0; k < 2; ++k) dst[m][k] = *(const PG8_LAS bf16x8*)(lds + PG8_SA(b, h) + aoff + m * 2048 + k * 1024); } while (0)
; #define PG8_LDB(dst, b, h) do { _Pragma("unroll") for (int n = 0; n < 2; ++n) _Pragma("unroll") for (int k = 0; k < 2; ++k) dst[n][k] = *(const PG8_LAS bf16x8*)(lds + PG8_SB(b, h) + boff + n * 2048 + k * 1024); } while (0)
; #define PG8_MMA(ai, bj, At, Bt) do { __builtin_amdgcn_s_setprio(1); _Pragma("unroll") for (int m = 0; m < 4; ++m) _Pragma("unroll") for (int n = 0; n < 2; ++n) _Pragma("unroll") for (int k = 0; k < 2; ++k) \
;         acc[ai][bj][m][n] = __builtin_amdgcn_mfma_f32_16x16x32_bf16(Bt[n][k], At[m][k], acc[ai][bj][m][n], 0, 0, 0); __builtin_amdgcn_s_setprio(0); } while (0)
; #define PG8_WAIT_V(n) asm volatile("s_waitcnt vmcnt(" #n ")" ::: "memory")
; #define PG8_BAR __builtin_amdgcn_s_barrier()
; template <class Epi, class Sched, bool ALIGN_EPI = false, bool SP2 = false>
; __device__ __forceinline__ void gemm_phase(PG8_LAS unsigned char* lds, const Gemm g, const Sched& S, const Epi& E) {
;     ...
;         for (int t = 0; t < nt; t += 2) {
;             const bool last = (t == nt - 2);
;             const char* a1 = cA + (size_t)(t + 1) * kstep;
;             const char* a2 = last ? nA : cA + (size_t)(t + 2) * kstep; const char* b2 = last ? nB : cB + (size_t)(t + 2) * kstep;
;             const char* a3 = a2 + kstep; const char* b3 = b2 + kstep;
;             if (last && has_next) S.a_ready(nxt);
;             if constexpr (SP2) {
;             PG8_LDB(B0, 0, 0); PG8_LDB(B1, 0, 1); PG8_SCHED; PG8_LDA(At, 0, 0); PG8_STAGE(PG8_SA(1, 1), a1 + hstepA, voffA);
;             PG8_WAIT_V(8); PG8_WAIT_L(0); PG8_BAR; PG8_MMA(0, 0, At, B0); PG8_MMA(0, 1, At, B1); PG8_BAR; PG8_SCHED;
;             PG8_LDA(At, 0, 1); PG8_STAGE(PG8_SB(0, 0), b2, voffB); PG8_STAGE(PG8_SB(0, 1), b2 + hstep, voffB); PG8_STAGE(PG8_SA(0, 0), a2, voffA);
;             PG8_WAIT_V(8); PG8_WAIT_L(0); PG8_BAR; PG8_MMA(1, 0, At, B0); PG8_MMA(1, 1, At, B1); PG8_BAR; PG8_SCHED;
.LBB0_762:
	ds_read_b128 v[128:131], v169
	ds_read_b128 v[132:135], v169 offset:1024
	ds_read_b128 v[136:139], v169 offset:2048
	ds_read_b128 v[140:143], v169 offset:3072
	ds_read_b128 v[156:159], v170
	ds_read_b128 v[160:163], v170 offset:1024
	ds_read_b128 v[172:175], v170 offset:2048
	ds_read_b128 v[176:179], v170 offset:3072
	s_add_i32 s76, s48, 2
	s_add_u32 s77, s44, 0xfffc0080
	s_addc_u32 s49, s45, -1
	s_cmp_eq_u32 s70, s48
	s_cselect_b32 s48, s50, s77
	s_cselect_b32 s49, s37, s49
	s_cselect_b32 s79, s39, s75
	s_cselect_b32 s78, s38, s51
	s_add_i32 m0, s43, 0xc000
	ds_read_b128 v[180:183], v171
	ds_read_b128 v[184:187], v171 offset:1024
	ds_read_b128 v[190:193], v171 offset:2048
	ds_read_b128 v[194:197], v171 offset:3072
	ds_read_b128 v[198:201], v171 offset:4096
	ds_read_b128 v[202:205], v171 offset:5120
	ds_read_b128 v[206:209], v171 offset:6144
	ds_read_b128 v[210:213], v171 offset:7168
	global_load_lds_dwordx4 v152, s[44:45]
	s_add_i32 m0, s43, 0xe000
	s_nop 0
	global_load_lds_dwordx4 v154, s[44:45]
	s_waitcnt vmcnt(8)
	s_waitcnt lgkmcnt(0)
	s_barrier
	s_setprio 1
	v_mfma_f32_16x16x32_bf16 v[124:127], v[128:131], v[180:183], v[124:127]
	v_mfma_f32_16x16x32_bf16 v[120:123], v[136:139], v[180:183], v[120:123]
	v_mfma_f32_16x16x32_bf16 v[108:111], v[128:131], v[190:193], v[108:111]
	v_mfma_f32_16x16x32_bf16 v[104:107], v[136:139], v[190:193], v[104:107]
	v_mfma_f32_16x16x32_bf16 v[92:95], v[128:131], v[198:201], v[92:95]
	v_mfma_f32_16x16x32_bf16 v[88:91], v[136:139], v[198:201], v[88:91]
	v_mfma_f32_16x16x32_bf16 v[76:79], v[128:131], v[206:209], v[76:79]
	v_mfma_f32_16x16x32_bf16 v[72:75], v[136:139], v[206:209], v[72:75]
	v_mfma_f32_16x16x32_bf16 v[124:127], v[132:135], v[184:187], v[124:127]
	v_mfma_f32_16x16x32_bf16 v[120:123], v[140:143], v[184:187], v[120:123]
	v_mfma_f32_16x16x32_bf16 v[108:111], v[132:135], v[194:197], v[108:111]
	v_mfma_f32_16x16x32_bf16 v[104:107], v[140:143], v[194:197], v[104:107]
	v_mfma_f32_16x16x32_bf16 v[92:95], v[132:135], v[202:205], v[92:95]
	v_mfma_f32_16x16x32_bf16 v[88:91], v[140:143], v[202:205], v[88:91]
	v_mfma_f32_16x16x32_bf16 v[76:79], v[132:135], v[210:213], v[76:79]
	v_mfma_f32_16x16x32_bf16 v[72:75], v[140:143], v[210:213], v[72:75]
	v_mfma_f32_16x16x32_bf16 v[116:119], v[156:159], v[180:183], v[116:119]
	v_mfma_f32_16x16x32_bf16 v[112:115], v[172:175], v[180:183], v[112:115]
	v_mfma_f32_16x16x32_bf16 v[100:103], v[156:159], v[190:193], v[100:103]
	v_mfma_f32_16x16x32_bf16 v[96:99], v[172:175], v[190:193], v[96:99]
	v_mfma_f32_16x16x32_bf16 v[84:87], v[156:159], v[198:201], v[84:87]
	v_mfma_f32_16x16x32_bf16 v[80:83], v[172:175], v[198:201], v[80:83]
	v_mfma_f32_16x16x32_bf16 v[68:71], v[156:159], v[206:209], v[68:71]
	v_mfma_f32_16x16x32_bf16 v[64:67], v[172:175], v[206:209], v[64:67]
	v_mfma_f32_16x16x32_bf16 v[116:119], v[160:163], v[184:187], v[116:119]
	v_mfma_f32_16x16x32_bf16 v[112:115], v[176:179], v[184:187], v[112:115]
	v_mfma_f32_16x16x32_bf16 v[100:103], v[160:163], v[194:197], v[100:103]
	v_mfma_f32_16x16x32_bf16 v[96:99], v[176:179], v[194:197], v[96:99]
	v_mfma_f32_16x16x32_bf16 v[84:87], v[160:163], v[202:205], v[84:87]
	v_mfma_f32_16x16x32_bf16 v[80:83], v[176:179], v[202:205], v[80:83]
	v_mfma_f32_16x16x32_bf16 v[68:71], v[160:163], v[210:213], v[68:71]
	v_mfma_f32_16x16x32_bf16 v[64:67], v[176:179], v[210:213], v[64:67]
	s_setprio 0
	s_barrier
	s_add_i32 s77, s71, s57
	s_mov_b32 m0, s77
	ds_read_b128 v[180:183], v171 offset:16384
	ds_read_b128 v[184:187], v171 offset:17408
	ds_read_b128 v[190:193], v171 offset:18432
	ds_read_b128 v[194:197], v171 offset:19456
	ds_read_b128 v[198:201], v171 offset:20480
	ds_read_b128 v[202:205], v171 offset:21504
	ds_read_b128 v[206:209], v171 offset:22528
	ds_read_b128 v[210:213], v171 offset:23552
	global_load_lds_dwordx4 v150, s[78:79]
	s_add_i32 m0, s77, 0x2000
	s_mov_b64 s[100:101], s[78:79]
	s_add_i32 s77, s72, s57
	global_load_lds_dwordx4 v148, s[78:79]
	s_add_u32 s78, s78, s8
	s_addc_u32 s79, s79, s9
	s_mov_b32 m0, s77
	s_nop 0
	global_load_lds_dwordx4 v150, s[78:79]
	s_add_i32 m0, s77, 0x2000
	s_nop 0
	global_load_lds_dwordx4 v148, s[78:79]
	s_mov_b32 m0, s43
	s_nop 0
	global_load_lds_dwordx4 v144, s[48:49]
	s_mov_b32 m0, s59
	s_nop 0
	global_load_lds_dwordx4 v146, s[48:49]
	s_waitcnt vmcnt(8)
	s_waitcnt lgkmcnt(0)
	s_barrier
	s_setprio 1
	v_mfma_f32_16x16x32_bf16 v[60:63], v[128:131], v[180:183], v[60:63]
	v_mfma_f32_16x16x32_bf16 v[56:59], v[136:139], v[180:183], v[56:59]
	v_mfma_f32_16x16x32_bf16 v[44:47], v[128:131], v[190:193], v[44:47]
	v_mfma_f32_16x16x32_bf16 v[40:43], v[136:139], v[190:193], v[40:43]
	v_mfma_f32_16x16x32_bf16 v[28:31], v[128:131], v[198:201], v[28:31]
	v_mfma_f32_16x16x32_bf16 v[24:27], v[136:139], v[198:201], v[24:27]
	v_mfma_f32_16x16x32_bf16 v[12:15], v[128:131], v[206:209], v[12:15]
	v_mfma_f32_16x16x32_bf16 v[8:11], v[136:139], v[206:209], v[8:11]
	v_mfma_f32_16x16x32_bf16 v[60:63], v[132:135], v[184:187], v[60:63]
	v_mfma_f32_16x16x32_bf16 v[56:59], v[140:143], v[184:187], v[56:59]
	v_mfma_f32_16x16x32_bf16 v[44:47], v[132:135], v[194:197], v[44:47]
	v_mfma_f32_16x16x32_bf16 v[40:43], v[140:143], v[194:197], v[40:43]
	v_mfma_f32_16x16x32_bf16 v[28:31], v[132:135], v[202:205], v[28:31]
	v_mfma_f32_16x16x32_bf16 v[24:27], v[140:143], v[202:205], v[24:27]
	v_mfma_f32_16x16x32_bf16 v[12:15], v[132:135], v[210:213], v[12:15]
	v_mfma_f32_16x16x32_bf16 v[8:11], v[140:143], v[210:213], v[8:11]
	v_mfma_f32_16x16x32_bf16 v[52:55], v[156:159], v[180:183], v[52:55]
	v_mfma_f32_16x16x32_bf16 v[48:51], v[172:175], v[180:183], v[48:51]
	v_mfma_f32_16x16x32_bf16 v[36:39], v[156:159], v[190:193], v[36:39]
	v_mfma_f32_16x16x32_bf16 v[32:35], v[172:175], v[190:193], v[32:35]
	v_mfma_f32_16x16x32_bf16 v[20:23], v[156:159], v[198:201], v[20:23]
	v_mfma_f32_16x16x32_bf16 v[16:19], v[172:175], v[198:201], v[16:19]
	v_mfma_f32_16x16x32_bf16 v[4:7], v[156:159], v[206:209], v[4:7]
	v_mfma_f32_16x16x32_bf16 v[0:3], v[172:175], v[206:209], v[0:3]
	v_mfma_f32_16x16x32_bf16 v[52:55], v[160:163], v[184:187], v[52:55]
	v_mfma_f32_16x16x32_bf16 v[48:51], v[176:179], v[184:187], v[48:51]
	v_mfma_f32_16x16x32_bf16 v[36:39], v[160:163], v[194:197], v[36:39]
	v_mfma_f32_16x16x32_bf16 v[32:35], v[176:179], v[194:197], v[32:35]
	v_mfma_f32_16x16x32_bf16 v[20:23], v[160:163], v[202:205], v[20:23]
	v_mfma_f32_16x16x32_bf16 v[16:19], v[176:179], v[202:205], v[16:19]
	v_mfma_f32_16x16x32_bf16 v[4:7], v[160:163], v[210:213], v[4:7]
	v_mfma_f32_16x16x32_bf16 v[0:3], v[176:179], v[210:213], v[0:3]
	s_setprio 0
	s_barrier
; #define PG8_STAGE(bufoff, gbase, voff) do { _Pragma("unroll") for (int _i = 0; _i < 2; ++_i) \
;         __builtin_amdgcn_global_load_lds((const unsigned*)((const char*)(gbase) + (voff)[_i]), (PG8_LAS unsigned*)(lds + (bufoff) + ldsw + _i * 8192), 16, 0, 0); } while (0)
; #define PG8_LDA(dst, b, h) do { _Pragma("unroll") for (int m = 0; m < 4; ++m) _Pragma("unroll") for (int k = 0; k < 2; ++k) dst[m][k] = *(const PG8_LAS bf16x8*)(lds + PG8_SA(b, h) + aoff + m * 2048 + k * 1024); } while (0)
; #define PG8_LDB(dst, b, h) do { _Pragma("unroll") for (int n = 0; n < 2; ++n) _Pragma("unroll") for (int k = 0; k < 2; ++k) dst[n][k] = *(const PG8_LAS bf16x8*)(lds + PG8_SB(b, h) + boff + n * 2048 + k * 1024); } while (0)
; #define PG8_MMA(ai, bj, At, Bt) do { __builtin_amdgcn_s_setprio(1); _Pragma("unroll") for (int m = 0; m < 4; ++m) _Pragma("unroll") for (int n = 0; n < 2; ++n) _Pragma("unroll") for (int k = 0; k < 2; ++k) \
;         acc[ai][bj][m][n] = __builtin_amdgcn_mfma_f32_16x16x32_bf16(Bt[n][k], At[m][k], acc[ai][bj][m][n], 0, 0, 0); __builtin_amdgcn_s_setprio(0); } while (0)
; #define PG8_WAIT_V(n) asm volatile("s_waitcnt vmcnt(" #n ")" ::: "memory")
; #define PG8_WAIT_L(n) asm volatile("s_waitcnt lgkmcnt(" #n ")" ::: "memory")
; #define PG8_BAR __builtin_amdgcn_s_barrier()
; #define PG8_SCHED __builtin_amdgcn_sched_barrier(0)
; template <class Epi, class Sched, bool ALIGN_EPI = false, bool SP2 = false>
; __device__ __forceinline__ void gemm_phase(PG8_LAS unsigned char* lds, const Gemm g, const Sched& S, const Epi& E) {
;     ...
;             PG8_LDB(B0, 1, 0); PG8_LDB(B1, 1, 1); PG8_SCHED; PG8_LDA(At, 1, 0); PG8_STAGE(PG8_SA(0, 1), a2 + hstepA, voffA);
;             PG8_WAIT_V(8); PG8_WAIT_L(0); PG8_BAR; PG8_MMA(0, 0, At, B0); PG8_MMA(0, 1, At, B1); PG8_BAR; PG8_SCHED;
;             PG8_LDA(At, 1, 1); PG8_STAGE(PG8_SB(1, 0), b3, voffB); PG8_STAGE(PG8_SB(1, 1), b3 + hstep, voffB); PG8_STAGE(PG8_SA(1, 0), a3, voffA);
;             PG8_WAIT_V(8); PG8_WAIT_L(0); PG8_BAR; PG8_MMA(1, 0, At, B0); PG8_MMA(1, 1, At, B1); PG8_BAR; PG8_SCHED;
	s_add_i32 s77, 0, 0x18000
	s_add_i32 s78, 0, 0x1c000
	v_add_u32_e32 v140, s77, v167
	v_add_u32_e32 v176, s78, v167
	ds_read_b128 v[128:131], v140
	ds_read_b128 v[132:135], v140 offset:1024
	ds_read_b128 v[136:139], v140 offset:2048
	ds_read_b128 v[140:143], v140 offset:3072
	ds_read_b128 v[156:159], v176
	ds_read_b128 v[160:163], v176 offset:1024
	ds_read_b128 v[172:175], v176 offset:2048
	ds_read_b128 v[176:179], v176 offset:3072
	s_mov_b64 vcc, s[48:49]
	s_add_u32 s48, s48, 0x40000
	s_addc_u32 s49, s49, 0
	s_mov_b32 m0, s60
	ds_read_b128 v[180:183], v171 offset:32768
	ds_read_b128 v[184:187], v171 offset:33792
	ds_read_b128 v[190:193], v171 offset:34816
	ds_read_b128 v[194:197], v171 offset:35840
	ds_read_b128 v[198:201], v171 offset:36864
	ds_read_b128 v[202:205], v171 offset:37888
	ds_read_b128 v[206:209], v171 offset:38912
	ds_read_b128 v[210:213], v171 offset:39936
	global_load_lds_dwordx4 v144, s[48:49]
	s_mov_b32 m0, s61
	s_nop 0
	global_load_lds_dwordx4 v146, s[48:49]
	s_waitcnt vmcnt(8)
	s_waitcnt lgkmcnt(0)
	s_barrier
	s_setprio 1
	v_mfma_f32_16x16x32_bf16 v[124:127], v[128:131], v[180:183], v[124:127]
	v_mfma_f32_16x16x32_bf16 v[120:123], v[136:139], v[180:183], v[120:123]
	v_mfma_f32_16x16x32_bf16 v[108:111], v[128:131], v[190:193], v[108:111]
	v_mfma_f32_16x16x32_bf16 v[104:107], v[136:139], v[190:193], v[104:107]
	v_mfma_f32_16x16x32_bf16 v[92:95], v[128:131], v[198:201], v[92:95]
	v_mfma_f32_16x16x32_bf16 v[88:91], v[136:139], v[198:201], v[88:91]
	v_mfma_f32_16x16x32_bf16 v[76:79], v[128:131], v[206:209], v[76:79]
	v_mfma_f32_16x16x32_bf16 v[72:75], v[136:139], v[206:209], v[72:75]
	v_mfma_f32_16x16x32_bf16 v[124:127], v[132:135], v[184:187], v[124:127]
	v_mfma_f32_16x16x32_bf16 v[120:123], v[140:143], v[184:187], v[120:123]
	v_mfma_f32_16x16x32_bf16 v[108:111], v[132:135], v[194:197], v[108:111]
	v_mfma_f32_16x16x32_bf16 v[104:107], v[140:143], v[194:197], v[104:107]
	v_mfma_f32_16x16x32_bf16 v[92:95], v[132:135], v[202:205], v[92:95]
	v_mfma_f32_16x16x32_bf16 v[88:91], v[140:143], v[202:205], v[88:91]
	v_mfma_f32_16x16x32_bf16 v[76:79], v[132:135], v[210:213], v[76:79]
	v_mfma_f32_16x16x32_bf16 v[72:75], v[140:143], v[210:213], v[72:75]
	v_mfma_f32_16x16x32_bf16 v[116:119], v[156:159], v[180:183], v[116:119]
	v_mfma_f32_16x16x32_bf16 v[112:115], v[172:175], v[180:183], v[112:115]
	v_mfma_f32_16x16x32_bf16 v[100:103], v[156:159], v[190:193], v[100:103]
	v_mfma_f32_16x16x32_bf16 v[96:99], v[172:175], v[190:193], v[96:99]
	v_mfma_f32_16x16x32_bf16 v[84:87], v[156:159], v[198:201], v[84:87]
	v_mfma_f32_16x16x32_bf16 v[80:83], v[172:175], v[198:201], v[80:83]
	v_mfma_f32_16x16x32_bf16 v[68:71], v[156:159], v[206:209], v[68:71]
	v_mfma_f32_16x16x32_bf16 v[64:67], v[172:175], v[206:209], v[64:67]
	v_mfma_f32_16x16x32_bf16 v[116:119], v[160:163], v[184:187], v[116:119]
	v_mfma_f32_16x16x32_bf16 v[112:115], v[176:179], v[184:187], v[112:115]
	v_mfma_f32_16x16x32_bf16 v[100:103], v[160:163], v[194:197], v[100:103]
	v_mfma_f32_16x16x32_bf16 v[96:99], v[176:179], v[194:197], v[96:99]
	v_mfma_f32_16x16x32_bf16 v[84:87], v[160:163], v[202:205], v[84:87]
	v_mfma_f32_16x16x32_bf16 v[80:83], v[176:179], v[202:205], v[80:83]
	v_mfma_f32_16x16x32_bf16 v[68:71], v[160:163], v[210:213], v[68:71]
	v_mfma_f32_16x16x32_bf16 v[64:67], v[176:179], v[210:213], v[64:67]
	s_setprio 0
	s_barrier
	s_add_i32 s48, s77, s57
	s_add_i32 m0, s48, 0xffffff80
	ds_read_b128 v[180:183], v171 offset:49152
	ds_read_b128 v[184:187], v171 offset:50176
	ds_read_b128 v[190:193], v171 offset:51200
	ds_read_b128 v[194:197], v171 offset:52224
	ds_read_b128 v[198:201], v171 offset:53248
	ds_read_b128 v[202:205], v171 offset:54272
	ds_read_b128 v[206:209], v171 offset:55296
	ds_read_b128 v[210:213], v171 offset:56320
	global_load_lds_dwordx4 v150, s[100:101] offset:128
	s_add_i32 m0, s48, 0x1f80
	s_add_i32 s48, s78, s57
	global_load_lds_dwordx4 v148, s[100:101] offset:128
	s_add_u32 s100, s100, s8
	s_addc_u32 s101, s101, s9
	s_add_i32 m0, s48, 0xffffff80
	s_nop 0
	global_load_lds_dwordx4 v150, s[100:101] offset:128
	s_add_i32 m0, s48, 0x1f80
	s_nop 0
	global_load_lds_dwordx4 v148, s[100:101] offset:128
	s_add_i32 m0, s65, 0xffffff80
	s_nop 0
	global_load_lds_dwordx4 v144, vcc offset:128
	s_add_i32 m0, s66, 0xffffff80
	s_nop 0
	global_load_lds_dwordx4 v146, vcc offset:128
	s_waitcnt vmcnt(8)
	s_waitcnt lgkmcnt(0)
	s_barrier
	s_setprio 1
	v_mfma_f32_16x16x32_bf16 v[60:63], v[128:131], v[180:183], v[60:63]
	v_mfma_f32_16x16x32_bf16 v[56:59], v[136:139], v[180:183], v[56:59]
	v_mfma_f32_16x16x32_bf16 v[44:47], v[128:131], v[190:193], v[44:47]
	v_mfma_f32_16x16x32_bf16 v[40:43], v[136:139], v[190:193], v[40:43]
	v_mfma_f32_16x16x32_bf16 v[28:31], v[128:131], v[198:201], v[28:31]
	v_mfma_f32_16x16x32_bf16 v[24:27], v[136:139], v[198:201], v[24:27]
	v_mfma_f32_16x16x32_bf16 v[12:15], v[128:131], v[206:209], v[12:15]
	v_mfma_f32_16x16x32_bf16 v[8:11], v[136:139], v[206:209], v[8:11]
	v_mfma_f32_16x16x32_bf16 v[60:63], v[132:135], v[184:187], v[60:63]
	v_mfma_f32_16x16x32_bf16 v[56:59], v[140:143], v[184:187], v[56:59]
	v_mfma_f32_16x16x32_bf16 v[44:47], v[132:135], v[194:197], v[44:47]
	v_mfma_f32_16x16x32_bf16 v[40:43], v[140:143], v[194:197], v[40:43]
	v_mfma_f32_16x16x32_bf16 v[28:31], v[132:135], v[202:205], v[28:31]
	v_mfma_f32_16x16x32_bf16 v[24:27], v[140:143], v[202:205], v[24:27]
	v_mfma_f32_16x16x32_bf16 v[12:15], v[132:135], v[210:213], v[12:15]
	v_mfma_f32_16x16x32_bf16 v[8:11], v[140:143], v[210:213], v[8:11]
	v_mfma_f32_16x16x32_bf16 v[52:55], v[156:159], v[180:183], v[52:55]
	v_mfma_f32_16x16x32_bf16 v[48:51], v[172:175], v[180:183], v[48:51]
	v_mfma_f32_16x16x32_bf16 v[36:39], v[156:159], v[190:193], v[36:39]
	v_mfma_f32_16x16x32_bf16 v[32:35], v[172:175], v[190:193], v[32:35]
	v_mfma_f32_16x16x32_bf16 v[20:23], v[156:159], v[198:201], v[20:23]
	v_mfma_f32_16x16x32_bf16 v[16:19], v[172:175], v[198:201], v[16:19]
	v_mfma_f32_16x16x32_bf16 v[4:7], v[156:159], v[206:209], v[4:7]
	v_mfma_f32_16x16x32_bf16 v[0:3], v[172:175], v[206:209], v[0:3]
	v_mfma_f32_16x16x32_bf16 v[52:55], v[160:163], v[184:187], v[52:55]
	v_mfma_f32_16x16x32_bf16 v[48:51], v[176:179], v[184:187], v[48:51]
	v_mfma_f32_16x16x32_bf16 v[36:39], v[160:163], v[194:197], v[36:39]
	v_mfma_f32_16x16x32_bf16 v[32:35], v[176:179], v[194:197], v[32:35]
	v_mfma_f32_16x16x32_bf16 v[20:23], v[160:163], v[202:205], v[20:23]
	v_mfma_f32_16x16x32_bf16 v[16:19], v[176:179], v[202:205], v[16:19]
	v_mfma_f32_16x16x32_bf16 v[4:7], v[160:163], v[210:213], v[4:7]
	v_mfma_f32_16x16x32_bf16 v[0:3], v[176:179], v[210:213], v[0:3]
	s_setprio 0
	s_barrier
	s_add_u32 s44, s44, 0x100
	s_addc_u32 s45, s45, 0
	s_add_u32 s51, s51, 0x100
	s_addc_u32 s75, s75, 0
	s_cmp_ge_i32 s76, s67
	s_mov_b32 s48, s76
	s_cbranch_scc0 .LBB0_762

; #define PG8_STAGE(bufoff, gbase, voff) do { _Pragma("unroll") for (int _i = 0; _i < 2; ++_i) \
;         __builtin_amdgcn_global_load_lds((const unsigned*)((const char*)(gbase) + (voff)[_i]), (PG8_LAS unsigned*)(lds + (bufoff) + ldsw + _i * 8192), 16, 0, 0); } while (0)
; #define PG8_LDA(dst, b, h) do { _Pragma("unroll") for (int m = 0; m < 4; ++m) _Pragma("unroll") for (int k = 0; k < 2; ++k) dst[m][k] = *(const PG8_LAS bf16x8*)(lds + PG8_SA(b, h) + aoff + m * 2048 + k * 1024); } while (0)
; #define PG8_LDB(dst, b, h) do { _Pragma("unroll") for (int n = 0; n < 2; ++n) _Pragma("unroll") for (int k = 0; k < 2; ++k) dst[n][k] = *(const PG8_LAS bf16x8*)(lds + PG8_SB(b, h) + boff + n * 2048 + k * 1024); } while (0)
; #define PG8_MMA(ai, bj, At, Bt) do { __builtin_amdgcn_s_setprio(1); _Pragma("unroll") for (int m = 0; m < 4; ++m) _Pragma("unroll") for (int n = 0; n < 2; ++n) _Pragma("unroll") for (int k = 0; k < 2; ++k) \
;         acc[ai][bj][m][n] = __builtin_amdgcn_mfma_f32_16x16x32_bf16(Bt[n][k], At[m][k], acc[ai][bj][m][n], 0, 0, 0); __builtin_amdgcn_s_setprio(0); } while (0)
; #define PG8_WAIT_V(n) asm volatile("s_waitcnt vmcnt(" #n ")" ::: "memory")
; #define PG8_BAR __builtin_amdgcn_s_barrier()
; template <class Epi, class Sched, bool ALIGN_EPI = false, bool SP2 = false>
; __device__ __forceinline__ void gemm_phase(PG8_LAS unsigned char* lds, const Gemm g, const Sched& S, const Epi& E) {
;     ...
;         for (int t = 0; t < nt; t += 2) {
;             const bool last = (t == nt - 2);
;             const char* a1 = cA + (size_t)(t + 1) * kstep;
;             const char* a2 = last ? nA : cA + (size_t)(t + 2) * kstep; const char* b2 = last ? nB : cB + (size_t)(t + 2) * kstep;
;             const char* a3 = a2 + kstep; const char* b3 = b2 + kstep;
;             if (last && has_next) S.a_ready(nxt);
;             if constexpr (SP2) {
;             PG8_LDB(B0, 0, 0); PG8_LDB(B1, 0, 1); PG8_SCHED; PG8_LDA(At, 0, 0); PG8_STAGE(PG8_SA(1, 1), a1 + hstepA, voffA);
;             PG8_WAIT_V(8); PG8_WAIT_L(0); PG8_BAR; PG8_MMA(0, 0, At, B0); PG8_MMA(0, 1, At, B1); PG8_BAR; PG8_SCHED;
;             PG8_LDA(At, 0, 1); PG8_STAGE(PG8_SB(0, 0), b2, voffB); PG8_STAGE(PG8_SB(0, 1), b2 + hstep, voffB); PG8_STAGE(PG8_SA(0, 0), a2, voffA);
;             PG8_WAIT_V(8); PG8_WAIT_L(0); PG8_BAR; PG8_MMA(1, 0, At, B0); PG8_MMA(1, 1, At, B1); PG8_BAR; PG8_SCHED;
.LBB0_898:
	ds_read_b128 v[150:153], v147
	ds_read_b128 v[154:157], v147 offset:1024
	ds_read_b128 v[158:161], v147 offset:2048
	ds_read_b128 v[162:165], v147 offset:3072
	ds_read_b128 v[166:169], v148
	ds_read_b128 v[170:173], v148 offset:1024
	ds_read_b128 v[174:177], v148 offset:2048
	ds_read_b128 v[178:181], v148 offset:3072
	s_add_i32 s58, s30, 2
	s_add_u32 s59, s10, 0xfffc0080
	s_addc_u32 s31, s11, -1
	s_cmp_eq_u32 s51, s30
	s_cselect_b32 s30, s57, s59
	s_cselect_b32 s31, s23, s31
	s_cselect_b32 s61, s25, s35
	s_cselect_b32 s60, s24, s34
	s_add_i32 m0, s29, 0xc000
	ds_read_b128 v[182:185], v149
	ds_read_b128 v[190:193], v149 offset:1024
	ds_read_b128 v[194:197], v149 offset:2048
	ds_read_b128 v[198:201], v149 offset:3072
	ds_read_b128 v[202:205], v149 offset:4096
	ds_read_b128 v[206:209], v149 offset:5120
	ds_read_b128 v[210:213], v149 offset:6144
	ds_read_b128 v[214:217], v149 offset:7168
	global_load_lds_dwordx4 v136, s[10:11]
	s_add_i32 m0, s29, 0xe000
	s_nop 0
	global_load_lds_dwordx4 v138, s[10:11]
	s_waitcnt vmcnt(8)
	s_waitcnt lgkmcnt(0)
	s_barrier
	s_setprio 1
	v_mfma_f32_16x16x32_bf16 v[124:127], v[150:153], v[182:185], v[124:127]
	v_mfma_f32_16x16x32_bf16 v[116:119], v[158:161], v[182:185], v[116:119]
	v_mfma_f32_16x16x32_bf16 v[108:111], v[150:153], v[194:197], v[108:111]
	v_mfma_f32_16x16x32_bf16 v[100:103], v[158:161], v[194:197], v[100:103]
	v_mfma_f32_16x16x32_bf16 v[92:95], v[150:153], v[202:205], v[92:95]
	v_mfma_f32_16x16x32_bf16 v[84:87], v[158:161], v[202:205], v[84:87]
	v_mfma_f32_16x16x32_bf16 v[76:79], v[150:153], v[210:213], v[76:79]
	v_mfma_f32_16x16x32_bf16 v[68:71], v[158:161], v[210:213], v[68:71]
	v_mfma_f32_16x16x32_bf16 v[124:127], v[154:157], v[190:193], v[124:127]
	v_mfma_f32_16x16x32_bf16 v[116:119], v[162:165], v[190:193], v[116:119]
	v_mfma_f32_16x16x32_bf16 v[108:111], v[154:157], v[198:201], v[108:111]
	v_mfma_f32_16x16x32_bf16 v[100:103], v[162:165], v[198:201], v[100:103]
	v_mfma_f32_16x16x32_bf16 v[92:95], v[154:157], v[206:209], v[92:95]
	v_mfma_f32_16x16x32_bf16 v[84:87], v[162:165], v[206:209], v[84:87]
	v_mfma_f32_16x16x32_bf16 v[76:79], v[154:157], v[214:217], v[76:79]
	v_mfma_f32_16x16x32_bf16 v[68:71], v[162:165], v[214:217], v[68:71]
	v_mfma_f32_16x16x32_bf16 v[120:123], v[166:169], v[182:185], v[120:123]
	v_mfma_f32_16x16x32_bf16 v[112:115], v[174:177], v[182:185], v[112:115]
	v_mfma_f32_16x16x32_bf16 v[104:107], v[166:169], v[194:197], v[104:107]
	v_mfma_f32_16x16x32_bf16 v[96:99], v[174:177], v[194:197], v[96:99]
	v_mfma_f32_16x16x32_bf16 v[88:91], v[166:169], v[202:205], v[88:91]
	v_mfma_f32_16x16x32_bf16 v[80:83], v[174:177], v[202:205], v[80:83]
	v_mfma_f32_16x16x32_bf16 v[72:75], v[166:169], v[210:213], v[72:75]
	v_mfma_f32_16x16x32_bf16 v[64:67], v[174:177], v[210:213], v[64:67]
	v_mfma_f32_16x16x32_bf16 v[120:123], v[170:173], v[190:193], v[120:123]
	v_mfma_f32_16x16x32_bf16 v[112:115], v[178:181], v[190:193], v[112:115]
	v_mfma_f32_16x16x32_bf16 v[104:107], v[170:173], v[198:201], v[104:107]
	v_mfma_f32_16x16x32_bf16 v[96:99], v[178:181], v[198:201], v[96:99]
	v_mfma_f32_16x16x32_bf16 v[88:91], v[170:173], v[206:209], v[88:91]
	v_mfma_f32_16x16x32_bf16 v[80:83], v[178:181], v[206:209], v[80:83]
	v_mfma_f32_16x16x32_bf16 v[72:75], v[170:173], v[214:217], v[72:75]
	v_mfma_f32_16x16x32_bf16 v[64:67], v[178:181], v[214:217], v[64:67]
	s_setprio 0
	s_barrier
	s_add_i32 s59, s52, s38
	s_mov_b32 m0, s59
	ds_read_b128 v[182:185], v149 offset:16384
	ds_read_b128 v[190:193], v149 offset:17408
	ds_read_b128 v[194:197], v149 offset:18432
	ds_read_b128 v[198:201], v149 offset:19456
	ds_read_b128 v[202:205], v149 offset:20480
	ds_read_b128 v[206:209], v149 offset:21504
	ds_read_b128 v[210:213], v149 offset:22528
	ds_read_b128 v[214:217], v149 offset:23552
	global_load_lds_dwordx4 v134, s[60:61]
	s_add_i32 m0, s59, 0x2000
	s_mov_b64 s[100:101], s[60:61]
	s_add_i32 s59, s53, s38
	global_load_lds_dwordx4 v132, s[60:61]
	s_add_u32 s60, s60, s4
	s_addc_u32 s61, s61, s5
	s_mov_b32 m0, s59
	s_nop 0
	global_load_lds_dwordx4 v134, s[60:61]
	s_add_i32 m0, s59, 0x2000
	s_nop 0
	global_load_lds_dwordx4 v132, s[60:61]
	s_mov_b32 m0, s29
	s_nop 0
	global_load_lds_dwordx4 v128, s[30:31]
	s_mov_b32 m0, s41
	s_nop 0
	global_load_lds_dwordx4 v130, s[30:31]
	s_waitcnt vmcnt(8)
	s_waitcnt lgkmcnt(0)
	s_barrier
	s_setprio 1
	v_mfma_f32_16x16x32_bf16 v[60:63], v[150:153], v[182:185], v[60:63]
	v_mfma_f32_16x16x32_bf16 v[52:55], v[158:161], v[182:185], v[52:55]
	v_mfma_f32_16x16x32_bf16 v[44:47], v[150:153], v[194:197], v[44:47]
	v_mfma_f32_16x16x32_bf16 v[36:39], v[158:161], v[194:197], v[36:39]
	v_mfma_f32_16x16x32_bf16 v[28:31], v[150:153], v[202:205], v[28:31]
	v_mfma_f32_16x16x32_bf16 v[20:23], v[158:161], v[202:205], v[20:23]
	v_mfma_f32_16x16x32_bf16 v[12:15], v[150:153], v[210:213], v[12:15]
	v_mfma_f32_16x16x32_bf16 v[4:7], v[158:161], v[210:213], v[4:7]
	v_mfma_f32_16x16x32_bf16 v[60:63], v[154:157], v[190:193], v[60:63]
	v_mfma_f32_16x16x32_bf16 v[52:55], v[162:165], v[190:193], v[52:55]
	v_mfma_f32_16x16x32_bf16 v[44:47], v[154:157], v[198:201], v[44:47]
	v_mfma_f32_16x16x32_bf16 v[36:39], v[162:165], v[198:201], v[36:39]
	v_mfma_f32_16x16x32_bf16 v[28:31], v[154:157], v[206:209], v[28:31]
	v_mfma_f32_16x16x32_bf16 v[20:23], v[162:165], v[206:209], v[20:23]
	v_mfma_f32_16x16x32_bf16 v[12:15], v[154:157], v[214:217], v[12:15]
	v_mfma_f32_16x16x32_bf16 v[4:7], v[162:165], v[214:217], v[4:7]
	v_mfma_f32_16x16x32_bf16 v[56:59], v[166:169], v[182:185], v[56:59]
	v_mfma_f32_16x16x32_bf16 v[48:51], v[174:177], v[182:185], v[48:51]
	v_mfma_f32_16x16x32_bf16 v[40:43], v[166:169], v[194:197], v[40:43]
	v_mfma_f32_16x16x32_bf16 v[32:35], v[174:177], v[194:197], v[32:35]
	v_mfma_f32_16x16x32_bf16 v[24:27], v[166:169], v[202:205], v[24:27]
	v_mfma_f32_16x16x32_bf16 v[16:19], v[174:177], v[202:205], v[16:19]
	v_mfma_f32_16x16x32_bf16 v[8:11], v[166:169], v[210:213], v[8:11]
	v_mfma_f32_16x16x32_bf16 v[0:3], v[174:177], v[210:213], v[0:3]
	v_mfma_f32_16x16x32_bf16 v[56:59], v[170:173], v[190:193], v[56:59]
	v_mfma_f32_16x16x32_bf16 v[48:51], v[178:181], v[190:193], v[48:51]
	v_mfma_f32_16x16x32_bf16 v[40:43], v[170:173], v[198:201], v[40:43]
	v_mfma_f32_16x16x32_bf16 v[32:35], v[178:181], v[198:201], v[32:35]
	v_mfma_f32_16x16x32_bf16 v[24:27], v[170:173], v[206:209], v[24:27]
	v_mfma_f32_16x16x32_bf16 v[16:19], v[178:181], v[206:209], v[16:19]
	v_mfma_f32_16x16x32_bf16 v[8:11], v[170:173], v[214:217], v[8:11]
	v_mfma_f32_16x16x32_bf16 v[0:3], v[178:181], v[214:217], v[0:3]
	s_setprio 0
	s_barrier
; #define PG8_STAGE(bufoff, gbase, voff) do { _Pragma("unroll") for (int _i = 0; _i < 2; ++_i) \
;         __builtin_amdgcn_global_load_lds((const unsigned*)((const char*)(gbase) + (voff)[_i]), (PG8_LAS unsigned*)(lds + (bufoff) + ldsw + _i * 8192), 16, 0, 0); } while (0)
; #define PG8_LDA(dst, b, h) do { _Pragma("unroll") for (int m = 0; m < 4; ++m) _Pragma("unroll") for (int k = 0; k < 2; ++k) dst[m][k] = *(const PG8_LAS bf16x8*)(lds + PG8_SA(b, h) + aoff + m * 2048 + k * 1024); } while (0)
; #define PG8_LDB(dst, b, h) do { _Pragma("unroll") for (int n = 0; n < 2; ++n) _Pragma("unroll") for (int k = 0; k < 2; ++k) dst[n][k] = *(const PG8_LAS bf16x8*)(lds + PG8_SB(b, h) + boff + n * 2048 + k * 1024); } while (0)
; #define PG8_MMA(ai, bj, At, Bt) do { __builtin_amdgcn_s_setprio(1); _Pragma("unroll") for (int m = 0; m < 4; ++m) _Pragma("unroll") for (int n = 0; n < 2; ++n) _Pragma("unroll") for (int k = 0; k < 2; ++k) \
;         acc[ai][bj][m][n] = __builtin_amdgcn_mfma_f32_16x16x32_bf16(Bt[n][k], At[m][k], acc[ai][bj][m][n], 0, 0, 0); __builtin_amdgcn_s_setprio(0); } while (0)
; #define PG8_WAIT_V(n) asm volatile("s_waitcnt vmcnt(" #n ")" ::: "memory")
; #define PG8_WAIT_L(n) asm volatile("s_waitcnt lgkmcnt(" #n ")" ::: "memory")
; #define PG8_BAR __builtin_amdgcn_s_barrier()
; #define PG8_SCHED __builtin_amdgcn_sched_barrier(0)
; template <class Epi, class Sched, bool ALIGN_EPI = false, bool SP2 = false>
; __device__ __forceinline__ void gemm_phase(PG8_LAS unsigned char* lds, const Gemm g, const Sched& S, const Epi& E) {
;     ...
;             PG8_LDB(B0, 1, 0); PG8_LDB(B1, 1, 1); PG8_SCHED; PG8_LDA(At, 1, 0); PG8_STAGE(PG8_SA(0, 1), a2 + hstepA, voffA);
;             PG8_WAIT_V(8); PG8_WAIT_L(0); PG8_BAR; PG8_MMA(0, 0, At, B0); PG8_MMA(0, 1, At, B1); PG8_BAR; PG8_SCHED;
;             PG8_LDA(At, 1, 1); PG8_STAGE(PG8_SB(1, 0), b3, voffB); PG8_STAGE(PG8_SB(1, 1), b3 + hstep, voffB); PG8_STAGE(PG8_SA(1, 0), a3, voffA);
;             PG8_WAIT_V(8); PG8_WAIT_L(0); PG8_BAR; PG8_MMA(1, 0, At, B0); PG8_MMA(1, 1, At, B1); PG8_BAR; PG8_SCHED;
	s_add_i32 s59, 0, 0x18000
	s_add_i32 s60, 0, 0x1c000
	v_add_u32_e32 v162, s59, v145
	v_add_u32_e32 v178, s60, v145
	ds_read_b128 v[150:153], v162
	ds_read_b128 v[154:157], v162 offset:1024
	ds_read_b128 v[158:161], v162 offset:2048
	ds_read_b128 v[162:165], v162 offset:3072
	ds_read_b128 v[166:169], v178
	ds_read_b128 v[170:173], v178 offset:1024
	ds_read_b128 v[174:177], v178 offset:2048
	ds_read_b128 v[178:181], v178 offset:3072
	s_mov_b64 vcc, s[30:31]
	s_add_u32 s30, s30, 0x40000
	s_addc_u32 s31, s31, 0
	s_mov_b32 m0, s42
	ds_read_b128 v[182:185], v149 offset:32768
	ds_read_b128 v[190:193], v149 offset:33792
	ds_read_b128 v[194:197], v149 offset:34816
	ds_read_b128 v[198:201], v149 offset:35840
	ds_read_b128 v[202:205], v149 offset:36864
	ds_read_b128 v[206:209], v149 offset:37888
	ds_read_b128 v[210:213], v149 offset:38912
	ds_read_b128 v[214:217], v149 offset:39936
	global_load_lds_dwordx4 v128, s[30:31]
	s_mov_b32 m0, s43
	s_nop 0
	global_load_lds_dwordx4 v130, s[30:31]
	s_waitcnt vmcnt(8)
	s_waitcnt lgkmcnt(0)
	s_barrier
	s_setprio 1
	v_mfma_f32_16x16x32_bf16 v[124:127], v[150:153], v[182:185], v[124:127]
	v_mfma_f32_16x16x32_bf16 v[116:119], v[158:161], v[182:185], v[116:119]
	v_mfma_f32_16x16x32_bf16 v[108:111], v[150:153], v[194:197], v[108:111]
	v_mfma_f32_16x16x32_bf16 v[100:103], v[158:161], v[194:197], v[100:103]
	v_mfma_f32_16x16x32_bf16 v[92:95], v[150:153], v[202:205], v[92:95]
	v_mfma_f32_16x16x32_bf16 v[84:87], v[158:161], v[202:205], v[84:87]
	v_mfma_f32_16x16x32_bf16 v[76:79], v[150:153], v[210:213], v[76:79]
	v_mfma_f32_16x16x32_bf16 v[68:71], v[158:161], v[210:213], v[68:71]
	v_mfma_f32_16x16x32_bf16 v[124:127], v[154:157], v[190:193], v[124:127]
	v_mfma_f32_16x16x32_bf16 v[116:119], v[162:165], v[190:193], v[116:119]
	v_mfma_f32_16x16x32_bf16 v[108:111], v[154:157], v[198:201], v[108:111]
	v_mfma_f32_16x16x32_bf16 v[100:103], v[162:165], v[198:201], v[100:103]
	v_mfma_f32_16x16x32_bf16 v[92:95], v[154:157], v[206:209], v[92:95]
	v_mfma_f32_16x16x32_bf16 v[84:87], v[162:165], v[206:209], v[84:87]
	v_mfma_f32_16x16x32_bf16 v[76:79], v[154:157], v[214:217], v[76:79]
	v_mfma_f32_16x16x32_bf16 v[68:71], v[162:165], v[214:217], v[68:71]
	v_mfma_f32_16x16x32_bf16 v[120:123], v[166:169], v[182:185], v[120:123]
	v_mfma_f32_16x16x32_bf16 v[112:115], v[174:177], v[182:185], v[112:115]
	v_mfma_f32_16x16x32_bf16 v[104:107], v[166:169], v[194:197], v[104:107]
	v_mfma_f32_16x16x32_bf16 v[96:99], v[174:177], v[194:197], v[96:99]
	v_mfma_f32_16x16x32_bf16 v[88:91], v[166:169], v[202:205], v[88:91]
	v_mfma_f32_16x16x32_bf16 v[80:83], v[174:177], v[202:205], v[80:83]
	v_mfma_f32_16x16x32_bf16 v[72:75], v[166:169], v[210:213], v[72:75]
	v_mfma_f32_16x16x32_bf16 v[64:67], v[174:177], v[210:213], v[64:67]
	v_mfma_f32_16x16x32_bf16 v[120:123], v[170:173], v[190:193], v[120:123]
	v_mfma_f32_16x16x32_bf16 v[112:115], v[178:181], v[190:193], v[112:115]
	v_mfma_f32_16x16x32_bf16 v[104:107], v[170:173], v[198:201], v[104:107]
	v_mfma_f32_16x16x32_bf16 v[96:99], v[178:181], v[198:201], v[96:99]
	v_mfma_f32_16x16x32_bf16 v[88:91], v[170:173], v[206:209], v[88:91]
	v_mfma_f32_16x16x32_bf16 v[80:83], v[178:181], v[206:209], v[80:83]
	v_mfma_f32_16x16x32_bf16 v[72:75], v[170:173], v[214:217], v[72:75]
	v_mfma_f32_16x16x32_bf16 v[64:67], v[178:181], v[214:217], v[64:67]
	s_setprio 0
	s_barrier
	s_add_i32 s30, s59, s38
	s_add_i32 m0, s30, 0xffffff80
	ds_read_b128 v[182:185], v149 offset:49152
	ds_read_b128 v[190:193], v149 offset:50176
	ds_read_b128 v[194:197], v149 offset:51200
	ds_read_b128 v[198:201], v149 offset:52224
	ds_read_b128 v[202:205], v149 offset:53248
	ds_read_b128 v[206:209], v149 offset:54272
	ds_read_b128 v[210:213], v149 offset:55296
	ds_read_b128 v[214:217], v149 offset:56320
	global_load_lds_dwordx4 v134, s[100:101] offset:128
	s_add_i32 m0, s30, 0x1f80
	s_add_i32 s30, s60, s38
	global_load_lds_dwordx4 v132, s[100:101] offset:128
	s_add_u32 s100, s100, s4
	s_addc_u32 s101, s101, s5
	s_add_i32 m0, s30, 0xffffff80
	s_nop 0
	global_load_lds_dwordx4 v134, s[100:101] offset:128
	s_add_i32 m0, s30, 0x1f80
	s_nop 0
	global_load_lds_dwordx4 v132, s[100:101] offset:128
	s_add_i32 m0, s47, 0xffffff80
	s_nop 0
	global_load_lds_dwordx4 v128, vcc offset:128
	s_add_i32 m0, s48, 0xffffff80
	s_nop 0
	global_load_lds_dwordx4 v130, vcc offset:128
	s_waitcnt vmcnt(8)
	s_waitcnt lgkmcnt(0)
	s_barrier
	s_setprio 1
	v_mfma_f32_16x16x32_bf16 v[60:63], v[150:153], v[182:185], v[60:63]
	v_mfma_f32_16x16x32_bf16 v[52:55], v[158:161], v[182:185], v[52:55]
	v_mfma_f32_16x16x32_bf16 v[44:47], v[150:153], v[194:197], v[44:47]
	v_mfma_f32_16x16x32_bf16 v[36:39], v[158:161], v[194:197], v[36:39]
	v_mfma_f32_16x16x32_bf16 v[28:31], v[150:153], v[202:205], v[28:31]
	v_mfma_f32_16x16x32_bf16 v[20:23], v[158:161], v[202:205], v[20:23]
	v_mfma_f32_16x16x32_bf16 v[12:15], v[150:153], v[210:213], v[12:15]
	v_mfma_f32_16x16x32_bf16 v[4:7], v[158:161], v[210:213], v[4:7]
	v_mfma_f32_16x16x32_bf16 v[60:63], v[154:157], v[190:193], v[60:63]
	v_mfma_f32_16x16x32_bf16 v[52:55], v[162:165], v[190:193], v[52:55]
	v_mfma_f32_16x16x32_bf16 v[44:47], v[154:157], v[198:201], v[44:47]
	v_mfma_f32_16x16x32_bf16 v[36:39], v[162:165], v[198:201], v[36:39]
	v_mfma_f32_16x16x32_bf16 v[28:31], v[154:157], v[206:209], v[28:31]
	v_mfma_f32_16x16x32_bf16 v[20:23], v[162:165], v[206:209], v[20:23]
	v_mfma_f32_16x16x32_bf16 v[12:15], v[154:157], v[214:217], v[12:15]
	v_mfma_f32_16x16x32_bf16 v[4:7], v[162:165], v[214:217], v[4:7]
	v_mfma_f32_16x16x32_bf16 v[56:59], v[166:169], v[182:185], v[56:59]
	v_mfma_f32_16x16x32_bf16 v[48:51], v[174:177], v[182:185], v[48:51]
	v_mfma_f32_16x16x32_bf16 v[40:43], v[166:169], v[194:197], v[40:43]
	v_mfma_f32_16x16x32_bf16 v[32:35], v[174:177], v[194:197], v[32:35]
	v_mfma_f32_16x16x32_bf16 v[24:27], v[166:169], v[202:205], v[24:27]
	v_mfma_f32_16x16x32_bf16 v[16:19], v[174:177], v[202:205], v[16:19]
	v_mfma_f32_16x16x32_bf16 v[8:11], v[166:169], v[210:213], v[8:11]
	v_mfma_f32_16x16x32_bf16 v[0:3], v[174:177], v[210:213], v[0:3]
	v_mfma_f32_16x16x32_bf16 v[56:59], v[170:173], v[190:193], v[56:59]
	v_mfma_f32_16x16x32_bf16 v[48:51], v[178:181], v[190:193], v[48:51]
	v_mfma_f32_16x16x32_bf16 v[40:43], v[170:173], v[198:201], v[40:43]
	v_mfma_f32_16x16x32_bf16 v[32:35], v[178:181], v[198:201], v[32:35]
	v_mfma_f32_16x16x32_bf16 v[24:27], v[170:173], v[206:209], v[24:27]
	v_mfma_f32_16x16x32_bf16 v[16:19], v[178:181], v[206:209], v[16:19]
	v_mfma_f32_16x16x32_bf16 v[8:11], v[170:173], v[214:217], v[8:11]
	v_mfma_f32_16x16x32_bf16 v[0:3], v[178:181], v[214:217], v[0:3]
	s_setprio 0
	s_barrier
	s_add_u32 s10, s10, 0x100
	s_addc_u32 s11, s11, 0
	s_add_u32 s34, s34, 0x100
	s_addc_u32 s35, s35, 0
	s_cmp_ge_i32 s58, s50
	s_mov_b32 s30, s58
	s_cbranch_scc0 .LBB0_898

; #define PG8_STAGE(bufoff, gbase, voff) do { _Pragma("unroll") for (int _i = 0; _i < 2; ++_i) \
;         __builtin_amdgcn_global_load_lds((const unsigned*)((const char*)(gbase) + (voff)[_i]), (PG8_LAS unsigned*)(lds + (bufoff) + ldsw + _i * 8192), 16, 0, 0); } while (0)
; #define PG8_LDA(dst, b, h) do { _Pragma("unroll") for (int m = 0; m < 4; ++m) _Pragma("unroll") for (int k = 0; k < 2; ++k) dst[m][k] = *(const PG8_LAS bf16x8*)(lds + PG8_SA(b, h) + aoff + m * 2048 + k * 1024); } while (0)
; #define PG8_LDB(dst, b, h) do { _Pragma("unroll") for (int n = 0; n < 2; ++n) _Pragma("unroll") for (int k = 0; k < 2; ++k) dst[n][k] = *(const PG8_LAS bf16x8*)(lds + PG8_SB(b, h) + boff + n * 2048 + k * 1024); } while (0)
; #define PG8_MMA(ai, bj, At, Bt) do { __builtin_amdgcn_s_setprio(1); _Pragma("unroll") for (int m = 0; m < 4; ++m) _Pragma("unroll") for (int n = 0; n < 2; ++n) _Pragma("unroll") for (int k = 0; k < 2; ++k) \
;         acc[ai][bj][m][n] = __builtin_amdgcn_mfma_f32_16x16x32_bf16(Bt[n][k], At[m][k], acc[ai][bj][m][n], 0, 0, 0); __builtin_amdgcn_s_setprio(0); } while (0)
; #define PG8_WAIT_V(n) asm volatile("s_waitcnt vmcnt(" #n ")" ::: "memory")
; #define PG8_WAIT_L(n) asm volatile("s_waitcnt lgkmcnt(" #n ")" ::: "memory")
; template <class Epi, class Sched, bool ALIGN_EPI = false, bool SP2 = false>
; __device__ __forceinline__ void gemm_phase(PG8_LAS unsigned char* lds, const Gemm g, const Sched& S, const Epi& E) {
;     ...
;             const bool last = (t == nt - 2);
;             const char* a1 = cA + (size_t)(t + 1) * kstep;
;             const char* a2 = last ? nA : cA + (size_t)(t + 2) * kstep; const char* b2 = last ? nB : cB + (size_t)(t + 2) * kstep;
;             const char* a3 = a2 + kstep; const char* b3 = b2 + kstep;
;             if (last && has_next) S.a_ready(nxt);
;             if constexpr (SP2) {
;             PG8_LDB(B0, 0, 0); PG8_LDB(B1, 0, 1); PG8_SCHED; PG8_LDA(At, 0, 0); PG8_STAGE(PG8_SA(1, 1), a1 + hstepA, voffA);
;             PG8_WAIT_V(8); PG8_WAIT_L(0); PG8_BAR; PG8_MMA(0, 0, At, B0); PG8_MMA(0, 1, At, B1); PG8_BAR; PG8_SCHED;
;             PG8_LDA(At, 0, 1); PG8_STAGE(PG8_SB(0, 0), b2, voffB); PG8_STAGE(PG8_SB(0, 1), b2 + hstep, voffB); PG8_STAGE(PG8_SA(0, 0), a2, voffA);
;             PG8_WAIT_V(8); PG8_WAIT_L(0); PG8_BAR; PG8_MMA(1, 0, At, B0); PG8_MMA(1, 1, At, B1); PG8_BAR; PG8_SCHED;
.LBB0_980:
	ds_read_b128 v[128:131], v169
	ds_read_b128 v[132:135], v169 offset:1024
	ds_read_b128 v[136:139], v169 offset:2048
	ds_read_b128 v[140:143], v169 offset:3072
	ds_read_b128 v[160:163], v170
	ds_read_b128 v[172:175], v170 offset:1024
	ds_read_b128 v[176:179], v170 offset:2048
	ds_read_b128 v[180:183], v170 offset:3072
	s_add_i32 s69, s38, 2
	s_add_u32 s70, s36, 0xfff50080
	s_addc_u32 s39, s37, -1
	s_cmp_eq_u32 s55, s38
	s_cselect_b32 s38, s8, s70
	s_cselect_b32 s39, s9, s39
	s_cselect_b32 s71, s35, s68
	s_cselect_b32 s70, s34, s67
	s_add_i32 m0, s44, 0xc000
	ds_read_b128 v[184:187], v171
	ds_read_b128 v[190:193], v171 offset:1024
	ds_read_b128 v[194:197], v171 offset:2048
	ds_read_b128 v[198:201], v171 offset:3072
	ds_read_b128 v[202:205], v171 offset:4096
	ds_read_b128 v[206:209], v171 offset:5120
	ds_read_b128 v[210:213], v171 offset:6144
	ds_read_b128 v[214:217], v171 offset:7168
	global_load_lds_dwordx4 v152, s[36:37]
	s_add_i32 m0, s44, 0xe000
	s_nop 0
	global_load_lds_dwordx4 v154, s[36:37]
	s_waitcnt vmcnt(8)
	s_waitcnt lgkmcnt(0)
	s_barrier
	s_setprio 1
	v_mfma_f32_16x16x32_bf16 v[124:127], v[128:131], v[184:187], v[124:127]
	v_mfma_f32_16x16x32_bf16 v[120:123], v[136:139], v[184:187], v[120:123]
	v_mfma_f32_16x16x32_bf16 v[108:111], v[128:131], v[194:197], v[108:111]
	v_mfma_f32_16x16x32_bf16 v[104:107], v[136:139], v[194:197], v[104:107]
	v_mfma_f32_16x16x32_bf16 v[92:95], v[128:131], v[202:205], v[92:95]
	v_mfma_f32_16x16x32_bf16 v[88:91], v[136:139], v[202:205], v[88:91]
	v_mfma_f32_16x16x32_bf16 v[76:79], v[128:131], v[210:213], v[76:79]
	v_mfma_f32_16x16x32_bf16 v[72:75], v[136:139], v[210:213], v[72:75]
	v_mfma_f32_16x16x32_bf16 v[124:127], v[132:135], v[190:193], v[124:127]
	v_mfma_f32_16x16x32_bf16 v[120:123], v[140:143], v[190:193], v[120:123]
	v_mfma_f32_16x16x32_bf16 v[108:111], v[132:135], v[198:201], v[108:111]
	v_mfma_f32_16x16x32_bf16 v[104:107], v[140:143], v[198:201], v[104:107]
	v_mfma_f32_16x16x32_bf16 v[92:95], v[132:135], v[206:209], v[92:95]
	v_mfma_f32_16x16x32_bf16 v[88:91], v[140:143], v[206:209], v[88:91]
	v_mfma_f32_16x16x32_bf16 v[76:79], v[132:135], v[214:217], v[76:79]
	v_mfma_f32_16x16x32_bf16 v[72:75], v[140:143], v[214:217], v[72:75]
	v_mfma_f32_16x16x32_bf16 v[116:119], v[160:163], v[184:187], v[116:119]
	v_mfma_f32_16x16x32_bf16 v[112:115], v[176:179], v[184:187], v[112:115]
	v_mfma_f32_16x16x32_bf16 v[100:103], v[160:163], v[194:197], v[100:103]
	v_mfma_f32_16x16x32_bf16 v[96:99], v[176:179], v[194:197], v[96:99]
	v_mfma_f32_16x16x32_bf16 v[84:87], v[160:163], v[202:205], v[84:87]
	v_mfma_f32_16x16x32_bf16 v[80:83], v[176:179], v[202:205], v[80:83]
	v_mfma_f32_16x16x32_bf16 v[68:71], v[160:163], v[210:213], v[68:71]
	v_mfma_f32_16x16x32_bf16 v[64:67], v[176:179], v[210:213], v[64:67]
	v_mfma_f32_16x16x32_bf16 v[116:119], v[172:175], v[190:193], v[116:119]
	v_mfma_f32_16x16x32_bf16 v[112:115], v[180:183], v[190:193], v[112:115]
	v_mfma_f32_16x16x32_bf16 v[100:103], v[172:175], v[198:201], v[100:103]
	v_mfma_f32_16x16x32_bf16 v[96:99], v[180:183], v[198:201], v[96:99]
	v_mfma_f32_16x16x32_bf16 v[84:87], v[172:175], v[206:209], v[84:87]
	v_mfma_f32_16x16x32_bf16 v[80:83], v[180:183], v[206:209], v[80:83]
	v_mfma_f32_16x16x32_bf16 v[68:71], v[172:175], v[214:217], v[68:71]
	v_mfma_f32_16x16x32_bf16 v[64:67], v[180:183], v[214:217], v[64:67]
	s_setprio 0
	s_barrier
	s_add_i32 s72, s56, s42
	s_mov_b32 m0, s72
	ds_read_b128 v[184:187], v171 offset:16384
	ds_read_b128 v[190:193], v171 offset:17408
	ds_read_b128 v[194:197], v171 offset:18432
	ds_read_b128 v[198:201], v171 offset:19456
	ds_read_b128 v[202:205], v171 offset:20480
	ds_read_b128 v[206:209], v171 offset:21504
	ds_read_b128 v[210:213], v171 offset:22528
	ds_read_b128 v[214:217], v171 offset:23552
	global_load_lds_dwordx4 v150, s[70:71]
	s_add_i32 m0, s72, 0x2000
	s_mov_b64 s[100:101], s[70:71]
	s_add_i32 s72, s57, s42
	global_load_lds_dwordx4 v148, s[70:71]
	s_add_u32 s70, s70, s4
	s_addc_u32 s71, s71, s5
	s_mov_b32 m0, s72
	s_nop 0
	global_load_lds_dwordx4 v150, s[70:71]
	s_add_i32 m0, s72, 0x2000
	s_nop 0
	global_load_lds_dwordx4 v148, s[70:71]
	s_mov_b32 m0, s44
	s_nop 0
	global_load_lds_dwordx4 v144, s[38:39]
	s_mov_b32 m0, s45
	s_nop 0
	global_load_lds_dwordx4 v146, s[38:39]
	s_waitcnt vmcnt(8)
	s_waitcnt lgkmcnt(0)
	s_barrier
	s_setprio 1
	v_mfma_f32_16x16x32_bf16 v[60:63], v[128:131], v[184:187], v[60:63]
	v_mfma_f32_16x16x32_bf16 v[56:59], v[136:139], v[184:187], v[56:59]
	v_mfma_f32_16x16x32_bf16 v[44:47], v[128:131], v[194:197], v[44:47]
	v_mfma_f32_16x16x32_bf16 v[40:43], v[136:139], v[194:197], v[40:43]
	v_mfma_f32_16x16x32_bf16 v[28:31], v[128:131], v[202:205], v[28:31]
	v_mfma_f32_16x16x32_bf16 v[24:27], v[136:139], v[202:205], v[24:27]
	v_mfma_f32_16x16x32_bf16 v[12:15], v[128:131], v[210:213], v[12:15]
	v_mfma_f32_16x16x32_bf16 v[8:11], v[136:139], v[210:213], v[8:11]
	v_mfma_f32_16x16x32_bf16 v[60:63], v[132:135], v[190:193], v[60:63]
	v_mfma_f32_16x16x32_bf16 v[56:59], v[140:143], v[190:193], v[56:59]
	v_mfma_f32_16x16x32_bf16 v[44:47], v[132:135], v[198:201], v[44:47]
	v_mfma_f32_16x16x32_bf16 v[40:43], v[140:143], v[198:201], v[40:43]
	v_mfma_f32_16x16x32_bf16 v[28:31], v[132:135], v[206:209], v[28:31]
	v_mfma_f32_16x16x32_bf16 v[24:27], v[140:143], v[206:209], v[24:27]
	v_mfma_f32_16x16x32_bf16 v[12:15], v[132:135], v[214:217], v[12:15]
	v_mfma_f32_16x16x32_bf16 v[8:11], v[140:143], v[214:217], v[8:11]
	v_mfma_f32_16x16x32_bf16 v[52:55], v[160:163], v[184:187], v[52:55]
	v_mfma_f32_16x16x32_bf16 v[48:51], v[176:179], v[184:187], v[48:51]
	v_mfma_f32_16x16x32_bf16 v[36:39], v[160:163], v[194:197], v[36:39]
	v_mfma_f32_16x16x32_bf16 v[32:35], v[176:179], v[194:197], v[32:35]
	v_mfma_f32_16x16x32_bf16 v[20:23], v[160:163], v[202:205], v[20:23]
	v_mfma_f32_16x16x32_bf16 v[16:19], v[176:179], v[202:205], v[16:19]
	v_mfma_f32_16x16x32_bf16 v[4:7], v[160:163], v[210:213], v[4:7]
	v_mfma_f32_16x16x32_bf16 v[0:3], v[176:179], v[210:213], v[0:3]
	v_mfma_f32_16x16x32_bf16 v[52:55], v[172:175], v[190:193], v[52:55]
	v_mfma_f32_16x16x32_bf16 v[48:51], v[180:183], v[190:193], v[48:51]
	v_mfma_f32_16x16x32_bf16 v[36:39], v[172:175], v[198:201], v[36:39]
	v_mfma_f32_16x16x32_bf16 v[32:35], v[180:183], v[198:201], v[32:35]
	v_mfma_f32_16x16x32_bf16 v[20:23], v[172:175], v[206:209], v[20:23]
	v_mfma_f32_16x16x32_bf16 v[16:19], v[180:183], v[206:209], v[16:19]
	v_mfma_f32_16x16x32_bf16 v[4:7], v[172:175], v[214:217], v[4:7]
	v_mfma_f32_16x16x32_bf16 v[0:3], v[180:183], v[214:217], v[0:3]
	s_setprio 0
	s_barrier
; #define PG8_STAGE(bufoff, gbase, voff) do { _Pragma("unroll") for (int _i = 0; _i < 2; ++_i) \
;         __builtin_amdgcn_global_load_lds((const unsigned*)((const char*)(gbase) + (voff)[_i]), (PG8_LAS unsigned*)(lds + (bufoff) + ldsw + _i * 8192), 16, 0, 0); } while (0)
; #define PG8_LDA(dst, b, h) do { _Pragma("unroll") for (int m = 0; m < 4; ++m) _Pragma("unroll") for (int k = 0; k < 2; ++k) dst[m][k] = *(const PG8_LAS bf16x8*)(lds + PG8_SA(b, h) + aoff + m * 2048 + k * 1024); } while (0)
; #define PG8_LDB(dst, b, h) do { _Pragma("unroll") for (int n = 0; n < 2; ++n) _Pragma("unroll") for (int k = 0; k < 2; ++k) dst[n][k] = *(const PG8_LAS bf16x8*)(lds + PG8_SB(b, h) + boff + n * 2048 + k * 1024); } while (0)
; #define PG8_MMA(ai, bj, At, Bt) do { __builtin_amdgcn_s_setprio(1); _Pragma("unroll") for (int m = 0; m < 4; ++m) _Pragma("unroll") for (int n = 0; n < 2; ++n) _Pragma("unroll") for (int k = 0; k < 2; ++k) \
;         acc[ai][bj][m][n] = __builtin_amdgcn_mfma_f32_16x16x32_bf16(Bt[n][k], At[m][k], acc[ai][bj][m][n], 0, 0, 0); __builtin_amdgcn_s_setprio(0); } while (0)
; #define PG8_WAIT_V(n) asm volatile("s_waitcnt vmcnt(" #n ")" ::: "memory")
; #define PG8_WAIT_L(n) asm volatile("s_waitcnt lgkmcnt(" #n ")" ::: "memory")
; #define PG8_BAR __builtin_amdgcn_s_barrier()
; #define PG8_SCHED __builtin_amdgcn_sched_barrier(0)
; template <class Epi, class Sched, bool ALIGN_EPI = false, bool SP2 = false>
; __device__ __forceinline__ void gemm_phase(PG8_LAS unsigned char* lds, const Gemm g, const Sched& S, const Epi& E) {
;     ...
;             PG8_LDB(B0, 1, 0); PG8_LDB(B1, 1, 1); PG8_SCHED; PG8_LDA(At, 1, 0); PG8_STAGE(PG8_SA(0, 1), a2 + hstepA, voffA);
;             PG8_WAIT_V(8); PG8_WAIT_L(0); PG8_BAR; PG8_MMA(0, 0, At, B0); PG8_MMA(0, 1, At, B1); PG8_BAR; PG8_SCHED;
;             PG8_LDA(At, 1, 1); PG8_STAGE(PG8_SB(1, 0), b3, voffB); PG8_STAGE(PG8_SB(1, 1), b3 + hstep, voffB); PG8_STAGE(PG8_SA(1, 0), a3, voffA);
;             PG8_WAIT_V(8); PG8_WAIT_L(0); PG8_BAR; PG8_MMA(1, 0, At, B0); PG8_MMA(1, 1, At, B1); PG8_BAR; PG8_SCHED;
	s_add_i32 s70, 0, 0x18000
	s_add_i32 s71, 0, 0x1c000
	v_add_u32_e32 v140, s70, v167
	v_add_u32_e32 v180, s71, v167
	ds_read_b128 v[128:131], v140
	ds_read_b128 v[132:135], v140 offset:1024
	ds_read_b128 v[136:139], v140 offset:2048
	ds_read_b128 v[140:143], v140 offset:3072
	ds_read_b128 v[160:163], v180
	ds_read_b128 v[172:175], v180 offset:1024
	ds_read_b128 v[176:179], v180 offset:2048
	ds_read_b128 v[180:183], v180 offset:3072
	s_mov_b64 vcc, s[38:39]
	s_add_u32 s38, s38, 0xb0000
	s_addc_u32 s39, s39, 0
	s_mov_b32 m0, s47
	ds_read_b128 v[184:187], v171 offset:32768
	ds_read_b128 v[190:193], v171 offset:33792
	ds_read_b128 v[194:197], v171 offset:34816
	ds_read_b128 v[198:201], v171 offset:35840
	ds_read_b128 v[202:205], v171 offset:36864
	ds_read_b128 v[206:209], v171 offset:37888
	ds_read_b128 v[210:213], v171 offset:38912
	ds_read_b128 v[214:217], v171 offset:39936
	global_load_lds_dwordx4 v144, s[38:39]
	s_mov_b32 m0, s48
	s_nop 0
	global_load_lds_dwordx4 v146, s[38:39]
	s_waitcnt vmcnt(8)
	s_waitcnt lgkmcnt(0)
	s_barrier
	s_setprio 1
	v_mfma_f32_16x16x32_bf16 v[124:127], v[128:131], v[184:187], v[124:127]
	v_mfma_f32_16x16x32_bf16 v[120:123], v[136:139], v[184:187], v[120:123]
	v_mfma_f32_16x16x32_bf16 v[108:111], v[128:131], v[194:197], v[108:111]
	v_mfma_f32_16x16x32_bf16 v[104:107], v[136:139], v[194:197], v[104:107]
	v_mfma_f32_16x16x32_bf16 v[92:95], v[128:131], v[202:205], v[92:95]
	v_mfma_f32_16x16x32_bf16 v[88:91], v[136:139], v[202:205], v[88:91]
	v_mfma_f32_16x16x32_bf16 v[76:79], v[128:131], v[210:213], v[76:79]
	v_mfma_f32_16x16x32_bf16 v[72:75], v[136:139], v[210:213], v[72:75]
	v_mfma_f32_16x16x32_bf16 v[124:127], v[132:135], v[190:193], v[124:127]
	v_mfma_f32_16x16x32_bf16 v[120:123], v[140:143], v[190:193], v[120:123]
	v_mfma_f32_16x16x32_bf16 v[108:111], v[132:135], v[198:201], v[108:111]
	v_mfma_f32_16x16x32_bf16 v[104:107], v[140:143], v[198:201], v[104:107]
	v_mfma_f32_16x16x32_bf16 v[92:95], v[132:135], v[206:209], v[92:95]
	v_mfma_f32_16x16x32_bf16 v[88:91], v[140:143], v[206:209], v[88:91]
	v_mfma_f32_16x16x32_bf16 v[76:79], v[132:135], v[214:217], v[76:79]
	v_mfma_f32_16x16x32_bf16 v[72:75], v[140:143], v[214:217], v[72:75]
	v_mfma_f32_16x16x32_bf16 v[116:119], v[160:163], v[184:187], v[116:119]
	v_mfma_f32_16x16x32_bf16 v[112:115], v[176:179], v[184:187], v[112:115]
	v_mfma_f32_16x16x32_bf16 v[100:103], v[160:163], v[194:197], v[100:103]
	v_mfma_f32_16x16x32_bf16 v[96:99], v[176:179], v[194:197], v[96:99]
	v_mfma_f32_16x16x32_bf16 v[84:87], v[160:163], v[202:205], v[84:87]
	v_mfma_f32_16x16x32_bf16 v[80:83], v[176:179], v[202:205], v[80:83]
	v_mfma_f32_16x16x32_bf16 v[68:71], v[160:163], v[210:213], v[68:71]
	v_mfma_f32_16x16x32_bf16 v[64:67], v[176:179], v[210:213], v[64:67]
	v_mfma_f32_16x16x32_bf16 v[116:119], v[172:175], v[190:193], v[116:119]
	v_mfma_f32_16x16x32_bf16 v[112:115], v[180:183], v[190:193], v[112:115]
	v_mfma_f32_16x16x32_bf16 v[100:103], v[172:175], v[198:201], v[100:103]
	v_mfma_f32_16x16x32_bf16 v[96:99], v[180:183], v[198:201], v[96:99]
	v_mfma_f32_16x16x32_bf16 v[84:87], v[172:175], v[206:209], v[84:87]
	v_mfma_f32_16x16x32_bf16 v[80:83], v[180:183], v[206:209], v[80:83]
	v_mfma_f32_16x16x32_bf16 v[68:71], v[172:175], v[214:217], v[68:71]
	v_mfma_f32_16x16x32_bf16 v[64:67], v[180:183], v[214:217], v[64:67]
	s_setprio 0
	s_barrier
	s_add_i32 s38, s70, s42
	s_add_i32 m0, s38, 0xffffff80
	ds_read_b128 v[184:187], v171 offset:49152
	ds_read_b128 v[190:193], v171 offset:50176
	ds_read_b128 v[194:197], v171 offset:51200
	ds_read_b128 v[198:201], v171 offset:52224
	ds_read_b128 v[202:205], v171 offset:53248
	ds_read_b128 v[206:209], v171 offset:54272
	ds_read_b128 v[210:213], v171 offset:55296
	ds_read_b128 v[214:217], v171 offset:56320
	global_load_lds_dwordx4 v150, s[100:101] offset:128
	s_add_i32 m0, s38, 0x1f80
	s_add_i32 s38, s71, s42
	global_load_lds_dwordx4 v148, s[100:101] offset:128
	s_add_u32 s100, s100, s4
	s_addc_u32 s101, s101, s5
	s_add_i32 m0, s38, 0xffffff80
	s_nop 0
	global_load_lds_dwordx4 v150, s[100:101] offset:128
	s_add_i32 m0, s38, 0x1f80
	s_nop 0
	global_load_lds_dwordx4 v148, s[100:101] offset:128
	s_add_i32 m0, s51, 0xffffff80
	s_nop 0
	global_load_lds_dwordx4 v144, vcc offset:128
	s_add_i32 m0, s52, 0xffffff80
	s_nop 0
	global_load_lds_dwordx4 v146, vcc offset:128
	s_waitcnt vmcnt(8)
	s_waitcnt lgkmcnt(0)
	s_barrier
	s_setprio 1
	v_mfma_f32_16x16x32_bf16 v[60:63], v[128:131], v[184:187], v[60:63]
	v_mfma_f32_16x16x32_bf16 v[56:59], v[136:139], v[184:187], v[56:59]
	v_mfma_f32_16x16x32_bf16 v[44:47], v[128:131], v[194:197], v[44:47]
	v_mfma_f32_16x16x32_bf16 v[40:43], v[136:139], v[194:197], v[40:43]
	v_mfma_f32_16x16x32_bf16 v[28:31], v[128:131], v[202:205], v[28:31]
	v_mfma_f32_16x16x32_bf16 v[24:27], v[136:139], v[202:205], v[24:27]
	v_mfma_f32_16x16x32_bf16 v[12:15], v[128:131], v[210:213], v[12:15]
	v_mfma_f32_16x16x32_bf16 v[8:11], v[136:139], v[210:213], v[8:11]
	v_mfma_f32_16x16x32_bf16 v[60:63], v[132:135], v[190:193], v[60:63]
	v_mfma_f32_16x16x32_bf16 v[56:59], v[140:143], v[190:193], v[56:59]
	v_mfma_f32_16x16x32_bf16 v[44:47], v[132:135], v[198:201], v[44:47]
	v_mfma_f32_16x16x32_bf16 v[40:43], v[140:143], v[198:201], v[40:43]
	v_mfma_f32_16x16x32_bf16 v[28:31], v[132:135], v[206:209], v[28:31]
	v_mfma_f32_16x16x32_bf16 v[24:27], v[140:143], v[206:209], v[24:27]
	v_mfma_f32_16x16x32_bf16 v[12:15], v[132:135], v[214:217], v[12:15]
	v_mfma_f32_16x16x32_bf16 v[8:11], v[140:143], v[214:217], v[8:11]
	v_mfma_f32_16x16x32_bf16 v[52:55], v[160:163], v[184:187], v[52:55]
	v_mfma_f32_16x16x32_bf16 v[48:51], v[176:179], v[184:187], v[48:51]
	v_mfma_f32_16x16x32_bf16 v[36:39], v[160:163], v[194:197], v[36:39]
	v_mfma_f32_16x16x32_bf16 v[32:35], v[176:179], v[194:197], v[32:35]
	v_mfma_f32_16x16x32_bf16 v[20:23], v[160:163], v[202:205], v[20:23]
	v_mfma_f32_16x16x32_bf16 v[16:19], v[176:179], v[202:205], v[16:19]
	v_mfma_f32_16x16x32_bf16 v[4:7], v[160:163], v[210:213], v[4:7]
	v_mfma_f32_16x16x32_bf16 v[0:3], v[176:179], v[210:213], v[0:3]
	v_mfma_f32_16x16x32_bf16 v[52:55], v[172:175], v[190:193], v[52:55]
	v_mfma_f32_16x16x32_bf16 v[48:51], v[180:183], v[190:193], v[48:51]
	v_mfma_f32_16x16x32_bf16 v[36:39], v[172:175], v[198:201], v[36:39]
	v_mfma_f32_16x16x32_bf16 v[32:35], v[180:183], v[198:201], v[32:35]
	v_mfma_f32_16x16x32_bf16 v[20:23], v[172:175], v[206:209], v[20:23]
	v_mfma_f32_16x16x32_bf16 v[16:19], v[180:183], v[206:209], v[16:19]
	v_mfma_f32_16x16x32_bf16 v[4:7], v[172:175], v[214:217], v[4:7]
	v_mfma_f32_16x16x32_bf16 v[0:3], v[180:183], v[214:217], v[0:3]
	s_setprio 0
	s_barrier
	s_add_u32 s36, s36, 0x100
	s_addc_u32 s37, s37, 0
	s_add_u32 s67, s67, 0x100
	s_addc_u32 s68, s68, 0
	s_cmp_ge_i32 s69, s54
	s_mov_b32 s38, s69
	s_cbranch_scc0 .LBB0_980

; #define PG8_STAGE(bufoff, gbase, voff) do { _Pragma("unroll") for (int _i = 0; _i < 2; ++_i) \
;         __builtin_amdgcn_global_load_lds((const unsigned*)((const char*)(gbase) + (voff)[_i]), (PG8_LAS unsigned*)(lds + (bufoff) + ldsw + _i * 8192), 16, 0, 0); } while (0)
; #define PG8_LDA(dst, b, h) do { _Pragma("unroll") for (int m = 0; m < 4; ++m) _Pragma("unroll") for (int k = 0; k < 2; ++k) dst[m][k] = *(const PG8_LAS bf16x8*)(lds + PG8_SA(b, h) + aoff + m * 2048 + k * 1024); } while (0)
; #define PG8_LDB(dst, b, h) do { _Pragma("unroll") for (int n = 0; n < 2; ++n) _Pragma("unroll") for (int k = 0; k < 2; ++k) dst[n][k] = *(const PG8_LAS bf16x8*)(lds + PG8_SB(b, h) + boff + n * 2048 + k * 1024); } while (0)
; #define PG8_MMA(ai, bj, At, Bt) do { __builtin_amdgcn_s_setprio(1); _Pragma("unroll") for (int m = 0; m < 4; ++m) _Pragma("unroll") for (int n = 0; n < 2; ++n) _Pragma("unroll") for (int k = 0; k < 2; ++k) \
;         acc[ai][bj][m][n] = __builtin_amdgcn_mfma_f32_16x16x32_bf16(Bt[n][k], At[m][k], acc[ai][bj][m][n], 0, 0, 0); __builtin_amdgcn_s_setprio(0); } while (0)
; #define PG8_WAIT_V(n) asm volatile("s_waitcnt vmcnt(" #n ")" ::: "memory")
; #define PG8_WAIT_L(n) asm volatile("s_waitcnt lgkmcnt(" #n ")" ::: "memory")
; template <class Epi, class Sched, bool ALIGN_EPI = false, bool SP2 = false>
; __device__ __forceinline__ void gemm_phase(PG8_LAS unsigned char* lds, const Gemm g, const Sched& S, const Epi& E) {
;     ...
;             const bool last = (t == nt - 2);
;             const char* a1 = cA + (size_t)(t + 1) * kstep;
;             const char* a2 = last ? nA : cA + (size_t)(t + 2) * kstep; const char* b2 = last ? nB : cB + (size_t)(t + 2) * kstep;
;             const char* a3 = a2 + kstep; const char* b3 = b2 + kstep;
;             if (last && has_next) S.a_ready(nxt);
;             if constexpr (SP2) {
;             PG8_LDB(B0, 0, 0); PG8_LDB(B1, 0, 1); PG8_SCHED; PG8_LDA(At, 0, 0); PG8_STAGE(PG8_SA(1, 1), a1 + hstepA, voffA);
;             PG8_WAIT_V(8); PG8_WAIT_L(0); PG8_BAR; PG8_MMA(0, 0, At, B0); PG8_MMA(0, 1, At, B1); PG8_BAR; PG8_SCHED;
;             PG8_LDA(At, 0, 1); PG8_STAGE(PG8_SB(0, 0), b2, voffB); PG8_STAGE(PG8_SB(0, 1), b2 + hstep, voffB); PG8_STAGE(PG8_SA(0, 0), a2, voffA);
;             PG8_WAIT_V(8); PG8_WAIT_L(0); PG8_BAR; PG8_MMA(1, 0, At, B0); PG8_MMA(1, 1, At, B1); PG8_BAR; PG8_SCHED;
.LBB0_1068:
	ds_read_b128 v[152:155], v148
	ds_read_b128 v[156:159], v148 offset:1024
	ds_read_b128 v[160:163], v148 offset:2048
	ds_read_b128 v[164:167], v148 offset:3072
	ds_read_b128 v[168:171], v149
	ds_read_b128 v[172:175], v149 offset:1024
	ds_read_b128 v[176:179], v149 offset:2048
	ds_read_b128 v[180:183], v149 offset:3072
	s_add_i32 s69, s26, 2
	s_add_u32 s27, s24, 0xfff50080
	s_addc_u32 s28, s25, -1
	s_cmp_eq_u32 s51, s26
	s_cselect_b32 s26, s22, s67
	s_cselect_b32 s29, s21, s28
	s_cselect_b32 s28, s20, s27
	s_cselect_b32 s27, s23, s68
	s_add_i32 m0, s42, 0xc000
	ds_read_b128 v[184:187], v150
	ds_read_b128 v[190:193], v150 offset:1024
	ds_read_b128 v[194:197], v150 offset:2048
	ds_read_b128 v[198:201], v150 offset:3072
	ds_read_b128 v[202:205], v150 offset:4096
	ds_read_b128 v[206:209], v150 offset:5120
	ds_read_b128 v[210:213], v150 offset:6144
	ds_read_b128 v[214:217], v150 offset:7168
	global_load_lds_dwordx4 v132, s[24:25]
	s_add_i32 m0, s42, 0xe000
	s_nop 0
	global_load_lds_dwordx4 v136, s[24:25]
	s_waitcnt vmcnt(8)
	s_waitcnt lgkmcnt(0)
	s_barrier
	s_setprio 1
	v_mfma_f32_16x16x32_bf16 v[124:127], v[152:155], v[184:187], v[124:127]
	v_mfma_f32_16x16x32_bf16 v[120:123], v[160:163], v[184:187], v[120:123]
	v_mfma_f32_16x16x32_bf16 v[108:111], v[152:155], v[194:197], v[108:111]
	v_mfma_f32_16x16x32_bf16 v[104:107], v[160:163], v[194:197], v[104:107]
	v_mfma_f32_16x16x32_bf16 v[92:95], v[152:155], v[202:205], v[92:95]
	v_mfma_f32_16x16x32_bf16 v[88:91], v[160:163], v[202:205], v[88:91]
	v_mfma_f32_16x16x32_bf16 v[76:79], v[152:155], v[210:213], v[76:79]
	v_mfma_f32_16x16x32_bf16 v[72:75], v[160:163], v[210:213], v[72:75]
	v_mfma_f32_16x16x32_bf16 v[124:127], v[156:159], v[190:193], v[124:127]
	v_mfma_f32_16x16x32_bf16 v[120:123], v[164:167], v[190:193], v[120:123]
	v_mfma_f32_16x16x32_bf16 v[108:111], v[156:159], v[198:201], v[108:111]
	v_mfma_f32_16x16x32_bf16 v[104:107], v[164:167], v[198:201], v[104:107]
	v_mfma_f32_16x16x32_bf16 v[92:95], v[156:159], v[206:209], v[92:95]
	v_mfma_f32_16x16x32_bf16 v[88:91], v[164:167], v[206:209], v[88:91]
	v_mfma_f32_16x16x32_bf16 v[76:79], v[156:159], v[214:217], v[76:79]
	v_mfma_f32_16x16x32_bf16 v[72:75], v[164:167], v[214:217], v[72:75]
	v_mfma_f32_16x16x32_bf16 v[116:119], v[168:171], v[184:187], v[116:119]
	v_mfma_f32_16x16x32_bf16 v[112:115], v[176:179], v[184:187], v[112:115]
	v_mfma_f32_16x16x32_bf16 v[100:103], v[168:171], v[194:197], v[100:103]
	v_mfma_f32_16x16x32_bf16 v[96:99], v[176:179], v[194:197], v[96:99]
	v_mfma_f32_16x16x32_bf16 v[84:87], v[168:171], v[202:205], v[84:87]
	v_mfma_f32_16x16x32_bf16 v[80:83], v[176:179], v[202:205], v[80:83]
	v_mfma_f32_16x16x32_bf16 v[68:71], v[168:171], v[210:213], v[68:71]
	v_mfma_f32_16x16x32_bf16 v[64:67], v[176:179], v[210:213], v[64:67]
	v_mfma_f32_16x16x32_bf16 v[116:119], v[172:175], v[190:193], v[116:119]
	v_mfma_f32_16x16x32_bf16 v[112:115], v[180:183], v[190:193], v[112:115]
	v_mfma_f32_16x16x32_bf16 v[100:103], v[172:175], v[198:201], v[100:103]
	v_mfma_f32_16x16x32_bf16 v[96:99], v[180:183], v[198:201], v[96:99]
	v_mfma_f32_16x16x32_bf16 v[84:87], v[172:175], v[206:209], v[84:87]
	v_mfma_f32_16x16x32_bf16 v[80:83], v[180:183], v[206:209], v[80:83]
	v_mfma_f32_16x16x32_bf16 v[68:71], v[172:175], v[214:217], v[68:71]
	v_mfma_f32_16x16x32_bf16 v[64:67], v[180:183], v[214:217], v[64:67]
	s_setprio 0
	s_barrier
	s_add_i32 s70, s54, s41
	s_mov_b32 m0, s70
	ds_read_b128 v[184:187], v150 offset:16384
	ds_read_b128 v[190:193], v150 offset:17408
	ds_read_b128 v[194:197], v150 offset:18432
	ds_read_b128 v[198:201], v150 offset:19456
	ds_read_b128 v[202:205], v150 offset:20480
	ds_read_b128 v[206:209], v150 offset:21504
	ds_read_b128 v[210:213], v150 offset:22528
	ds_read_b128 v[214:217], v150 offset:23552
	global_load_lds_dwordx4 v128, s[26:27]
	s_add_i32 m0, s70, 0x2000
	s_add_u32 s70, s26, 0xb0000
	s_addc_u32 s71, s27, 0
	s_add_i32 s72, s55, s41
	global_load_lds_dwordx4 v130, s[26:27]
	s_mov_b32 m0, s72
	s_nop 0
	global_load_lds_dwordx4 v128, s[70:71]
	s_add_i32 m0, s72, 0x2000
	s_nop 0
	global_load_lds_dwordx4 v130, s[70:71]
	s_mov_b32 m0, s42
	s_nop 0
	global_load_lds_dwordx4 v128, s[28:29]
	s_mov_b32 m0, s43
	s_nop 0
	global_load_lds_dwordx4 v130, s[28:29]
	s_waitcnt vmcnt(8)
	s_waitcnt lgkmcnt(0)
	s_barrier
	s_setprio 1
	v_mfma_f32_16x16x32_bf16 v[60:63], v[152:155], v[184:187], v[60:63]
	v_mfma_f32_16x16x32_bf16 v[56:59], v[160:163], v[184:187], v[56:59]
	v_mfma_f32_16x16x32_bf16 v[44:47], v[152:155], v[194:197], v[44:47]
	v_mfma_f32_16x16x32_bf16 v[40:43], v[160:163], v[194:197], v[40:43]
	v_mfma_f32_16x16x32_bf16 v[28:31], v[152:155], v[202:205], v[28:31]
	v_mfma_f32_16x16x32_bf16 v[24:27], v[160:163], v[202:205], v[24:27]
	v_mfma_f32_16x16x32_bf16 v[12:15], v[152:155], v[210:213], v[12:15]
	v_mfma_f32_16x16x32_bf16 v[8:11], v[160:163], v[210:213], v[8:11]
	v_mfma_f32_16x16x32_bf16 v[60:63], v[156:159], v[190:193], v[60:63]
	v_mfma_f32_16x16x32_bf16 v[56:59], v[164:167], v[190:193], v[56:59]
	v_mfma_f32_16x16x32_bf16 v[44:47], v[156:159], v[198:201], v[44:47]
	v_mfma_f32_16x16x32_bf16 v[40:43], v[164:167], v[198:201], v[40:43]
	v_mfma_f32_16x16x32_bf16 v[28:31], v[156:159], v[206:209], v[28:31]
	v_mfma_f32_16x16x32_bf16 v[24:27], v[164:167], v[206:209], v[24:27]
	v_mfma_f32_16x16x32_bf16 v[12:15], v[156:159], v[214:217], v[12:15]
	v_mfma_f32_16x16x32_bf16 v[8:11], v[164:167], v[214:217], v[8:11]
	v_mfma_f32_16x16x32_bf16 v[52:55], v[168:171], v[184:187], v[52:55]
	v_mfma_f32_16x16x32_bf16 v[48:51], v[176:179], v[184:187], v[48:51]
	v_mfma_f32_16x16x32_bf16 v[36:39], v[168:171], v[194:197], v[36:39]
	v_mfma_f32_16x16x32_bf16 v[32:35], v[176:179], v[194:197], v[32:35]
	v_mfma_f32_16x16x32_bf16 v[20:23], v[168:171], v[202:205], v[20:23]
	v_mfma_f32_16x16x32_bf16 v[16:19], v[176:179], v[202:205], v[16:19]
	v_mfma_f32_16x16x32_bf16 v[4:7], v[168:171], v[210:213], v[4:7]
	v_mfma_f32_16x16x32_bf16 v[0:3], v[176:179], v[210:213], v[0:3]
	v_mfma_f32_16x16x32_bf16 v[52:55], v[172:175], v[190:193], v[52:55]
	v_mfma_f32_16x16x32_bf16 v[48:51], v[180:183], v[190:193], v[48:51]
	v_mfma_f32_16x16x32_bf16 v[36:39], v[172:175], v[198:201], v[36:39]
	v_mfma_f32_16x16x32_bf16 v[32:35], v[180:183], v[198:201], v[32:35]
	v_mfma_f32_16x16x32_bf16 v[20:23], v[172:175], v[206:209], v[20:23]
	v_mfma_f32_16x16x32_bf16 v[16:19], v[180:183], v[206:209], v[16:19]
	v_mfma_f32_16x16x32_bf16 v[4:7], v[172:175], v[214:217], v[4:7]
	v_mfma_f32_16x16x32_bf16 v[0:3], v[180:183], v[214:217], v[0:3]
	s_setprio 0
	s_barrier
; #define PG8_STAGE(bufoff, gbase, voff) do { _Pragma("unroll") for (int _i = 0; _i < 2; ++_i) \
;         __builtin_amdgcn_global_load_lds((const unsigned*)((const char*)(gbase) + (voff)[_i]), (PG8_LAS unsigned*)(lds + (bufoff) + ldsw + _i * 8192), 16, 0, 0); } while (0)
; #define PG8_LDA(dst, b, h) do { _Pragma("unroll") for (int m = 0; m < 4; ++m) _Pragma("unroll") for (int k = 0; k < 2; ++k) dst[m][k] = *(const PG8_LAS bf16x8*)(lds + PG8_SA(b, h) + aoff + m * 2048 + k * 1024); } while (0)
; #define PG8_LDB(dst, b, h) do { _Pragma("unroll") for (int n = 0; n < 2; ++n) _Pragma("unroll") for (int k = 0; k < 2; ++k) dst[n][k] = *(const PG8_LAS bf16x8*)(lds + PG8_SB(b, h) + boff + n * 2048 + k * 1024); } while (0)
; #define PG8_MMA(ai, bj, At, Bt) do { __builtin_amdgcn_s_setprio(1); _Pragma("unroll") for (int m = 0; m < 4; ++m) _Pragma("unroll") for (int n = 0; n < 2; ++n) _Pragma("unroll") for (int k = 0; k < 2; ++k) \
;         acc[ai][bj][m][n] = __builtin_amdgcn_mfma_f32_16x16x32_bf16(Bt[n][k], At[m][k], acc[ai][bj][m][n], 0, 0, 0); __builtin_amdgcn_s_setprio(0); } while (0)
; #define PG8_WAIT_V(n) asm volatile("s_waitcnt vmcnt(" #n ")" ::: "memory")
; #define PG8_WAIT_L(n) asm volatile("s_waitcnt lgkmcnt(" #n ")" ::: "memory")
; #define PG8_BAR __builtin_amdgcn_s_barrier()
; #define PG8_SCHED __builtin_amdgcn_sched_barrier(0)
; template <class Epi, class Sched, bool ALIGN_EPI = false, bool SP2 = false>
; __device__ __forceinline__ void gemm_phase(PG8_LAS unsigned char* lds, const Gemm g, const Sched& S, const Epi& E) {
;     ...
;             PG8_LDB(B0, 1, 0); PG8_LDB(B1, 1, 1); PG8_SCHED; PG8_LDA(At, 1, 0); PG8_STAGE(PG8_SA(0, 1), a2 + hstepA, voffA);
;             PG8_WAIT_V(8); PG8_WAIT_L(0); PG8_BAR; PG8_MMA(0, 0, At, B0); PG8_MMA(0, 1, At, B1); PG8_BAR; PG8_SCHED;
;             PG8_LDA(At, 1, 1); PG8_STAGE(PG8_SB(1, 0), b3, voffB); PG8_STAGE(PG8_SB(1, 1), b3 + hstep, voffB); PG8_STAGE(PG8_SA(1, 0), a3, voffA);
;             PG8_WAIT_V(8); PG8_WAIT_L(0); PG8_BAR; PG8_MMA(1, 0, At, B0); PG8_MMA(1, 1, At, B1); PG8_BAR; PG8_SCHED;
	s_add_i32 s70, 0, 0x18000
	v_add_u32_e32 v151, s70, v147
	s_add_i32 s71, 0, 0x1c000
	ds_read_b128 v[152:155], v151
	ds_read_b128 v[156:159], v151 offset:1024
	ds_read_b128 v[160:163], v151 offset:2048
	ds_read_b128 v[164:167], v151 offset:3072
	v_add_u32_e32 v151, s71, v147
	ds_read_b128 v[168:171], v151
	ds_read_b128 v[172:175], v151 offset:1024
	ds_read_b128 v[176:179], v151 offset:2048
	ds_read_b128 v[180:183], v151 offset:3072
	s_mov_b64 vcc, s[28:29]
	s_add_u32 s28, s28, 0xb0000
	s_addc_u32 s29, s29, 0
	s_mov_b32 m0, s44
	ds_read_b128 v[184:187], v150 offset:32768
	ds_read_b128 v[190:193], v150 offset:33792
	ds_read_b128 v[194:197], v150 offset:34816
	ds_read_b128 v[198:201], v150 offset:35840
	ds_read_b128 v[202:205], v150 offset:36864
	ds_read_b128 v[206:209], v150 offset:37888
	ds_read_b128 v[210:213], v150 offset:38912
	ds_read_b128 v[214:217], v150 offset:39936
	global_load_lds_dwordx4 v128, s[28:29]
	s_mov_b32 m0, s45
	s_nop 0
	global_load_lds_dwordx4 v130, s[28:29]
	s_waitcnt vmcnt(8)
	s_waitcnt lgkmcnt(0)
	s_barrier
	s_setprio 1
	v_mfma_f32_16x16x32_bf16 v[124:127], v[152:155], v[184:187], v[124:127]
	v_mfma_f32_16x16x32_bf16 v[120:123], v[160:163], v[184:187], v[120:123]
	v_mfma_f32_16x16x32_bf16 v[108:111], v[152:155], v[194:197], v[108:111]
	v_mfma_f32_16x16x32_bf16 v[104:107], v[160:163], v[194:197], v[104:107]
	v_mfma_f32_16x16x32_bf16 v[92:95], v[152:155], v[202:205], v[92:95]
	v_mfma_f32_16x16x32_bf16 v[88:91], v[160:163], v[202:205], v[88:91]
	v_mfma_f32_16x16x32_bf16 v[76:79], v[152:155], v[210:213], v[76:79]
	v_mfma_f32_16x16x32_bf16 v[72:75], v[160:163], v[210:213], v[72:75]
	v_mfma_f32_16x16x32_bf16 v[124:127], v[156:159], v[190:193], v[124:127]
	v_mfma_f32_16x16x32_bf16 v[120:123], v[164:167], v[190:193], v[120:123]
	v_mfma_f32_16x16x32_bf16 v[108:111], v[156:159], v[198:201], v[108:111]
	v_mfma_f32_16x16x32_bf16 v[104:107], v[164:167], v[198:201], v[104:107]
	v_mfma_f32_16x16x32_bf16 v[92:95], v[156:159], v[206:209], v[92:95]
	v_mfma_f32_16x16x32_bf16 v[88:91], v[164:167], v[206:209], v[88:91]
	v_mfma_f32_16x16x32_bf16 v[76:79], v[156:159], v[214:217], v[76:79]
	v_mfma_f32_16x16x32_bf16 v[72:75], v[164:167], v[214:217], v[72:75]
	v_mfma_f32_16x16x32_bf16 v[116:119], v[168:171], v[184:187], v[116:119]
	v_mfma_f32_16x16x32_bf16 v[112:115], v[176:179], v[184:187], v[112:115]
	v_mfma_f32_16x16x32_bf16 v[100:103], v[168:171], v[194:197], v[100:103]
	v_mfma_f32_16x16x32_bf16 v[96:99], v[176:179], v[194:197], v[96:99]
	v_mfma_f32_16x16x32_bf16 v[84:87], v[168:171], v[202:205], v[84:87]
	v_mfma_f32_16x16x32_bf16 v[80:83], v[176:179], v[202:205], v[80:83]
	v_mfma_f32_16x16x32_bf16 v[68:71], v[168:171], v[210:213], v[68:71]
	v_mfma_f32_16x16x32_bf16 v[64:67], v[176:179], v[210:213], v[64:67]
	v_mfma_f32_16x16x32_bf16 v[116:119], v[172:175], v[190:193], v[116:119]
	v_mfma_f32_16x16x32_bf16 v[112:115], v[180:183], v[190:193], v[112:115]
	v_mfma_f32_16x16x32_bf16 v[100:103], v[172:175], v[198:201], v[100:103]
	v_mfma_f32_16x16x32_bf16 v[96:99], v[180:183], v[198:201], v[96:99]
	v_mfma_f32_16x16x32_bf16 v[84:87], v[172:175], v[206:209], v[84:87]
	v_mfma_f32_16x16x32_bf16 v[80:83], v[180:183], v[206:209], v[80:83]
	v_mfma_f32_16x16x32_bf16 v[68:71], v[172:175], v[214:217], v[68:71]
	v_mfma_f32_16x16x32_bf16 v[64:67], v[180:183], v[214:217], v[64:67]
	s_setprio 0
	s_barrier
	s_add_i32 s28, s70, s41
	s_add_i32 m0, s28, 0xffffff80
	ds_read_b128 v[184:187], v150 offset:49152
	ds_read_b128 v[190:193], v150 offset:50176
	ds_read_b128 v[194:197], v150 offset:51200
	ds_read_b128 v[198:201], v150 offset:52224
	ds_read_b128 v[202:205], v150 offset:53248
	ds_read_b128 v[206:209], v150 offset:54272
	ds_read_b128 v[210:213], v150 offset:55296
	ds_read_b128 v[214:217], v150 offset:56320
	global_load_lds_dwordx4 v128, s[26:27] offset:128
	s_add_i32 m0, s28, 0x1f80
	s_mov_b64 s[100:101], s[26:27]
	s_add_u32 s26, s26, 0xb0080
	s_addc_u32 s27, s27, 0
	s_add_i32 s28, s71, s41
	global_load_lds_dwordx4 v130, s[100:101] offset:128
	s_mov_b32 m0, s28
	s_nop 0
	global_load_lds_dwordx4 v128, s[26:27]
	s_add_i32 m0, s28, 0x2000
	s_nop 0
	global_load_lds_dwordx4 v130, s[26:27]
	s_add_i32 m0, s49, 0xffffff80
	s_nop 0
	global_load_lds_dwordx4 v128, vcc offset:128
	s_add_i32 m0, s50, 0xffffff80
	s_nop 0
	global_load_lds_dwordx4 v130, vcc offset:128
	s_waitcnt vmcnt(8)
	s_waitcnt lgkmcnt(0)
	s_barrier
	s_setprio 1
	v_mfma_f32_16x16x32_bf16 v[60:63], v[152:155], v[184:187], v[60:63]
	v_mfma_f32_16x16x32_bf16 v[56:59], v[160:163], v[184:187], v[56:59]
	v_mfma_f32_16x16x32_bf16 v[44:47], v[152:155], v[194:197], v[44:47]
	v_mfma_f32_16x16x32_bf16 v[40:43], v[160:163], v[194:197], v[40:43]
	v_mfma_f32_16x16x32_bf16 v[28:31], v[152:155], v[202:205], v[28:31]
	v_mfma_f32_16x16x32_bf16 v[24:27], v[160:163], v[202:205], v[24:27]
	v_mfma_f32_16x16x32_bf16 v[12:15], v[152:155], v[210:213], v[12:15]
	v_mfma_f32_16x16x32_bf16 v[8:11], v[160:163], v[210:213], v[8:11]
	v_mfma_f32_16x16x32_bf16 v[60:63], v[156:159], v[190:193], v[60:63]
	v_mfma_f32_16x16x32_bf16 v[56:59], v[164:167], v[190:193], v[56:59]
	v_mfma_f32_16x16x32_bf16 v[44:47], v[156:159], v[198:201], v[44:47]
	v_mfma_f32_16x16x32_bf16 v[40:43], v[164:167], v[198:201], v[40:43]
	v_mfma_f32_16x16x32_bf16 v[28:31], v[156:159], v[206:209], v[28:31]
	v_mfma_f32_16x16x32_bf16 v[24:27], v[164:167], v[206:209], v[24:27]
	v_mfma_f32_16x16x32_bf16 v[12:15], v[156:159], v[214:217], v[12:15]
	v_mfma_f32_16x16x32_bf16 v[8:11], v[164:167], v[214:217], v[8:11]
	v_mfma_f32_16x16x32_bf16 v[52:55], v[168:171], v[184:187], v[52:55]
	v_mfma_f32_16x16x32_bf16 v[48:51], v[176:179], v[184:187], v[48:51]
	v_mfma_f32_16x16x32_bf16 v[36:39], v[168:171], v[194:197], v[36:39]
	v_mfma_f32_16x16x32_bf16 v[32:35], v[176:179], v[194:197], v[32:35]
	v_mfma_f32_16x16x32_bf16 v[20:23], v[168:171], v[202:205], v[20:23]
	v_mfma_f32_16x16x32_bf16 v[16:19], v[176:179], v[202:205], v[16:19]
	v_mfma_f32_16x16x32_bf16 v[4:7], v[168:171], v[210:213], v[4:7]
	v_mfma_f32_16x16x32_bf16 v[0:3], v[176:179], v[210:213], v[0:3]
	v_mfma_f32_16x16x32_bf16 v[52:55], v[172:175], v[190:193], v[52:55]
	v_mfma_f32_16x16x32_bf16 v[48:51], v[180:183], v[190:193], v[48:51]
	v_mfma_f32_16x16x32_bf16 v[36:39], v[172:175], v[198:201], v[36:39]
	v_mfma_f32_16x16x32_bf16 v[32:35], v[180:183], v[198:201], v[32:35]
	v_mfma_f32_16x16x32_bf16 v[20:23], v[172:175], v[206:209], v[20:23]
	v_mfma_f32_16x16x32_bf16 v[16:19], v[180:183], v[206:209], v[16:19]
	v_mfma_f32_16x16x32_bf16 v[4:7], v[172:175], v[214:217], v[4:7]
	v_mfma_f32_16x16x32_bf16 v[0:3], v[180:183], v[214:217], v[0:3]
	s_setprio 0
	s_barrier
	s_add_u32 s24, s24, 0x100
	s_addc_u32 s25, s25, 0
	s_add_u32 s67, s67, 0x100
	s_addc_u32 s68, s68, 0
	s_cmp_ge_i32 s69, s48
	s_mov_b32 s26, s69
	s_cbranch_scc0 .LBB0_1068

; #define PG8_STAGE(bufoff, gbase, voff) do { _Pragma("unroll") for (int _i = 0; _i < 2; ++_i) \
;         __builtin_amdgcn_global_load_lds((const unsigned*)((const char*)(gbase) + (voff)[_i]), (PG8_LAS unsigned*)(lds + (bufoff) + ldsw + _i * 8192), 16, 0, 0); } while (0)
; #define PG8_LDA(dst, b, h) do { _Pragma("unroll") for (int m = 0; m < 4; ++m) _Pragma("unroll") for (int k = 0; k < 2; ++k) dst[m][k] = *(const PG8_LAS bf16x8*)(lds + PG8_SA(b, h) + aoff + m * 2048 + k * 1024); } while (0)
; #define PG8_LDB(dst, b, h) do { _Pragma("unroll") for (int n = 0; n < 2; ++n) _Pragma("unroll") for (int k = 0; k < 2; ++k) dst[n][k] = *(const PG8_LAS bf16x8*)(lds + PG8_SB(b, h) + boff + n * 2048 + k * 1024); } while (0)
; #define PG8_MMA(ai, bj, At, Bt) do { __builtin_amdgcn_s_setprio(1); _Pragma("unroll") for (int m = 0; m < 4; ++m) _Pragma("unroll") for (int n = 0; n < 2; ++n) _Pragma("unroll") for (int k = 0; k < 2; ++k) \
;         acc[ai][bj][m][n] = __builtin_amdgcn_mfma_f32_16x16x32_bf16(Bt[n][k], At[m][k], acc[ai][bj][m][n], 0, 0, 0); __builtin_amdgcn_s_setprio(0); } while (0)
; #define PG8_WAIT_V(n) asm volatile("s_waitcnt vmcnt(" #n ")" ::: "memory")
; #define PG8_WAIT_L(n) asm volatile("s_waitcnt lgkmcnt(" #n ")" ::: "memory")
; template <class Epi, class Sched, bool ALIGN_EPI = false, bool SP2 = false>
; __device__ __forceinline__ void gemm_phase(PG8_LAS unsigned char* lds, const Gemm g, const Sched& S, const Epi& E) {
;     ...
;             const bool last = (t == nt - 2);
;             const char* a1 = cA + (size_t)(t + 1) * kstep;
;             const char* a2 = last ? nA : cA + (size_t)(t + 2) * kstep; const char* b2 = last ? nB : cB + (size_t)(t + 2) * kstep;
;             const char* a3 = a2 + kstep; const char* b3 = b2 + kstep;
;             if (last && has_next) S.a_ready(nxt);
;             if constexpr (SP2) {
;             PG8_LDB(B0, 0, 0); PG8_LDB(B1, 0, 1); PG8_SCHED; PG8_LDA(At, 0, 0); PG8_STAGE(PG8_SA(1, 1), a1 + hstepA, voffA);
;             PG8_WAIT_V(8); PG8_WAIT_L(0); PG8_BAR; PG8_MMA(0, 0, At, B0); PG8_MMA(0, 1, At, B1); PG8_BAR; PG8_SCHED;
;             PG8_LDA(At, 0, 1); PG8_STAGE(PG8_SB(0, 0), b2, voffB); PG8_STAGE(PG8_SB(0, 1), b2 + hstep, voffB); PG8_STAGE(PG8_SA(0, 0), a2, voffA);
;             PG8_WAIT_V(8); PG8_WAIT_L(0); PG8_BAR; PG8_MMA(1, 0, At, B0); PG8_MMA(1, 1, At, B1); PG8_BAR; PG8_SCHED;
.LBB0_1236:
	ds_read_b128 v[150:153], v147
	ds_read_b128 v[154:157], v147 offset:1024
	ds_read_b128 v[158:161], v147 offset:2048
	ds_read_b128 v[162:165], v147 offset:3072
	ds_read_b128 v[166:169], v148
	ds_read_b128 v[170:173], v148 offset:1024
	ds_read_b128 v[174:177], v148 offset:2048
	ds_read_b128 v[178:181], v148 offset:3072
	s_add_i32 s68, s40, 2
	s_add_u32 s69, s8, 0xfffc0080
	s_addc_u32 s41, s9, -1
	s_cmp_eq_u32 s59, s40
	s_cselect_b32 s40, s67, s69
	s_cselect_b32 s41, s35, s41
	s_cselect_b32 s71, s37, s43
	s_cselect_b32 s70, s36, s42
	s_add_i32 m0, s31, 0xc000
	ds_read_b128 v[182:185], v149
	ds_read_b128 v[190:193], v149 offset:1024
	ds_read_b128 v[194:197], v149 offset:2048
	ds_read_b128 v[198:201], v149 offset:3072
	ds_read_b128 v[202:205], v149 offset:4096
	ds_read_b128 v[206:209], v149 offset:5120
	ds_read_b128 v[210:213], v149 offset:6144
	ds_read_b128 v[214:217], v149 offset:7168
	global_load_lds_dwordx4 v136, s[8:9]
	s_add_i32 m0, s31, 0xe000
	s_nop 0
	global_load_lds_dwordx4 v138, s[8:9]
	s_waitcnt vmcnt(8)
	s_waitcnt lgkmcnt(0)
	s_barrier
	s_setprio 1
	v_mfma_f32_16x16x32_bf16 v[120:123], v[150:153], v[182:185], v[120:123]
	v_mfma_f32_16x16x32_bf16 v[124:127], v[158:161], v[182:185], v[124:127]
	v_mfma_f32_16x16x32_bf16 v[108:111], v[150:153], v[194:197], v[108:111]
	v_mfma_f32_16x16x32_bf16 v[104:107], v[158:161], v[194:197], v[104:107]
	v_mfma_f32_16x16x32_bf16 v[92:95], v[150:153], v[202:205], v[92:95]
	v_mfma_f32_16x16x32_bf16 v[88:91], v[158:161], v[202:205], v[88:91]
	v_mfma_f32_16x16x32_bf16 v[76:79], v[150:153], v[210:213], v[76:79]
	v_mfma_f32_16x16x32_bf16 v[72:75], v[158:161], v[210:213], v[72:75]
	v_mfma_f32_16x16x32_bf16 v[120:123], v[154:157], v[190:193], v[120:123]
	v_mfma_f32_16x16x32_bf16 v[124:127], v[162:165], v[190:193], v[124:127]
	v_mfma_f32_16x16x32_bf16 v[108:111], v[154:157], v[198:201], v[108:111]
	v_mfma_f32_16x16x32_bf16 v[104:107], v[162:165], v[198:201], v[104:107]
	v_mfma_f32_16x16x32_bf16 v[92:95], v[154:157], v[206:209], v[92:95]
	v_mfma_f32_16x16x32_bf16 v[88:91], v[162:165], v[206:209], v[88:91]
	v_mfma_f32_16x16x32_bf16 v[76:79], v[154:157], v[214:217], v[76:79]
	v_mfma_f32_16x16x32_bf16 v[72:75], v[162:165], v[214:217], v[72:75]
	v_mfma_f32_16x16x32_bf16 v[116:119], v[166:169], v[182:185], v[116:119]
	v_mfma_f32_16x16x32_bf16 v[112:115], v[174:177], v[182:185], v[112:115]
	v_mfma_f32_16x16x32_bf16 v[100:103], v[166:169], v[194:197], v[100:103]
	v_mfma_f32_16x16x32_bf16 v[96:99], v[174:177], v[194:197], v[96:99]
	v_mfma_f32_16x16x32_bf16 v[84:87], v[166:169], v[202:205], v[84:87]
	v_mfma_f32_16x16x32_bf16 v[80:83], v[174:177], v[202:205], v[80:83]
	v_mfma_f32_16x16x32_bf16 v[68:71], v[166:169], v[210:213], v[68:71]
	v_mfma_f32_16x16x32_bf16 v[64:67], v[174:177], v[210:213], v[64:67]
	v_mfma_f32_16x16x32_bf16 v[116:119], v[170:173], v[190:193], v[116:119]
	v_mfma_f32_16x16x32_bf16 v[112:115], v[178:181], v[190:193], v[112:115]
	v_mfma_f32_16x16x32_bf16 v[100:103], v[170:173], v[198:201], v[100:103]
	v_mfma_f32_16x16x32_bf16 v[96:99], v[178:181], v[198:201], v[96:99]
	v_mfma_f32_16x16x32_bf16 v[84:87], v[170:173], v[206:209], v[84:87]
	v_mfma_f32_16x16x32_bf16 v[80:83], v[178:181], v[206:209], v[80:83]
	v_mfma_f32_16x16x32_bf16 v[68:71], v[170:173], v[214:217], v[68:71]
	v_mfma_f32_16x16x32_bf16 v[64:67], v[178:181], v[214:217], v[64:67]
	s_setprio 0
	s_barrier
	s_add_i32 s69, s60, s47
	s_mov_b32 m0, s69
	ds_read_b128 v[182:185], v149 offset:16384
	ds_read_b128 v[190:193], v149 offset:17408
	ds_read_b128 v[194:197], v149 offset:18432
	ds_read_b128 v[198:201], v149 offset:19456
	ds_read_b128 v[202:205], v149 offset:20480
	ds_read_b128 v[206:209], v149 offset:21504
	ds_read_b128 v[210:213], v149 offset:22528
	ds_read_b128 v[214:217], v149 offset:23552
	global_load_lds_dwordx4 v134, s[70:71]
	s_add_i32 m0, s69, 0x2000
	s_mov_b64 s[100:101], s[70:71]
	s_add_i32 s69, s61, s47
	global_load_lds_dwordx4 v132, s[70:71]
	s_add_u32 s70, s70, s4
	s_addc_u32 s71, s71, s5
	s_mov_b32 m0, s69
	s_nop 0
	global_load_lds_dwordx4 v134, s[70:71]
	s_add_i32 m0, s69, 0x2000
	s_nop 0
	global_load_lds_dwordx4 v132, s[70:71]
	s_mov_b32 m0, s31
	s_nop 0
	global_load_lds_dwordx4 v128, s[40:41]
	s_mov_b32 m0, s50
	s_nop 0
	global_load_lds_dwordx4 v130, s[40:41]
	s_waitcnt vmcnt(8)
	s_waitcnt lgkmcnt(0)
	s_barrier
	s_setprio 1
	v_mfma_f32_16x16x32_bf16 v[60:63], v[150:153], v[182:185], v[60:63]
	v_mfma_f32_16x16x32_bf16 v[56:59], v[158:161], v[182:185], v[56:59]
	v_mfma_f32_16x16x32_bf16 v[44:47], v[150:153], v[194:197], v[44:47]
	v_mfma_f32_16x16x32_bf16 v[40:43], v[158:161], v[194:197], v[40:43]
	v_mfma_f32_16x16x32_bf16 v[28:31], v[150:153], v[202:205], v[28:31]
	v_mfma_f32_16x16x32_bf16 v[24:27], v[158:161], v[202:205], v[24:27]
	v_mfma_f32_16x16x32_bf16 v[12:15], v[150:153], v[210:213], v[12:15]
	v_mfma_f32_16x16x32_bf16 v[8:11], v[158:161], v[210:213], v[8:11]
	v_mfma_f32_16x16x32_bf16 v[60:63], v[154:157], v[190:193], v[60:63]
	v_mfma_f32_16x16x32_bf16 v[56:59], v[162:165], v[190:193], v[56:59]
	v_mfma_f32_16x16x32_bf16 v[44:47], v[154:157], v[198:201], v[44:47]
	v_mfma_f32_16x16x32_bf16 v[40:43], v[162:165], v[198:201], v[40:43]
	v_mfma_f32_16x16x32_bf16 v[28:31], v[154:157], v[206:209], v[28:31]
	v_mfma_f32_16x16x32_bf16 v[24:27], v[162:165], v[206:209], v[24:27]
	v_mfma_f32_16x16x32_bf16 v[12:15], v[154:157], v[214:217], v[12:15]
	v_mfma_f32_16x16x32_bf16 v[8:11], v[162:165], v[214:217], v[8:11]
	v_mfma_f32_16x16x32_bf16 v[52:55], v[166:169], v[182:185], v[52:55]
	v_mfma_f32_16x16x32_bf16 v[48:51], v[174:177], v[182:185], v[48:51]
	v_mfma_f32_16x16x32_bf16 v[36:39], v[166:169], v[194:197], v[36:39]
	v_mfma_f32_16x16x32_bf16 v[32:35], v[174:177], v[194:197], v[32:35]
	v_mfma_f32_16x16x32_bf16 v[20:23], v[166:169], v[202:205], v[20:23]
	v_mfma_f32_16x16x32_bf16 v[16:19], v[174:177], v[202:205], v[16:19]
	v_mfma_f32_16x16x32_bf16 v[4:7], v[166:169], v[210:213], v[4:7]
	v_mfma_f32_16x16x32_bf16 v[0:3], v[174:177], v[210:213], v[0:3]
	v_mfma_f32_16x16x32_bf16 v[52:55], v[170:173], v[190:193], v[52:55]
	v_mfma_f32_16x16x32_bf16 v[48:51], v[178:181], v[190:193], v[48:51]
	v_mfma_f32_16x16x32_bf16 v[36:39], v[170:173], v[198:201], v[36:39]
	v_mfma_f32_16x16x32_bf16 v[32:35], v[178:181], v[198:201], v[32:35]
	v_mfma_f32_16x16x32_bf16 v[20:23], v[170:173], v[206:209], v[20:23]
	v_mfma_f32_16x16x32_bf16 v[16:19], v[178:181], v[206:209], v[16:19]
	v_mfma_f32_16x16x32_bf16 v[4:7], v[170:173], v[214:217], v[4:7]
	v_mfma_f32_16x16x32_bf16 v[0:3], v[178:181], v[214:217], v[0:3]
	s_setprio 0
	s_barrier
; #define PG8_STAGE(bufoff, gbase, voff) do { _Pragma("unroll") for (int _i = 0; _i < 2; ++_i) \
;         __builtin_amdgcn_global_load_lds((const unsigned*)((const char*)(gbase) + (voff)[_i]), (PG8_LAS unsigned*)(lds + (bufoff) + ldsw + _i * 8192), 16, 0, 0); } while (0)
; #define PG8_LDA(dst, b, h) do { _Pragma("unroll") for (int m = 0; m < 4; ++m) _Pragma("unroll") for (int k = 0; k < 2; ++k) dst[m][k] = *(const PG8_LAS bf16x8*)(lds + PG8_SA(b, h) + aoff + m * 2048 + k * 1024); } while (0)
; #define PG8_LDB(dst, b, h) do { _Pragma("unroll") for (int n = 0; n < 2; ++n) _Pragma("unroll") for (int k = 0; k < 2; ++k) dst[n][k] = *(const PG8_LAS bf16x8*)(lds + PG8_SB(b, h) + boff + n * 2048 + k * 1024); } while (0)
; #define PG8_MMA(ai, bj, At, Bt) do { __builtin_amdgcn_s_setprio(1); _Pragma("unroll") for (int m = 0; m < 4; ++m) _Pragma("unroll") for (int n = 0; n < 2; ++n) _Pragma("unroll") for (int k = 0; k < 2; ++k) \
;         acc[ai][bj][m][n] = __builtin_amdgcn_mfma_f32_16x16x32_bf16(Bt[n][k], At[m][k], acc[ai][bj][m][n], 0, 0, 0); __builtin_amdgcn_s_setprio(0); } while (0)
; #define PG8_WAIT_V(n) asm volatile("s_waitcnt vmcnt(" #n ")" ::: "memory")
; #define PG8_WAIT_L(n) asm volatile("s_waitcnt lgkmcnt(" #n ")" ::: "memory")
; #define PG8_BAR __builtin_amdgcn_s_barrier()
; #define PG8_SCHED __builtin_amdgcn_sched_barrier(0)
; template <class Epi, class Sched, bool ALIGN_EPI = false, bool SP2 = false>
; __device__ __forceinline__ void gemm_phase(PG8_LAS unsigned char* lds, const Gemm g, const Sched& S, const Epi& E) {
;     ...
;             PG8_LDB(B0, 1, 0); PG8_LDB(B1, 1, 1); PG8_SCHED; PG8_LDA(At, 1, 0); PG8_STAGE(PG8_SA(0, 1), a2 + hstepA, voffA);
;             PG8_WAIT_V(8); PG8_WAIT_L(0); PG8_BAR; PG8_MMA(0, 0, At, B0); PG8_MMA(0, 1, At, B1); PG8_BAR; PG8_SCHED;
;             PG8_LDA(At, 1, 1); PG8_STAGE(PG8_SB(1, 0), b3, voffB); PG8_STAGE(PG8_SB(1, 1), b3 + hstep, voffB); PG8_STAGE(PG8_SA(1, 0), a3, voffA);
;             PG8_WAIT_V(8); PG8_WAIT_L(0); PG8_BAR; PG8_MMA(1, 0, At, B0); PG8_MMA(1, 1, At, B1); PG8_BAR; PG8_SCHED;
	s_add_i32 s69, 0, 0x18000
	s_add_i32 s70, 0, 0x1c000
	v_add_u32_e32 v162, s69, v145
	v_add_u32_e32 v178, s70, v145
	ds_read_b128 v[150:153], v162
	ds_read_b128 v[154:157], v162 offset:1024
	ds_read_b128 v[158:161], v162 offset:2048
	ds_read_b128 v[162:165], v162 offset:3072
	ds_read_b128 v[166:169], v178
	ds_read_b128 v[170:173], v178 offset:1024
	ds_read_b128 v[174:177], v178 offset:2048
	ds_read_b128 v[178:181], v178 offset:3072
	s_mov_b64 vcc, s[40:41]
	s_add_u32 s40, s40, 0x40000
	s_addc_u32 s41, s41, 0
	s_mov_b32 m0, s51
	ds_read_b128 v[182:185], v149 offset:32768
	ds_read_b128 v[190:193], v149 offset:33792
	ds_read_b128 v[194:197], v149 offset:34816
	ds_read_b128 v[198:201], v149 offset:35840
	ds_read_b128 v[202:205], v149 offset:36864
	ds_read_b128 v[206:209], v149 offset:37888
	ds_read_b128 v[210:213], v149 offset:38912
	ds_read_b128 v[214:217], v149 offset:39936
	global_load_lds_dwordx4 v128, s[40:41]
	s_mov_b32 m0, s52
	s_nop 0
	global_load_lds_dwordx4 v130, s[40:41]
	s_waitcnt vmcnt(8)
	s_waitcnt lgkmcnt(0)
	s_barrier
	s_setprio 1
	v_mfma_f32_16x16x32_bf16 v[120:123], v[150:153], v[182:185], v[120:123]
	v_mfma_f32_16x16x32_bf16 v[124:127], v[158:161], v[182:185], v[124:127]
	v_mfma_f32_16x16x32_bf16 v[108:111], v[150:153], v[194:197], v[108:111]
	v_mfma_f32_16x16x32_bf16 v[104:107], v[158:161], v[194:197], v[104:107]
	v_mfma_f32_16x16x32_bf16 v[92:95], v[150:153], v[202:205], v[92:95]
	v_mfma_f32_16x16x32_bf16 v[88:91], v[158:161], v[202:205], v[88:91]
	v_mfma_f32_16x16x32_bf16 v[76:79], v[150:153], v[210:213], v[76:79]
	v_mfma_f32_16x16x32_bf16 v[72:75], v[158:161], v[210:213], v[72:75]
	v_mfma_f32_16x16x32_bf16 v[120:123], v[154:157], v[190:193], v[120:123]
	v_mfma_f32_16x16x32_bf16 v[124:127], v[162:165], v[190:193], v[124:127]
	v_mfma_f32_16x16x32_bf16 v[108:111], v[154:157], v[198:201], v[108:111]
	v_mfma_f32_16x16x32_bf16 v[104:107], v[162:165], v[198:201], v[104:107]
	v_mfma_f32_16x16x32_bf16 v[92:95], v[154:157], v[206:209], v[92:95]
	v_mfma_f32_16x16x32_bf16 v[88:91], v[162:165], v[206:209], v[88:91]
	v_mfma_f32_16x16x32_bf16 v[76:79], v[154:157], v[214:217], v[76:79]
	v_mfma_f32_16x16x32_bf16 v[72:75], v[162:165], v[214:217], v[72:75]
	v_mfma_f32_16x16x32_bf16 v[116:119], v[166:169], v[182:185], v[116:119]
	v_mfma_f32_16x16x32_bf16 v[112:115], v[174:177], v[182:185], v[112:115]
	v_mfma_f32_16x16x32_bf16 v[100:103], v[166:169], v[194:197], v[100:103]
	v_mfma_f32_16x16x32_bf16 v[96:99], v[174:177], v[194:197], v[96:99]
	v_mfma_f32_16x16x32_bf16 v[84:87], v[166:169], v[202:205], v[84:87]
	v_mfma_f32_16x16x32_bf16 v[80:83], v[174:177], v[202:205], v[80:83]
	v_mfma_f32_16x16x32_bf16 v[68:71], v[166:169], v[210:213], v[68:71]
	v_mfma_f32_16x16x32_bf16 v[64:67], v[174:177], v[210:213], v[64:67]
	v_mfma_f32_16x16x32_bf16 v[116:119], v[170:173], v[190:193], v[116:119]
	v_mfma_f32_16x16x32_bf16 v[112:115], v[178:181], v[190:193], v[112:115]
	v_mfma_f32_16x16x32_bf16 v[100:103], v[170:173], v[198:201], v[100:103]
	v_mfma_f32_16x16x32_bf16 v[96:99], v[178:181], v[198:201], v[96:99]
	v_mfma_f32_16x16x32_bf16 v[84:87], v[170:173], v[206:209], v[84:87]
	v_mfma_f32_16x16x32_bf16 v[80:83], v[178:181], v[206:209], v[80:83]
	v_mfma_f32_16x16x32_bf16 v[68:71], v[170:173], v[214:217], v[68:71]
	v_mfma_f32_16x16x32_bf16 v[64:67], v[178:181], v[214:217], v[64:67]
	s_setprio 0
	s_barrier
	s_add_i32 s40, s69, s47
	s_add_i32 m0, s40, 0xffffff80
	ds_read_b128 v[182:185], v149 offset:49152
	ds_read_b128 v[190:193], v149 offset:50176
	ds_read_b128 v[194:197], v149 offset:51200
	ds_read_b128 v[198:201], v149 offset:52224
	ds_read_b128 v[202:205], v149 offset:53248
	ds_read_b128 v[206:209], v149 offset:54272
	ds_read_b128 v[210:213], v149 offset:55296
	ds_read_b128 v[214:217], v149 offset:56320
	global_load_lds_dwordx4 v134, s[100:101] offset:128
	s_add_i32 m0, s40, 0x1f80
	s_add_i32 s40, s70, s47
	global_load_lds_dwordx4 v132, s[100:101] offset:128
	s_add_u32 s100, s100, s4
	s_addc_u32 s101, s101, s5
	s_add_i32 m0, s40, 0xffffff80
	s_nop 0
	global_load_lds_dwordx4 v134, s[100:101] offset:128
	s_add_i32 m0, s40, 0x1f80
	s_nop 0
	global_load_lds_dwordx4 v132, s[100:101] offset:128
	s_add_i32 m0, s55, 0xffffff80
	s_nop 0
	global_load_lds_dwordx4 v128, vcc offset:128
	s_add_i32 m0, s56, 0xffffff80
	s_nop 0
	global_load_lds_dwordx4 v130, vcc offset:128
	s_waitcnt vmcnt(8)
	s_waitcnt lgkmcnt(0)
	s_barrier
	s_setprio 1
	v_mfma_f32_16x16x32_bf16 v[60:63], v[150:153], v[182:185], v[60:63]
	v_mfma_f32_16x16x32_bf16 v[56:59], v[158:161], v[182:185], v[56:59]
	v_mfma_f32_16x16x32_bf16 v[44:47], v[150:153], v[194:197], v[44:47]
	v_mfma_f32_16x16x32_bf16 v[40:43], v[158:161], v[194:197], v[40:43]
	v_mfma_f32_16x16x32_bf16 v[28:31], v[150:153], v[202:205], v[28:31]
	v_mfma_f32_16x16x32_bf16 v[24:27], v[158:161], v[202:205], v[24:27]
	v_mfma_f32_16x16x32_bf16 v[12:15], v[150:153], v[210:213], v[12:15]
	v_mfma_f32_16x16x32_bf16 v[8:11], v[158:161], v[210:213], v[8:11]
	v_mfma_f32_16x16x32_bf16 v[60:63], v[154:157], v[190:193], v[60:63]
	v_mfma_f32_16x16x32_bf16 v[56:59], v[162:165], v[190:193], v[56:59]
	v_mfma_f32_16x16x32_bf16 v[44:47], v[154:157], v[198:201], v[44:47]
	v_mfma_f32_16x16x32_bf16 v[40:43], v[162:165], v[198:201], v[40:43]
	v_mfma_f32_16x16x32_bf16 v[28:31], v[154:157], v[206:209], v[28:31]
	v_mfma_f32_16x16x32_bf16 v[24:27], v[162:165], v[206:209], v[24:27]
	v_mfma_f32_16x16x32_bf16 v[12:15], v[154:157], v[214:217], v[12:15]
	v_mfma_f32_16x16x32_bf16 v[8:11], v[162:165], v[214:217], v[8:11]
	v_mfma_f32_16x16x32_bf16 v[52:55], v[166:169], v[182:185], v[52:55]
	v_mfma_f32_16x16x32_bf16 v[48:51], v[174:177], v[182:185], v[48:51]
	v_mfma_f32_16x16x32_bf16 v[36:39], v[166:169], v[194:197], v[36:39]
	v_mfma_f32_16x16x32_bf16 v[32:35], v[174:177], v[194:197], v[32:35]
	v_mfma_f32_16x16x32_bf16 v[20:23], v[166:169], v[202:205], v[20:23]
	v_mfma_f32_16x16x32_bf16 v[16:19], v[174:177], v[202:205], v[16:19]
	v_mfma_f32_16x16x32_bf16 v[4:7], v[166:169], v[210:213], v[4:7]
	v_mfma_f32_16x16x32_bf16 v[0:3], v[174:177], v[210:213], v[0:3]
	v_mfma_f32_16x16x32_bf16 v[52:55], v[170:173], v[190:193], v[52:55]
	v_mfma_f32_16x16x32_bf16 v[48:51], v[178:181], v[190:193], v[48:51]
	v_mfma_f32_16x16x32_bf16 v[36:39], v[170:173], v[198:201], v[36:39]
	v_mfma_f32_16x16x32_bf16 v[32:35], v[178:181], v[198:201], v[32:35]
	v_mfma_f32_16x16x32_bf16 v[20:23], v[170:173], v[206:209], v[20:23]
	v_mfma_f32_16x16x32_bf16 v[16:19], v[178:181], v[206:209], v[16:19]
	v_mfma_f32_16x16x32_bf16 v[4:7], v[170:173], v[214:217], v[4:7]
	v_mfma_f32_16x16x32_bf16 v[0:3], v[178:181], v[214:217], v[0:3]
	s_setprio 0
	s_barrier
	s_add_u32 s8, s8, 0x100
	s_addc_u32 s9, s9, 0
	s_add_u32 s42, s42, 0x100
	s_addc_u32 s43, s43, 0
	s_cmp_ge_i32 s68, s58
	s_mov_b32 s40, s68
	s_cbranch_scc0 .LBB0_1236

; #define PG8_STAGE(bufoff, gbase, voff) do { _Pragma("unroll") for (int _i = 0; _i < 2; ++_i) \
;         __builtin_amdgcn_global_load_lds((const unsigned*)((const char*)(gbase) + (voff)[_i]), (PG8_LAS unsigned*)(lds + (bufoff) + ldsw + _i * 8192), 16, 0, 0); } while (0)
; #define PG8_LDA(dst, b, h) do { _Pragma("unroll") for (int m = 0; m < 4; ++m) _Pragma("unroll") for (int k = 0; k < 2; ++k) dst[m][k] = *(const PG8_LAS bf16x8*)(lds + PG8_SA(b, h) + aoff + m * 2048 + k * 1024); } while (0)
; #define PG8_LDB(dst, b, h) do { _Pragma("unroll") for (int n = 0; n < 2; ++n) _Pragma("unroll") for (int k = 0; k < 2; ++k) dst[n][k] = *(const PG8_LAS bf16x8*)(lds + PG8_SB(b, h) + boff + n * 2048 + k * 1024); } while (0)
; #define PG8_MMA(ai, bj, At, Bt) do { __builtin_amdgcn_s_setprio(1); _Pragma("unroll") for (int m = 0; m < 4; ++m) _Pragma("unroll") for (int n = 0; n < 2; ++n) _Pragma("unroll") for (int k = 0; k < 2; ++k) \
;         acc[ai][bj][m][n] = __builtin_amdgcn_mfma_f32_16x16x32_bf16(Bt[n][k], At[m][k], acc[ai][bj][m][n], 0, 0, 0); __builtin_amdgcn_s_setprio(0); } while (0)
; #define PG8_WAIT_V(n) asm volatile("s_waitcnt vmcnt(" #n ")" ::: "memory")
; #define PG8_WAIT_L(n) asm volatile("s_waitcnt lgkmcnt(" #n ")" ::: "memory")
; template <class Epi, class Sched, bool ALIGN_EPI = false, bool SP2 = false>
; __device__ __forceinline__ void gemm_phase(PG8_LAS unsigned char* lds, const Gemm g, const Sched& S, const Epi& E) {
;     ...
;             const bool last = (t == nt - 2);
;             const char* a1 = cA + (size_t)(t + 1) * kstep;
;             const char* a2 = last ? nA : cA + (size_t)(t + 2) * kstep; const char* b2 = last ? nB : cB + (size_t)(t + 2) * kstep;
;             const char* a3 = a2 + kstep; const char* b3 = b2 + kstep;
;             if (last && has_next) S.a_ready(nxt);
;             if constexpr (SP2) {
;             PG8_LDB(B0, 0, 0); PG8_LDB(B1, 0, 1); PG8_SCHED; PG8_LDA(At, 0, 0); PG8_STAGE(PG8_SA(1, 1), a1 + hstepA, voffA);
;             PG8_WAIT_V(8); PG8_WAIT_L(0); PG8_BAR; PG8_MMA(0, 0, At, B0); PG8_MMA(0, 1, At, B1); PG8_BAR; PG8_SCHED;
;             PG8_LDA(At, 0, 1); PG8_STAGE(PG8_SB(0, 0), b2, voffB); PG8_STAGE(PG8_SB(0, 1), b2 + hstep, voffB); PG8_STAGE(PG8_SA(0, 0), a2, voffA);
;             PG8_WAIT_V(8); PG8_WAIT_L(0); PG8_BAR; PG8_MMA(1, 0, At, B0); PG8_MMA(1, 1, At, B1); PG8_BAR; PG8_SCHED;
.LBB0_1480:
	ds_read_b128 v[162:165], v159
	ds_read_b128 v[166:169], v159 offset:1024
	ds_read_b128 v[170:173], v159 offset:2048
	ds_read_b128 v[174:177], v159 offset:3072
	ds_read_b128 v[178:181], v160
	ds_read_b128 v[182:185], v160 offset:1024
	ds_read_b128 v[190:193], v160 offset:2048
	ds_read_b128 v[194:197], v160 offset:3072
	s_add_i32 s63, s36, 2
	s_add_u32 s64, s10, 0xfffe0080
	s_addc_u32 s37, s11, -1
	s_cmp_eq_u32 s56, s36
	s_cselect_b32 s36, s62, s64
	s_cselect_b32 s37, s29, s37
	s_cselect_b32 s65, s31, s39
	s_cselect_b32 s64, s30, s38
	s_add_i32 m0, s27, 0xc000
	ds_read_b128 v[198:201], v161
	ds_read_b128 v[202:205], v161 offset:1024
	ds_read_b128 v[206:209], v161 offset:2048
	ds_read_b128 v[210:213], v161 offset:3072
	ds_read_b128 v[214:217], v161 offset:4096
	ds_read_b128 v[218:221], v161 offset:5120
	ds_read_b128 v[222:225], v161 offset:6144
	ds_read_b128 v[226:229], v161 offset:7168
	global_load_lds_dwordx4 v138, s[10:11]
	s_add_i32 m0, s27, 0xe000
	s_nop 0
	global_load_lds_dwordx4 v140, s[10:11]
	s_waitcnt vmcnt(8)
	s_waitcnt lgkmcnt(0)
	s_barrier
	s_setprio 1
	v_mfma_f32_16x16x32_bf16 v[124:127], v[162:165], v[198:201], v[124:127]
	v_mfma_f32_16x16x32_bf16 v[120:123], v[170:173], v[198:201], v[120:123]
	v_mfma_f32_16x16x32_bf16 v[108:111], v[162:165], v[206:209], v[108:111]
	v_mfma_f32_16x16x32_bf16 v[104:107], v[170:173], v[206:209], v[104:107]
	v_mfma_f32_16x16x32_bf16 v[92:95], v[162:165], v[214:217], v[92:95]
	v_mfma_f32_16x16x32_bf16 v[88:91], v[170:173], v[214:217], v[88:91]
	v_mfma_f32_16x16x32_bf16 v[76:79], v[162:165], v[222:225], v[76:79]
	v_mfma_f32_16x16x32_bf16 v[72:75], v[170:173], v[222:225], v[72:75]
	v_mfma_f32_16x16x32_bf16 v[124:127], v[166:169], v[202:205], v[124:127]
	v_mfma_f32_16x16x32_bf16 v[120:123], v[174:177], v[202:205], v[120:123]
	v_mfma_f32_16x16x32_bf16 v[108:111], v[166:169], v[210:213], v[108:111]
	v_mfma_f32_16x16x32_bf16 v[104:107], v[174:177], v[210:213], v[104:107]
	v_mfma_f32_16x16x32_bf16 v[92:95], v[166:169], v[218:221], v[92:95]
	v_mfma_f32_16x16x32_bf16 v[88:91], v[174:177], v[218:221], v[88:91]
	v_mfma_f32_16x16x32_bf16 v[76:79], v[166:169], v[226:229], v[76:79]
	v_mfma_f32_16x16x32_bf16 v[72:75], v[174:177], v[226:229], v[72:75]
	v_mfma_f32_16x16x32_bf16 v[116:119], v[178:181], v[198:201], v[116:119]
	v_mfma_f32_16x16x32_bf16 v[112:115], v[190:193], v[198:201], v[112:115]
	v_mfma_f32_16x16x32_bf16 v[100:103], v[178:181], v[206:209], v[100:103]
	v_mfma_f32_16x16x32_bf16 v[96:99], v[190:193], v[206:209], v[96:99]
	v_mfma_f32_16x16x32_bf16 v[84:87], v[178:181], v[214:217], v[84:87]
	v_mfma_f32_16x16x32_bf16 v[80:83], v[190:193], v[214:217], v[80:83]
	v_mfma_f32_16x16x32_bf16 v[68:71], v[178:181], v[222:225], v[68:71]
	v_mfma_f32_16x16x32_bf16 v[64:67], v[190:193], v[222:225], v[64:67]
	v_mfma_f32_16x16x32_bf16 v[116:119], v[182:185], v[202:205], v[116:119]
	v_mfma_f32_16x16x32_bf16 v[112:115], v[194:197], v[202:205], v[112:115]
	v_mfma_f32_16x16x32_bf16 v[100:103], v[182:185], v[210:213], v[100:103]
	v_mfma_f32_16x16x32_bf16 v[96:99], v[194:197], v[210:213], v[96:99]
	v_mfma_f32_16x16x32_bf16 v[84:87], v[182:185], v[218:221], v[84:87]
	v_mfma_f32_16x16x32_bf16 v[80:83], v[194:197], v[218:221], v[80:83]
	v_mfma_f32_16x16x32_bf16 v[68:71], v[182:185], v[226:229], v[68:71]
	v_mfma_f32_16x16x32_bf16 v[64:67], v[194:197], v[226:229], v[64:67]
	s_setprio 0
	s_barrier
	s_add_i32 s66, s57, s47
	s_mov_b32 m0, s66
	ds_read_b128 v[198:201], v161 offset:16384
	ds_read_b128 v[202:205], v161 offset:17408
	ds_read_b128 v[206:209], v161 offset:18432
	ds_read_b128 v[210:213], v161 offset:19456
	ds_read_b128 v[214:217], v161 offset:20480
	ds_read_b128 v[218:221], v161 offset:21504
	ds_read_b128 v[222:225], v161 offset:22528
	ds_read_b128 v[226:229], v161 offset:23552
	global_load_lds_dwordx4 v136, s[64:65]
	s_add_i32 m0, s66, 0x2000
	s_mov_b64 s[100:101], s[64:65]
	s_add_i32 s66, s58, s47
	global_load_lds_dwordx4 v134, s[64:65]
	s_add_u32 s64, s64, s16
	s_addc_u32 s65, s65, s17
	s_mov_b32 m0, s66
	s_nop 0
	global_load_lds_dwordx4 v136, s[64:65]
	s_add_i32 m0, s66, 0x2000
	s_nop 0
	global_load_lds_dwordx4 v134, s[64:65]
	s_mov_b32 m0, s27
	s_nop 0
	global_load_lds_dwordx4 v130, s[36:37]
	s_mov_b32 m0, s48
	s_nop 0
	global_load_lds_dwordx4 v132, s[36:37]
	s_waitcnt vmcnt(8)
	s_waitcnt lgkmcnt(0)
	s_barrier
	s_setprio 1
	v_mfma_f32_16x16x32_bf16 v[60:63], v[162:165], v[198:201], v[60:63]
	v_mfma_f32_16x16x32_bf16 v[56:59], v[170:173], v[198:201], v[56:59]
	v_mfma_f32_16x16x32_bf16 v[44:47], v[162:165], v[206:209], v[44:47]
	v_mfma_f32_16x16x32_bf16 v[40:43], v[170:173], v[206:209], v[40:43]
	v_mfma_f32_16x16x32_bf16 v[28:31], v[162:165], v[214:217], v[28:31]
	v_mfma_f32_16x16x32_bf16 v[24:27], v[170:173], v[214:217], v[24:27]
	v_mfma_f32_16x16x32_bf16 v[12:15], v[162:165], v[222:225], v[12:15]
	v_mfma_f32_16x16x32_bf16 v[8:11], v[170:173], v[222:225], v[8:11]
	v_mfma_f32_16x16x32_bf16 v[60:63], v[166:169], v[202:205], v[60:63]
	v_mfma_f32_16x16x32_bf16 v[56:59], v[174:177], v[202:205], v[56:59]
	v_mfma_f32_16x16x32_bf16 v[44:47], v[166:169], v[210:213], v[44:47]
	v_mfma_f32_16x16x32_bf16 v[40:43], v[174:177], v[210:213], v[40:43]
	v_mfma_f32_16x16x32_bf16 v[28:31], v[166:169], v[218:221], v[28:31]
	v_mfma_f32_16x16x32_bf16 v[24:27], v[174:177], v[218:221], v[24:27]
	v_mfma_f32_16x16x32_bf16 v[12:15], v[166:169], v[226:229], v[12:15]
	v_mfma_f32_16x16x32_bf16 v[8:11], v[174:177], v[226:229], v[8:11]
	v_mfma_f32_16x16x32_bf16 v[52:55], v[178:181], v[198:201], v[52:55]
	v_mfma_f32_16x16x32_bf16 v[48:51], v[190:193], v[198:201], v[48:51]
	v_mfma_f32_16x16x32_bf16 v[36:39], v[178:181], v[206:209], v[36:39]
	v_mfma_f32_16x16x32_bf16 v[32:35], v[190:193], v[206:209], v[32:35]
	v_mfma_f32_16x16x32_bf16 v[20:23], v[178:181], v[214:217], v[20:23]
	v_mfma_f32_16x16x32_bf16 v[16:19], v[190:193], v[214:217], v[16:19]
	v_mfma_f32_16x16x32_bf16 v[4:7], v[178:181], v[222:225], v[4:7]
	v_mfma_f32_16x16x32_bf16 v[0:3], v[190:193], v[222:225], v[0:3]
	v_mfma_f32_16x16x32_bf16 v[52:55], v[182:185], v[202:205], v[52:55]
	v_mfma_f32_16x16x32_bf16 v[48:51], v[194:197], v[202:205], v[48:51]
	v_mfma_f32_16x16x32_bf16 v[36:39], v[182:185], v[210:213], v[36:39]
	v_mfma_f32_16x16x32_bf16 v[32:35], v[194:197], v[210:213], v[32:35]
	v_mfma_f32_16x16x32_bf16 v[20:23], v[182:185], v[218:221], v[20:23]
	v_mfma_f32_16x16x32_bf16 v[16:19], v[194:197], v[218:221], v[16:19]
	v_mfma_f32_16x16x32_bf16 v[4:7], v[182:185], v[226:229], v[4:7]
	v_mfma_f32_16x16x32_bf16 v[0:3], v[194:197], v[226:229], v[0:3]
	s_setprio 0
	s_barrier
; #define PG8_STAGE(bufoff, gbase, voff) do { _Pragma("unroll") for (int _i = 0; _i < 2; ++_i) \
;         __builtin_amdgcn_global_load_lds((const unsigned*)((const char*)(gbase) + (voff)[_i]), (PG8_LAS unsigned*)(lds + (bufoff) + ldsw + _i * 8192), 16, 0, 0); } while (0)
; #define PG8_LDA(dst, b, h) do { _Pragma("unroll") for (int m = 0; m < 4; ++m) _Pragma("unroll") for (int k = 0; k < 2; ++k) dst[m][k] = *(const PG8_LAS bf16x8*)(lds + PG8_SA(b, h) + aoff + m * 2048 + k * 1024); } while (0)
; #define PG8_LDB(dst, b, h) do { _Pragma("unroll") for (int n = 0; n < 2; ++n) _Pragma("unroll") for (int k = 0; k < 2; ++k) dst[n][k] = *(const PG8_LAS bf16x8*)(lds + PG8_SB(b, h) + boff + n * 2048 + k * 1024); } while (0)
; #define PG8_MMA(ai, bj, At, Bt) do { __builtin_amdgcn_s_setprio(1); _Pragma("unroll") for (int m = 0; m < 4; ++m) _Pragma("unroll") for (int n = 0; n < 2; ++n) _Pragma("unroll") for (int k = 0; k < 2; ++k) \
;         acc[ai][bj][m][n] = __builtin_amdgcn_mfma_f32_16x16x32_bf16(Bt[n][k], At[m][k], acc[ai][bj][m][n], 0, 0, 0); __builtin_amdgcn_s_setprio(0); } while (0)
; #define PG8_WAIT_V(n) asm volatile("s_waitcnt vmcnt(" #n ")" ::: "memory")
; #define PG8_WAIT_L(n) asm volatile("s_waitcnt lgkmcnt(" #n ")" ::: "memory")
; #define PG8_BAR __builtin_amdgcn_s_barrier()
; #define PG8_SCHED __builtin_amdgcn_sched_barrier(0)
; template <class Epi, class Sched, bool ALIGN_EPI = false, bool SP2 = false>
; __device__ __forceinline__ void gemm_phase(PG8_LAS unsigned char* lds, const Gemm g, const Sched& S, const Epi& E) {
;     ...
;             PG8_LDB(B0, 1, 0); PG8_LDB(B1, 1, 1); PG8_SCHED; PG8_LDA(At, 1, 0); PG8_STAGE(PG8_SA(0, 1), a2 + hstepA, voffA);
;             PG8_WAIT_V(8); PG8_WAIT_L(0); PG8_BAR; PG8_MMA(0, 0, At, B0); PG8_MMA(0, 1, At, B1); PG8_BAR; PG8_SCHED;
;             PG8_LDA(At, 1, 1); PG8_STAGE(PG8_SB(1, 0), b3, voffB); PG8_STAGE(PG8_SB(1, 1), b3 + hstep, voffB); PG8_STAGE(PG8_SA(1, 0), a3, voffA);
;             PG8_WAIT_V(8); PG8_WAIT_L(0); PG8_BAR; PG8_MMA(1, 0, At, B0); PG8_MMA(1, 1, At, B1); PG8_BAR; PG8_SCHED;
	s_add_i32 s64, 0, 0x18000
	s_add_i32 s65, 0, 0x1c000
	v_add_u32_e32 v174, s64, v157
	v_add_u32_e32 v194, s65, v157
	ds_read_b128 v[162:165], v174
	ds_read_b128 v[166:169], v174 offset:1024
	ds_read_b128 v[170:173], v174 offset:2048
	ds_read_b128 v[174:177], v174 offset:3072
	ds_read_b128 v[178:181], v194
	ds_read_b128 v[182:185], v194 offset:1024
	ds_read_b128 v[190:193], v194 offset:2048
	ds_read_b128 v[194:197], v194 offset:3072
	s_mov_b64 vcc, s[36:37]
	s_add_u32 s36, s36, 0x20000
	s_addc_u32 s37, s37, 0
	s_mov_b32 m0, s49
	ds_read_b128 v[198:201], v161 offset:32768
	ds_read_b128 v[202:205], v161 offset:33792
	ds_read_b128 v[206:209], v161 offset:34816
	ds_read_b128 v[210:213], v161 offset:35840
	ds_read_b128 v[214:217], v161 offset:36864
	ds_read_b128 v[218:221], v161 offset:37888
	ds_read_b128 v[222:225], v161 offset:38912
	ds_read_b128 v[226:229], v161 offset:39936
	global_load_lds_dwordx4 v130, s[36:37]
	s_mov_b32 m0, s50
	s_nop 0
	global_load_lds_dwordx4 v132, s[36:37]
	s_waitcnt vmcnt(8)
	s_waitcnt lgkmcnt(0)
	s_barrier
	s_setprio 1
	v_mfma_f32_16x16x32_bf16 v[124:127], v[162:165], v[198:201], v[124:127]
	v_mfma_f32_16x16x32_bf16 v[120:123], v[170:173], v[198:201], v[120:123]
	v_mfma_f32_16x16x32_bf16 v[108:111], v[162:165], v[206:209], v[108:111]
	v_mfma_f32_16x16x32_bf16 v[104:107], v[170:173], v[206:209], v[104:107]
	v_mfma_f32_16x16x32_bf16 v[92:95], v[162:165], v[214:217], v[92:95]
	v_mfma_f32_16x16x32_bf16 v[88:91], v[170:173], v[214:217], v[88:91]
	v_mfma_f32_16x16x32_bf16 v[76:79], v[162:165], v[222:225], v[76:79]
	v_mfma_f32_16x16x32_bf16 v[72:75], v[170:173], v[222:225], v[72:75]
	v_mfma_f32_16x16x32_bf16 v[124:127], v[166:169], v[202:205], v[124:127]
	v_mfma_f32_16x16x32_bf16 v[120:123], v[174:177], v[202:205], v[120:123]
	v_mfma_f32_16x16x32_bf16 v[108:111], v[166:169], v[210:213], v[108:111]
	v_mfma_f32_16x16x32_bf16 v[104:107], v[174:177], v[210:213], v[104:107]
	v_mfma_f32_16x16x32_bf16 v[92:95], v[166:169], v[218:221], v[92:95]
	v_mfma_f32_16x16x32_bf16 v[88:91], v[174:177], v[218:221], v[88:91]
	v_mfma_f32_16x16x32_bf16 v[76:79], v[166:169], v[226:229], v[76:79]
	v_mfma_f32_16x16x32_bf16 v[72:75], v[174:177], v[226:229], v[72:75]
	v_mfma_f32_16x16x32_bf16 v[116:119], v[178:181], v[198:201], v[116:119]
	v_mfma_f32_16x16x32_bf16 v[112:115], v[190:193], v[198:201], v[112:115]
	v_mfma_f32_16x16x32_bf16 v[100:103], v[178:181], v[206:209], v[100:103]
	v_mfma_f32_16x16x32_bf16 v[96:99], v[190:193], v[206:209], v[96:99]
	v_mfma_f32_16x16x32_bf16 v[84:87], v[178:181], v[214:217], v[84:87]
	v_mfma_f32_16x16x32_bf16 v[80:83], v[190:193], v[214:217], v[80:83]
	v_mfma_f32_16x16x32_bf16 v[68:71], v[178:181], v[222:225], v[68:71]
	v_mfma_f32_16x16x32_bf16 v[64:67], v[190:193], v[222:225], v[64:67]
	v_mfma_f32_16x16x32_bf16 v[116:119], v[182:185], v[202:205], v[116:119]
	v_mfma_f32_16x16x32_bf16 v[112:115], v[194:197], v[202:205], v[112:115]
	v_mfma_f32_16x16x32_bf16 v[100:103], v[182:185], v[210:213], v[100:103]
	v_mfma_f32_16x16x32_bf16 v[96:99], v[194:197], v[210:213], v[96:99]
	v_mfma_f32_16x16x32_bf16 v[84:87], v[182:185], v[218:221], v[84:87]
	v_mfma_f32_16x16x32_bf16 v[80:83], v[194:197], v[218:221], v[80:83]
	v_mfma_f32_16x16x32_bf16 v[68:71], v[182:185], v[226:229], v[68:71]
	v_mfma_f32_16x16x32_bf16 v[64:67], v[194:197], v[226:229], v[64:67]
	s_setprio 0
	s_barrier
	s_add_i32 s36, s64, s47
	s_add_i32 m0, s36, 0xffffff80
	ds_read_b128 v[198:201], v161 offset:49152
	ds_read_b128 v[202:205], v161 offset:50176
	ds_read_b128 v[206:209], v161 offset:51200
	ds_read_b128 v[210:213], v161 offset:52224
	ds_read_b128 v[214:217], v161 offset:53248
	ds_read_b128 v[218:221], v161 offset:54272
	ds_read_b128 v[222:225], v161 offset:55296
	ds_read_b128 v[226:229], v161 offset:56320
	global_load_lds_dwordx4 v136, s[100:101] offset:128
	s_add_i32 m0, s36, 0x1f80
	s_add_i32 s36, s65, s47
	global_load_lds_dwordx4 v134, s[100:101] offset:128
	s_add_u32 s100, s100, s16
	s_addc_u32 s101, s101, s17
	s_add_i32 m0, s36, 0xffffff80
	s_nop 0
	global_load_lds_dwordx4 v136, s[100:101] offset:128
	s_add_i32 m0, s36, 0x1f80
	s_nop 0
	global_load_lds_dwordx4 v134, s[100:101] offset:128
	s_add_i32 m0, s51, 0xffffff80
	s_nop 0
	global_load_lds_dwordx4 v130, vcc offset:128
	s_add_i32 m0, s52, 0xffffff80
	s_nop 0
	global_load_lds_dwordx4 v132, vcc offset:128
	s_waitcnt vmcnt(8)
	s_waitcnt lgkmcnt(0)
	s_barrier
	s_setprio 1
	v_mfma_f32_16x16x32_bf16 v[60:63], v[162:165], v[198:201], v[60:63]
	v_mfma_f32_16x16x32_bf16 v[56:59], v[170:173], v[198:201], v[56:59]
	v_mfma_f32_16x16x32_bf16 v[44:47], v[162:165], v[206:209], v[44:47]
	v_mfma_f32_16x16x32_bf16 v[40:43], v[170:173], v[206:209], v[40:43]
	v_mfma_f32_16x16x32_bf16 v[28:31], v[162:165], v[214:217], v[28:31]
	v_mfma_f32_16x16x32_bf16 v[24:27], v[170:173], v[214:217], v[24:27]
	v_mfma_f32_16x16x32_bf16 v[12:15], v[162:165], v[222:225], v[12:15]
	v_mfma_f32_16x16x32_bf16 v[8:11], v[170:173], v[222:225], v[8:11]
	v_mfma_f32_16x16x32_bf16 v[60:63], v[166:169], v[202:205], v[60:63]
	v_mfma_f32_16x16x32_bf16 v[56:59], v[174:177], v[202:205], v[56:59]
	v_mfma_f32_16x16x32_bf16 v[44:47], v[166:169], v[210:213], v[44:47]
	v_mfma_f32_16x16x32_bf16 v[40:43], v[174:177], v[210:213], v[40:43]
	v_mfma_f32_16x16x32_bf16 v[28:31], v[166:169], v[218:221], v[28:31]
	v_mfma_f32_16x16x32_bf16 v[24:27], v[174:177], v[218:221], v[24:27]
	v_mfma_f32_16x16x32_bf16 v[12:15], v[166:169], v[226:229], v[12:15]
	v_mfma_f32_16x16x32_bf16 v[8:11], v[174:177], v[226:229], v[8:11]
	v_mfma_f32_16x16x32_bf16 v[52:55], v[178:181], v[198:201], v[52:55]
	v_mfma_f32_16x16x32_bf16 v[48:51], v[190:193], v[198:201], v[48:51]
	v_mfma_f32_16x16x32_bf16 v[36:39], v[178:181], v[206:209], v[36:39]
	v_mfma_f32_16x16x32_bf16 v[32:35], v[190:193], v[206:209], v[32:35]
	v_mfma_f32_16x16x32_bf16 v[20:23], v[178:181], v[214:217], v[20:23]
	v_mfma_f32_16x16x32_bf16 v[16:19], v[190:193], v[214:217], v[16:19]
	v_mfma_f32_16x16x32_bf16 v[4:7], v[178:181], v[222:225], v[4:7]
	v_mfma_f32_16x16x32_bf16 v[0:3], v[190:193], v[222:225], v[0:3]
	v_mfma_f32_16x16x32_bf16 v[52:55], v[182:185], v[202:205], v[52:55]
	v_mfma_f32_16x16x32_bf16 v[48:51], v[194:197], v[202:205], v[48:51]
	v_mfma_f32_16x16x32_bf16 v[36:39], v[182:185], v[210:213], v[36:39]
	v_mfma_f32_16x16x32_bf16 v[32:35], v[194:197], v[210:213], v[32:35]
	v_mfma_f32_16x16x32_bf16 v[20:23], v[182:185], v[218:221], v[20:23]
	v_mfma_f32_16x16x32_bf16 v[16:19], v[194:197], v[218:221], v[16:19]
	v_mfma_f32_16x16x32_bf16 v[4:7], v[182:185], v[226:229], v[4:7]
	v_mfma_f32_16x16x32_bf16 v[0:3], v[194:197], v[226:229], v[0:3]
	s_setprio 0
	s_barrier
	s_add_u32 s10, s10, 0x100
	s_addc_u32 s11, s11, 0
	s_add_u32 s38, s38, 0x100
	s_addc_u32 s39, s39, 0
	s_cmp_ge_i32 s63, s53
	s_mov_b32 s36, s63
	s_cbranch_scc0 .LBB0_1480

; #define PG8_STAGE(bufoff, gbase, voff) do { _Pragma("unroll") for (int _i = 0; _i < 2; ++_i) \
;         __builtin_amdgcn_global_load_lds((const unsigned*)((const char*)(gbase) + (voff)[_i]), (PG8_LAS unsigned*)(lds + (bufoff) + ldsw + _i * 8192), 16, 0, 0); } while (0)
; #define PG8_LDA(dst, b, h) do { _Pragma("unroll") for (int m = 0; m < 4; ++m) _Pragma("unroll") for (int k = 0; k < 2; ++k) dst[m][k] = *(const PG8_LAS bf16x8*)(lds + PG8_SA(b, h) + aoff + m * 2048 + k * 1024); } while (0)
; #define PG8_LDB(dst, b, h) do { _Pragma("unroll") for (int n = 0; n < 2; ++n) _Pragma("unroll") for (int k = 0; k < 2; ++k) dst[n][k] = *(const PG8_LAS bf16x8*)(lds + PG8_SB(b, h) + boff + n * 2048 + k * 1024); } while (0)
; #define PG8_MMA(ai, bj, At, Bt) do { __builtin_amdgcn_s_setprio(1); _Pragma("unroll") for (int m = 0; m < 4; ++m) _Pragma("unroll") for (int n = 0; n < 2; ++n) _Pragma("unroll") for (int k = 0; k < 2; ++k) \
;         acc[ai][bj][m][n] = __builtin_amdgcn_mfma_f32_16x16x32_bf16(Bt[n][k], At[m][k], acc[ai][bj][m][n], 0, 0, 0); __builtin_amdgcn_s_setprio(0); } while (0)
; #define PG8_WAIT_V(n) asm volatile("s_waitcnt vmcnt(" #n ")" ::: "memory")
; #define PG8_WAIT_L(n) asm volatile("s_waitcnt lgkmcnt(" #n ")" ::: "memory")
; template <class Epi, class Sched, bool ALIGN_EPI = false, bool SP2 = false>
; __device__ __forceinline__ void gemm_phase(PG8_LAS unsigned char* lds, const Gemm g, const Sched& S, const Epi& E) {
;     ...
;             const bool last = (t == nt - 2);
;             const char* a1 = cA + (size_t)(t + 1) * kstep;
;             const char* a2 = last ? nA : cA + (size_t)(t + 2) * kstep; const char* b2 = last ? nB : cB + (size_t)(t + 2) * kstep;
;             const char* a3 = a2 + kstep; const char* b3 = b2 + kstep;
;             if (last && has_next) S.a_ready(nxt);
;             if constexpr (SP2) {
;             PG8_LDB(B0, 0, 0); PG8_LDB(B1, 0, 1); PG8_SCHED; PG8_LDA(At, 0, 0); PG8_STAGE(PG8_SA(1, 1), a1 + hstepA, voffA);
;             PG8_WAIT_V(8); PG8_WAIT_L(0); PG8_BAR; PG8_MMA(0, 0, At, B0); PG8_MMA(0, 1, At, B1); PG8_BAR; PG8_SCHED;
;             PG8_LDA(At, 0, 1); PG8_STAGE(PG8_SB(0, 0), b2, voffB); PG8_STAGE(PG8_SB(0, 1), b2 + hstep, voffB); PG8_STAGE(PG8_SA(0, 0), a2, voffA);
;             PG8_WAIT_V(8); PG8_WAIT_L(0); PG8_BAR; PG8_MMA(1, 0, At, B0); PG8_MMA(1, 1, At, B1); PG8_BAR; PG8_SCHED;
.LBB0_1501:
	ds_read_b128 v[68:71], v196
	ds_read_b128 v[72:75], v196 offset:1024
	ds_read_b128 v[76:79], v196 offset:2048
	ds_read_b128 v[80:83], v196 offset:3072
	ds_read_b128 v[84:87], v197
	ds_read_b128 v[88:91], v197 offset:1024
	ds_read_b128 v[182:185], v197 offset:2048
	ds_read_b128 v[202:205], v197 offset:3072
	s_add_i32 s38, s14, 2
	s_add_u32 s39, s4, 0xffff0080
	s_addc_u32 s15, s5, -1
	s_cmp_eq_u32 s58, s14
	s_cselect_b32 s14, s35, s39
	s_cselect_b32 s15, s27, s15
	s_cselect_b32 s73, s29, s37
	s_cselect_b32 s72, s28, s36
	s_add_i32 m0, s47, 0xc000
	ds_read_b128 v[206:209], v198
	ds_read_b128 v[210:213], v198 offset:1024
	ds_read_b128 v[214:217], v198 offset:2048
	ds_read_b128 v[218:221], v198 offset:3072
	ds_read_b128 v[222:225], v198 offset:4096
	ds_read_b128 v[226:229], v198 offset:5120
	ds_read_b128 v[230:233], v198 offset:6144
	ds_read_b128 v[234:237], v198 offset:7168
	global_load_lds_dwordx4 v174, s[4:5]
	s_add_i32 m0, s47, 0xe000
	s_nop 0
	global_load_lds_dwordx4 v176, s[4:5]
	s_waitcnt vmcnt(8)
	s_waitcnt lgkmcnt(0)
	s_barrier
	s_setprio 1
	v_mfma_f32_16x16x32_bf16 v[152:155], v[68:71], v[206:209], v[152:155]
	v_mfma_f32_16x16x32_bf16 v[148:151], v[76:79], v[206:209], v[148:151]
	v_mfma_f32_16x16x32_bf16 v[136:139], v[68:71], v[214:217], v[136:139]
	v_mfma_f32_16x16x32_bf16 v[132:135], v[76:79], v[214:217], v[132:135]
	v_mfma_f32_16x16x32_bf16 v[120:123], v[68:71], v[222:225], v[120:123]
	v_mfma_f32_16x16x32_bf16 v[116:119], v[76:79], v[222:225], v[116:119]
	v_mfma_f32_16x16x32_bf16 v[104:107], v[68:71], v[230:233], v[104:107]
	v_mfma_f32_16x16x32_bf16 v[100:103], v[76:79], v[230:233], v[100:103]
	v_mfma_f32_16x16x32_bf16 v[152:155], v[72:75], v[210:213], v[152:155]
	v_mfma_f32_16x16x32_bf16 v[148:151], v[80:83], v[210:213], v[148:151]
	v_mfma_f32_16x16x32_bf16 v[136:139], v[72:75], v[218:221], v[136:139]
	v_mfma_f32_16x16x32_bf16 v[132:135], v[80:83], v[218:221], v[132:135]
	v_mfma_f32_16x16x32_bf16 v[120:123], v[72:75], v[226:229], v[120:123]
	v_mfma_f32_16x16x32_bf16 v[116:119], v[80:83], v[226:229], v[116:119]
	v_mfma_f32_16x16x32_bf16 v[104:107], v[72:75], v[234:237], v[104:107]
	v_mfma_f32_16x16x32_bf16 v[100:103], v[80:83], v[234:237], v[100:103]
	v_mfma_f32_16x16x32_bf16 v[144:147], v[84:87], v[206:209], v[144:147]
	v_mfma_f32_16x16x32_bf16 v[140:143], v[182:185], v[206:209], v[140:143]
	v_mfma_f32_16x16x32_bf16 v[128:131], v[84:87], v[214:217], v[128:131]
	v_mfma_f32_16x16x32_bf16 v[124:127], v[182:185], v[214:217], v[124:127]
	v_mfma_f32_16x16x32_bf16 v[112:115], v[84:87], v[222:225], v[112:115]
	v_mfma_f32_16x16x32_bf16 v[108:111], v[182:185], v[222:225], v[108:111]
	v_mfma_f32_16x16x32_bf16 v[96:99], v[84:87], v[230:233], v[96:99]
	v_mfma_f32_16x16x32_bf16 v[92:95], v[182:185], v[230:233], v[92:95]
	v_mfma_f32_16x16x32_bf16 v[144:147], v[88:91], v[210:213], v[144:147]
	v_mfma_f32_16x16x32_bf16 v[140:143], v[202:205], v[210:213], v[140:143]
	v_mfma_f32_16x16x32_bf16 v[128:131], v[88:91], v[218:221], v[128:131]
	v_mfma_f32_16x16x32_bf16 v[124:127], v[202:205], v[218:221], v[124:127]
	v_mfma_f32_16x16x32_bf16 v[112:115], v[88:91], v[226:229], v[112:115]
	v_mfma_f32_16x16x32_bf16 v[108:111], v[202:205], v[226:229], v[108:111]
	v_mfma_f32_16x16x32_bf16 v[96:99], v[88:91], v[234:237], v[96:99]
	v_mfma_f32_16x16x32_bf16 v[92:95], v[202:205], v[234:237], v[92:95]
	s_setprio 0
	s_barrier
	s_add_i32 s39, s61, s45
	s_mov_b32 m0, s39
	ds_read_b128 v[206:209], v198 offset:16384
	ds_read_b128 v[210:213], v198 offset:17408
	ds_read_b128 v[214:217], v198 offset:18432
	ds_read_b128 v[218:221], v198 offset:19456
	ds_read_b128 v[222:225], v198 offset:20480
	ds_read_b128 v[226:229], v198 offset:21504
	ds_read_b128 v[230:233], v198 offset:22528
	ds_read_b128 v[234:237], v198 offset:23552
	global_load_lds_dwordx4 v156, s[72:73]
	s_add_i32 m0, s39, 0x2000
	s_mov_b64 s[100:101], s[72:73]
	s_add_i32 s39, s62, s45
	global_load_lds_dwordx4 v158, s[72:73]
	s_add_u32 s72, s72, s16
	s_addc_u32 s73, s73, s17
	s_mov_b32 m0, s39
	s_nop 0
	global_load_lds_dwordx4 v156, s[72:73]
	s_add_i32 m0, s39, 0x2000
	s_nop 0
	global_load_lds_dwordx4 v158, s[72:73]
	s_mov_b32 m0, s47
	s_nop 0
	global_load_lds_dwordx4 v160, s[14:15]
	s_mov_b32 m0, s48
	s_nop 0
	global_load_lds_dwordx4 v162, s[14:15]
	s_waitcnt vmcnt(8)
	s_waitcnt lgkmcnt(0)
	s_barrier
	s_setprio 1
	v_mfma_f32_16x16x32_bf16 v[64:67], v[68:71], v[206:209], v[64:67]
	v_mfma_f32_16x16x32_bf16 v[60:63], v[76:79], v[206:209], v[60:63]
	v_mfma_f32_16x16x32_bf16 v[48:51], v[68:71], v[214:217], v[48:51]
	v_mfma_f32_16x16x32_bf16 v[44:47], v[76:79], v[214:217], v[44:47]
	v_mfma_f32_16x16x32_bf16 v[32:35], v[68:71], v[222:225], v[32:35]
	v_mfma_f32_16x16x32_bf16 v[28:31], v[76:79], v[222:225], v[28:31]
	v_mfma_f32_16x16x32_bf16 v[16:19], v[68:71], v[230:233], v[16:19]
	v_mfma_f32_16x16x32_bf16 v[12:15], v[76:79], v[230:233], v[12:15]
	v_mfma_f32_16x16x32_bf16 v[64:67], v[72:75], v[210:213], v[64:67]
	v_mfma_f32_16x16x32_bf16 v[60:63], v[80:83], v[210:213], v[60:63]
	v_mfma_f32_16x16x32_bf16 v[48:51], v[72:75], v[218:221], v[48:51]
	v_mfma_f32_16x16x32_bf16 v[44:47], v[80:83], v[218:221], v[44:47]
	v_mfma_f32_16x16x32_bf16 v[32:35], v[72:75], v[226:229], v[32:35]
	v_mfma_f32_16x16x32_bf16 v[28:31], v[80:83], v[226:229], v[28:31]
	v_mfma_f32_16x16x32_bf16 v[16:19], v[72:75], v[234:237], v[16:19]
	v_mfma_f32_16x16x32_bf16 v[12:15], v[80:83], v[234:237], v[12:15]
	v_mfma_f32_16x16x32_bf16 v[56:59], v[84:87], v[206:209], v[56:59]
	v_mfma_f32_16x16x32_bf16 v[52:55], v[182:185], v[206:209], v[52:55]
	v_mfma_f32_16x16x32_bf16 v[40:43], v[84:87], v[214:217], v[40:43]
	v_mfma_f32_16x16x32_bf16 v[36:39], v[182:185], v[214:217], v[36:39]
	v_mfma_f32_16x16x32_bf16 v[24:27], v[84:87], v[222:225], v[24:27]
	v_mfma_f32_16x16x32_bf16 v[20:23], v[182:185], v[222:225], v[20:23]
	v_mfma_f32_16x16x32_bf16 v[8:11], v[84:87], v[230:233], v[8:11]
	v_mfma_f32_16x16x32_bf16 v[4:7], v[182:185], v[230:233], v[4:7]
	v_mfma_f32_16x16x32_bf16 v[56:59], v[88:91], v[210:213], v[56:59]
	v_mfma_f32_16x16x32_bf16 v[52:55], v[202:205], v[210:213], v[52:55]
	v_mfma_f32_16x16x32_bf16 v[40:43], v[88:91], v[218:221], v[40:43]
	v_mfma_f32_16x16x32_bf16 v[36:39], v[202:205], v[218:221], v[36:39]
	v_mfma_f32_16x16x32_bf16 v[24:27], v[88:91], v[226:229], v[24:27]
	v_mfma_f32_16x16x32_bf16 v[20:23], v[202:205], v[226:229], v[20:23]
	v_mfma_f32_16x16x32_bf16 v[8:11], v[88:91], v[234:237], v[8:11]
	v_mfma_f32_16x16x32_bf16 v[4:7], v[202:205], v[234:237], v[4:7]
	s_setprio 0
	s_barrier
; #define PG8_STAGE(bufoff, gbase, voff) do { _Pragma("unroll") for (int _i = 0; _i < 2; ++_i) \
;         __builtin_amdgcn_global_load_lds((const unsigned*)((const char*)(gbase) + (voff)[_i]), (PG8_LAS unsigned*)(lds + (bufoff) + ldsw + _i * 8192), 16, 0, 0); } while (0)
; #define PG8_LDA(dst, b, h) do { _Pragma("unroll") for (int m = 0; m < 4; ++m) _Pragma("unroll") for (int k = 0; k < 2; ++k) dst[m][k] = *(const PG8_LAS bf16x8*)(lds + PG8_SA(b, h) + aoff + m * 2048 + k * 1024); } while (0)
; #define PG8_LDB(dst, b, h) do { _Pragma("unroll") for (int n = 0; n < 2; ++n) _Pragma("unroll") for (int k = 0; k < 2; ++k) dst[n][k] = *(const PG8_LAS bf16x8*)(lds + PG8_SB(b, h) + boff + n * 2048 + k * 1024); } while (0)
; #define PG8_MMA(ai, bj, At, Bt) do { __builtin_amdgcn_s_setprio(1); _Pragma("unroll") for (int m = 0; m < 4; ++m) _Pragma("unroll") for (int n = 0; n < 2; ++n) _Pragma("unroll") for (int k = 0; k < 2; ++k) \
;         acc[ai][bj][m][n] = __builtin_amdgcn_mfma_f32_16x16x32_bf16(Bt[n][k], At[m][k], acc[ai][bj][m][n], 0, 0, 0); __builtin_amdgcn_s_setprio(0); } while (0)
; #define PG8_WAIT_V(n) asm volatile("s_waitcnt vmcnt(" #n ")" ::: "memory")
; #define PG8_WAIT_L(n) asm volatile("s_waitcnt lgkmcnt(" #n ")" ::: "memory")
; #define PG8_BAR __builtin_amdgcn_s_barrier()
; #define PG8_SCHED __builtin_amdgcn_sched_barrier(0)
; template <class Epi, class Sched, bool ALIGN_EPI = false, bool SP2 = false>
; __device__ __forceinline__ void gemm_phase(PG8_LAS unsigned char* lds, const Gemm g, const Sched& S, const Epi& E) {
;     ...
;             PG8_LDB(B0, 1, 0); PG8_LDB(B1, 1, 1); PG8_SCHED; PG8_LDA(At, 1, 0); PG8_STAGE(PG8_SA(0, 1), a2 + hstepA, voffA);
;             PG8_WAIT_V(8); PG8_WAIT_L(0); PG8_BAR; PG8_MMA(0, 0, At, B0); PG8_MMA(0, 1, At, B1); PG8_BAR; PG8_SCHED;
;             PG8_LDA(At, 1, 1); PG8_STAGE(PG8_SB(1, 0), b3, voffB); PG8_STAGE(PG8_SB(1, 1), b3 + hstep, voffB); PG8_STAGE(PG8_SA(1, 0), a3, voffA);
;             PG8_WAIT_V(8); PG8_WAIT_L(0); PG8_BAR; PG8_MMA(1, 0, At, B0); PG8_MMA(1, 1, At, B1); PG8_BAR; PG8_SCHED;
	s_add_i32 s39, 0, 0x18000
	s_add_i32 s71, 0, 0x1c000
	v_add_u32_e32 v80, s39, v191
	v_add_u32_e32 v164, s71, v191
	ds_read_b128 v[68:71], v80
	ds_read_b128 v[72:75], v80 offset:1024
	ds_read_b128 v[76:79], v80 offset:2048
	ds_read_b128 v[80:83], v80 offset:3072
	ds_read_b128 v[84:87], v164
	ds_read_b128 v[88:91], v164 offset:1024
	ds_read_b128 v[182:185], v164 offset:2048
	ds_read_b128 v[202:205], v164 offset:3072
	s_mov_b64 vcc, s[14:15]
	s_add_u32 s14, s14, 0x10000
	s_addc_u32 s15, s15, 0
	s_mov_b32 m0, s49
	ds_read_b128 v[206:209], v198 offset:32768
	ds_read_b128 v[210:213], v198 offset:33792
	ds_read_b128 v[214:217], v198 offset:34816
	ds_read_b128 v[218:221], v198 offset:35840
	ds_read_b128 v[222:225], v198 offset:36864
	ds_read_b128 v[226:229], v198 offset:37888
	ds_read_b128 v[230:233], v198 offset:38912
	ds_read_b128 v[234:237], v198 offset:39936
	global_load_lds_dwordx4 v160, s[14:15]
	s_mov_b32 m0, s50
	s_nop 0
	global_load_lds_dwordx4 v162, s[14:15]
	s_waitcnt vmcnt(8)
	s_waitcnt lgkmcnt(0)
	s_barrier
	s_setprio 1
	v_mfma_f32_16x16x32_bf16 v[152:155], v[68:71], v[206:209], v[152:155]
	v_mfma_f32_16x16x32_bf16 v[148:151], v[76:79], v[206:209], v[148:151]
	v_mfma_f32_16x16x32_bf16 v[136:139], v[68:71], v[214:217], v[136:139]
	v_mfma_f32_16x16x32_bf16 v[132:135], v[76:79], v[214:217], v[132:135]
	v_mfma_f32_16x16x32_bf16 v[120:123], v[68:71], v[222:225], v[120:123]
	v_mfma_f32_16x16x32_bf16 v[116:119], v[76:79], v[222:225], v[116:119]
	v_mfma_f32_16x16x32_bf16 v[104:107], v[68:71], v[230:233], v[104:107]
	v_mfma_f32_16x16x32_bf16 v[100:103], v[76:79], v[230:233], v[100:103]
	v_mfma_f32_16x16x32_bf16 v[152:155], v[72:75], v[210:213], v[152:155]
	v_mfma_f32_16x16x32_bf16 v[148:151], v[80:83], v[210:213], v[148:151]
	v_mfma_f32_16x16x32_bf16 v[136:139], v[72:75], v[218:221], v[136:139]
	v_mfma_f32_16x16x32_bf16 v[132:135], v[80:83], v[218:221], v[132:135]
	v_mfma_f32_16x16x32_bf16 v[120:123], v[72:75], v[226:229], v[120:123]
	v_mfma_f32_16x16x32_bf16 v[116:119], v[80:83], v[226:229], v[116:119]
	v_mfma_f32_16x16x32_bf16 v[104:107], v[72:75], v[234:237], v[104:107]
	v_mfma_f32_16x16x32_bf16 v[100:103], v[80:83], v[234:237], v[100:103]
	v_mfma_f32_16x16x32_bf16 v[144:147], v[84:87], v[206:209], v[144:147]
	v_mfma_f32_16x16x32_bf16 v[140:143], v[182:185], v[206:209], v[140:143]
	v_mfma_f32_16x16x32_bf16 v[128:131], v[84:87], v[214:217], v[128:131]
	v_mfma_f32_16x16x32_bf16 v[124:127], v[182:185], v[214:217], v[124:127]
	v_mfma_f32_16x16x32_bf16 v[112:115], v[84:87], v[222:225], v[112:115]
	v_mfma_f32_16x16x32_bf16 v[108:111], v[182:185], v[222:225], v[108:111]
	v_mfma_f32_16x16x32_bf16 v[96:99], v[84:87], v[230:233], v[96:99]
	v_mfma_f32_16x16x32_bf16 v[92:95], v[182:185], v[230:233], v[92:95]
	v_mfma_f32_16x16x32_bf16 v[144:147], v[88:91], v[210:213], v[144:147]
	v_mfma_f32_16x16x32_bf16 v[140:143], v[202:205], v[210:213], v[140:143]
	v_mfma_f32_16x16x32_bf16 v[128:131], v[88:91], v[218:221], v[128:131]
	v_mfma_f32_16x16x32_bf16 v[124:127], v[202:205], v[218:221], v[124:127]
	v_mfma_f32_16x16x32_bf16 v[112:115], v[88:91], v[226:229], v[112:115]
	v_mfma_f32_16x16x32_bf16 v[108:111], v[202:205], v[226:229], v[108:111]
	v_mfma_f32_16x16x32_bf16 v[96:99], v[88:91], v[234:237], v[96:99]
	v_mfma_f32_16x16x32_bf16 v[92:95], v[202:205], v[234:237], v[92:95]
	s_setprio 0
	s_barrier
	s_add_i32 s14, s39, s45
	s_add_i32 m0, s14, 0xffffff80
	ds_read_b128 v[206:209], v198 offset:49152
	ds_read_b128 v[210:213], v198 offset:50176
	ds_read_b128 v[214:217], v198 offset:51200
	ds_read_b128 v[218:221], v198 offset:52224
	ds_read_b128 v[222:225], v198 offset:53248
	ds_read_b128 v[226:229], v198 offset:54272
	ds_read_b128 v[230:233], v198 offset:55296
	ds_read_b128 v[234:237], v198 offset:56320
	global_load_lds_dwordx4 v156, s[100:101] offset:128
	s_add_i32 m0, s14, 0x1f80
	s_add_i32 s14, s71, s45
	global_load_lds_dwordx4 v158, s[100:101] offset:128
	s_add_i32 m0, s14, 0xffffff80
	s_nop 0
	global_load_lds_dwordx4 v156, s[72:73] offset:128
	s_add_i32 m0, s14, 0x1f80
	s_nop 0
	global_load_lds_dwordx4 v158, s[72:73] offset:128
	s_add_i32 m0, s56, 0xffffff80
	s_nop 0
	global_load_lds_dwordx4 v160, vcc offset:128
	s_add_i32 m0, s57, 0xffffff80
	s_nop 0
	global_load_lds_dwordx4 v162, vcc offset:128
	s_waitcnt vmcnt(8)
	s_waitcnt lgkmcnt(0)
	s_barrier
	s_setprio 1
	v_mfma_f32_16x16x32_bf16 v[64:67], v[68:71], v[206:209], v[64:67]
	v_mfma_f32_16x16x32_bf16 v[60:63], v[76:79], v[206:209], v[60:63]
	v_mfma_f32_16x16x32_bf16 v[48:51], v[68:71], v[214:217], v[48:51]
	v_mfma_f32_16x16x32_bf16 v[44:47], v[76:79], v[214:217], v[44:47]
	v_mfma_f32_16x16x32_bf16 v[32:35], v[68:71], v[222:225], v[32:35]
	v_mfma_f32_16x16x32_bf16 v[28:31], v[76:79], v[222:225], v[28:31]
	v_mfma_f32_16x16x32_bf16 v[16:19], v[68:71], v[230:233], v[16:19]
	v_mfma_f32_16x16x32_bf16 v[12:15], v[76:79], v[230:233], v[12:15]
	v_mfma_f32_16x16x32_bf16 v[64:67], v[72:75], v[210:213], v[64:67]
	v_mfma_f32_16x16x32_bf16 v[60:63], v[80:83], v[210:213], v[60:63]
	v_mfma_f32_16x16x32_bf16 v[48:51], v[72:75], v[218:221], v[48:51]
	v_mfma_f32_16x16x32_bf16 v[44:47], v[80:83], v[218:221], v[44:47]
	v_mfma_f32_16x16x32_bf16 v[32:35], v[72:75], v[226:229], v[32:35]
	v_mfma_f32_16x16x32_bf16 v[28:31], v[80:83], v[226:229], v[28:31]
	v_mfma_f32_16x16x32_bf16 v[16:19], v[72:75], v[234:237], v[16:19]
	v_mfma_f32_16x16x32_bf16 v[12:15], v[80:83], v[234:237], v[12:15]
	v_mfma_f32_16x16x32_bf16 v[56:59], v[84:87], v[206:209], v[56:59]
	v_mfma_f32_16x16x32_bf16 v[52:55], v[182:185], v[206:209], v[52:55]
	v_mfma_f32_16x16x32_bf16 v[40:43], v[84:87], v[214:217], v[40:43]
	v_mfma_f32_16x16x32_bf16 v[36:39], v[182:185], v[214:217], v[36:39]
	v_mfma_f32_16x16x32_bf16 v[24:27], v[84:87], v[222:225], v[24:27]
	v_mfma_f32_16x16x32_bf16 v[20:23], v[182:185], v[222:225], v[20:23]
	v_mfma_f32_16x16x32_bf16 v[8:11], v[84:87], v[230:233], v[8:11]
	v_mfma_f32_16x16x32_bf16 v[4:7], v[182:185], v[230:233], v[4:7]
	v_mfma_f32_16x16x32_bf16 v[56:59], v[88:91], v[210:213], v[56:59]
	v_mfma_f32_16x16x32_bf16 v[52:55], v[202:205], v[210:213], v[52:55]
	v_mfma_f32_16x16x32_bf16 v[40:43], v[88:91], v[218:221], v[40:43]
	v_mfma_f32_16x16x32_bf16 v[36:39], v[202:205], v[218:221], v[36:39]
	v_mfma_f32_16x16x32_bf16 v[24:27], v[88:91], v[226:229], v[24:27]
	v_mfma_f32_16x16x32_bf16 v[20:23], v[202:205], v[226:229], v[20:23]
	v_mfma_f32_16x16x32_bf16 v[8:11], v[88:91], v[234:237], v[8:11]
	v_mfma_f32_16x16x32_bf16 v[4:7], v[202:205], v[234:237], v[4:7]
	s_setprio 0
	s_barrier
	s_add_u32 s4, s4, 0x100
	s_addc_u32 s5, s5, 0
	s_add_u32 s36, s36, 0x100
	s_addc_u32 s37, s37, 0
	s_cmp_ge_i32 s38, s54
	s_mov_b32 s14, s38
	s_cbranch_scc0 .LBB0_1501

; #define PG8_STAGE(bufoff, gbase, voff) do { _Pragma("unroll") for (int _i = 0; _i < 2; ++_i) \
;         __builtin_amdgcn_global_load_lds((const unsigned*)((const char*)(gbase) + (voff)[_i]), (PG8_LAS unsigned*)(lds + (bufoff) + ldsw + _i * 8192), 16, 0, 0); } while (0)
; #define PG8_LDA(dst, b, h) do { _Pragma("unroll") for (int m = 0; m < 4; ++m) _Pragma("unroll") for (int k = 0; k < 2; ++k) dst[m][k] = *(const PG8_LAS bf16x8*)(lds + PG8_SA(b, h) + aoff + m * 2048 + k * 1024); } while (0)
; #define PG8_LDB(dst, b, h) do { _Pragma("unroll") for (int n = 0; n < 2; ++n) _Pragma("unroll") for (int k = 0; k < 2; ++k) dst[n][k] = *(const PG8_LAS bf16x8*)(lds + PG8_SB(b, h) + boff + n * 2048 + k * 1024); } while (0)
; #define PG8_MMA(ai, bj, At, Bt) do { __builtin_amdgcn_s_setprio(1); _Pragma("unroll") for (int m = 0; m < 4; ++m) _Pragma("unroll") for (int n = 0; n < 2; ++n) _Pragma("unroll") for (int k = 0; k < 2; ++k) \
;         acc[ai][bj][m][n] = __builtin_amdgcn_mfma_f32_16x16x32_bf16(Bt[n][k], At[m][k], acc[ai][bj][m][n], 0, 0, 0); __builtin_amdgcn_s_setprio(0); } while (0)
; #define PG8_WAIT_V(n) asm volatile("s_waitcnt vmcnt(" #n ")" ::: "memory")
; #define PG8_WAIT_L(n) asm volatile("s_waitcnt lgkmcnt(" #n ")" ::: "memory")
; template <class Epi, class Sched, bool ALIGN_EPI = false, bool SP2 = false>
; __device__ __forceinline__ void gemm_phase(PG8_LAS unsigned char* lds, const Gemm g, const Sched& S, const Epi& E) {
;     ...
;             const bool last = (t == nt - 2);
;             const char* a1 = cA + (size_t)(t + 1) * kstep;
;             const char* a2 = last ? nA : cA + (size_t)(t + 2) * kstep; const char* b2 = last ? nB : cB + (size_t)(t + 2) * kstep;
;             const char* a3 = a2 + kstep; const char* b3 = b2 + kstep;
;             if (last && has_next) S.a_ready(nxt);
;             if constexpr (SP2) {
;             PG8_LDB(B0, 0, 0); PG8_LDB(B1, 0, 1); PG8_SCHED; PG8_LDA(At, 0, 0); PG8_STAGE(PG8_SA(1, 1), a1 + hstepA, voffA);
;             PG8_WAIT_V(8); PG8_WAIT_L(0); PG8_BAR; PG8_MMA(0, 0, At, B0); PG8_MMA(0, 1, At, B1); PG8_BAR; PG8_SCHED;
;             PG8_LDA(At, 0, 1); PG8_STAGE(PG8_SB(0, 0), b2, voffB); PG8_STAGE(PG8_SB(0, 1), b2 + hstep, voffB); PG8_STAGE(PG8_SA(0, 0), a2, voffA);
;             PG8_WAIT_V(8); PG8_WAIT_L(0); PG8_BAR; PG8_MMA(1, 0, At, B0); PG8_MMA(1, 1, At, B1); PG8_BAR; PG8_SCHED;
.LBB0_1679:
	ds_read_b128 v[120:123], v169
	ds_read_b128 v[128:131], v169 offset:1024
	ds_read_b128 v[136:139], v169 offset:2048
	ds_read_b128 v[140:143], v169 offset:3072
	ds_read_b128 v[160:163], v170
	ds_read_b128 v[172:175], v170 offset:1024
	ds_read_b128 v[176:179], v170 offset:2048
	ds_read_b128 v[180:183], v170 offset:3072
	s_add_i32 s90, s68, 2
	s_add_u32 s91, s8, 0xfffc0080
	s_addc_u32 s69, s9, -1
	s_cmp_eq_u32 s84, s68
	s_cselect_b32 s68, s89, s91
	s_cselect_b32 s69, s61, s69
	s_cselect_b32 s93, s63, s71
	s_cselect_b32 s92, s62, s70
	s_add_i32 m0, s67, 0xc000
	ds_read_b128 v[184:187], v171
	ds_read_b128 v[190:193], v171 offset:1024
	ds_read_b128 v[194:197], v171 offset:2048
	ds_read_b128 v[198:201], v171 offset:3072
	ds_read_b128 v[202:205], v171 offset:4096
	ds_read_b128 v[206:209], v171 offset:5120
	ds_read_b128 v[210:213], v171 offset:6144
	ds_read_b128 v[214:217], v171 offset:7168
	global_load_lds_dwordx4 v152, s[8:9]
	s_add_i32 m0, s67, 0xe000
	s_nop 0
	global_load_lds_dwordx4 v154, s[8:9]
	s_waitcnt vmcnt(8)
	s_waitcnt lgkmcnt(0)
	s_barrier
	s_setprio 1
	v_mfma_f32_16x16x32_bf16 v[132:135], v[120:123], v[184:187], v[132:135]
	v_mfma_f32_16x16x32_bf16 v[124:127], v[136:139], v[184:187], v[124:127]
	v_mfma_f32_16x16x32_bf16 v[108:111], v[120:123], v[194:197], v[108:111]
	v_mfma_f32_16x16x32_bf16 v[104:107], v[136:139], v[194:197], v[104:107]
	v_mfma_f32_16x16x32_bf16 v[92:95], v[120:123], v[202:205], v[92:95]
	v_mfma_f32_16x16x32_bf16 v[88:91], v[136:139], v[202:205], v[88:91]
	v_mfma_f32_16x16x32_bf16 v[76:79], v[120:123], v[210:213], v[76:79]
	v_mfma_f32_16x16x32_bf16 v[72:75], v[136:139], v[210:213], v[72:75]
	v_mfma_f32_16x16x32_bf16 v[132:135], v[128:131], v[190:193], v[132:135]
	v_mfma_f32_16x16x32_bf16 v[124:127], v[140:143], v[190:193], v[124:127]
	v_mfma_f32_16x16x32_bf16 v[108:111], v[128:131], v[198:201], v[108:111]
	v_mfma_f32_16x16x32_bf16 v[104:107], v[140:143], v[198:201], v[104:107]
	v_mfma_f32_16x16x32_bf16 v[92:95], v[128:131], v[206:209], v[92:95]
	v_mfma_f32_16x16x32_bf16 v[88:91], v[140:143], v[206:209], v[88:91]
	v_mfma_f32_16x16x32_bf16 v[76:79], v[128:131], v[214:217], v[76:79]
	v_mfma_f32_16x16x32_bf16 v[72:75], v[140:143], v[214:217], v[72:75]
	v_mfma_f32_16x16x32_bf16 v[116:119], v[160:163], v[184:187], v[116:119]
	v_mfma_f32_16x16x32_bf16 v[112:115], v[176:179], v[184:187], v[112:115]
	v_mfma_f32_16x16x32_bf16 v[100:103], v[160:163], v[194:197], v[100:103]
	v_mfma_f32_16x16x32_bf16 v[96:99], v[176:179], v[194:197], v[96:99]
	v_mfma_f32_16x16x32_bf16 v[84:87], v[160:163], v[202:205], v[84:87]
	v_mfma_f32_16x16x32_bf16 v[80:83], v[176:179], v[202:205], v[80:83]
	v_mfma_f32_16x16x32_bf16 v[68:71], v[160:163], v[210:213], v[68:71]
	v_mfma_f32_16x16x32_bf16 v[64:67], v[176:179], v[210:213], v[64:67]
	v_mfma_f32_16x16x32_bf16 v[116:119], v[172:175], v[190:193], v[116:119]
	v_mfma_f32_16x16x32_bf16 v[112:115], v[180:183], v[190:193], v[112:115]
	v_mfma_f32_16x16x32_bf16 v[100:103], v[172:175], v[198:201], v[100:103]
	v_mfma_f32_16x16x32_bf16 v[96:99], v[180:183], v[198:201], v[96:99]
	v_mfma_f32_16x16x32_bf16 v[84:87], v[172:175], v[206:209], v[84:87]
	v_mfma_f32_16x16x32_bf16 v[80:83], v[180:183], v[206:209], v[80:83]
	v_mfma_f32_16x16x32_bf16 v[68:71], v[172:175], v[214:217], v[68:71]
	v_mfma_f32_16x16x32_bf16 v[64:67], v[180:183], v[214:217], v[64:67]
	s_setprio 0
	s_barrier
	s_add_i32 s91, s85, s73
	s_mov_b32 m0, s91
	ds_read_b128 v[184:187], v171 offset:16384
	ds_read_b128 v[190:193], v171 offset:17408
	ds_read_b128 v[194:197], v171 offset:18432
	ds_read_b128 v[198:201], v171 offset:19456
	ds_read_b128 v[202:205], v171 offset:20480
	ds_read_b128 v[206:209], v171 offset:21504
	ds_read_b128 v[210:213], v171 offset:22528
	ds_read_b128 v[214:217], v171 offset:23552
	global_load_lds_dwordx4 v150, s[92:93]
	s_add_i32 m0, s91, 0x2000
	s_mov_b64 s[100:101], s[92:93]
	s_add_i32 s91, s86, s73
	global_load_lds_dwordx4 v148, s[92:93]
	s_add_u32 s92, s92, s10
	s_addc_u32 s93, s93, s11
	s_mov_b32 m0, s91
	s_nop 0
	global_load_lds_dwordx4 v150, s[92:93]
	s_add_i32 m0, s91, 0x2000
	s_nop 0
	global_load_lds_dwordx4 v148, s[92:93]
	s_mov_b32 m0, s67
	s_nop 0
	global_load_lds_dwordx4 v144, s[68:69]
	s_mov_b32 m0, s75
	s_nop 0
	global_load_lds_dwordx4 v146, s[68:69]
	s_waitcnt vmcnt(8)
	s_waitcnt lgkmcnt(0)
	s_barrier
	s_setprio 1
	v_mfma_f32_16x16x32_bf16 v[60:63], v[120:123], v[184:187], v[60:63]
	v_mfma_f32_16x16x32_bf16 v[56:59], v[136:139], v[184:187], v[56:59]
	v_mfma_f32_16x16x32_bf16 v[44:47], v[120:123], v[194:197], v[44:47]
	v_mfma_f32_16x16x32_bf16 v[40:43], v[136:139], v[194:197], v[40:43]
	v_mfma_f32_16x16x32_bf16 v[28:31], v[120:123], v[202:205], v[28:31]
	v_mfma_f32_16x16x32_bf16 v[24:27], v[136:139], v[202:205], v[24:27]
	v_mfma_f32_16x16x32_bf16 v[12:15], v[120:123], v[210:213], v[12:15]
	v_mfma_f32_16x16x32_bf16 v[8:11], v[136:139], v[210:213], v[8:11]
	v_mfma_f32_16x16x32_bf16 v[60:63], v[128:131], v[190:193], v[60:63]
	v_mfma_f32_16x16x32_bf16 v[56:59], v[140:143], v[190:193], v[56:59]
	v_mfma_f32_16x16x32_bf16 v[44:47], v[128:131], v[198:201], v[44:47]
	v_mfma_f32_16x16x32_bf16 v[40:43], v[140:143], v[198:201], v[40:43]
	v_mfma_f32_16x16x32_bf16 v[28:31], v[128:131], v[206:209], v[28:31]
	v_mfma_f32_16x16x32_bf16 v[24:27], v[140:143], v[206:209], v[24:27]
	v_mfma_f32_16x16x32_bf16 v[12:15], v[128:131], v[214:217], v[12:15]
	v_mfma_f32_16x16x32_bf16 v[8:11], v[140:143], v[214:217], v[8:11]
	v_mfma_f32_16x16x32_bf16 v[52:55], v[160:163], v[184:187], v[52:55]
	v_mfma_f32_16x16x32_bf16 v[48:51], v[176:179], v[184:187], v[48:51]
	v_mfma_f32_16x16x32_bf16 v[36:39], v[160:163], v[194:197], v[36:39]
	v_mfma_f32_16x16x32_bf16 v[32:35], v[176:179], v[194:197], v[32:35]
	v_mfma_f32_16x16x32_bf16 v[20:23], v[160:163], v[202:205], v[20:23]
	v_mfma_f32_16x16x32_bf16 v[16:19], v[176:179], v[202:205], v[16:19]
	v_mfma_f32_16x16x32_bf16 v[4:7], v[160:163], v[210:213], v[4:7]
	v_mfma_f32_16x16x32_bf16 v[0:3], v[176:179], v[210:213], v[0:3]
	v_mfma_f32_16x16x32_bf16 v[52:55], v[172:175], v[190:193], v[52:55]
	v_mfma_f32_16x16x32_bf16 v[48:51], v[180:183], v[190:193], v[48:51]
	v_mfma_f32_16x16x32_bf16 v[36:39], v[172:175], v[198:201], v[36:39]
	v_mfma_f32_16x16x32_bf16 v[32:35], v[180:183], v[198:201], v[32:35]
	v_mfma_f32_16x16x32_bf16 v[20:23], v[172:175], v[206:209], v[20:23]
	v_mfma_f32_16x16x32_bf16 v[16:19], v[180:183], v[206:209], v[16:19]
	v_mfma_f32_16x16x32_bf16 v[4:7], v[172:175], v[214:217], v[4:7]
	v_mfma_f32_16x16x32_bf16 v[0:3], v[180:183], v[214:217], v[0:3]
	s_setprio 0
	s_barrier
; #define PG8_STAGE(bufoff, gbase, voff) do { _Pragma("unroll") for (int _i = 0; _i < 2; ++_i) \
;         __builtin_amdgcn_global_load_lds((const unsigned*)((const char*)(gbase) + (voff)[_i]), (PG8_LAS unsigned*)(lds + (bufoff) + ldsw + _i * 8192), 16, 0, 0); } while (0)
; #define PG8_LDA(dst, b, h) do { _Pragma("unroll") for (int m = 0; m < 4; ++m) _Pragma("unroll") for (int k = 0; k < 2; ++k) dst[m][k] = *(const PG8_LAS bf16x8*)(lds + PG8_SA(b, h) + aoff + m * 2048 + k * 1024); } while (0)
; #define PG8_LDB(dst, b, h) do { _Pragma("unroll") for (int n = 0; n < 2; ++n) _Pragma("unroll") for (int k = 0; k < 2; ++k) dst[n][k] = *(const PG8_LAS bf16x8*)(lds + PG8_SB(b, h) + boff + n * 2048 + k * 1024); } while (0)
; #define PG8_MMA(ai, bj, At, Bt) do { __builtin_amdgcn_s_setprio(1); _Pragma("unroll") for (int m = 0; m < 4; ++m) _Pragma("unroll") for (int n = 0; n < 2; ++n) _Pragma("unroll") for (int k = 0; k < 2; ++k) \
;         acc[ai][bj][m][n] = __builtin_amdgcn_mfma_f32_16x16x32_bf16(Bt[n][k], At[m][k], acc[ai][bj][m][n], 0, 0, 0); __builtin_amdgcn_s_setprio(0); } while (0)
; #define PG8_WAIT_V(n) asm volatile("s_waitcnt vmcnt(" #n ")" ::: "memory")
; #define PG8_WAIT_L(n) asm volatile("s_waitcnt lgkmcnt(" #n ")" ::: "memory")
; #define PG8_BAR __builtin_amdgcn_s_barrier()
; #define PG8_SCHED __builtin_amdgcn_sched_barrier(0)
; template <class Epi, class Sched, bool ALIGN_EPI = false, bool SP2 = false>
; __device__ __forceinline__ void gemm_phase(PG8_LAS unsigned char* lds, const Gemm g, const Sched& S, const Epi& E) {
;     ...
;             PG8_LDB(B0, 1, 0); PG8_LDB(B1, 1, 1); PG8_SCHED; PG8_LDA(At, 1, 0); PG8_STAGE(PG8_SA(0, 1), a2 + hstepA, voffA);
;             PG8_WAIT_V(8); PG8_WAIT_L(0); PG8_BAR; PG8_MMA(0, 0, At, B0); PG8_MMA(0, 1, At, B1); PG8_BAR; PG8_SCHED;
;             PG8_LDA(At, 1, 1); PG8_STAGE(PG8_SB(1, 0), b3, voffB); PG8_STAGE(PG8_SB(1, 1), b3 + hstep, voffB); PG8_STAGE(PG8_SA(1, 0), a3, voffA);
;             PG8_WAIT_V(8); PG8_WAIT_L(0); PG8_BAR; PG8_MMA(1, 0, At, B0); PG8_MMA(1, 1, At, B1); PG8_BAR; PG8_SCHED;
	s_add_i32 s91, 0, 0x18000
	s_add_i32 s92, 0, 0x1c000
	v_add_u32_e32 v140, s91, v167
	v_add_u32_e32 v180, s92, v167
	ds_read_b128 v[120:123], v140
	ds_read_b128 v[128:131], v140 offset:1024
	ds_read_b128 v[136:139], v140 offset:2048
	ds_read_b128 v[140:143], v140 offset:3072
	ds_read_b128 v[160:163], v180
	ds_read_b128 v[172:175], v180 offset:1024
	ds_read_b128 v[176:179], v180 offset:2048
	ds_read_b128 v[180:183], v180 offset:3072
	s_mov_b64 vcc, s[68:69]
	s_add_u32 s68, s68, 0x40000
	s_addc_u32 s69, s69, 0
	s_mov_b32 m0, s76
	ds_read_b128 v[184:187], v171 offset:32768
	ds_read_b128 v[190:193], v171 offset:33792
	ds_read_b128 v[194:197], v171 offset:34816
	ds_read_b128 v[198:201], v171 offset:35840
	ds_read_b128 v[202:205], v171 offset:36864
	ds_read_b128 v[206:209], v171 offset:37888
	ds_read_b128 v[210:213], v171 offset:38912
	ds_read_b128 v[214:217], v171 offset:39936
	global_load_lds_dwordx4 v144, s[68:69]
	s_mov_b32 m0, s77
	s_nop 0
	global_load_lds_dwordx4 v146, s[68:69]
	s_waitcnt vmcnt(8)
	s_waitcnt lgkmcnt(0)
	s_barrier
	s_setprio 1
	v_mfma_f32_16x16x32_bf16 v[132:135], v[120:123], v[184:187], v[132:135]
	v_mfma_f32_16x16x32_bf16 v[124:127], v[136:139], v[184:187], v[124:127]
	v_mfma_f32_16x16x32_bf16 v[108:111], v[120:123], v[194:197], v[108:111]
	v_mfma_f32_16x16x32_bf16 v[104:107], v[136:139], v[194:197], v[104:107]
	v_mfma_f32_16x16x32_bf16 v[92:95], v[120:123], v[202:205], v[92:95]
	v_mfma_f32_16x16x32_bf16 v[88:91], v[136:139], v[202:205], v[88:91]
	v_mfma_f32_16x16x32_bf16 v[76:79], v[120:123], v[210:213], v[76:79]
	v_mfma_f32_16x16x32_bf16 v[72:75], v[136:139], v[210:213], v[72:75]
	v_mfma_f32_16x16x32_bf16 v[132:135], v[128:131], v[190:193], v[132:135]
	v_mfma_f32_16x16x32_bf16 v[124:127], v[140:143], v[190:193], v[124:127]
	v_mfma_f32_16x16x32_bf16 v[108:111], v[128:131], v[198:201], v[108:111]
	v_mfma_f32_16x16x32_bf16 v[104:107], v[140:143], v[198:201], v[104:107]
	v_mfma_f32_16x16x32_bf16 v[92:95], v[128:131], v[206:209], v[92:95]
	v_mfma_f32_16x16x32_bf16 v[88:91], v[140:143], v[206:209], v[88:91]
	v_mfma_f32_16x16x32_bf16 v[76:79], v[128:131], v[214:217], v[76:79]
	v_mfma_f32_16x16x32_bf16 v[72:75], v[140:143], v[214:217], v[72:75]
	v_mfma_f32_16x16x32_bf16 v[116:119], v[160:163], v[184:187], v[116:119]
	v_mfma_f32_16x16x32_bf16 v[112:115], v[176:179], v[184:187], v[112:115]
	v_mfma_f32_16x16x32_bf16 v[100:103], v[160:163], v[194:197], v[100:103]
	v_mfma_f32_16x16x32_bf16 v[96:99], v[176:179], v[194:197], v[96:99]
	v_mfma_f32_16x16x32_bf16 v[84:87], v[160:163], v[202:205], v[84:87]
	v_mfma_f32_16x16x32_bf16 v[80:83], v[176:179], v[202:205], v[80:83]
	v_mfma_f32_16x16x32_bf16 v[68:71], v[160:163], v[210:213], v[68:71]
	v_mfma_f32_16x16x32_bf16 v[64:67], v[176:179], v[210:213], v[64:67]
	v_mfma_f32_16x16x32_bf16 v[116:119], v[172:175], v[190:193], v[116:119]
	v_mfma_f32_16x16x32_bf16 v[112:115], v[180:183], v[190:193], v[112:115]
	v_mfma_f32_16x16x32_bf16 v[100:103], v[172:175], v[198:201], v[100:103]
	v_mfma_f32_16x16x32_bf16 v[96:99], v[180:183], v[198:201], v[96:99]
	v_mfma_f32_16x16x32_bf16 v[84:87], v[172:175], v[206:209], v[84:87]
	v_mfma_f32_16x16x32_bf16 v[80:83], v[180:183], v[206:209], v[80:83]
	v_mfma_f32_16x16x32_bf16 v[68:71], v[172:175], v[214:217], v[68:71]
	v_mfma_f32_16x16x32_bf16 v[64:67], v[180:183], v[214:217], v[64:67]
	s_setprio 0
	s_barrier
	s_add_i32 s68, s91, s73
	s_add_i32 m0, s68, 0xffffff80
	ds_read_b128 v[184:187], v171 offset:49152
	ds_read_b128 v[190:193], v171 offset:50176
	ds_read_b128 v[194:197], v171 offset:51200
	ds_read_b128 v[198:201], v171 offset:52224
	ds_read_b128 v[202:205], v171 offset:53248
	ds_read_b128 v[206:209], v171 offset:54272
	ds_read_b128 v[210:213], v171 offset:55296
	ds_read_b128 v[214:217], v171 offset:56320
	global_load_lds_dwordx4 v150, s[100:101] offset:128
	s_add_i32 m0, s68, 0x1f80
	s_add_i32 s68, s92, s73
	global_load_lds_dwordx4 v148, s[100:101] offset:128
	s_add_u32 s100, s100, s10
	s_addc_u32 s101, s101, s11
	s_add_i32 m0, s68, 0xffffff80
	s_nop 0
	global_load_lds_dwordx4 v150, s[100:101] offset:128
	s_add_i32 m0, s68, 0x1f80
	s_nop 0
	global_load_lds_dwordx4 v148, s[100:101] offset:128
	s_add_i32 m0, s80, 0xffffff80
	s_nop 0
	global_load_lds_dwordx4 v144, vcc offset:128
	s_add_i32 m0, s81, 0xffffff80
	s_nop 0
	global_load_lds_dwordx4 v146, vcc offset:128
	s_waitcnt vmcnt(8)
	s_waitcnt lgkmcnt(0)
	s_barrier
	s_setprio 1
	v_mfma_f32_16x16x32_bf16 v[60:63], v[120:123], v[184:187], v[60:63]
	v_mfma_f32_16x16x32_bf16 v[56:59], v[136:139], v[184:187], v[56:59]
	v_mfma_f32_16x16x32_bf16 v[44:47], v[120:123], v[194:197], v[44:47]
	v_mfma_f32_16x16x32_bf16 v[40:43], v[136:139], v[194:197], v[40:43]
	v_mfma_f32_16x16x32_bf16 v[28:31], v[120:123], v[202:205], v[28:31]
	v_mfma_f32_16x16x32_bf16 v[24:27], v[136:139], v[202:205], v[24:27]
	v_mfma_f32_16x16x32_bf16 v[12:15], v[120:123], v[210:213], v[12:15]
	v_mfma_f32_16x16x32_bf16 v[8:11], v[136:139], v[210:213], v[8:11]
	v_mfma_f32_16x16x32_bf16 v[60:63], v[128:131], v[190:193], v[60:63]
	v_mfma_f32_16x16x32_bf16 v[56:59], v[140:143], v[190:193], v[56:59]
	v_mfma_f32_16x16x32_bf16 v[44:47], v[128:131], v[198:201], v[44:47]
	v_mfma_f32_16x16x32_bf16 v[40:43], v[140:143], v[198:201], v[40:43]
	v_mfma_f32_16x16x32_bf16 v[28:31], v[128:131], v[206:209], v[28:31]
	v_mfma_f32_16x16x32_bf16 v[24:27], v[140:143], v[206:209], v[24:27]
	v_mfma_f32_16x16x32_bf16 v[12:15], v[128:131], v[214:217], v[12:15]
	v_mfma_f32_16x16x32_bf16 v[8:11], v[140:143], v[214:217], v[8:11]
	v_mfma_f32_16x16x32_bf16 v[52:55], v[160:163], v[184:187], v[52:55]
	v_mfma_f32_16x16x32_bf16 v[48:51], v[176:179], v[184:187], v[48:51]
	v_mfma_f32_16x16x32_bf16 v[36:39], v[160:163], v[194:197], v[36:39]
	v_mfma_f32_16x16x32_bf16 v[32:35], v[176:179], v[194:197], v[32:35]
	v_mfma_f32_16x16x32_bf16 v[20:23], v[160:163], v[202:205], v[20:23]
	v_mfma_f32_16x16x32_bf16 v[16:19], v[176:179], v[202:205], v[16:19]
	v_mfma_f32_16x16x32_bf16 v[4:7], v[160:163], v[210:213], v[4:7]
	v_mfma_f32_16x16x32_bf16 v[0:3], v[176:179], v[210:213], v[0:3]
	v_mfma_f32_16x16x32_bf16 v[52:55], v[172:175], v[190:193], v[52:55]
	v_mfma_f32_16x16x32_bf16 v[48:51], v[180:183], v[190:193], v[48:51]
	v_mfma_f32_16x16x32_bf16 v[36:39], v[172:175], v[198:201], v[36:39]
	v_mfma_f32_16x16x32_bf16 v[32:35], v[180:183], v[198:201], v[32:35]
	v_mfma_f32_16x16x32_bf16 v[20:23], v[172:175], v[206:209], v[20:23]
	v_mfma_f32_16x16x32_bf16 v[16:19], v[180:183], v[206:209], v[16:19]
	v_mfma_f32_16x16x32_bf16 v[4:7], v[172:175], v[214:217], v[4:7]
	v_mfma_f32_16x16x32_bf16 v[0:3], v[180:183], v[214:217], v[0:3]
	s_setprio 0
	s_barrier
	s_add_u32 s8, s8, 0x100
	s_addc_u32 s9, s9, 0
	s_add_u32 s70, s70, 0x100
	s_addc_u32 s71, s71, 0
	s_cmp_ge_i32 s90, s83
	s_mov_b32 s68, s90
	s_cbranch_scc0 .LBB0_1679

; #define PG8_STAGE(bufoff, gbase, voff) do { _Pragma("unroll") for (int _i = 0; _i < 2; ++_i) \
;         __builtin_amdgcn_global_load_lds((const unsigned*)((const char*)(gbase) + (voff)[_i]), (PG8_LAS unsigned*)(lds + (bufoff) + ldsw + _i * 8192), 16, 0, 0); } while (0)
; #define PG8_LDA(dst, b, h) do { _Pragma("unroll") for (int m = 0; m < 4; ++m) _Pragma("unroll") for (int k = 0; k < 2; ++k) dst[m][k] = *(const PG8_LAS bf16x8*)(lds + PG8_SA(b, h) + aoff + m * 2048 + k * 1024); } while (0)
; #define PG8_LDB(dst, b, h) do { _Pragma("unroll") for (int n = 0; n < 2; ++n) _Pragma("unroll") for (int k = 0; k < 2; ++k) dst[n][k] = *(const PG8_LAS bf16x8*)(lds + PG8_SB(b, h) + boff + n * 2048 + k * 1024); } while (0)
; #define PG8_MMA(ai, bj, At, Bt) do { __builtin_amdgcn_s_setprio(1); _Pragma("unroll") for (int m = 0; m < 4; ++m) _Pragma("unroll") for (int n = 0; n < 2; ++n) _Pragma("unroll") for (int k = 0; k < 2; ++k) \
;         acc[ai][bj][m][n] = __builtin_amdgcn_mfma_f32_16x16x32_bf16(Bt[n][k], At[m][k], acc[ai][bj][m][n], 0, 0, 0); __builtin_amdgcn_s_setprio(0); } while (0)
; #define PG8_WAIT_V(n) asm volatile("s_waitcnt vmcnt(" #n ")" ::: "memory")
; #define PG8_WAIT_L(n) asm volatile("s_waitcnt lgkmcnt(" #n ")" ::: "memory")
; template <class Epi, class Sched, bool ALIGN_EPI = false, bool SP2 = false>
; __device__ __forceinline__ void gemm_phase(PG8_LAS unsigned char* lds, const Gemm g, const Sched& S, const Epi& E) {
;     ...
;             const bool last = (t == nt - 2);
;             const char* a1 = cA + (size_t)(t + 1) * kstep;
;             const char* a2 = last ? nA : cA + (size_t)(t + 2) * kstep; const char* b2 = last ? nB : cB + (size_t)(t + 2) * kstep;
;             const char* a3 = a2 + kstep; const char* b3 = b2 + kstep;
;             if (last && has_next) S.a_ready(nxt);
;             if constexpr (SP2) {
;             PG8_LDB(B0, 0, 0); PG8_LDB(B1, 0, 1); PG8_SCHED; PG8_LDA(At, 0, 0); PG8_STAGE(PG8_SA(1, 1), a1 + hstepA, voffA);
;             PG8_WAIT_V(8); PG8_WAIT_L(0); PG8_BAR; PG8_MMA(0, 0, At, B0); PG8_MMA(0, 1, At, B1); PG8_BAR; PG8_SCHED;
;             PG8_LDA(At, 0, 1); PG8_STAGE(PG8_SB(0, 0), b2, voffB); PG8_STAGE(PG8_SB(0, 1), b2 + hstep, voffB); PG8_STAGE(PG8_SA(0, 0), a2, voffA);
;             PG8_WAIT_V(8); PG8_WAIT_L(0); PG8_BAR; PG8_MMA(1, 0, At, B0); PG8_MMA(1, 1, At, B1); PG8_BAR; PG8_SCHED;
.LBB0_1815:
	ds_read_b128 v[150:153], v147
	ds_read_b128 v[154:157], v147 offset:1024
	ds_read_b128 v[158:161], v147 offset:2048
	ds_read_b128 v[162:165], v147 offset:3072
	ds_read_b128 v[166:169], v148
	ds_read_b128 v[170:173], v148 offset:1024
	ds_read_b128 v[174:177], v148 offset:2048
	ds_read_b128 v[178:181], v148 offset:3072
	s_add_i32 s57, s30, 2
	s_add_u32 s58, s10, 0xfffc0080
	s_addc_u32 s31, s11, -1
	s_cmp_eq_u32 s50, s30
	s_cselect_b32 s30, s56, s58
	s_cselect_b32 s31, s23, s31
	s_cselect_b32 s59, s25, s35
	s_cselect_b32 s58, s24, s34
	s_add_i32 m0, s29, 0xc000
	ds_read_b128 v[182:185], v149
	ds_read_b128 v[190:193], v149 offset:1024
	ds_read_b128 v[194:197], v149 offset:2048
	ds_read_b128 v[198:201], v149 offset:3072
	ds_read_b128 v[202:205], v149 offset:4096
	ds_read_b128 v[206:209], v149 offset:5120
	ds_read_b128 v[210:213], v149 offset:6144
	ds_read_b128 v[214:217], v149 offset:7168
	global_load_lds_dwordx4 v136, s[10:11]
	s_add_i32 m0, s29, 0xe000
	s_nop 0
	global_load_lds_dwordx4 v138, s[10:11]
	s_waitcnt vmcnt(8)
	s_waitcnt lgkmcnt(0)
	s_barrier
	s_setprio 1
	v_mfma_f32_16x16x32_bf16 v[124:127], v[150:153], v[182:185], v[124:127]
	v_mfma_f32_16x16x32_bf16 v[116:119], v[158:161], v[182:185], v[116:119]
	v_mfma_f32_16x16x32_bf16 v[108:111], v[150:153], v[194:197], v[108:111]
	v_mfma_f32_16x16x32_bf16 v[100:103], v[158:161], v[194:197], v[100:103]
	v_mfma_f32_16x16x32_bf16 v[92:95], v[150:153], v[202:205], v[92:95]
	v_mfma_f32_16x16x32_bf16 v[84:87], v[158:161], v[202:205], v[84:87]
	v_mfma_f32_16x16x32_bf16 v[76:79], v[150:153], v[210:213], v[76:79]
	v_mfma_f32_16x16x32_bf16 v[68:71], v[158:161], v[210:213], v[68:71]
	v_mfma_f32_16x16x32_bf16 v[124:127], v[154:157], v[190:193], v[124:127]
	v_mfma_f32_16x16x32_bf16 v[116:119], v[162:165], v[190:193], v[116:119]
	v_mfma_f32_16x16x32_bf16 v[108:111], v[154:157], v[198:201], v[108:111]
	v_mfma_f32_16x16x32_bf16 v[100:103], v[162:165], v[198:201], v[100:103]
	v_mfma_f32_16x16x32_bf16 v[92:95], v[154:157], v[206:209], v[92:95]
	v_mfma_f32_16x16x32_bf16 v[84:87], v[162:165], v[206:209], v[84:87]
	v_mfma_f32_16x16x32_bf16 v[76:79], v[154:157], v[214:217], v[76:79]
	v_mfma_f32_16x16x32_bf16 v[68:71], v[162:165], v[214:217], v[68:71]
	v_mfma_f32_16x16x32_bf16 v[120:123], v[166:169], v[182:185], v[120:123]
	v_mfma_f32_16x16x32_bf16 v[112:115], v[174:177], v[182:185], v[112:115]
	v_mfma_f32_16x16x32_bf16 v[104:107], v[166:169], v[194:197], v[104:107]
	v_mfma_f32_16x16x32_bf16 v[96:99], v[174:177], v[194:197], v[96:99]
	v_mfma_f32_16x16x32_bf16 v[88:91], v[166:169], v[202:205], v[88:91]
	v_mfma_f32_16x16x32_bf16 v[80:83], v[174:177], v[202:205], v[80:83]
	v_mfma_f32_16x16x32_bf16 v[72:75], v[166:169], v[210:213], v[72:75]
	v_mfma_f32_16x16x32_bf16 v[64:67], v[174:177], v[210:213], v[64:67]
	v_mfma_f32_16x16x32_bf16 v[120:123], v[170:173], v[190:193], v[120:123]
	v_mfma_f32_16x16x32_bf16 v[112:115], v[178:181], v[190:193], v[112:115]
	v_mfma_f32_16x16x32_bf16 v[104:107], v[170:173], v[198:201], v[104:107]
	v_mfma_f32_16x16x32_bf16 v[96:99], v[178:181], v[198:201], v[96:99]
	v_mfma_f32_16x16x32_bf16 v[88:91], v[170:173], v[206:209], v[88:91]
	v_mfma_f32_16x16x32_bf16 v[80:83], v[178:181], v[206:209], v[80:83]
	v_mfma_f32_16x16x32_bf16 v[72:75], v[170:173], v[214:217], v[72:75]
	v_mfma_f32_16x16x32_bf16 v[64:67], v[178:181], v[214:217], v[64:67]
	s_setprio 0
	s_barrier
	s_add_i32 s60, s51, s38
	s_mov_b32 m0, s60
	ds_read_b128 v[182:185], v149 offset:16384
	ds_read_b128 v[190:193], v149 offset:17408
	ds_read_b128 v[194:197], v149 offset:18432
	ds_read_b128 v[198:201], v149 offset:19456
	ds_read_b128 v[202:205], v149 offset:20480
	ds_read_b128 v[206:209], v149 offset:21504
	ds_read_b128 v[210:213], v149 offset:22528
	ds_read_b128 v[214:217], v149 offset:23552
	global_load_lds_dwordx4 v134, s[58:59]
	s_add_i32 m0, s60, 0x2000
	s_mov_b64 s[100:101], s[58:59]
	s_add_i32 s60, s52, s38
	global_load_lds_dwordx4 v132, s[58:59]
	s_add_u32 s58, s58, s4
	s_addc_u32 s59, s59, s5
	s_mov_b32 m0, s60
	s_nop 0
	global_load_lds_dwordx4 v134, s[58:59]
	s_add_i32 m0, s60, 0x2000
	s_nop 0
	global_load_lds_dwordx4 v132, s[58:59]
	s_mov_b32 m0, s29
	s_nop 0
	global_load_lds_dwordx4 v128, s[30:31]
	s_mov_b32 m0, s41
	s_nop 0
	global_load_lds_dwordx4 v130, s[30:31]
	s_waitcnt vmcnt(8)
	s_waitcnt lgkmcnt(0)
	s_barrier
	s_setprio 1
	v_mfma_f32_16x16x32_bf16 v[60:63], v[150:153], v[182:185], v[60:63]
	v_mfma_f32_16x16x32_bf16 v[52:55], v[158:161], v[182:185], v[52:55]
	v_mfma_f32_16x16x32_bf16 v[44:47], v[150:153], v[194:197], v[44:47]
	v_mfma_f32_16x16x32_bf16 v[36:39], v[158:161], v[194:197], v[36:39]
	v_mfma_f32_16x16x32_bf16 v[28:31], v[150:153], v[202:205], v[28:31]
	v_mfma_f32_16x16x32_bf16 v[20:23], v[158:161], v[202:205], v[20:23]
	v_mfma_f32_16x16x32_bf16 v[12:15], v[150:153], v[210:213], v[12:15]
	v_mfma_f32_16x16x32_bf16 v[4:7], v[158:161], v[210:213], v[4:7]
	v_mfma_f32_16x16x32_bf16 v[60:63], v[154:157], v[190:193], v[60:63]
	v_mfma_f32_16x16x32_bf16 v[52:55], v[162:165], v[190:193], v[52:55]
	v_mfma_f32_16x16x32_bf16 v[44:47], v[154:157], v[198:201], v[44:47]
	v_mfma_f32_16x16x32_bf16 v[36:39], v[162:165], v[198:201], v[36:39]
	v_mfma_f32_16x16x32_bf16 v[28:31], v[154:157], v[206:209], v[28:31]
	v_mfma_f32_16x16x32_bf16 v[20:23], v[162:165], v[206:209], v[20:23]
	v_mfma_f32_16x16x32_bf16 v[12:15], v[154:157], v[214:217], v[12:15]
	v_mfma_f32_16x16x32_bf16 v[4:7], v[162:165], v[214:217], v[4:7]
	v_mfma_f32_16x16x32_bf16 v[56:59], v[166:169], v[182:185], v[56:59]
	v_mfma_f32_16x16x32_bf16 v[48:51], v[174:177], v[182:185], v[48:51]
	v_mfma_f32_16x16x32_bf16 v[40:43], v[166:169], v[194:197], v[40:43]
	v_mfma_f32_16x16x32_bf16 v[32:35], v[174:177], v[194:197], v[32:35]
	v_mfma_f32_16x16x32_bf16 v[24:27], v[166:169], v[202:205], v[24:27]
	v_mfma_f32_16x16x32_bf16 v[16:19], v[174:177], v[202:205], v[16:19]
	v_mfma_f32_16x16x32_bf16 v[8:11], v[166:169], v[210:213], v[8:11]
	v_mfma_f32_16x16x32_bf16 v[0:3], v[174:177], v[210:213], v[0:3]
	v_mfma_f32_16x16x32_bf16 v[56:59], v[170:173], v[190:193], v[56:59]
	v_mfma_f32_16x16x32_bf16 v[48:51], v[178:181], v[190:193], v[48:51]
	v_mfma_f32_16x16x32_bf16 v[40:43], v[170:173], v[198:201], v[40:43]
	v_mfma_f32_16x16x32_bf16 v[32:35], v[178:181], v[198:201], v[32:35]
	v_mfma_f32_16x16x32_bf16 v[24:27], v[170:173], v[206:209], v[24:27]
	v_mfma_f32_16x16x32_bf16 v[16:19], v[178:181], v[206:209], v[16:19]
	v_mfma_f32_16x16x32_bf16 v[8:11], v[170:173], v[214:217], v[8:11]
	v_mfma_f32_16x16x32_bf16 v[0:3], v[178:181], v[214:217], v[0:3]
	s_setprio 0
	s_barrier
; #define PG8_STAGE(bufoff, gbase, voff) do { _Pragma("unroll") for (int _i = 0; _i < 2; ++_i) \
;         __builtin_amdgcn_global_load_lds((const unsigned*)((const char*)(gbase) + (voff)[_i]), (PG8_LAS unsigned*)(lds + (bufoff) + ldsw + _i * 8192), 16, 0, 0); } while (0)
; #define PG8_LDA(dst, b, h) do { _Pragma("unroll") for (int m = 0; m < 4; ++m) _Pragma("unroll") for (int k = 0; k < 2; ++k) dst[m][k] = *(const PG8_LAS bf16x8*)(lds + PG8_SA(b, h) + aoff + m * 2048 + k * 1024); } while (0)
; #define PG8_LDB(dst, b, h) do { _Pragma("unroll") for (int n = 0; n < 2; ++n) _Pragma("unroll") for (int k = 0; k < 2; ++k) dst[n][k] = *(const PG8_LAS bf16x8*)(lds + PG8_SB(b, h) + boff + n * 2048 + k * 1024); } while (0)
; #define PG8_MMA(ai, bj, At, Bt) do { __builtin_amdgcn_s_setprio(1); _Pragma("unroll") for (int m = 0; m < 4; ++m) _Pragma("unroll") for (int n = 0; n < 2; ++n) _Pragma("unroll") for (int k = 0; k < 2; ++k) \
;         acc[ai][bj][m][n] = __builtin_amdgcn_mfma_f32_16x16x32_bf16(Bt[n][k], At[m][k], acc[ai][bj][m][n], 0, 0, 0); __builtin_amdgcn_s_setprio(0); } while (0)
; #define PG8_WAIT_V(n) asm volatile("s_waitcnt vmcnt(" #n ")" ::: "memory")
; #define PG8_WAIT_L(n) asm volatile("s_waitcnt lgkmcnt(" #n ")" ::: "memory")
; #define PG8_BAR __builtin_amdgcn_s_barrier()
; #define PG8_SCHED __builtin_amdgcn_sched_barrier(0)
; template <class Epi, class Sched, bool ALIGN_EPI = false, bool SP2 = false>
; __device__ __forceinline__ void gemm_phase(PG8_LAS unsigned char* lds, const Gemm g, const Sched& S, const Epi& E) {
;     ...
;             PG8_LDB(B0, 1, 0); PG8_LDB(B1, 1, 1); PG8_SCHED; PG8_LDA(At, 1, 0); PG8_STAGE(PG8_SA(0, 1), a2 + hstepA, voffA);
;             PG8_WAIT_V(8); PG8_WAIT_L(0); PG8_BAR; PG8_MMA(0, 0, At, B0); PG8_MMA(0, 1, At, B1); PG8_BAR; PG8_SCHED;
;             PG8_LDA(At, 1, 1); PG8_STAGE(PG8_SB(1, 0), b3, voffB); PG8_STAGE(PG8_SB(1, 1), b3 + hstep, voffB); PG8_STAGE(PG8_SA(1, 0), a3, voffA);
;             PG8_WAIT_V(8); PG8_WAIT_L(0); PG8_BAR; PG8_MMA(1, 0, At, B0); PG8_MMA(1, 1, At, B1); PG8_BAR; PG8_SCHED;
	s_add_i32 s58, 0, 0x18000
	s_add_i32 s59, 0, 0x1c000
	v_add_u32_e32 v162, s58, v145
	v_add_u32_e32 v178, s59, v145
	ds_read_b128 v[150:153], v162
	ds_read_b128 v[154:157], v162 offset:1024
	ds_read_b128 v[158:161], v162 offset:2048
	ds_read_b128 v[162:165], v162 offset:3072
	ds_read_b128 v[166:169], v178
	ds_read_b128 v[170:173], v178 offset:1024
	ds_read_b128 v[174:177], v178 offset:2048
	ds_read_b128 v[178:181], v178 offset:3072
	s_mov_b64 vcc, s[30:31]
	s_add_u32 s30, s30, 0x40000
	s_addc_u32 s31, s31, 0
	s_mov_b32 m0, s42
	ds_read_b128 v[182:185], v149 offset:32768
	ds_read_b128 v[190:193], v149 offset:33792
	ds_read_b128 v[194:197], v149 offset:34816
	ds_read_b128 v[198:201], v149 offset:35840
	ds_read_b128 v[202:205], v149 offset:36864
	ds_read_b128 v[206:209], v149 offset:37888
	ds_read_b128 v[210:213], v149 offset:38912
	ds_read_b128 v[214:217], v149 offset:39936
	global_load_lds_dwordx4 v128, s[30:31]
	s_mov_b32 m0, s43
	s_nop 0
	global_load_lds_dwordx4 v130, s[30:31]
	s_waitcnt vmcnt(8)
	s_waitcnt lgkmcnt(0)
	s_barrier
	s_setprio 1
	v_mfma_f32_16x16x32_bf16 v[124:127], v[150:153], v[182:185], v[124:127]
	v_mfma_f32_16x16x32_bf16 v[116:119], v[158:161], v[182:185], v[116:119]
	v_mfma_f32_16x16x32_bf16 v[108:111], v[150:153], v[194:197], v[108:111]
	v_mfma_f32_16x16x32_bf16 v[100:103], v[158:161], v[194:197], v[100:103]
	v_mfma_f32_16x16x32_bf16 v[92:95], v[150:153], v[202:205], v[92:95]
	v_mfma_f32_16x16x32_bf16 v[84:87], v[158:161], v[202:205], v[84:87]
	v_mfma_f32_16x16x32_bf16 v[76:79], v[150:153], v[210:213], v[76:79]
	v_mfma_f32_16x16x32_bf16 v[68:71], v[158:161], v[210:213], v[68:71]
	v_mfma_f32_16x16x32_bf16 v[124:127], v[154:157], v[190:193], v[124:127]
	v_mfma_f32_16x16x32_bf16 v[116:119], v[162:165], v[190:193], v[116:119]
	v_mfma_f32_16x16x32_bf16 v[108:111], v[154:157], v[198:201], v[108:111]
	v_mfma_f32_16x16x32_bf16 v[100:103], v[162:165], v[198:201], v[100:103]
	v_mfma_f32_16x16x32_bf16 v[92:95], v[154:157], v[206:209], v[92:95]
	v_mfma_f32_16x16x32_bf16 v[84:87], v[162:165], v[206:209], v[84:87]
	v_mfma_f32_16x16x32_bf16 v[76:79], v[154:157], v[214:217], v[76:79]
	v_mfma_f32_16x16x32_bf16 v[68:71], v[162:165], v[214:217], v[68:71]
	v_mfma_f32_16x16x32_bf16 v[120:123], v[166:169], v[182:185], v[120:123]
	v_mfma_f32_16x16x32_bf16 v[112:115], v[174:177], v[182:185], v[112:115]
	v_mfma_f32_16x16x32_bf16 v[104:107], v[166:169], v[194:197], v[104:107]
	v_mfma_f32_16x16x32_bf16 v[96:99], v[174:177], v[194:197], v[96:99]
	v_mfma_f32_16x16x32_bf16 v[88:91], v[166:169], v[202:205], v[88:91]
	v_mfma_f32_16x16x32_bf16 v[80:83], v[174:177], v[202:205], v[80:83]
	v_mfma_f32_16x16x32_bf16 v[72:75], v[166:169], v[210:213], v[72:75]
	v_mfma_f32_16x16x32_bf16 v[64:67], v[174:177], v[210:213], v[64:67]
	v_mfma_f32_16x16x32_bf16 v[120:123], v[170:173], v[190:193], v[120:123]
	v_mfma_f32_16x16x32_bf16 v[112:115], v[178:181], v[190:193], v[112:115]
	v_mfma_f32_16x16x32_bf16 v[104:107], v[170:173], v[198:201], v[104:107]
	v_mfma_f32_16x16x32_bf16 v[96:99], v[178:181], v[198:201], v[96:99]
	v_mfma_f32_16x16x32_bf16 v[88:91], v[170:173], v[206:209], v[88:91]
	v_mfma_f32_16x16x32_bf16 v[80:83], v[178:181], v[206:209], v[80:83]
	v_mfma_f32_16x16x32_bf16 v[72:75], v[170:173], v[214:217], v[72:75]
	v_mfma_f32_16x16x32_bf16 v[64:67], v[178:181], v[214:217], v[64:67]
	s_setprio 0
	s_barrier
	s_add_i32 s30, s58, s38
	s_add_i32 m0, s30, 0xffffff80
	ds_read_b128 v[182:185], v149 offset:49152
	ds_read_b128 v[190:193], v149 offset:50176
	ds_read_b128 v[194:197], v149 offset:51200
	ds_read_b128 v[198:201], v149 offset:52224
	ds_read_b128 v[202:205], v149 offset:53248
	ds_read_b128 v[206:209], v149 offset:54272
	ds_read_b128 v[210:213], v149 offset:55296
	ds_read_b128 v[214:217], v149 offset:56320
	global_load_lds_dwordx4 v134, s[100:101] offset:128
	s_add_i32 m0, s30, 0x1f80
	s_add_i32 s30, s59, s38
	global_load_lds_dwordx4 v132, s[100:101] offset:128
	s_add_u32 s100, s100, s4
	s_addc_u32 s101, s101, s5
	s_add_i32 m0, s30, 0xffffff80
	s_nop 0
	global_load_lds_dwordx4 v134, s[100:101] offset:128
	s_add_i32 m0, s30, 0x1f80
	s_nop 0
	global_load_lds_dwordx4 v132, s[100:101] offset:128
	s_add_i32 m0, s46, 0xffffff80
	s_nop 0
	global_load_lds_dwordx4 v128, vcc offset:128
	s_add_i32 m0, s47, 0xffffff80
	s_nop 0
	global_load_lds_dwordx4 v130, vcc offset:128
	s_waitcnt vmcnt(8)
	s_waitcnt lgkmcnt(0)
	s_barrier
	s_setprio 1
	v_mfma_f32_16x16x32_bf16 v[60:63], v[150:153], v[182:185], v[60:63]
	v_mfma_f32_16x16x32_bf16 v[52:55], v[158:161], v[182:185], v[52:55]
	v_mfma_f32_16x16x32_bf16 v[44:47], v[150:153], v[194:197], v[44:47]
	v_mfma_f32_16x16x32_bf16 v[36:39], v[158:161], v[194:197], v[36:39]
	v_mfma_f32_16x16x32_bf16 v[28:31], v[150:153], v[202:205], v[28:31]
	v_mfma_f32_16x16x32_bf16 v[20:23], v[158:161], v[202:205], v[20:23]
	v_mfma_f32_16x16x32_bf16 v[12:15], v[150:153], v[210:213], v[12:15]
	v_mfma_f32_16x16x32_bf16 v[4:7], v[158:161], v[210:213], v[4:7]
	v_mfma_f32_16x16x32_bf16 v[60:63], v[154:157], v[190:193], v[60:63]
	v_mfma_f32_16x16x32_bf16 v[52:55], v[162:165], v[190:193], v[52:55]
	v_mfma_f32_16x16x32_bf16 v[44:47], v[154:157], v[198:201], v[44:47]
	v_mfma_f32_16x16x32_bf16 v[36:39], v[162:165], v[198:201], v[36:39]
	v_mfma_f32_16x16x32_bf16 v[28:31], v[154:157], v[206:209], v[28:31]
	v_mfma_f32_16x16x32_bf16 v[20:23], v[162:165], v[206:209], v[20:23]
	v_mfma_f32_16x16x32_bf16 v[12:15], v[154:157], v[214:217], v[12:15]
	v_mfma_f32_16x16x32_bf16 v[4:7], v[162:165], v[214:217], v[4:7]
	v_mfma_f32_16x16x32_bf16 v[56:59], v[166:169], v[182:185], v[56:59]
	v_mfma_f32_16x16x32_bf16 v[48:51], v[174:177], v[182:185], v[48:51]
	v_mfma_f32_16x16x32_bf16 v[40:43], v[166:169], v[194:197], v[40:43]
	v_mfma_f32_16x16x32_bf16 v[32:35], v[174:177], v[194:197], v[32:35]
	v_mfma_f32_16x16x32_bf16 v[24:27], v[166:169], v[202:205], v[24:27]
	v_mfma_f32_16x16x32_bf16 v[16:19], v[174:177], v[202:205], v[16:19]
	v_mfma_f32_16x16x32_bf16 v[8:11], v[166:169], v[210:213], v[8:11]
	v_mfma_f32_16x16x32_bf16 v[0:3], v[174:177], v[210:213], v[0:3]
	v_mfma_f32_16x16x32_bf16 v[56:59], v[170:173], v[190:193], v[56:59]
	v_mfma_f32_16x16x32_bf16 v[48:51], v[178:181], v[190:193], v[48:51]
	v_mfma_f32_16x16x32_bf16 v[40:43], v[170:173], v[198:201], v[40:43]
	v_mfma_f32_16x16x32_bf16 v[32:35], v[178:181], v[198:201], v[32:35]
	v_mfma_f32_16x16x32_bf16 v[24:27], v[170:173], v[206:209], v[24:27]
	v_mfma_f32_16x16x32_bf16 v[16:19], v[178:181], v[206:209], v[16:19]
	v_mfma_f32_16x16x32_bf16 v[8:11], v[170:173], v[214:217], v[8:11]
	v_mfma_f32_16x16x32_bf16 v[0:3], v[178:181], v[214:217], v[0:3]
	s_setprio 0
	s_barrier
	s_add_u32 s10, s10, 0x100
	s_addc_u32 s11, s11, 0
	s_add_u32 s34, s34, 0x100
	s_addc_u32 s35, s35, 0
	s_cmp_ge_i32 s57, s49
	s_mov_b32 s30, s57
	s_cbranch_scc0 .LBB0_1815

; #define PG8_STAGE(bufoff, gbase, voff) do { _Pragma("unroll") for (int _i = 0; _i < 2; ++_i) \
;         __builtin_amdgcn_global_load_lds((const unsigned*)((const char*)(gbase) + (voff)[_i]), (PG8_LAS unsigned*)(lds + (bufoff) + ldsw + _i * 8192), 16, 0, 0); } while (0)
; #define PG8_LDA(dst, b, h) do { _Pragma("unroll") for (int m = 0; m < 4; ++m) _Pragma("unroll") for (int k = 0; k < 2; ++k) dst[m][k] = *(const PG8_LAS bf16x8*)(lds + PG8_SA(b, h) + aoff + m * 2048 + k * 1024); } while (0)
; #define PG8_LDB(dst, b, h) do { _Pragma("unroll") for (int n = 0; n < 2; ++n) _Pragma("unroll") for (int k = 0; k < 2; ++k) dst[n][k] = *(const PG8_LAS bf16x8*)(lds + PG8_SB(b, h) + boff + n * 2048 + k * 1024); } while (0)
; #define PG8_MMA(ai, bj, At, Bt) do { __builtin_amdgcn_s_setprio(1); _Pragma("unroll") for (int m = 0; m < 4; ++m) _Pragma("unroll") for (int n = 0; n < 2; ++n) _Pragma("unroll") for (int k = 0; k < 2; ++k) \
;         acc[ai][bj][m][n] = __builtin_amdgcn_mfma_f32_16x16x32_bf16(Bt[n][k], At[m][k], acc[ai][bj][m][n], 0, 0, 0); __builtin_amdgcn_s_setprio(0); } while (0)
; #define PG8_WAIT_V(n) asm volatile("s_waitcnt vmcnt(" #n ")" ::: "memory")
; #define PG8_WAIT_L(n) asm volatile("s_waitcnt lgkmcnt(" #n ")" ::: "memory")
; template <class Epi, class Sched, bool ALIGN_EPI = false, bool SP2 = false>
; __device__ __forceinline__ void gemm_phase(PG8_LAS unsigned char* lds, const Gemm g, const Sched& S, const Epi& E) {
;     ...
;             const bool last = (t == nt - 2);
;             const char* a1 = cA + (size_t)(t + 1) * kstep;
;             const char* a2 = last ? nA : cA + (size_t)(t + 2) * kstep; const char* b2 = last ? nB : cB + (size_t)(t + 2) * kstep;
;             const char* a3 = a2 + kstep; const char* b3 = b2 + kstep;
;             if (last && has_next) S.a_ready(nxt);
;             if constexpr (SP2) {
;             PG8_LDB(B0, 0, 0); PG8_LDB(B1, 0, 1); PG8_SCHED; PG8_LDA(At, 0, 0); PG8_STAGE(PG8_SA(1, 1), a1 + hstepA, voffA);
;             PG8_WAIT_V(8); PG8_WAIT_L(0); PG8_BAR; PG8_MMA(0, 0, At, B0); PG8_MMA(0, 1, At, B1); PG8_BAR; PG8_SCHED;
;             PG8_LDA(At, 0, 1); PG8_STAGE(PG8_SB(0, 0), b2, voffB); PG8_STAGE(PG8_SB(0, 1), b2 + hstep, voffB); PG8_STAGE(PG8_SA(0, 0), a2, voffA);
;             PG8_WAIT_V(8); PG8_WAIT_L(0); PG8_BAR; PG8_MMA(1, 0, At, B0); PG8_MMA(1, 1, At, B1); PG8_BAR; PG8_SCHED;
.LBB0_1897:
	ds_read_b128 v[128:131], v169
	ds_read_b128 v[132:135], v169 offset:1024
	ds_read_b128 v[136:139], v169 offset:2048
	ds_read_b128 v[140:143], v169 offset:3072
	ds_read_b128 v[160:163], v170
	ds_read_b128 v[172:175], v170 offset:1024
	ds_read_b128 v[176:179], v170 offset:2048
	ds_read_b128 v[180:183], v170 offset:3072
	s_add_i32 s63, s38, 2
	s_add_u32 s64, s36, 0xfff50080
	s_addc_u32 s39, s37, -1
	s_cmp_eq_u32 s53, s38
	s_cselect_b32 s38, s4, s64
	s_cselect_b32 s39, s5, s39
	s_cselect_b32 s65, s35, s62
	s_cselect_b32 s64, s34, s61
	s_add_i32 m0, s44, 0xc000
	ds_read_b128 v[184:187], v171
	ds_read_b128 v[188:191], v171 offset:1024
	ds_read_b128 v[192:195], v171 offset:2048
	ds_read_b128 v[196:199], v171 offset:3072
	ds_read_b128 v[200:203], v171 offset:4096
	ds_read_b128 v[204:207], v171 offset:5120
	ds_read_b128 v[208:211], v171 offset:6144
	ds_read_b128 v[212:215], v171 offset:7168
	global_load_lds_dwordx4 v152, s[36:37]
	s_add_i32 m0, s44, 0xe000
	s_nop 0
	global_load_lds_dwordx4 v154, s[36:37]
	s_waitcnt vmcnt(8)
	s_waitcnt lgkmcnt(0)
	s_barrier
	s_setprio 1
	v_mfma_f32_16x16x32_bf16 v[124:127], v[128:131], v[184:187], v[124:127]
	v_mfma_f32_16x16x32_bf16 v[120:123], v[136:139], v[184:187], v[120:123]
	v_mfma_f32_16x16x32_bf16 v[108:111], v[128:131], v[192:195], v[108:111]
	v_mfma_f32_16x16x32_bf16 v[104:107], v[136:139], v[192:195], v[104:107]
	v_mfma_f32_16x16x32_bf16 v[92:95], v[128:131], v[200:203], v[92:95]
	v_mfma_f32_16x16x32_bf16 v[88:91], v[136:139], v[200:203], v[88:91]
	v_mfma_f32_16x16x32_bf16 v[76:79], v[128:131], v[208:211], v[76:79]
	v_mfma_f32_16x16x32_bf16 v[72:75], v[136:139], v[208:211], v[72:75]
	v_mfma_f32_16x16x32_bf16 v[124:127], v[132:135], v[188:191], v[124:127]
	v_mfma_f32_16x16x32_bf16 v[120:123], v[140:143], v[188:191], v[120:123]
	v_mfma_f32_16x16x32_bf16 v[108:111], v[132:135], v[196:199], v[108:111]
	v_mfma_f32_16x16x32_bf16 v[104:107], v[140:143], v[196:199], v[104:107]
	v_mfma_f32_16x16x32_bf16 v[92:95], v[132:135], v[204:207], v[92:95]
	v_mfma_f32_16x16x32_bf16 v[88:91], v[140:143], v[204:207], v[88:91]
	v_mfma_f32_16x16x32_bf16 v[76:79], v[132:135], v[212:215], v[76:79]
	v_mfma_f32_16x16x32_bf16 v[72:75], v[140:143], v[212:215], v[72:75]
	v_mfma_f32_16x16x32_bf16 v[116:119], v[160:163], v[184:187], v[116:119]
	v_mfma_f32_16x16x32_bf16 v[112:115], v[176:179], v[184:187], v[112:115]
	v_mfma_f32_16x16x32_bf16 v[100:103], v[160:163], v[192:195], v[100:103]
	v_mfma_f32_16x16x32_bf16 v[96:99], v[176:179], v[192:195], v[96:99]
	v_mfma_f32_16x16x32_bf16 v[84:87], v[160:163], v[200:203], v[84:87]
	v_mfma_f32_16x16x32_bf16 v[80:83], v[176:179], v[200:203], v[80:83]
	v_mfma_f32_16x16x32_bf16 v[68:71], v[160:163], v[208:211], v[68:71]
	v_mfma_f32_16x16x32_bf16 v[64:67], v[176:179], v[208:211], v[64:67]
	v_mfma_f32_16x16x32_bf16 v[116:119], v[172:175], v[188:191], v[116:119]
	v_mfma_f32_16x16x32_bf16 v[112:115], v[180:183], v[188:191], v[112:115]
	v_mfma_f32_16x16x32_bf16 v[100:103], v[172:175], v[196:199], v[100:103]
	v_mfma_f32_16x16x32_bf16 v[96:99], v[180:183], v[196:199], v[96:99]
	v_mfma_f32_16x16x32_bf16 v[84:87], v[172:175], v[204:207], v[84:87]
	v_mfma_f32_16x16x32_bf16 v[80:83], v[180:183], v[204:207], v[80:83]
	v_mfma_f32_16x16x32_bf16 v[68:71], v[172:175], v[212:215], v[68:71]
	v_mfma_f32_16x16x32_bf16 v[64:67], v[180:183], v[212:215], v[64:67]
	s_setprio 0
	s_barrier
	s_add_i32 s66, s54, s42
	s_mov_b32 m0, s66
	ds_read_b128 v[184:187], v171 offset:16384
	ds_read_b128 v[188:191], v171 offset:17408
	ds_read_b128 v[192:195], v171 offset:18432
	ds_read_b128 v[196:199], v171 offset:19456
	ds_read_b128 v[200:203], v171 offset:20480
	ds_read_b128 v[204:207], v171 offset:21504
	ds_read_b128 v[208:211], v171 offset:22528
	ds_read_b128 v[212:215], v171 offset:23552
	global_load_lds_dwordx4 v150, s[64:65]
	s_add_i32 m0, s66, 0x2000
	s_mov_b64 s[100:101], s[64:65]
	s_add_i32 s66, s55, s42
	global_load_lds_dwordx4 v148, s[64:65]
	s_add_u32 s64, s64, s6
	s_addc_u32 s65, s65, s7
	s_mov_b32 m0, s66
	s_nop 0
	global_load_lds_dwordx4 v150, s[64:65]
	s_add_i32 m0, s66, 0x2000
	s_nop 0
	global_load_lds_dwordx4 v148, s[64:65]
	s_mov_b32 m0, s44
	s_nop 0
	global_load_lds_dwordx4 v144, s[38:39]
	s_mov_b32 m0, s45
	s_nop 0
	global_load_lds_dwordx4 v146, s[38:39]
	s_waitcnt vmcnt(8)
	s_waitcnt lgkmcnt(0)
	s_barrier
	s_setprio 1
	v_mfma_f32_16x16x32_bf16 v[60:63], v[128:131], v[184:187], v[60:63]
	v_mfma_f32_16x16x32_bf16 v[56:59], v[136:139], v[184:187], v[56:59]
	v_mfma_f32_16x16x32_bf16 v[44:47], v[128:131], v[192:195], v[44:47]
	v_mfma_f32_16x16x32_bf16 v[40:43], v[136:139], v[192:195], v[40:43]
	v_mfma_f32_16x16x32_bf16 v[28:31], v[128:131], v[200:203], v[28:31]
	v_mfma_f32_16x16x32_bf16 v[24:27], v[136:139], v[200:203], v[24:27]
	v_mfma_f32_16x16x32_bf16 v[12:15], v[128:131], v[208:211], v[12:15]
	v_mfma_f32_16x16x32_bf16 v[8:11], v[136:139], v[208:211], v[8:11]
	v_mfma_f32_16x16x32_bf16 v[60:63], v[132:135], v[188:191], v[60:63]
	v_mfma_f32_16x16x32_bf16 v[56:59], v[140:143], v[188:191], v[56:59]
	v_mfma_f32_16x16x32_bf16 v[44:47], v[132:135], v[196:199], v[44:47]
	v_mfma_f32_16x16x32_bf16 v[40:43], v[140:143], v[196:199], v[40:43]
	v_mfma_f32_16x16x32_bf16 v[28:31], v[132:135], v[204:207], v[28:31]
	v_mfma_f32_16x16x32_bf16 v[24:27], v[140:143], v[204:207], v[24:27]
	v_mfma_f32_16x16x32_bf16 v[12:15], v[132:135], v[212:215], v[12:15]
	v_mfma_f32_16x16x32_bf16 v[8:11], v[140:143], v[212:215], v[8:11]
	v_mfma_f32_16x16x32_bf16 v[52:55], v[160:163], v[184:187], v[52:55]
	v_mfma_f32_16x16x32_bf16 v[48:51], v[176:179], v[184:187], v[48:51]
	v_mfma_f32_16x16x32_bf16 v[36:39], v[160:163], v[192:195], v[36:39]
	v_mfma_f32_16x16x32_bf16 v[32:35], v[176:179], v[192:195], v[32:35]
	v_mfma_f32_16x16x32_bf16 v[20:23], v[160:163], v[200:203], v[20:23]
	v_mfma_f32_16x16x32_bf16 v[16:19], v[176:179], v[200:203], v[16:19]
	v_mfma_f32_16x16x32_bf16 v[4:7], v[160:163], v[208:211], v[4:7]
	v_mfma_f32_16x16x32_bf16 v[0:3], v[176:179], v[208:211], v[0:3]
	v_mfma_f32_16x16x32_bf16 v[52:55], v[172:175], v[188:191], v[52:55]
	v_mfma_f32_16x16x32_bf16 v[48:51], v[180:183], v[188:191], v[48:51]
	v_mfma_f32_16x16x32_bf16 v[36:39], v[172:175], v[196:199], v[36:39]
	v_mfma_f32_16x16x32_bf16 v[32:35], v[180:183], v[196:199], v[32:35]
	v_mfma_f32_16x16x32_bf16 v[20:23], v[172:175], v[204:207], v[20:23]
	v_mfma_f32_16x16x32_bf16 v[16:19], v[180:183], v[204:207], v[16:19]
	v_mfma_f32_16x16x32_bf16 v[4:7], v[172:175], v[212:215], v[4:7]
	v_mfma_f32_16x16x32_bf16 v[0:3], v[180:183], v[212:215], v[0:3]
	s_setprio 0
	s_barrier
; #define PG8_STAGE(bufoff, gbase, voff) do { _Pragma("unroll") for (int _i = 0; _i < 2; ++_i) \
;         __builtin_amdgcn_global_load_lds((const unsigned*)((const char*)(gbase) + (voff)[_i]), (PG8_LAS unsigned*)(lds + (bufoff) + ldsw + _i * 8192), 16, 0, 0); } while (0)
; #define PG8_LDA(dst, b, h) do { _Pragma("unroll") for (int m = 0; m < 4; ++m) _Pragma("unroll") for (int k = 0; k < 2; ++k) dst[m][k] = *(const PG8_LAS bf16x8*)(lds + PG8_SA(b, h) + aoff + m * 2048 + k * 1024); } while (0)
; #define PG8_LDB(dst, b, h) do { _Pragma("unroll") for (int n = 0; n < 2; ++n) _Pragma("unroll") for (int k = 0; k < 2; ++k) dst[n][k] = *(const PG8_LAS bf16x8*)(lds + PG8_SB(b, h) + boff + n * 2048 + k * 1024); } while (0)
; #define PG8_MMA(ai, bj, At, Bt) do { __builtin_amdgcn_s_setprio(1); _Pragma("unroll") for (int m = 0; m < 4; ++m) _Pragma("unroll") for (int n = 0; n < 2; ++n) _Pragma("unroll") for (int k = 0; k < 2; ++k) \
;         acc[ai][bj][m][n] = __builtin_amdgcn_mfma_f32_16x16x32_bf16(Bt[n][k], At[m][k], acc[ai][bj][m][n], 0, 0, 0); __builtin_amdgcn_s_setprio(0); } while (0)
; #define PG8_WAIT_V(n) asm volatile("s_waitcnt vmcnt(" #n ")" ::: "memory")
; #define PG8_WAIT_L(n) asm volatile("s_waitcnt lgkmcnt(" #n ")" ::: "memory")
; #define PG8_BAR __builtin_amdgcn_s_barrier()
; #define PG8_SCHED __builtin_amdgcn_sched_barrier(0)
; template <class Epi, class Sched, bool ALIGN_EPI = false, bool SP2 = false>
; __device__ __forceinline__ void gemm_phase(PG8_LAS unsigned char* lds, const Gemm g, const Sched& S, const Epi& E) {
;     ...
;             PG8_LDB(B0, 1, 0); PG8_LDB(B1, 1, 1); PG8_SCHED; PG8_LDA(At, 1, 0); PG8_STAGE(PG8_SA(0, 1), a2 + hstepA, voffA);
;             PG8_WAIT_V(8); PG8_WAIT_L(0); PG8_BAR; PG8_MMA(0, 0, At, B0); PG8_MMA(0, 1, At, B1); PG8_BAR; PG8_SCHED;
;             PG8_LDA(At, 1, 1); PG8_STAGE(PG8_SB(1, 0), b3, voffB); PG8_STAGE(PG8_SB(1, 1), b3 + hstep, voffB); PG8_STAGE(PG8_SA(1, 0), a3, voffA);
;             PG8_WAIT_V(8); PG8_WAIT_L(0); PG8_BAR; PG8_MMA(1, 0, At, B0); PG8_MMA(1, 1, At, B1); PG8_BAR; PG8_SCHED;
	s_add_i32 s64, 0, 0x18000
	s_add_i32 s65, 0, 0x1c000
	v_add_u32_e32 v140, s64, v167
	v_add_u32_e32 v180, s65, v167
	ds_read_b128 v[128:131], v140
	ds_read_b128 v[132:135], v140 offset:1024
	ds_read_b128 v[136:139], v140 offset:2048
	ds_read_b128 v[140:143], v140 offset:3072
	ds_read_b128 v[160:163], v180
	ds_read_b128 v[172:175], v180 offset:1024
	ds_read_b128 v[176:179], v180 offset:2048
	ds_read_b128 v[180:183], v180 offset:3072
	s_mov_b64 vcc, s[38:39]
	s_add_u32 s38, s38, 0xb0000
	s_addc_u32 s39, s39, 0
	s_mov_b32 m0, s46
	ds_read_b128 v[184:187], v171 offset:32768
	ds_read_b128 v[188:191], v171 offset:33792
	ds_read_b128 v[192:195], v171 offset:34816
	ds_read_b128 v[196:199], v171 offset:35840
	ds_read_b128 v[200:203], v171 offset:36864
	ds_read_b128 v[204:207], v171 offset:37888
	ds_read_b128 v[208:211], v171 offset:38912
	ds_read_b128 v[212:215], v171 offset:39936
	global_load_lds_dwordx4 v144, s[38:39]
	s_mov_b32 m0, s47
	s_nop 0
	global_load_lds_dwordx4 v146, s[38:39]
	s_waitcnt vmcnt(8)
	s_waitcnt lgkmcnt(0)
	s_barrier
	s_setprio 1
	v_mfma_f32_16x16x32_bf16 v[124:127], v[128:131], v[184:187], v[124:127]
	v_mfma_f32_16x16x32_bf16 v[120:123], v[136:139], v[184:187], v[120:123]
	v_mfma_f32_16x16x32_bf16 v[108:111], v[128:131], v[192:195], v[108:111]
	v_mfma_f32_16x16x32_bf16 v[104:107], v[136:139], v[192:195], v[104:107]
	v_mfma_f32_16x16x32_bf16 v[92:95], v[128:131], v[200:203], v[92:95]
	v_mfma_f32_16x16x32_bf16 v[88:91], v[136:139], v[200:203], v[88:91]
	v_mfma_f32_16x16x32_bf16 v[76:79], v[128:131], v[208:211], v[76:79]
	v_mfma_f32_16x16x32_bf16 v[72:75], v[136:139], v[208:211], v[72:75]
	v_mfma_f32_16x16x32_bf16 v[124:127], v[132:135], v[188:191], v[124:127]
	v_mfma_f32_16x16x32_bf16 v[120:123], v[140:143], v[188:191], v[120:123]
	v_mfma_f32_16x16x32_bf16 v[108:111], v[132:135], v[196:199], v[108:111]
	v_mfma_f32_16x16x32_bf16 v[104:107], v[140:143], v[196:199], v[104:107]
	v_mfma_f32_16x16x32_bf16 v[92:95], v[132:135], v[204:207], v[92:95]
	v_mfma_f32_16x16x32_bf16 v[88:91], v[140:143], v[204:207], v[88:91]
	v_mfma_f32_16x16x32_bf16 v[76:79], v[132:135], v[212:215], v[76:79]
	v_mfma_f32_16x16x32_bf16 v[72:75], v[140:143], v[212:215], v[72:75]
	v_mfma_f32_16x16x32_bf16 v[116:119], v[160:163], v[184:187], v[116:119]
	v_mfma_f32_16x16x32_bf16 v[112:115], v[176:179], v[184:187], v[112:115]
	v_mfma_f32_16x16x32_bf16 v[100:103], v[160:163], v[192:195], v[100:103]
	v_mfma_f32_16x16x32_bf16 v[96:99], v[176:179], v[192:195], v[96:99]
	v_mfma_f32_16x16x32_bf16 v[84:87], v[160:163], v[200:203], v[84:87]
	v_mfma_f32_16x16x32_bf16 v[80:83], v[176:179], v[200:203], v[80:83]
	v_mfma_f32_16x16x32_bf16 v[68:71], v[160:163], v[208:211], v[68:71]
	v_mfma_f32_16x16x32_bf16 v[64:67], v[176:179], v[208:211], v[64:67]
	v_mfma_f32_16x16x32_bf16 v[116:119], v[172:175], v[188:191], v[116:119]
	v_mfma_f32_16x16x32_bf16 v[112:115], v[180:183], v[188:191], v[112:115]
	v_mfma_f32_16x16x32_bf16 v[100:103], v[172:175], v[196:199], v[100:103]
	v_mfma_f32_16x16x32_bf16 v[96:99], v[180:183], v[196:199], v[96:99]
	v_mfma_f32_16x16x32_bf16 v[84:87], v[172:175], v[204:207], v[84:87]
	v_mfma_f32_16x16x32_bf16 v[80:83], v[180:183], v[204:207], v[80:83]
	v_mfma_f32_16x16x32_bf16 v[68:71], v[172:175], v[212:215], v[68:71]
	v_mfma_f32_16x16x32_bf16 v[64:67], v[180:183], v[212:215], v[64:67]
	s_setprio 0
	s_barrier
	s_add_i32 s38, s64, s42
	s_add_i32 m0, s38, 0xffffff80
	ds_read_b128 v[184:187], v171 offset:49152
	ds_read_b128 v[188:191], v171 offset:50176
	ds_read_b128 v[192:195], v171 offset:51200
	ds_read_b128 v[196:199], v171 offset:52224
	ds_read_b128 v[200:203], v171 offset:53248
	ds_read_b128 v[204:207], v171 offset:54272
	ds_read_b128 v[208:211], v171 offset:55296
	ds_read_b128 v[212:215], v171 offset:56320
	global_load_lds_dwordx4 v150, s[100:101] offset:128
	s_add_i32 m0, s38, 0x1f80
	s_add_i32 s38, s65, s42
	global_load_lds_dwordx4 v148, s[100:101] offset:128
	s_add_u32 s100, s100, s6
	s_addc_u32 s101, s101, s7
	s_add_i32 m0, s38, 0xffffff80
	s_nop 0
	global_load_lds_dwordx4 v150, s[100:101] offset:128
	s_add_i32 m0, s38, 0x1f80
	s_nop 0
	global_load_lds_dwordx4 v148, s[100:101] offset:128
	s_add_i32 m0, s50, 0xffffff80
	s_nop 0
	global_load_lds_dwordx4 v144, vcc offset:128
	s_add_i32 m0, s51, 0xffffff80
	s_nop 0
	global_load_lds_dwordx4 v146, vcc offset:128
	s_waitcnt vmcnt(8)
	s_waitcnt lgkmcnt(0)
	s_barrier
	s_setprio 1
	v_mfma_f32_16x16x32_bf16 v[60:63], v[128:131], v[184:187], v[60:63]
	v_mfma_f32_16x16x32_bf16 v[56:59], v[136:139], v[184:187], v[56:59]
	v_mfma_f32_16x16x32_bf16 v[44:47], v[128:131], v[192:195], v[44:47]
	v_mfma_f32_16x16x32_bf16 v[40:43], v[136:139], v[192:195], v[40:43]
	v_mfma_f32_16x16x32_bf16 v[28:31], v[128:131], v[200:203], v[28:31]
	v_mfma_f32_16x16x32_bf16 v[24:27], v[136:139], v[200:203], v[24:27]
	v_mfma_f32_16x16x32_bf16 v[12:15], v[128:131], v[208:211], v[12:15]
	v_mfma_f32_16x16x32_bf16 v[8:11], v[136:139], v[208:211], v[8:11]
	v_mfma_f32_16x16x32_bf16 v[60:63], v[132:135], v[188:191], v[60:63]
	v_mfma_f32_16x16x32_bf16 v[56:59], v[140:143], v[188:191], v[56:59]
	v_mfma_f32_16x16x32_bf16 v[44:47], v[132:135], v[196:199], v[44:47]
	v_mfma_f32_16x16x32_bf16 v[40:43], v[140:143], v[196:199], v[40:43]
	v_mfma_f32_16x16x32_bf16 v[28:31], v[132:135], v[204:207], v[28:31]
	v_mfma_f32_16x16x32_bf16 v[24:27], v[140:143], v[204:207], v[24:27]
	v_mfma_f32_16x16x32_bf16 v[12:15], v[132:135], v[212:215], v[12:15]
	v_mfma_f32_16x16x32_bf16 v[8:11], v[140:143], v[212:215], v[8:11]
	v_mfma_f32_16x16x32_bf16 v[52:55], v[160:163], v[184:187], v[52:55]
	v_mfma_f32_16x16x32_bf16 v[48:51], v[176:179], v[184:187], v[48:51]
	v_mfma_f32_16x16x32_bf16 v[36:39], v[160:163], v[192:195], v[36:39]
	v_mfma_f32_16x16x32_bf16 v[32:35], v[176:179], v[192:195], v[32:35]
	v_mfma_f32_16x16x32_bf16 v[20:23], v[160:163], v[200:203], v[20:23]
	v_mfma_f32_16x16x32_bf16 v[16:19], v[176:179], v[200:203], v[16:19]
	v_mfma_f32_16x16x32_bf16 v[4:7], v[160:163], v[208:211], v[4:7]
	v_mfma_f32_16x16x32_bf16 v[0:3], v[176:179], v[208:211], v[0:3]
	v_mfma_f32_16x16x32_bf16 v[52:55], v[172:175], v[188:191], v[52:55]
	v_mfma_f32_16x16x32_bf16 v[48:51], v[180:183], v[188:191], v[48:51]
	v_mfma_f32_16x16x32_bf16 v[36:39], v[172:175], v[196:199], v[36:39]
	v_mfma_f32_16x16x32_bf16 v[32:35], v[180:183], v[196:199], v[32:35]
	v_mfma_f32_16x16x32_bf16 v[20:23], v[172:175], v[204:207], v[20:23]
	v_mfma_f32_16x16x32_bf16 v[16:19], v[180:183], v[204:207], v[16:19]
	v_mfma_f32_16x16x32_bf16 v[4:7], v[172:175], v[212:215], v[4:7]
	v_mfma_f32_16x16x32_bf16 v[0:3], v[180:183], v[212:215], v[0:3]
	s_setprio 0
	s_barrier
	s_add_u32 s36, s36, 0x100
	s_addc_u32 s37, s37, 0
	s_add_u32 s61, s61, 0x100
	s_addc_u32 s62, s62, 0
	s_cmp_ge_i32 s63, s52
	s_mov_b32 s38, s63
	s_cbranch_scc0 .LBB0_1897

; __global__ void __launch_bounds__(NWAVES * 64, 2) mk_fwd(Args args) {
	.amdhsa_kernel _Z6mk_fwd4Args
		.amdhsa_group_segment_fixed_size 0
		.amdhsa_private_segment_fixed_size 0
		.amdhsa_kernarg_size 512
		.amdhsa_user_sgpr_count 2
		.amdhsa_user_sgpr_dispatch_ptr 0
		.amdhsa_user_sgpr_queue_ptr 0
		.amdhsa_user_sgpr_kernarg_segment_ptr 1
		.amdhsa_user_sgpr_dispatch_id 0
		.amdhsa_user_sgpr_kernarg_preload_length 0
		.amdhsa_user_sgpr_kernarg_preload_offset 0
		.amdhsa_user_sgpr_private_segment_size 0
		.amdhsa_uses_dynamic_stack 0
		.amdhsa_enable_private_segment 0
		.amdhsa_system_sgpr_workgroup_id_x 1
		.amdhsa_system_sgpr_workgroup_id_y 0
		.amdhsa_system_sgpr_workgroup_id_z 0
		.amdhsa_system_sgpr_workgroup_info 0
		.amdhsa_system_vgpr_workitem_id 2
		.amdhsa_next_free_vgpr 252
		.amdhsa_next_free_sgpr 102
		.amdhsa_accum_offset 252
		.amdhsa_reserve_vcc 1
		.amdhsa_float_round_mode_32 0
		.amdhsa_float_round_mode_16_64 0
		.amdhsa_float_denorm_mode_32 3
		.amdhsa_float_denorm_mode_16_64 3
		.amdhsa_dx10_clamp 1
		.amdhsa_ieee_mode 1
		.amdhsa_fp16_overflow 0
		.amdhsa_tg_split 0
		.amdhsa_exception_fp_ieee_invalid_op 0
		.amdhsa_exception_fp_denorm_src 0
		.amdhsa_exception_fp_ieee_div_zero 0
		.amdhsa_exception_fp_ieee_overflow 0
		.amdhsa_exception_fp_ieee_underflow 0
		.amdhsa_exception_fp_ieee_inexact 0
		.amdhsa_exception_int_div_zero 0
	.end_amdhsa_kernel

; __global__ void __launch_bounds__(NWAVES * 64, 2) mk_fwd(Args args) {
;     extern __shared__ __attribute__((aligned(16))) unsigned char lds[];
amdhsa.kernels:
  - .agpr_count:     0
    .args:
      - .offset:         0
        .size:           256
        .value_kind:     by_value
      - .offset:         256
        .size:           4
        .value_kind:     hidden_block_count_x
      - .offset:         260
        .size:           4
        .value_kind:     hidden_block_count_y
      - .offset:         264
        .size:           4
        .value_kind:     hidden_block_count_z
      - .offset:         268
        .size:           2
        .value_kind:     hidden_group_size_x
      - .offset:         270
        .size:           2
        .value_kind:     hidden_group_size_y
      - .offset:         272
        .size:           2
        .value_kind:     hidden_group_size_z
      - .offset:         274
        .size:           2
        .value_kind:     hidden_remainder_x
      - .offset:         276
        .size:           2
        .value_kind:     hidden_remainder_y
      - .offset:         278
        .size:           2
        .value_kind:     hidden_remainder_z
      - .offset:         296
        .size:           8
        .value_kind:     hidden_global_offset_x
      - .offset:         304
        .size:           8
        .value_kind:     hidden_global_offset_y
      - .offset:         312
        .size:           8
        .value_kind:     hidden_global_offset_z
      - .offset:         320
        .size:           2
        .value_kind:     hidden_grid_dims
      - .offset:         344
        .size:           8
        .value_kind:     hidden_multigrid_sync_arg
      - .offset:         376
        .size:           4
        .value_kind:     hidden_dynamic_lds_size
    .group_segment_fixed_size: 0
    .kernarg_segment_align: 8
    .kernarg_segment_size: 512
    .language:       OpenCL C
    .language_version:
      - 2
      - 0
    .max_flat_workgroup_size: 512
    .name:           _Z6mk_fwd4Args
    .private_segment_fixed_size: 0
    .sgpr_count:     108
    .sgpr_spill_count: 93
    .symbol:         _Z6mk_fwd4Args.kd
    .uniform_work_group_size: 1
    .uses_dynamic_stack: false
    .vgpr_count:     252
    .vgpr_spill_count: 0
    .wavefront_size: 64
